# row-wise phases: streaming (nt) loads and stores for the residual stream
# speedup vs baseline: 1.0188x; 1.0007x over previous
; __device__ __forceinline__ void phase_rowwise(const void* xsrc_, bool sbf, void* xdst_, bool dbf, const bf16_t* Y, bf16_t* H, const float* mods, int lprev, int iprev, const float* lnpost, float resw, ...
;     ...
;     const int lane = tid_ & 63, wid = __builtin_amdgcn_readfirstlane(tid_ >> 6), gw = blockIdx.x * 8 + wid, NGW = gridDim.x * 8;
;     const float* xsrc = (const float*)xsrc_; const bf16_t* xsrcb = (const bf16_t*)xsrc_; float* xdst = (float*)xdst_; bf16_t* xdstb = (bf16_t*)xdst_;
;     for (int ch = gw; ch < M / 32; ch += NGW) {
;         const int b = ch >> 6;
;         f32x4 gp[4], na[4], ns[4];
; #pragma unroll
;         for (int j = 0; j < 4; ++j) { const int c = 4 * lane + 256 * j;
;             if (hasprev) { const f32x4 g = *(const f32x4*)(mods + ((size_t)lprev * 32 + b) * 9216 + iprev * 3072 + 2048 + c); const f32x4 lp = *(const f32x4*)(lnpost + c); gp[j] = g * lp * resw; }
;             else gp[j] = (f32x4){0.f, 0.f, 0.f, 0.f};
;             if (hasnext) { const f32x4 sh = *(const f32x4*)(mods + ((size_t)lnext * 32 + b) * 9216 + inext * 3072 + c); const f32x4 scl = *(const f32x4*)(mods + ((size_t)lnext * 32 + b) * 9216 + inext * 3072 + 1024 + c);
;                 const f32x4 lp = *(const f32x4*)(lnpre + c); na[j] = lp * (scl + 1.0f); ns[j] = sh; }
;             else { na[j] = (f32x4){0.f, 0.f, 0.f, 0.f}; ns[j] = na[j]; } }
;         f32x4 xn[2][4]; u32x2 xnb[2][4]; u32x2 yn[2][4];
;         { const size_t m0 = (size_t)ch * 32;
; #pragma unroll
;           for (int r = 0; r < 2; ++r)
; #pragma unroll
;             for (int j = 0; j < 4; ++j) { if (sbf) { xnb[r][j] = *(const u32x2*)(xsrcb + (m0 + r) * DM + 4 * lane + 256 * j); xn[r][j] = (f32x4){0.f, 0.f, 0.f, 0.f}; } else { xn[r][j] = *(const f32x4*)(xsrc + (m0 + r) * DM + 4 * lane + 256 * j); xnb[r][j] = (u32x2){0u, 0u}; }
;                 yn[r][j] = hasprev ? *(const u32x2*)(Y + (m0 + r) * DM + 4 * lane + 256 * j) : (u32x2){0u, 0u}; } }
.Lrw_MID:
	v_readfirstlane_b32 s40, v214
	v_readlane_b32 s41, v254, 46
	s_lshr_b32 s40, s40, 6
	s_add_i32 s40, s40, s41
	s_lshr_b32 s41, s40, 6
	v_and_b32_e32 v1, 63, v214
	v_lshlrev_b32_e32 v3, 5, v1
	v_lshlrev_b32_e32 v1, 4, v1
	v_mov_b32_e32 v212, 0x3a800000
	s_cmp_eq_u32 s74, 2
	s_cselect_b32 s42, 1, 0
	s_add_i32 s42, s73, s42
	s_add_i32 s43, s74, 1
	s_cmp_eq_u32 s74, 2
	s_cselect_b32 s43, 0, s43
	s_cmp_eq_u32 s74, 1
	s_cselect_b32 s90, 1.0, 0.5
	s_mov_b32 s91, s90
	v_readlane_b32 s44, v255, 22
	v_readlane_b32 s45, v255, 23
	s_lshl_b32 s46, s73, 5
	s_add_i32 s46, s46, s41
	s_mul_i32 s46, s46, 0x9000
	s_mul_i32 s47, s74, 0x3000
	s_add_i32 s46, s46, s47
	s_add_i32 s46, s46, 0x2000
	s_add_u32 s48, s44, s46
	s_addc_u32 s49, s45, 0
	v_readlane_b32 s52, v255, 16
	v_readlane_b32 s53, v255, 17
	s_mul_i32 s46, s73, 3
	s_add_i32 s46, s46, s74
	s_lshl_b32 s46, s46, 12
	s_add_u32 s52, s52, s46
	s_addc_u32 s53, s53, 0
	global_load_dwordx4 v[8:11], v3, s[48:49]
	global_load_dwordx4 v[12:15], v3, s[48:49] offset:16
	global_load_dwordx4 v[16:19], v3, s[48:49] offset:2048
	global_load_dwordx4 v[20:23], v3, s[48:49] offset:2064
	global_load_dwordx4 v[56:59], v3, s[52:53]
	global_load_dwordx4 v[60:63], v3, s[52:53] offset:16
	global_load_dwordx4 v[64:67], v3, s[52:53] offset:2048
	global_load_dwordx4 v[68:71], v3, s[52:53] offset:2064
	s_lshl_b32 s46, s42, 5
	s_add_i32 s46, s46, s41
	s_mul_i32 s46, s46, 0x9000
	s_mul_i32 s47, s43, 0x3000
	s_add_i32 s46, s46, s47
	s_add_u32 s50, s44, s46
	s_addc_u32 s51, s45, 0
	s_add_u32 s56, s50, 0x1000
	s_addc_u32 s57, s51, 0
	v_readlane_b32 s54, v255, 14
	v_readlane_b32 s55, v255, 15
	s_mul_i32 s46, s42, 3
	s_add_i32 s46, s46, s43
	s_lshl_b32 s46, s46, 12
	s_add_u32 s54, s54, s46
	s_addc_u32 s55, s55, 0
	global_load_dwordx4 v[24:27], v3, s[56:57]
	global_load_dwordx4 v[28:31], v3, s[56:57] offset:16
	global_load_dwordx4 v[32:35], v3, s[56:57] offset:2048
	global_load_dwordx4 v[36:39], v3, s[56:57] offset:2064
	global_load_dwordx4 v[72:75], v3, s[54:55]
	global_load_dwordx4 v[76:79], v3, s[54:55] offset:16
	global_load_dwordx4 v[80:83], v3, s[54:55] offset:2048
	global_load_dwordx4 v[84:87], v3, s[54:55] offset:2064
	global_load_dwordx4 v[40:43], v3, s[50:51]
	global_load_dwordx4 v[44:47], v3, s[50:51] offset:16
	global_load_dwordx4 v[48:51], v3, s[50:51] offset:2048
	global_load_dwordx4 v[52:55], v3, s[50:51] offset:2064
	s_lshl_b32 s46, s40, 16
	s_lshl_b32 s47, s40, 17
	v_readlane_b32 s72, v252, 6
	v_readlane_b32 s73, v252, 7
	s_add_u32 s72, s72, s46
	s_addc_u32 s73, s73, 0
	v_readlane_b32 s74, v252, 22
	v_readlane_b32 s75, v252, 23
	s_add_u32 s74, s74, s46
	s_addc_u32 s75, s75, 0
	v_readlane_b32 s76, v252, 6
	v_readlane_b32 s77, v252, 7
	s_add_u32 s76, s76, s46
	s_addc_u32 s77, s77, 0
	v_readlane_b32 s58, v252, 26
	v_readlane_b32 s59, v252, 27
	v_readlane_b32 s83, v255, 2
	s_add_u32 s58, s58, s46
	s_addc_u32 s59, s59, 0
	s_cmp_eq_u32 s83, 50
	s_cselect_b32 s76, s58, s76
	s_cselect_b32 s77, s59, s77
	v_readlane_b32 s78, v252, 20
	v_readlane_b32 s79, v252, 21
	s_add_u32 s78, s78, s46
	s_addc_u32 s79, s79, 0
	s_and_b32 s80, s40, 15
	s_lshl_b32 s80, s80, 1
	s_waitcnt vmcnt(12)
	v_pk_mul_f32 v[8:9], v[8:9], v[56:57]
	v_pk_mul_f32 v[10:11], v[10:11], v[58:59]
	v_pk_mul_f32 v[12:13], v[12:13], v[60:61]
	v_pk_mul_f32 v[14:15], v[14:15], v[62:63]
	v_pk_mul_f32 v[16:17], v[16:17], v[64:65]
	v_pk_mul_f32 v[18:19], v[18:19], v[66:67]
	v_pk_mul_f32 v[20:21], v[20:21], v[68:69]
	v_pk_mul_f32 v[22:23], v[22:23], v[70:71]
	v_pk_mul_f32 v[8:9], v[8:9], s[90:91]
	v_pk_mul_f32 v[10:11], v[10:11], s[90:91]
	v_pk_mul_f32 v[12:13], v[12:13], s[90:91]
	v_pk_mul_f32 v[14:15], v[14:15], s[90:91]
	v_pk_mul_f32 v[16:17], v[16:17], s[90:91]
	v_pk_mul_f32 v[18:19], v[18:19], s[90:91]
	v_pk_mul_f32 v[20:21], v[20:21], s[90:91]
	v_pk_mul_f32 v[22:23], v[22:23], s[90:91]
	s_waitcnt vmcnt(4)
	v_pk_add_f32 v[24:25], v[24:25], 1.0 op_sel_hi:[1,0]
	v_pk_add_f32 v[26:27], v[26:27], 1.0 op_sel_hi:[1,0]
	v_pk_add_f32 v[28:29], v[28:29], 1.0 op_sel_hi:[1,0]
	v_pk_add_f32 v[30:31], v[30:31], 1.0 op_sel_hi:[1,0]
	v_pk_add_f32 v[32:33], v[32:33], 1.0 op_sel_hi:[1,0]
	v_pk_add_f32 v[34:35], v[34:35], 1.0 op_sel_hi:[1,0]
	v_pk_add_f32 v[36:37], v[36:37], 1.0 op_sel_hi:[1,0]
	v_pk_add_f32 v[38:39], v[38:39], 1.0 op_sel_hi:[1,0]
	v_pk_mul_f32 v[24:25], v[72:73], v[24:25]
	v_pk_mul_f32 v[26:27], v[74:75], v[26:27]
	v_pk_mul_f32 v[28:29], v[76:77], v[28:29]
	v_pk_mul_f32 v[30:31], v[78:79], v[30:31]
	v_pk_mul_f32 v[32:33], v[80:81], v[32:33]
	v_pk_mul_f32 v[34:35], v[82:83], v[34:35]
	v_pk_mul_f32 v[36:37], v[84:85], v[36:37]
	v_pk_mul_f32 v[38:39], v[86:87], v[38:39]
	s_waitcnt vmcnt(0)
	s_mov_b32 s82, 0
	s_add_i32 s81, s80, 0
	s_add_i32 s81, s81, s82
	s_and_b32 s81, s81, 31
	s_lshl_b32 s83, s81, 11
	v_add_u32_e32 v2, s83, v1
	global_load_dwordx4 v[56:59], v2, s[72:73] nt
	global_load_dwordx4 v[60:63], v2, s[72:73] offset:1024 nt
	global_load_dwordx4 v[64:67], v2, s[74:75] nt
	global_load_dwordx4 v[68:71], v2, s[74:75] offset:1024 nt
	s_add_i32 s81, s80, 1
	s_add_i32 s81, s81, s82
	s_and_b32 s81, s81, 31
	s_lshl_b32 s83, s81, 11
	v_add_u32_e32 v2, s83, v1
	global_load_dwordx4 v[72:75], v2, s[72:73] nt
	global_load_dwordx4 v[76:79], v2, s[72:73] offset:1024 nt
	global_load_dwordx4 v[80:83], v2, s[74:75] nt
	global_load_dwordx4 v[84:87], v2, s[74:75] offset:1024 nt
	s_add_i32 s81, s80, 2
	s_add_i32 s81, s81, s82
	s_and_b32 s81, s81, 31
	s_lshl_b32 s83, s81, 11
	v_add_u32_e32 v2, s83, v1
	global_load_dwordx4 v[88:91], v2, s[72:73] nt
	global_load_dwordx4 v[92:95], v2, s[72:73] offset:1024 nt
	global_load_dwordx4 v[96:99], v2, s[74:75] nt
	global_load_dwordx4 v[100:103], v2, s[74:75] offset:1024 nt
	s_add_i32 s81, s80, 3
	s_add_i32 s81, s81, s82
	s_and_b32 s81, s81, 31
	s_lshl_b32 s83, s81, 11
	v_add_u32_e32 v2, s83, v1
	global_load_dwordx4 v[104:107], v2, s[72:73] nt
	global_load_dwordx4 v[108:111], v2, s[72:73] offset:1024 nt
	global_load_dwordx4 v[112:115], v2, s[74:75] nt
	global_load_dwordx4 v[116:119], v2, s[74:75] offset:1024 nt
	s_add_i32 s81, s80, 4
	s_add_i32 s81, s81, s82
	s_and_b32 s81, s81, 31
	s_lshl_b32 s83, s81, 11
	v_add_u32_e32 v2, s83, v1
	global_load_dwordx4 v[120:123], v2, s[72:73] nt
	global_load_dwordx4 v[124:127], v2, s[72:73] offset:1024 nt
	global_load_dwordx4 v[128:131], v2, s[74:75] nt
	global_load_dwordx4 v[132:135], v2, s[74:75] offset:1024 nt
	s_waitcnt vmcnt(16)
; __device__ __forceinline__ float bflo(unsigned u) { return __uint_as_float(u << 16); }
; __device__ __forceinline__ void phase_rowwise(const void* xsrc_, bool sbf, void* xdst_, bool dbf, const bf16_t* Y, bf16_t* H, const float* mods, int lprev, int iprev, const float* lnpost, float resw, ...
;     ...
;             if (hasprev) {
;                 f32x4 y[2][4]; float ss[2] = {0.f, 0.f};
; #pragma unroll
;                 for (int r = 0; r < 2; ++r)
; #pragma unroll
;                     for (int j = 0; j < 4; ++j) { const u32x2 u = yr[r][j]; y[r][j] = (f32x4){bflo(u.x), bfhi(u.x), bflo(u.y), bfhi(u.y)};
;                         ss[r] += (y[r][j].x * y[r][j].x + y[r][j].y * y[r][j].y) + (y[r][j].z * y[r][j].z + y[r][j].w * y[r][j].w); }
; #pragma unroll
;                 for (int off = 1; off < 64; off <<= 1) { ss[0] += __shfl_xor(ss[0], off); ss[1] += __shfl_xor(ss[1], off); }
; #pragma unroll
;                 for (int r = 0; r < 2; ++r) { const float rs = __builtin_amdgcn_rsqf(ss[r] * (1.f / DM) + EPS);
; #pragma unroll
;                     for (int j = 0; j < 4; ++j) x[r][j] = x[r][j] + gp[j] * (y[r][j] * rs); }
;             }
; #pragma unroll
;             for (int r = 0; r < 2; ++r)
; #pragma unroll
;                 for (int j = 0; j < 4; ++j) { if (hasprev) { if (dbf) { u32x2 w; w.x = cvtpk(x[r][j].x, x[r][j].y); w.y = cvtpk(x[r][j].z, x[r][j].w); *(u32x2*)(xdstb + (m + r) * DM + 4 * lane + 256 * j) = w; } else *(f32x4*)(xdst + (m + r) * DM + 4 * lane + 256 * j) = x[r][j]; } }
;             if (hasnext) {
;                 float ss[2] = {0.f, 0.f};
; #pragma unroll
;                 for (int r = 0; r < 2; ++r)
; #pragma unroll
;                     for (int j = 0; j < 4; ++j) ss[r] += (x[r][j].x * x[r][j].x + x[r][j].y * x[r][j].y) + (x[r][j].z * x[r][j].z + x[r][j].w * x[r][j].w);
; #pragma unroll
;                 for (int off = 1; off < 64; off <<= 1) { ss[0] += __shfl_xor(ss[0], off); ss[1] += __shfl_xor(ss[1], off); }
; #pragma unroll
;                 for (int r = 0; r < 2; ++r) { const float rs = __builtin_amdgcn_rsqf(ss[r] * (1.f / DM) + EPS);
; #pragma unroll
;                     for (int j = 0; j < 4; ++j) { const f32x4 h = (x[r][j] * rs) * na[j] + ns[j]; u32x2 w; w.x = cvtpk(h.x, h.y); w.y = cvtpk(h.z, h.w); *(u32x2*)(H + (m + r) * DM + 4 * lane + 256 * j) = w; } }
	v_lshlrev_b32_e32 v200, 16, v64
	v_and_b32_e32 v201, 0xffff0000, v64
	v_pk_mul_f32 v[204:205], v[200:201], v[200:201]
	v_lshlrev_b32_e32 v202, 16, v65
	v_and_b32_e32 v203, 0xffff0000, v65
	v_pk_mul_f32 v[206:207], v[202:203], v[202:203]
	v_lshlrev_b32_e32 v200, 16, v66
	v_and_b32_e32 v201, 0xffff0000, v66
	v_pk_fma_f32 v[204:205], v[200:201], v[200:201], v[204:205]
	v_lshlrev_b32_e32 v202, 16, v67
	v_and_b32_e32 v203, 0xffff0000, v67
	v_pk_fma_f32 v[206:207], v[202:203], v[202:203], v[206:207]
	v_lshlrev_b32_e32 v200, 16, v68
	v_and_b32_e32 v201, 0xffff0000, v68
	v_pk_fma_f32 v[204:205], v[200:201], v[200:201], v[204:205]
	v_lshlrev_b32_e32 v202, 16, v69
	v_and_b32_e32 v203, 0xffff0000, v69
	v_pk_fma_f32 v[206:207], v[202:203], v[202:203], v[206:207]
	v_lshlrev_b32_e32 v200, 16, v70
	v_and_b32_e32 v201, 0xffff0000, v70
	v_pk_fma_f32 v[204:205], v[200:201], v[200:201], v[204:205]
	v_lshlrev_b32_e32 v202, 16, v71
	v_and_b32_e32 v203, 0xffff0000, v71
	v_pk_fma_f32 v[206:207], v[202:203], v[202:203], v[206:207]
	v_pk_add_f32 v[204:205], v[204:205], v[206:207]
	v_add_f32_e32 v208, v204, v205
	v_lshlrev_b32_e32 v184, 16, v56
	v_and_b32_e32 v185, 0xffff0000, v56
	v_add_f32_dpp v208, v208, v208 quad_perm:[1,0,3,2] row_mask:0xf bank_mask:0xf
	v_lshlrev_b32_e32 v186, 16, v57
	v_and_b32_e32 v187, 0xffff0000, v57
	v_add_f32_dpp v208, v208, v208 quad_perm:[2,3,0,1] row_mask:0xf bank_mask:0xf
	v_lshlrev_b32_e32 v188, 16, v58
	v_and_b32_e32 v189, 0xffff0000, v58
	v_add_f32_dpp v208, v208, v208 row_half_mirror row_mask:0xf bank_mask:0xf
	v_lshlrev_b32_e32 v190, 16, v59
	v_and_b32_e32 v191, 0xffff0000, v59
	v_add_f32_dpp v208, v208, v208 row_mirror row_mask:0xf bank_mask:0xf
	v_lshlrev_b32_e32 v192, 16, v60
	v_and_b32_e32 v193, 0xffff0000, v60
	v_add_f32_dpp v208, v208, v208 row_bcast:15 row_mask:0xa bank_mask:0xf
	v_lshlrev_b32_e32 v194, 16, v61
	v_and_b32_e32 v195, 0xffff0000, v61
	v_add_f32_dpp v208, v208, v208 row_bcast:31 row_mask:0xc bank_mask:0xf
	v_lshlrev_b32_e32 v196, 16, v62
	v_and_b32_e32 v197, 0xffff0000, v62
	v_readlane_b32 s60, v208, 63
	s_nop 1
	v_lshlrev_b32_e32 v198, 16, v63
	v_and_b32_e32 v199, 0xffff0000, v63
	v_mov_b32_e32 v210, s60
	v_fmaak_f32 v210, v210, v212, 0x358637bd
	v_rsq_f32_e32 v210, v210
	s_nop 0
	v_lshlrev_b32_e32 v200, 16, v64
	v_and_b32_e32 v201, 0xffff0000, v64
	v_pk_mul_f32 v[200:201], v[200:201], v[210:211] op_sel_hi:[1,0]
	v_pk_fma_f32 v[184:185], v[8:9], v[200:201], v[184:185]
	v_lshlrev_b32_e32 v202, 16, v65
	v_and_b32_e32 v203, 0xffff0000, v65
	v_pk_mul_f32 v[202:203], v[202:203], v[210:211] op_sel_hi:[1,0]
	v_pk_fma_f32 v[186:187], v[10:11], v[202:203], v[186:187]
	v_lshlrev_b32_e32 v200, 16, v66
	v_and_b32_e32 v201, 0xffff0000, v66
	v_pk_mul_f32 v[200:201], v[200:201], v[210:211] op_sel_hi:[1,0]
	v_pk_fma_f32 v[188:189], v[12:13], v[200:201], v[188:189]
	v_lshlrev_b32_e32 v202, 16, v67
	v_and_b32_e32 v203, 0xffff0000, v67
	v_pk_mul_f32 v[202:203], v[202:203], v[210:211] op_sel_hi:[1,0]
	v_pk_fma_f32 v[190:191], v[14:15], v[202:203], v[190:191]
	v_lshlrev_b32_e32 v200, 16, v68
	v_and_b32_e32 v201, 0xffff0000, v68
	v_pk_mul_f32 v[200:201], v[200:201], v[210:211] op_sel_hi:[1,0]
	v_pk_fma_f32 v[192:193], v[16:17], v[200:201], v[192:193]
	v_lshlrev_b32_e32 v202, 16, v69
	v_and_b32_e32 v203, 0xffff0000, v69
	v_pk_mul_f32 v[202:203], v[202:203], v[210:211] op_sel_hi:[1,0]
	v_pk_fma_f32 v[194:195], v[18:19], v[202:203], v[194:195]
	v_lshlrev_b32_e32 v200, 16, v70
	v_and_b32_e32 v201, 0xffff0000, v70
	v_pk_mul_f32 v[200:201], v[200:201], v[210:211] op_sel_hi:[1,0]
	v_pk_fma_f32 v[196:197], v[20:21], v[200:201], v[196:197]
	v_lshlrev_b32_e32 v202, 16, v71
	v_and_b32_e32 v203, 0xffff0000, v71
	v_pk_mul_f32 v[202:203], v[202:203], v[210:211] op_sel_hi:[1,0]
	v_pk_fma_f32 v[198:199], v[22:23], v[202:203], v[198:199]
	s_add_i32 s81, s80, 0
	s_add_i32 s81, s81, s82
	s_and_b32 s81, s81, 31
	s_lshl_b32 s83, s81, 11
	v_add_u32_e32 v2, s83, v1
	v_cvt_pk_bf16_f32 v64, v184, v185
	v_cvt_pk_bf16_f32 v65, v186, v187
	v_cvt_pk_bf16_f32 v66, v188, v189
	v_cvt_pk_bf16_f32 v67, v190, v191
	v_cvt_pk_bf16_f32 v68, v192, v193
	v_cvt_pk_bf16_f32 v69, v194, v195
	v_cvt_pk_bf16_f32 v70, v196, v197
	v_cvt_pk_bf16_f32 v71, v198, v199
	global_store_dwordx4 v2, v[64:67], s[76:77] nt
	global_store_dwordx4 v2, v[68:71], s[76:77] offset:1024 nt
	v_pk_mul_f32 v[204:205], v[184:185], v[184:185]
	v_pk_mul_f32 v[206:207], v[186:187], v[186:187]
	v_pk_fma_f32 v[204:205], v[188:189], v[188:189], v[204:205]
	v_pk_fma_f32 v[206:207], v[190:191], v[190:191], v[206:207]
	v_pk_fma_f32 v[204:205], v[192:193], v[192:193], v[204:205]
	v_pk_fma_f32 v[206:207], v[194:195], v[194:195], v[206:207]
	v_pk_fma_f32 v[204:205], v[196:197], v[196:197], v[204:205]
	v_pk_fma_f32 v[206:207], v[198:199], v[198:199], v[206:207]
	v_pk_add_f32 v[204:205], v[204:205], v[206:207]
	v_add_f32_e32 v208, v204, v205
	s_nop 0
	s_nop 0
	v_add_f32_dpp v208, v208, v208 quad_perm:[1,0,3,2] row_mask:0xf bank_mask:0xf
	s_nop 0
	s_nop 0
	v_add_f32_dpp v208, v208, v208 quad_perm:[2,3,0,1] row_mask:0xf bank_mask:0xf
	s_nop 0
	s_nop 0
	v_add_f32_dpp v208, v208, v208 row_half_mirror row_mask:0xf bank_mask:0xf
	s_nop 0
	s_nop 0
	v_add_f32_dpp v208, v208, v208 row_mirror row_mask:0xf bank_mask:0xf
	s_nop 0
	s_nop 0
	v_add_f32_dpp v208, v208, v208 row_bcast:15 row_mask:0xa bank_mask:0xf
	s_nop 0
	s_nop 0
	v_add_f32_dpp v208, v208, v208 row_bcast:31 row_mask:0xc bank_mask:0xf
	s_nop 0
	s_nop 0
	v_readlane_b32 s60, v208, 63
	s_nop 1
	v_mov_b32_e32 v210, s60
	v_fmaak_f32 v210, v210, v212, 0x358637bd
	v_rsq_f32_e32 v210, v210
	s_nop 0
	v_pk_mul_f32 v[200:201], v[184:185], v[210:211] op_sel_hi:[1,0]
; __device__ __forceinline__ float bflo(unsigned u) { return __uint_as_float(u << 16); }
; __device__ __forceinline__ void phase_rowwise(const void* xsrc_, bool sbf, void* xdst_, bool dbf, const bf16_t* Y, bf16_t* H, const float* mods, int lprev, int iprev, const float* lnpost, float resw, ...
;     ...
;             if (hasprev) {
;                 f32x4 y[2][4]; float ss[2] = {0.f, 0.f};
; #pragma unroll
;                 for (int r = 0; r < 2; ++r)
; #pragma unroll
;                     for (int j = 0; j < 4; ++j) { const u32x2 u = yr[r][j]; y[r][j] = (f32x4){bflo(u.x), bfhi(u.x), bflo(u.y), bfhi(u.y)};
;                         ss[r] += (y[r][j].x * y[r][j].x + y[r][j].y * y[r][j].y) + (y[r][j].z * y[r][j].z + y[r][j].w * y[r][j].w); }
; #pragma unroll
;                 for (int off = 1; off < 64; off <<= 1) { ss[0] += __shfl_xor(ss[0], off); ss[1] += __shfl_xor(ss[1], off); }
; #pragma unroll
;                 for (int r = 0; r < 2; ++r) { const float rs = __builtin_amdgcn_rsqf(ss[r] * (1.f / DM) + EPS);
; #pragma unroll
;                     for (int j = 0; j < 4; ++j) x[r][j] = x[r][j] + gp[j] * (y[r][j] * rs); }
;             }
; #pragma unroll
;             for (int r = 0; r < 2; ++r)
; #pragma unroll
;                 for (int j = 0; j < 4; ++j) { if (hasprev) { if (dbf) { u32x2 w; w.x = cvtpk(x[r][j].x, x[r][j].y); w.y = cvtpk(x[r][j].z, x[r][j].w); *(u32x2*)(xdstb + (m + r) * DM + 4 * lane + 256 * j) = w; } else *(f32x4*)(xdst + (m + r) * DM + 4 * lane + 256 * j) = x[r][j]; } }
;             if (hasnext) {
;                 float ss[2] = {0.f, 0.f};
; #pragma unroll
;                 for (int r = 0; r < 2; ++r)
; #pragma unroll
;                     for (int j = 0; j < 4; ++j) ss[r] += (x[r][j].x * x[r][j].x + x[r][j].y * x[r][j].y) + (x[r][j].z * x[r][j].z + x[r][j].w * x[r][j].w);
; #pragma unroll
;                 for (int off = 1; off < 64; off <<= 1) { ss[0] += __shfl_xor(ss[0], off); ss[1] += __shfl_xor(ss[1], off); }
; #pragma unroll
;                 for (int r = 0; r < 2; ++r) { const float rs = __builtin_amdgcn_rsqf(ss[r] * (1.f / DM) + EPS);
; #pragma unroll
;                     for (int j = 0; j < 4; ++j) { const f32x4 h = (x[r][j] * rs) * na[j] + ns[j]; u32x2 w; w.x = cvtpk(h.x, h.y); w.y = cvtpk(h.z, h.w); *(u32x2*)(H + (m + r) * DM + 4 * lane + 256 * j) = w; } }
	v_pk_fma_f32 v[200:201], v[200:201], v[24:25], v[40:41]
	v_cvt_pk_bf16_f32 v56, v200, v201
	v_pk_mul_f32 v[202:203], v[186:187], v[210:211] op_sel_hi:[1,0]
	v_pk_fma_f32 v[202:203], v[202:203], v[26:27], v[42:43]
	v_cvt_pk_bf16_f32 v57, v202, v203
	v_pk_mul_f32 v[200:201], v[188:189], v[210:211] op_sel_hi:[1,0]
	v_pk_fma_f32 v[200:201], v[200:201], v[28:29], v[44:45]
	v_cvt_pk_bf16_f32 v58, v200, v201
	v_pk_mul_f32 v[202:203], v[190:191], v[210:211] op_sel_hi:[1,0]
	v_pk_fma_f32 v[202:203], v[202:203], v[30:31], v[46:47]
	v_cvt_pk_bf16_f32 v59, v202, v203
	v_pk_mul_f32 v[200:201], v[192:193], v[210:211] op_sel_hi:[1,0]
	v_pk_fma_f32 v[200:201], v[200:201], v[32:33], v[48:49]
	v_cvt_pk_bf16_f32 v60, v200, v201
	v_pk_mul_f32 v[202:203], v[194:195], v[210:211] op_sel_hi:[1,0]
	v_pk_fma_f32 v[202:203], v[202:203], v[34:35], v[50:51]
	v_cvt_pk_bf16_f32 v61, v202, v203
	v_pk_mul_f32 v[200:201], v[196:197], v[210:211] op_sel_hi:[1,0]
	v_pk_fma_f32 v[200:201], v[200:201], v[36:37], v[52:53]
	v_cvt_pk_bf16_f32 v62, v200, v201
	v_pk_mul_f32 v[202:203], v[198:199], v[210:211] op_sel_hi:[1,0]
	v_pk_fma_f32 v[202:203], v[202:203], v[38:39], v[54:55]
	v_cvt_pk_bf16_f32 v63, v202, v203
	global_store_dwordx4 v2, v[56:59], s[78:79] nt
	global_store_dwordx4 v2, v[60:63], s[78:79] offset:1024 nt
	s_add_i32 s81, s80, 5
	s_add_i32 s81, s81, s82
	s_and_b32 s81, s81, 31
	s_lshl_b32 s83, s81, 11
	v_add_u32_e32 v2, s83, v1
	global_load_dwordx4 v[136:139], v2, s[72:73] nt
	global_load_dwordx4 v[140:143], v2, s[72:73] offset:1024 nt
	global_load_dwordx4 v[144:147], v2, s[74:75] nt
	global_load_dwordx4 v[148:151], v2, s[74:75] offset:1024 nt
	s_waitcnt vmcnt(20)
	v_lshlrev_b32_e32 v200, 16, v80
	v_and_b32_e32 v201, 0xffff0000, v80
	v_pk_mul_f32 v[204:205], v[200:201], v[200:201]
	v_lshlrev_b32_e32 v202, 16, v81
	v_and_b32_e32 v203, 0xffff0000, v81
	v_pk_mul_f32 v[206:207], v[202:203], v[202:203]
	v_lshlrev_b32_e32 v200, 16, v82
	v_and_b32_e32 v201, 0xffff0000, v82
	v_pk_fma_f32 v[204:205], v[200:201], v[200:201], v[204:205]
	v_lshlrev_b32_e32 v202, 16, v83
	v_and_b32_e32 v203, 0xffff0000, v83
	v_pk_fma_f32 v[206:207], v[202:203], v[202:203], v[206:207]
	v_lshlrev_b32_e32 v200, 16, v84
	v_and_b32_e32 v201, 0xffff0000, v84
	v_pk_fma_f32 v[204:205], v[200:201], v[200:201], v[204:205]
	v_lshlrev_b32_e32 v202, 16, v85
	v_and_b32_e32 v203, 0xffff0000, v85
	v_pk_fma_f32 v[206:207], v[202:203], v[202:203], v[206:207]
	v_lshlrev_b32_e32 v200, 16, v86
	v_and_b32_e32 v201, 0xffff0000, v86
	v_pk_fma_f32 v[204:205], v[200:201], v[200:201], v[204:205]
	v_lshlrev_b32_e32 v202, 16, v87
	v_and_b32_e32 v203, 0xffff0000, v87
	v_pk_fma_f32 v[206:207], v[202:203], v[202:203], v[206:207]
	v_pk_add_f32 v[204:205], v[204:205], v[206:207]
	v_add_f32_e32 v208, v204, v205
	v_lshlrev_b32_e32 v184, 16, v72
	v_and_b32_e32 v185, 0xffff0000, v72
	v_add_f32_dpp v208, v208, v208 quad_perm:[1,0,3,2] row_mask:0xf bank_mask:0xf
	v_lshlrev_b32_e32 v186, 16, v73
	v_and_b32_e32 v187, 0xffff0000, v73
	v_add_f32_dpp v208, v208, v208 quad_perm:[2,3,0,1] row_mask:0xf bank_mask:0xf
	v_lshlrev_b32_e32 v188, 16, v74
	v_and_b32_e32 v189, 0xffff0000, v74
	v_add_f32_dpp v208, v208, v208 row_half_mirror row_mask:0xf bank_mask:0xf
	v_lshlrev_b32_e32 v190, 16, v75
	v_and_b32_e32 v191, 0xffff0000, v75
	v_add_f32_dpp v208, v208, v208 row_mirror row_mask:0xf bank_mask:0xf
	v_lshlrev_b32_e32 v192, 16, v76
	v_and_b32_e32 v193, 0xffff0000, v76
	v_add_f32_dpp v208, v208, v208 row_bcast:15 row_mask:0xa bank_mask:0xf
	v_lshlrev_b32_e32 v194, 16, v77
	v_and_b32_e32 v195, 0xffff0000, v77
	v_add_f32_dpp v208, v208, v208 row_bcast:31 row_mask:0xc bank_mask:0xf
	v_lshlrev_b32_e32 v196, 16, v78
	v_and_b32_e32 v197, 0xffff0000, v78
	v_readlane_b32 s60, v208, 63
	s_nop 1
	v_lshlrev_b32_e32 v198, 16, v79
	v_and_b32_e32 v199, 0xffff0000, v79
	v_mov_b32_e32 v210, s60
	v_fmaak_f32 v210, v210, v212, 0x358637bd
	v_rsq_f32_e32 v210, v210
	s_nop 0
	v_lshlrev_b32_e32 v200, 16, v80
	v_and_b32_e32 v201, 0xffff0000, v80
	v_pk_mul_f32 v[200:201], v[200:201], v[210:211] op_sel_hi:[1,0]
	v_pk_fma_f32 v[184:185], v[8:9], v[200:201], v[184:185]
	v_lshlrev_b32_e32 v202, 16, v81
	v_and_b32_e32 v203, 0xffff0000, v81
	v_pk_mul_f32 v[202:203], v[202:203], v[210:211] op_sel_hi:[1,0]
	v_pk_fma_f32 v[186:187], v[10:11], v[202:203], v[186:187]
	v_lshlrev_b32_e32 v200, 16, v82
	v_and_b32_e32 v201, 0xffff0000, v82
	v_pk_mul_f32 v[200:201], v[200:201], v[210:211] op_sel_hi:[1,0]
	v_pk_fma_f32 v[188:189], v[12:13], v[200:201], v[188:189]
	v_lshlrev_b32_e32 v202, 16, v83
	v_and_b32_e32 v203, 0xffff0000, v83
	v_pk_mul_f32 v[202:203], v[202:203], v[210:211] op_sel_hi:[1,0]
	v_pk_fma_f32 v[190:191], v[14:15], v[202:203], v[190:191]
	v_lshlrev_b32_e32 v200, 16, v84
	v_and_b32_e32 v201, 0xffff0000, v84
	v_pk_mul_f32 v[200:201], v[200:201], v[210:211] op_sel_hi:[1,0]
	v_pk_fma_f32 v[192:193], v[16:17], v[200:201], v[192:193]
	v_lshlrev_b32_e32 v202, 16, v85
	v_and_b32_e32 v203, 0xffff0000, v85
	v_pk_mul_f32 v[202:203], v[202:203], v[210:211] op_sel_hi:[1,0]
	v_pk_fma_f32 v[194:195], v[18:19], v[202:203], v[194:195]
	v_lshlrev_b32_e32 v200, 16, v86
	v_and_b32_e32 v201, 0xffff0000, v86
	v_pk_mul_f32 v[200:201], v[200:201], v[210:211] op_sel_hi:[1,0]
	v_pk_fma_f32 v[196:197], v[20:21], v[200:201], v[196:197]
	v_lshlrev_b32_e32 v202, 16, v87
	v_and_b32_e32 v203, 0xffff0000, v87
	v_pk_mul_f32 v[202:203], v[202:203], v[210:211] op_sel_hi:[1,0]
	v_pk_fma_f32 v[198:199], v[22:23], v[202:203], v[198:199]
	s_add_i32 s81, s80, 1
	s_add_i32 s81, s81, s82
	s_and_b32 s81, s81, 31
	s_lshl_b32 s83, s81, 11
	v_add_u32_e32 v2, s83, v1
	v_cvt_pk_bf16_f32 v80, v184, v185
; __device__ __forceinline__ float bflo(unsigned u) { return __uint_as_float(u << 16); }
; __device__ __forceinline__ void phase_rowwise(const void* xsrc_, bool sbf, void* xdst_, bool dbf, const bf16_t* Y, bf16_t* H, const float* mods, int lprev, int iprev, const float* lnpost, float resw, ...
;     ...
;             if (hasprev) {
;                 f32x4 y[2][4]; float ss[2] = {0.f, 0.f};
; #pragma unroll
;                 for (int r = 0; r < 2; ++r)
; #pragma unroll
;                     for (int j = 0; j < 4; ++j) { const u32x2 u = yr[r][j]; y[r][j] = (f32x4){bflo(u.x), bfhi(u.x), bflo(u.y), bfhi(u.y)};
;                         ss[r] += (y[r][j].x * y[r][j].x + y[r][j].y * y[r][j].y) + (y[r][j].z * y[r][j].z + y[r][j].w * y[r][j].w); }
; #pragma unroll
;                 for (int off = 1; off < 64; off <<= 1) { ss[0] += __shfl_xor(ss[0], off); ss[1] += __shfl_xor(ss[1], off); }
; #pragma unroll
;                 for (int r = 0; r < 2; ++r) { const float rs = __builtin_amdgcn_rsqf(ss[r] * (1.f / DM) + EPS);
; #pragma unroll
;                     for (int j = 0; j < 4; ++j) x[r][j] = x[r][j] + gp[j] * (y[r][j] * rs); }
;             }
; #pragma unroll
;             for (int r = 0; r < 2; ++r)
; #pragma unroll
;                 for (int j = 0; j < 4; ++j) { if (hasprev) { if (dbf) { u32x2 w; w.x = cvtpk(x[r][j].x, x[r][j].y); w.y = cvtpk(x[r][j].z, x[r][j].w); *(u32x2*)(xdstb + (m + r) * DM + 4 * lane + 256 * j) = w; } else *(f32x4*)(xdst + (m + r) * DM + 4 * lane + 256 * j) = x[r][j]; } }
;             if (hasnext) {
;                 float ss[2] = {0.f, 0.f};
; #pragma unroll
;                 for (int r = 0; r < 2; ++r)
; #pragma unroll
;                     for (int j = 0; j < 4; ++j) ss[r] += (x[r][j].x * x[r][j].x + x[r][j].y * x[r][j].y) + (x[r][j].z * x[r][j].z + x[r][j].w * x[r][j].w);
; #pragma unroll
;                 for (int off = 1; off < 64; off <<= 1) { ss[0] += __shfl_xor(ss[0], off); ss[1] += __shfl_xor(ss[1], off); }
; #pragma unroll
;                 for (int r = 0; r < 2; ++r) { const float rs = __builtin_amdgcn_rsqf(ss[r] * (1.f / DM) + EPS);
; #pragma unroll
;                     for (int j = 0; j < 4; ++j) { const f32x4 h = (x[r][j] * rs) * na[j] + ns[j]; u32x2 w; w.x = cvtpk(h.x, h.y); w.y = cvtpk(h.z, h.w); *(u32x2*)(H + (m + r) * DM + 4 * lane + 256 * j) = w; } }
	v_cvt_pk_bf16_f32 v81, v186, v187
	v_cvt_pk_bf16_f32 v82, v188, v189
	v_cvt_pk_bf16_f32 v83, v190, v191
	v_cvt_pk_bf16_f32 v84, v192, v193
	v_cvt_pk_bf16_f32 v85, v194, v195
	v_cvt_pk_bf16_f32 v86, v196, v197
	v_cvt_pk_bf16_f32 v87, v198, v199
	global_store_dwordx4 v2, v[80:83], s[76:77] nt
	global_store_dwordx4 v2, v[84:87], s[76:77] offset:1024 nt
	v_pk_mul_f32 v[204:205], v[184:185], v[184:185]
	v_pk_mul_f32 v[206:207], v[186:187], v[186:187]
	v_pk_fma_f32 v[204:205], v[188:189], v[188:189], v[204:205]
	v_pk_fma_f32 v[206:207], v[190:191], v[190:191], v[206:207]
	v_pk_fma_f32 v[204:205], v[192:193], v[192:193], v[204:205]
	v_pk_fma_f32 v[206:207], v[194:195], v[194:195], v[206:207]
	v_pk_fma_f32 v[204:205], v[196:197], v[196:197], v[204:205]
	v_pk_fma_f32 v[206:207], v[198:199], v[198:199], v[206:207]
	v_pk_add_f32 v[204:205], v[204:205], v[206:207]
	v_add_f32_e32 v208, v204, v205
	s_nop 0
	s_nop 0
	v_add_f32_dpp v208, v208, v208 quad_perm:[1,0,3,2] row_mask:0xf bank_mask:0xf
	s_nop 0
	s_nop 0
	v_add_f32_dpp v208, v208, v208 quad_perm:[2,3,0,1] row_mask:0xf bank_mask:0xf
	s_nop 0
	s_nop 0
	v_add_f32_dpp v208, v208, v208 row_half_mirror row_mask:0xf bank_mask:0xf
	s_nop 0
	s_nop 0
	v_add_f32_dpp v208, v208, v208 row_mirror row_mask:0xf bank_mask:0xf
	s_nop 0
	s_nop 0
	v_add_f32_dpp v208, v208, v208 row_bcast:15 row_mask:0xa bank_mask:0xf
	s_nop 0
	s_nop 0
	v_add_f32_dpp v208, v208, v208 row_bcast:31 row_mask:0xc bank_mask:0xf
	s_nop 0
	s_nop 0
	v_readlane_b32 s60, v208, 63
	s_nop 1
	v_mov_b32_e32 v210, s60
	v_fmaak_f32 v210, v210, v212, 0x358637bd
	v_rsq_f32_e32 v210, v210
	s_nop 0
	v_pk_mul_f32 v[200:201], v[184:185], v[210:211] op_sel_hi:[1,0]
	v_pk_fma_f32 v[200:201], v[200:201], v[24:25], v[40:41]
	v_cvt_pk_bf16_f32 v72, v200, v201
	v_pk_mul_f32 v[202:203], v[186:187], v[210:211] op_sel_hi:[1,0]
	v_pk_fma_f32 v[202:203], v[202:203], v[26:27], v[42:43]
	v_cvt_pk_bf16_f32 v73, v202, v203
	v_pk_mul_f32 v[200:201], v[188:189], v[210:211] op_sel_hi:[1,0]
	v_pk_fma_f32 v[200:201], v[200:201], v[28:29], v[44:45]
	v_cvt_pk_bf16_f32 v74, v200, v201
	v_pk_mul_f32 v[202:203], v[190:191], v[210:211] op_sel_hi:[1,0]
	v_pk_fma_f32 v[202:203], v[202:203], v[30:31], v[46:47]
	v_cvt_pk_bf16_f32 v75, v202, v203
	v_pk_mul_f32 v[200:201], v[192:193], v[210:211] op_sel_hi:[1,0]
	v_pk_fma_f32 v[200:201], v[200:201], v[32:33], v[48:49]
	v_cvt_pk_bf16_f32 v76, v200, v201
	v_pk_mul_f32 v[202:203], v[194:195], v[210:211] op_sel_hi:[1,0]
	v_pk_fma_f32 v[202:203], v[202:203], v[34:35], v[50:51]
	v_cvt_pk_bf16_f32 v77, v202, v203
	v_pk_mul_f32 v[200:201], v[196:197], v[210:211] op_sel_hi:[1,0]
	v_pk_fma_f32 v[200:201], v[200:201], v[36:37], v[52:53]
	v_cvt_pk_bf16_f32 v78, v200, v201
	v_pk_mul_f32 v[202:203], v[198:199], v[210:211] op_sel_hi:[1,0]
	v_pk_fma_f32 v[202:203], v[202:203], v[38:39], v[54:55]
	v_cvt_pk_bf16_f32 v79, v202, v203
	global_store_dwordx4 v2, v[72:75], s[78:79] nt
	global_store_dwordx4 v2, v[76:79], s[78:79] offset:1024 nt
	s_add_i32 s81, s80, 6
	s_add_i32 s81, s81, s82
	s_and_b32 s81, s81, 31
	s_lshl_b32 s83, s81, 11
	v_add_u32_e32 v2, s83, v1
	global_load_dwordx4 v[152:155], v2, s[72:73] nt
	global_load_dwordx4 v[156:159], v2, s[72:73] offset:1024 nt
	global_load_dwordx4 v[160:163], v2, s[74:75] nt
	global_load_dwordx4 v[164:167], v2, s[74:75] offset:1024 nt
	s_waitcnt vmcnt(24)
	v_lshlrev_b32_e32 v200, 16, v96
	v_and_b32_e32 v201, 0xffff0000, v96
	v_pk_mul_f32 v[204:205], v[200:201], v[200:201]
	v_lshlrev_b32_e32 v202, 16, v97
	v_and_b32_e32 v203, 0xffff0000, v97
	v_pk_mul_f32 v[206:207], v[202:203], v[202:203]
	v_lshlrev_b32_e32 v200, 16, v98
	v_and_b32_e32 v201, 0xffff0000, v98
	v_pk_fma_f32 v[204:205], v[200:201], v[200:201], v[204:205]
	v_lshlrev_b32_e32 v202, 16, v99
	v_and_b32_e32 v203, 0xffff0000, v99
	v_pk_fma_f32 v[206:207], v[202:203], v[202:203], v[206:207]
	v_lshlrev_b32_e32 v200, 16, v100
	v_and_b32_e32 v201, 0xffff0000, v100
	v_pk_fma_f32 v[204:205], v[200:201], v[200:201], v[204:205]
	v_lshlrev_b32_e32 v202, 16, v101
	v_and_b32_e32 v203, 0xffff0000, v101
	v_pk_fma_f32 v[206:207], v[202:203], v[202:203], v[206:207]
	v_lshlrev_b32_e32 v200, 16, v102
	v_and_b32_e32 v201, 0xffff0000, v102
	v_pk_fma_f32 v[204:205], v[200:201], v[200:201], v[204:205]
	v_lshlrev_b32_e32 v202, 16, v103
	v_and_b32_e32 v203, 0xffff0000, v103
	v_pk_fma_f32 v[206:207], v[202:203], v[202:203], v[206:207]
	v_pk_add_f32 v[204:205], v[204:205], v[206:207]
	v_add_f32_e32 v208, v204, v205
	v_lshlrev_b32_e32 v184, 16, v88
	v_and_b32_e32 v185, 0xffff0000, v88
	v_add_f32_dpp v208, v208, v208 quad_perm:[1,0,3,2] row_mask:0xf bank_mask:0xf
	v_lshlrev_b32_e32 v186, 16, v89
	v_and_b32_e32 v187, 0xffff0000, v89
	v_add_f32_dpp v208, v208, v208 quad_perm:[2,3,0,1] row_mask:0xf bank_mask:0xf
	v_lshlrev_b32_e32 v188, 16, v90
	v_and_b32_e32 v189, 0xffff0000, v90
	v_add_f32_dpp v208, v208, v208 row_half_mirror row_mask:0xf bank_mask:0xf
	v_lshlrev_b32_e32 v190, 16, v91
	v_and_b32_e32 v191, 0xffff0000, v91
	v_add_f32_dpp v208, v208, v208 row_mirror row_mask:0xf bank_mask:0xf
	v_lshlrev_b32_e32 v192, 16, v92
	v_and_b32_e32 v193, 0xffff0000, v92
	v_add_f32_dpp v208, v208, v208 row_bcast:15 row_mask:0xa bank_mask:0xf
	v_lshlrev_b32_e32 v194, 16, v93
	v_and_b32_e32 v195, 0xffff0000, v93
	v_add_f32_dpp v208, v208, v208 row_bcast:31 row_mask:0xc bank_mask:0xf
	v_lshlrev_b32_e32 v196, 16, v94
	v_and_b32_e32 v197, 0xffff0000, v94
	v_readlane_b32 s60, v208, 63
	s_nop 1
	v_lshlrev_b32_e32 v198, 16, v95
	v_and_b32_e32 v199, 0xffff0000, v95
	v_mov_b32_e32 v210, s60
	v_fmaak_f32 v210, v210, v212, 0x358637bd
	v_rsq_f32_e32 v210, v210
	s_nop 0
	v_lshlrev_b32_e32 v200, 16, v96
; __device__ __forceinline__ unsigned cvtpk(float lo, float hi) { f32x2 v = {lo, hi}; bf16x2_t b = __builtin_convertvector(v, bf16x2_t); return __builtin_bit_cast(unsigned, b); }
; __device__ __forceinline__ void phase_rowwise(const void* xsrc_, bool sbf, void* xdst_, bool dbf, const bf16_t* Y, bf16_t* H, const float* mods, int lprev, int iprev, const float* lnpost, float resw, ...
;     ...
;                     for (int j = 0; j < 4; ++j) { if (sbf) xnb[r][j] = *(const u32x2*)(xsrcb + (m + 2 + r) * DM + 4 * lane + 256 * j); else xn[r][j] = *(const f32x4*)(xsrc + (m + 2 + r) * DM + 4 * lane + 256 * j); if (hasprev) yn[r][j] = *(const u32x2*)(Y + (m + 2 + r) * DM + 4 * lane + 256 * j); } }
;     ...
;                     for (int j = 0; j < 4; ++j) x[r][j] = x[r][j] + gp[j] * (y[r][j] * rs); }
;             }
; #pragma unroll
;             for (int r = 0; r < 2; ++r)
; #pragma unroll
;                 for (int j = 0; j < 4; ++j) { if (hasprev) { if (dbf) { u32x2 w; w.x = cvtpk(x[r][j].x, x[r][j].y); w.y = cvtpk(x[r][j].z, x[r][j].w); *(u32x2*)(xdstb + (m + r) * DM + 4 * lane + 256 * j) = w; } else *(f32x4*)(xdst + (m + r) * DM + 4 * lane + 256 * j) = x[r][j]; } }
;             if (hasnext) {
;                 float ss[2] = {0.f, 0.f};
; #pragma unroll
;                 for (int r = 0; r < 2; ++r)
; #pragma unroll
;                     for (int j = 0; j < 4; ++j) ss[r] += (x[r][j].x * x[r][j].x + x[r][j].y * x[r][j].y) + (x[r][j].z * x[r][j].z + x[r][j].w * x[r][j].w);
; #pragma unroll
;                 for (int off = 1; off < 64; off <<= 1) { ss[0] += __shfl_xor(ss[0], off); ss[1] += __shfl_xor(ss[1], off); }
; #pragma unroll
;                 for (int r = 0; r < 2; ++r) { const float rs = __builtin_amdgcn_rsqf(ss[r] * (1.f / DM) + EPS);
; #pragma unroll
;                     for (int j = 0; j < 4; ++j) { const f32x4 h = (x[r][j] * rs) * na[j] + ns[j]; u32x2 w; w.x = cvtpk(h.x, h.y); w.y = cvtpk(h.z, h.w); *(u32x2*)(H + (m + r) * DM + 4 * lane + 256 * j) = w; } }
	v_and_b32_e32 v201, 0xffff0000, v96
	v_pk_mul_f32 v[200:201], v[200:201], v[210:211] op_sel_hi:[1,0]
	v_pk_fma_f32 v[184:185], v[8:9], v[200:201], v[184:185]
	v_lshlrev_b32_e32 v202, 16, v97
	v_and_b32_e32 v203, 0xffff0000, v97
	v_pk_mul_f32 v[202:203], v[202:203], v[210:211] op_sel_hi:[1,0]
	v_pk_fma_f32 v[186:187], v[10:11], v[202:203], v[186:187]
	v_lshlrev_b32_e32 v200, 16, v98
	v_and_b32_e32 v201, 0xffff0000, v98
	v_pk_mul_f32 v[200:201], v[200:201], v[210:211] op_sel_hi:[1,0]
	v_pk_fma_f32 v[188:189], v[12:13], v[200:201], v[188:189]
	v_lshlrev_b32_e32 v202, 16, v99
	v_and_b32_e32 v203, 0xffff0000, v99
	v_pk_mul_f32 v[202:203], v[202:203], v[210:211] op_sel_hi:[1,0]
	v_pk_fma_f32 v[190:191], v[14:15], v[202:203], v[190:191]
	v_lshlrev_b32_e32 v200, 16, v100
	v_and_b32_e32 v201, 0xffff0000, v100
	v_pk_mul_f32 v[200:201], v[200:201], v[210:211] op_sel_hi:[1,0]
	v_pk_fma_f32 v[192:193], v[16:17], v[200:201], v[192:193]
	v_lshlrev_b32_e32 v202, 16, v101
	v_and_b32_e32 v203, 0xffff0000, v101
	v_pk_mul_f32 v[202:203], v[202:203], v[210:211] op_sel_hi:[1,0]
	v_pk_fma_f32 v[194:195], v[18:19], v[202:203], v[194:195]
	v_lshlrev_b32_e32 v200, 16, v102
	v_and_b32_e32 v201, 0xffff0000, v102
	v_pk_mul_f32 v[200:201], v[200:201], v[210:211] op_sel_hi:[1,0]
	v_pk_fma_f32 v[196:197], v[20:21], v[200:201], v[196:197]
	v_lshlrev_b32_e32 v202, 16, v103
	v_and_b32_e32 v203, 0xffff0000, v103
	v_pk_mul_f32 v[202:203], v[202:203], v[210:211] op_sel_hi:[1,0]
	v_pk_fma_f32 v[198:199], v[22:23], v[202:203], v[198:199]
	s_add_i32 s81, s80, 2
	s_add_i32 s81, s81, s82
	s_and_b32 s81, s81, 31
	s_lshl_b32 s83, s81, 11
	v_add_u32_e32 v2, s83, v1
	v_cvt_pk_bf16_f32 v96, v184, v185
	v_cvt_pk_bf16_f32 v97, v186, v187
	v_cvt_pk_bf16_f32 v98, v188, v189
	v_cvt_pk_bf16_f32 v99, v190, v191
	v_cvt_pk_bf16_f32 v100, v192, v193
	v_cvt_pk_bf16_f32 v101, v194, v195
	v_cvt_pk_bf16_f32 v102, v196, v197
	v_cvt_pk_bf16_f32 v103, v198, v199
	global_store_dwordx4 v2, v[96:99], s[76:77] nt
	global_store_dwordx4 v2, v[100:103], s[76:77] offset:1024 nt
	v_pk_mul_f32 v[204:205], v[184:185], v[184:185]
	v_pk_mul_f32 v[206:207], v[186:187], v[186:187]
	v_pk_fma_f32 v[204:205], v[188:189], v[188:189], v[204:205]
	v_pk_fma_f32 v[206:207], v[190:191], v[190:191], v[206:207]
	v_pk_fma_f32 v[204:205], v[192:193], v[192:193], v[204:205]
	v_pk_fma_f32 v[206:207], v[194:195], v[194:195], v[206:207]
	v_pk_fma_f32 v[204:205], v[196:197], v[196:197], v[204:205]
	v_pk_fma_f32 v[206:207], v[198:199], v[198:199], v[206:207]
	v_pk_add_f32 v[204:205], v[204:205], v[206:207]
	v_add_f32_e32 v208, v204, v205
	s_nop 0
	s_nop 0
	v_add_f32_dpp v208, v208, v208 quad_perm:[1,0,3,2] row_mask:0xf bank_mask:0xf
	s_nop 0
	s_nop 0
	v_add_f32_dpp v208, v208, v208 quad_perm:[2,3,0,1] row_mask:0xf bank_mask:0xf
	s_nop 0
	s_nop 0
	v_add_f32_dpp v208, v208, v208 row_half_mirror row_mask:0xf bank_mask:0xf
	s_nop 0
	s_nop 0
	v_add_f32_dpp v208, v208, v208 row_mirror row_mask:0xf bank_mask:0xf
	s_nop 0
	s_nop 0
	v_add_f32_dpp v208, v208, v208 row_bcast:15 row_mask:0xa bank_mask:0xf
	s_nop 0
	s_nop 0
	v_add_f32_dpp v208, v208, v208 row_bcast:31 row_mask:0xc bank_mask:0xf
	s_nop 0
	s_nop 0
	v_readlane_b32 s60, v208, 63
	s_nop 1
	v_mov_b32_e32 v210, s60
	v_fmaak_f32 v210, v210, v212, 0x358637bd
	v_rsq_f32_e32 v210, v210
	s_nop 0
	v_pk_mul_f32 v[200:201], v[184:185], v[210:211] op_sel_hi:[1,0]
	v_pk_fma_f32 v[200:201], v[200:201], v[24:25], v[40:41]
	v_cvt_pk_bf16_f32 v88, v200, v201
	v_pk_mul_f32 v[202:203], v[186:187], v[210:211] op_sel_hi:[1,0]
	v_pk_fma_f32 v[202:203], v[202:203], v[26:27], v[42:43]
	v_cvt_pk_bf16_f32 v89, v202, v203
	v_pk_mul_f32 v[200:201], v[188:189], v[210:211] op_sel_hi:[1,0]
	v_pk_fma_f32 v[200:201], v[200:201], v[28:29], v[44:45]
	v_cvt_pk_bf16_f32 v90, v200, v201
	v_pk_mul_f32 v[202:203], v[190:191], v[210:211] op_sel_hi:[1,0]
	v_pk_fma_f32 v[202:203], v[202:203], v[30:31], v[46:47]
	v_cvt_pk_bf16_f32 v91, v202, v203
	v_pk_mul_f32 v[200:201], v[192:193], v[210:211] op_sel_hi:[1,0]
	v_pk_fma_f32 v[200:201], v[200:201], v[32:33], v[48:49]
	v_cvt_pk_bf16_f32 v92, v200, v201
	v_pk_mul_f32 v[202:203], v[194:195], v[210:211] op_sel_hi:[1,0]
	v_pk_fma_f32 v[202:203], v[202:203], v[34:35], v[50:51]
	v_cvt_pk_bf16_f32 v93, v202, v203
	v_pk_mul_f32 v[200:201], v[196:197], v[210:211] op_sel_hi:[1,0]
	v_pk_fma_f32 v[200:201], v[200:201], v[36:37], v[52:53]
	v_cvt_pk_bf16_f32 v94, v200, v201
	v_pk_mul_f32 v[202:203], v[198:199], v[210:211] op_sel_hi:[1,0]
	v_pk_fma_f32 v[202:203], v[202:203], v[38:39], v[54:55]
	v_cvt_pk_bf16_f32 v95, v202, v203
	global_store_dwordx4 v2, v[88:91], s[78:79] nt
	global_store_dwordx4 v2, v[92:95], s[78:79] offset:1024 nt
	s_add_i32 s81, s80, 7
	s_add_i32 s81, s81, s82
	s_and_b32 s81, s81, 31
	s_lshl_b32 s83, s81, 11
	v_add_u32_e32 v2, s83, v1
	global_load_dwordx4 v[56:59], v2, s[72:73] nt
	global_load_dwordx4 v[60:63], v2, s[72:73] offset:1024 nt
	global_load_dwordx4 v[64:67], v2, s[74:75] nt
	global_load_dwordx4 v[68:71], v2, s[74:75] offset:1024 nt
	s_waitcnt vmcnt(28)
; __device__ __forceinline__ unsigned cvtpk(float lo, float hi) { f32x2 v = {lo, hi}; bf16x2_t b = __builtin_convertvector(v, bf16x2_t); return __builtin_bit_cast(unsigned, b); }
; __device__ __forceinline__ float bflo(unsigned u) { return __uint_as_float(u << 16); }
; __device__ __forceinline__ void phase_rowwise(const void* xsrc_, bool sbf, void* xdst_, bool dbf, const bf16_t* Y, bf16_t* H, const float* mods, int lprev, int iprev, const float* lnpost, float resw, ...
;     ...
;                     for (int j = 0; j < 4; ++j) { const u32x2 u = yr[r][j]; y[r][j] = (f32x4){bflo(u.x), bfhi(u.x), bflo(u.y), bfhi(u.y)};
;                         ss[r] += (y[r][j].x * y[r][j].x + y[r][j].y * y[r][j].y) + (y[r][j].z * y[r][j].z + y[r][j].w * y[r][j].w); }
; #pragma unroll
;                 for (int off = 1; off < 64; off <<= 1) { ss[0] += __shfl_xor(ss[0], off); ss[1] += __shfl_xor(ss[1], off); }
; #pragma unroll
;                 for (int r = 0; r < 2; ++r) { const float rs = __builtin_amdgcn_rsqf(ss[r] * (1.f / DM) + EPS);
; #pragma unroll
;                     for (int j = 0; j < 4; ++j) x[r][j] = x[r][j] + gp[j] * (y[r][j] * rs); }
;             }
; #pragma unroll
;             for (int r = 0; r < 2; ++r)
; #pragma unroll
;                 for (int j = 0; j < 4; ++j) { if (hasprev) { if (dbf) { u32x2 w; w.x = cvtpk(x[r][j].x, x[r][j].y); w.y = cvtpk(x[r][j].z, x[r][j].w); *(u32x2*)(xdstb + (m + r) * DM + 4 * lane + 256 * j) = w; } else *(f32x4*)(xdst + (m + r) * DM + 4 * lane + 256 * j) = x[r][j]; } }
;             if (hasnext) {
;                 float ss[2] = {0.f, 0.f};
; #pragma unroll
;                 for (int r = 0; r < 2; ++r)
; #pragma unroll
;                     for (int j = 0; j < 4; ++j) ss[r] += (x[r][j].x * x[r][j].x + x[r][j].y * x[r][j].y) + (x[r][j].z * x[r][j].z + x[r][j].w * x[r][j].w);
; #pragma unroll
;                 for (int off = 1; off < 64; off <<= 1) { ss[0] += __shfl_xor(ss[0], off); ss[1] += __shfl_xor(ss[1], off); }
; #pragma unroll
;                 for (int r = 0; r < 2; ++r) { const float rs = __builtin_amdgcn_rsqf(ss[r] * (1.f / DM) + EPS);
; #pragma unroll
;                     for (int j = 0; j < 4; ++j) { const f32x4 h = (x[r][j] * rs) * na[j] + ns[j]; u32x2 w; w.x = cvtpk(h.x, h.y); w.y = cvtpk(h.z, h.w); *(u32x2*)(H + (m + r) * DM + 4 * lane + 256 * j) = w; } }
	v_lshlrev_b32_e32 v200, 16, v112
	v_and_b32_e32 v201, 0xffff0000, v112
	v_pk_mul_f32 v[204:205], v[200:201], v[200:201]
	v_lshlrev_b32_e32 v202, 16, v113
	v_and_b32_e32 v203, 0xffff0000, v113
	v_pk_mul_f32 v[206:207], v[202:203], v[202:203]
	v_lshlrev_b32_e32 v200, 16, v114
	v_and_b32_e32 v201, 0xffff0000, v114
	v_pk_fma_f32 v[204:205], v[200:201], v[200:201], v[204:205]
	v_lshlrev_b32_e32 v202, 16, v115
	v_and_b32_e32 v203, 0xffff0000, v115
	v_pk_fma_f32 v[206:207], v[202:203], v[202:203], v[206:207]
	v_lshlrev_b32_e32 v200, 16, v116
	v_and_b32_e32 v201, 0xffff0000, v116
	v_pk_fma_f32 v[204:205], v[200:201], v[200:201], v[204:205]
	v_lshlrev_b32_e32 v202, 16, v117
	v_and_b32_e32 v203, 0xffff0000, v117
	v_pk_fma_f32 v[206:207], v[202:203], v[202:203], v[206:207]
	v_lshlrev_b32_e32 v200, 16, v118
	v_and_b32_e32 v201, 0xffff0000, v118
	v_pk_fma_f32 v[204:205], v[200:201], v[200:201], v[204:205]
	v_lshlrev_b32_e32 v202, 16, v119
	v_and_b32_e32 v203, 0xffff0000, v119
	v_pk_fma_f32 v[206:207], v[202:203], v[202:203], v[206:207]
	v_pk_add_f32 v[204:205], v[204:205], v[206:207]
	v_add_f32_e32 v208, v204, v205
	v_lshlrev_b32_e32 v184, 16, v104
	v_and_b32_e32 v185, 0xffff0000, v104
	v_add_f32_dpp v208, v208, v208 quad_perm:[1,0,3,2] row_mask:0xf bank_mask:0xf
	v_lshlrev_b32_e32 v186, 16, v105
	v_and_b32_e32 v187, 0xffff0000, v105
	v_add_f32_dpp v208, v208, v208 quad_perm:[2,3,0,1] row_mask:0xf bank_mask:0xf
	v_lshlrev_b32_e32 v188, 16, v106
	v_and_b32_e32 v189, 0xffff0000, v106
	v_add_f32_dpp v208, v208, v208 row_half_mirror row_mask:0xf bank_mask:0xf
	v_lshlrev_b32_e32 v190, 16, v107
	v_and_b32_e32 v191, 0xffff0000, v107
	v_add_f32_dpp v208, v208, v208 row_mirror row_mask:0xf bank_mask:0xf
	v_lshlrev_b32_e32 v192, 16, v108
	v_and_b32_e32 v193, 0xffff0000, v108
	v_add_f32_dpp v208, v208, v208 row_bcast:15 row_mask:0xa bank_mask:0xf
	v_lshlrev_b32_e32 v194, 16, v109
	v_and_b32_e32 v195, 0xffff0000, v109
	v_add_f32_dpp v208, v208, v208 row_bcast:31 row_mask:0xc bank_mask:0xf
	v_lshlrev_b32_e32 v196, 16, v110
	v_and_b32_e32 v197, 0xffff0000, v110
	v_readlane_b32 s60, v208, 63
	s_nop 1
	v_lshlrev_b32_e32 v198, 16, v111
	v_and_b32_e32 v199, 0xffff0000, v111
	v_mov_b32_e32 v210, s60
	v_fmaak_f32 v210, v210, v212, 0x358637bd
	v_rsq_f32_e32 v210, v210
	s_nop 0
	v_lshlrev_b32_e32 v200, 16, v112
	v_and_b32_e32 v201, 0xffff0000, v112
	v_pk_mul_f32 v[200:201], v[200:201], v[210:211] op_sel_hi:[1,0]
	v_pk_fma_f32 v[184:185], v[8:9], v[200:201], v[184:185]
	v_lshlrev_b32_e32 v202, 16, v113
	v_and_b32_e32 v203, 0xffff0000, v113
	v_pk_mul_f32 v[202:203], v[202:203], v[210:211] op_sel_hi:[1,0]
	v_pk_fma_f32 v[186:187], v[10:11], v[202:203], v[186:187]
	v_lshlrev_b32_e32 v200, 16, v114
	v_and_b32_e32 v201, 0xffff0000, v114
	v_pk_mul_f32 v[200:201], v[200:201], v[210:211] op_sel_hi:[1,0]
	v_pk_fma_f32 v[188:189], v[12:13], v[200:201], v[188:189]
	v_lshlrev_b32_e32 v202, 16, v115
	v_and_b32_e32 v203, 0xffff0000, v115
	v_pk_mul_f32 v[202:203], v[202:203], v[210:211] op_sel_hi:[1,0]
	v_pk_fma_f32 v[190:191], v[14:15], v[202:203], v[190:191]
	v_lshlrev_b32_e32 v200, 16, v116
	v_and_b32_e32 v201, 0xffff0000, v116
	v_pk_mul_f32 v[200:201], v[200:201], v[210:211] op_sel_hi:[1,0]
	v_pk_fma_f32 v[192:193], v[16:17], v[200:201], v[192:193]
	v_lshlrev_b32_e32 v202, 16, v117
	v_and_b32_e32 v203, 0xffff0000, v117
	v_pk_mul_f32 v[202:203], v[202:203], v[210:211] op_sel_hi:[1,0]
	v_pk_fma_f32 v[194:195], v[18:19], v[202:203], v[194:195]
	v_lshlrev_b32_e32 v200, 16, v118
	v_and_b32_e32 v201, 0xffff0000, v118
	v_pk_mul_f32 v[200:201], v[200:201], v[210:211] op_sel_hi:[1,0]
	v_pk_fma_f32 v[196:197], v[20:21], v[200:201], v[196:197]
	v_lshlrev_b32_e32 v202, 16, v119
	v_and_b32_e32 v203, 0xffff0000, v119
	v_pk_mul_f32 v[202:203], v[202:203], v[210:211] op_sel_hi:[1,0]
	v_pk_fma_f32 v[198:199], v[22:23], v[202:203], v[198:199]
	s_add_i32 s81, s80, 3
	s_add_i32 s81, s81, s82
	s_and_b32 s81, s81, 31
	s_lshl_b32 s83, s81, 11
	v_add_u32_e32 v2, s83, v1
	v_cvt_pk_bf16_f32 v112, v184, v185
	v_cvt_pk_bf16_f32 v113, v186, v187
	v_cvt_pk_bf16_f32 v114, v188, v189
	v_cvt_pk_bf16_f32 v115, v190, v191
	v_cvt_pk_bf16_f32 v116, v192, v193
	v_cvt_pk_bf16_f32 v117, v194, v195
	v_cvt_pk_bf16_f32 v118, v196, v197
	v_cvt_pk_bf16_f32 v119, v198, v199
	global_store_dwordx4 v2, v[112:115], s[76:77] nt
	global_store_dwordx4 v2, v[116:119], s[76:77] offset:1024 nt
	v_pk_mul_f32 v[204:205], v[184:185], v[184:185]
	v_pk_mul_f32 v[206:207], v[186:187], v[186:187]
	v_pk_fma_f32 v[204:205], v[188:189], v[188:189], v[204:205]
	v_pk_fma_f32 v[206:207], v[190:191], v[190:191], v[206:207]
	v_pk_fma_f32 v[204:205], v[192:193], v[192:193], v[204:205]
	v_pk_fma_f32 v[206:207], v[194:195], v[194:195], v[206:207]
	v_pk_fma_f32 v[204:205], v[196:197], v[196:197], v[204:205]
	v_pk_fma_f32 v[206:207], v[198:199], v[198:199], v[206:207]
	v_pk_add_f32 v[204:205], v[204:205], v[206:207]
	v_add_f32_e32 v208, v204, v205
	s_nop 0
	s_nop 0
	v_add_f32_dpp v208, v208, v208 quad_perm:[1,0,3,2] row_mask:0xf bank_mask:0xf
	s_nop 0
	s_nop 0
	v_add_f32_dpp v208, v208, v208 quad_perm:[2,3,0,1] row_mask:0xf bank_mask:0xf
	s_nop 0
	s_nop 0
	v_add_f32_dpp v208, v208, v208 row_half_mirror row_mask:0xf bank_mask:0xf
	s_nop 0
	s_nop 0
	v_add_f32_dpp v208, v208, v208 row_mirror row_mask:0xf bank_mask:0xf
	s_nop 0
	s_nop 0
	v_add_f32_dpp v208, v208, v208 row_bcast:15 row_mask:0xa bank_mask:0xf
	s_nop 0
	s_nop 0
	v_add_f32_dpp v208, v208, v208 row_bcast:31 row_mask:0xc bank_mask:0xf
	s_nop 0
	s_nop 0
	v_readlane_b32 s60, v208, 63
	s_nop 1
	v_mov_b32_e32 v210, s60
	v_fmaak_f32 v210, v210, v212, 0x358637bd
	v_rsq_f32_e32 v210, v210
	s_nop 0
	v_pk_mul_f32 v[200:201], v[184:185], v[210:211] op_sel_hi:[1,0]
	v_pk_fma_f32 v[200:201], v[200:201], v[24:25], v[40:41]
	v_cvt_pk_bf16_f32 v104, v200, v201
	v_pk_mul_f32 v[202:203], v[186:187], v[210:211] op_sel_hi:[1,0]
	v_pk_fma_f32 v[202:203], v[202:203], v[26:27], v[42:43]
	v_cvt_pk_bf16_f32 v105, v202, v203
	v_pk_mul_f32 v[200:201], v[188:189], v[210:211] op_sel_hi:[1,0]
	v_pk_fma_f32 v[200:201], v[200:201], v[28:29], v[44:45]
	v_cvt_pk_bf16_f32 v106, v200, v201
	v_pk_mul_f32 v[202:203], v[190:191], v[210:211] op_sel_hi:[1,0]
	v_pk_fma_f32 v[202:203], v[202:203], v[30:31], v[46:47]
	v_cvt_pk_bf16_f32 v107, v202, v203
	v_pk_mul_f32 v[200:201], v[192:193], v[210:211] op_sel_hi:[1,0]
	v_pk_fma_f32 v[200:201], v[200:201], v[32:33], v[48:49]
	v_cvt_pk_bf16_f32 v108, v200, v201
	v_pk_mul_f32 v[202:203], v[194:195], v[210:211] op_sel_hi:[1,0]
	v_pk_fma_f32 v[202:203], v[202:203], v[34:35], v[50:51]
	v_cvt_pk_bf16_f32 v109, v202, v203
	v_pk_mul_f32 v[200:201], v[196:197], v[210:211] op_sel_hi:[1,0]
	v_pk_fma_f32 v[200:201], v[200:201], v[36:37], v[52:53]
	v_cvt_pk_bf16_f32 v110, v200, v201
	v_pk_mul_f32 v[202:203], v[198:199], v[210:211] op_sel_hi:[1,0]
	v_pk_fma_f32 v[202:203], v[202:203], v[38:39], v[54:55]
	v_cvt_pk_bf16_f32 v111, v202, v203
	global_store_dwordx4 v2, v[104:107], s[78:79] nt
	global_store_dwordx4 v2, v[108:111], s[78:79] offset:1024 nt
	s_mov_b32 s82, 4
; __device__ __forceinline__ void phase_rowwise(const void* xsrc_, bool sbf, void* xdst_, bool dbf, const bf16_t* Y, bf16_t* H, const float* mods, int lprev, int iprev, const float* lnpost, float resw, ...
;     ...
;             if (rr + 2 < 32) {
; #pragma unroll
;                 for (int r = 0; r < 2; ++r)
; #pragma unroll
;                     for (int j = 0; j < 4; ++j) { if (sbf) xnb[r][j] = *(const u32x2*)(xsrcb + (m + 2 + r) * DM + 4 * lane + 256 * j); else xn[r][j] = *(const f32x4*)(xsrc + (m + 2 + r) * DM + 4 * lane + 256 * j); if (hasprev) yn[r][j] = *(const u32x2*)(Y + (m + 2 + r) * DM + 4 * lane + 256 * j); } }
.Lrw_MID_loop:
	s_add_i32 s81, s82, 4
	s_cmp_lt_u32 s81, 32
	s_cbranch_scc0 .Lrw_MID_l0_d
	s_add_i32 s81, s80, 4
	s_add_i32 s81, s81, s82
	s_and_b32 s81, s81, 31
	s_lshl_b32 s83, s81, 11
	v_add_u32_e32 v2, s83, v1
	global_load_dwordx4 v[72:75], v2, s[72:73] nt
	global_load_dwordx4 v[76:79], v2, s[72:73] offset:1024 nt
	global_load_dwordx4 v[80:83], v2, s[74:75] nt
	global_load_dwordx4 v[84:87], v2, s[74:75] offset:1024 nt
	s_branch .Lrw_MID_l0_e

; __device__ __forceinline__ float bflo(unsigned u) { return __uint_as_float(u << 16); }
; __device__ __forceinline__ float bfhi(unsigned u) { return __uint_as_float(u & 0xffff0000u); }
; __device__ __forceinline__ void phase_rowwise(const void* xsrc_, bool sbf, void* xdst_, bool dbf, const bf16_t* Y, bf16_t* H, const float* mods, int lprev, int iprev, const float* lnpost, float resw, ...
;     ...
;             if (hasprev) {
;                 f32x4 y[2][4]; float ss[2] = {0.f, 0.f};
; #pragma unroll
;                 for (int r = 0; r < 2; ++r)
; #pragma unroll
;                     for (int j = 0; j < 4; ++j) { const u32x2 u = yr[r][j]; y[r][j] = (f32x4){bflo(u.x), bfhi(u.x), bflo(u.y), bfhi(u.y)};
;                         ss[r] += (y[r][j].x * y[r][j].x + y[r][j].y * y[r][j].y) + (y[r][j].z * y[r][j].z + y[r][j].w * y[r][j].w); }
; #pragma unroll
;                 for (int off = 1; off < 64; off <<= 1) { ss[0] += __shfl_xor(ss[0], off); ss[1] += __shfl_xor(ss[1], off); }
; #pragma unroll
;                 for (int r = 0; r < 2; ++r) { const float rs = __builtin_amdgcn_rsqf(ss[r] * (1.f / DM) + EPS);
; #pragma unroll
;                     for (int j = 0; j < 4; ++j) x[r][j] = x[r][j] + gp[j] * (y[r][j] * rs); }
.Lrw_MID_l0_e:
	s_waitcnt vmcnt(32)
	v_lshlrev_b32_e32 v200, 16, v128
	v_and_b32_e32 v201, 0xffff0000, v128
	v_pk_mul_f32 v[204:205], v[200:201], v[200:201]
	v_lshlrev_b32_e32 v202, 16, v129
	v_and_b32_e32 v203, 0xffff0000, v129
	v_pk_mul_f32 v[206:207], v[202:203], v[202:203]
	v_lshlrev_b32_e32 v200, 16, v130
	v_and_b32_e32 v201, 0xffff0000, v130
	v_pk_fma_f32 v[204:205], v[200:201], v[200:201], v[204:205]
	v_lshlrev_b32_e32 v202, 16, v131
	v_and_b32_e32 v203, 0xffff0000, v131
	v_pk_fma_f32 v[206:207], v[202:203], v[202:203], v[206:207]
	v_lshlrev_b32_e32 v200, 16, v132
	v_and_b32_e32 v201, 0xffff0000, v132
	v_pk_fma_f32 v[204:205], v[200:201], v[200:201], v[204:205]
	v_lshlrev_b32_e32 v202, 16, v133
	v_and_b32_e32 v203, 0xffff0000, v133
	v_pk_fma_f32 v[206:207], v[202:203], v[202:203], v[206:207]
	v_lshlrev_b32_e32 v200, 16, v134
	v_and_b32_e32 v201, 0xffff0000, v134
	v_pk_fma_f32 v[204:205], v[200:201], v[200:201], v[204:205]
	v_lshlrev_b32_e32 v202, 16, v135
	v_and_b32_e32 v203, 0xffff0000, v135
	v_pk_fma_f32 v[206:207], v[202:203], v[202:203], v[206:207]
	v_pk_add_f32 v[204:205], v[204:205], v[206:207]
	v_add_f32_e32 v208, v204, v205
	v_lshlrev_b32_e32 v184, 16, v120
	v_and_b32_e32 v185, 0xffff0000, v120
	v_add_f32_dpp v208, v208, v208 quad_perm:[1,0,3,2] row_mask:0xf bank_mask:0xf
	v_lshlrev_b32_e32 v186, 16, v121
	v_and_b32_e32 v187, 0xffff0000, v121
	v_add_f32_dpp v208, v208, v208 quad_perm:[2,3,0,1] row_mask:0xf bank_mask:0xf
	v_lshlrev_b32_e32 v188, 16, v122
	v_and_b32_e32 v189, 0xffff0000, v122
	v_add_f32_dpp v208, v208, v208 row_half_mirror row_mask:0xf bank_mask:0xf
	v_lshlrev_b32_e32 v190, 16, v123
	v_and_b32_e32 v191, 0xffff0000, v123
	v_add_f32_dpp v208, v208, v208 row_mirror row_mask:0xf bank_mask:0xf
	v_lshlrev_b32_e32 v192, 16, v124
	v_and_b32_e32 v193, 0xffff0000, v124
	v_add_f32_dpp v208, v208, v208 row_bcast:15 row_mask:0xa bank_mask:0xf
	v_lshlrev_b32_e32 v194, 16, v125
	v_and_b32_e32 v195, 0xffff0000, v125
	v_add_f32_dpp v208, v208, v208 row_bcast:31 row_mask:0xc bank_mask:0xf
	v_lshlrev_b32_e32 v196, 16, v126
	v_and_b32_e32 v197, 0xffff0000, v126
	v_readlane_b32 s60, v208, 63
	s_nop 1
	v_lshlrev_b32_e32 v198, 16, v127
	v_and_b32_e32 v199, 0xffff0000, v127
	v_mov_b32_e32 v210, s60
	v_fmaak_f32 v210, v210, v212, 0x358637bd
	v_rsq_f32_e32 v210, v210
	s_nop 0
	v_lshlrev_b32_e32 v200, 16, v128
	v_and_b32_e32 v201, 0xffff0000, v128
	v_pk_mul_f32 v[200:201], v[200:201], v[210:211] op_sel_hi:[1,0]
	v_pk_fma_f32 v[184:185], v[8:9], v[200:201], v[184:185]
	v_lshlrev_b32_e32 v202, 16, v129
	v_and_b32_e32 v203, 0xffff0000, v129
	v_pk_mul_f32 v[202:203], v[202:203], v[210:211] op_sel_hi:[1,0]
	v_pk_fma_f32 v[186:187], v[10:11], v[202:203], v[186:187]
	v_lshlrev_b32_e32 v200, 16, v130
	v_and_b32_e32 v201, 0xffff0000, v130
	v_pk_mul_f32 v[200:201], v[200:201], v[210:211] op_sel_hi:[1,0]
	v_pk_fma_f32 v[188:189], v[12:13], v[200:201], v[188:189]
	v_lshlrev_b32_e32 v202, 16, v131
	v_and_b32_e32 v203, 0xffff0000, v131
	v_pk_mul_f32 v[202:203], v[202:203], v[210:211] op_sel_hi:[1,0]
	v_pk_fma_f32 v[190:191], v[14:15], v[202:203], v[190:191]
	v_lshlrev_b32_e32 v200, 16, v132
	v_and_b32_e32 v201, 0xffff0000, v132
	v_pk_mul_f32 v[200:201], v[200:201], v[210:211] op_sel_hi:[1,0]
	v_pk_fma_f32 v[192:193], v[16:17], v[200:201], v[192:193]
	v_lshlrev_b32_e32 v202, 16, v133
	v_and_b32_e32 v203, 0xffff0000, v133
	v_pk_mul_f32 v[202:203], v[202:203], v[210:211] op_sel_hi:[1,0]
	v_pk_fma_f32 v[194:195], v[18:19], v[202:203], v[194:195]
	v_lshlrev_b32_e32 v200, 16, v134
	v_and_b32_e32 v201, 0xffff0000, v134
	v_pk_mul_f32 v[200:201], v[200:201], v[210:211] op_sel_hi:[1,0]
	v_pk_fma_f32 v[196:197], v[20:21], v[200:201], v[196:197]
	v_lshlrev_b32_e32 v202, 16, v135
; __device__ __forceinline__ unsigned cvtpk(float lo, float hi) { f32x2 v = {lo, hi}; bf16x2_t b = __builtin_convertvector(v, bf16x2_t); return __builtin_bit_cast(unsigned, b); }
; __device__ __forceinline__ void phase_rowwise(const void* xsrc_, bool sbf, void* xdst_, bool dbf, const bf16_t* Y, bf16_t* H, const float* mods, int lprev, int iprev, const float* lnpost, float resw, ...
;     ...
;             if (rr + 2 < 32) {
; #pragma unroll
;                 for (int r = 0; r < 2; ++r)
; #pragma unroll
;                     for (int j = 0; j < 4; ++j) { if (sbf) xnb[r][j] = *(const u32x2*)(xsrcb + (m + 2 + r) * DM + 4 * lane + 256 * j); else xn[r][j] = *(const f32x4*)(xsrc + (m + 2 + r) * DM + 4 * lane + 256 * j); if (hasprev) yn[r][j] = *(const u32x2*)(Y + (m + 2 + r) * DM + 4 * lane + 256 * j); } }
;     ...
;                     for (int j = 0; j < 4; ++j) x[r][j] = x[r][j] + gp[j] * (y[r][j] * rs); }
;             }
; #pragma unroll
;             for (int r = 0; r < 2; ++r)
; #pragma unroll
;                 for (int j = 0; j < 4; ++j) { if (hasprev) { if (dbf) { u32x2 w; w.x = cvtpk(x[r][j].x, x[r][j].y); w.y = cvtpk(x[r][j].z, x[r][j].w); *(u32x2*)(xdstb + (m + r) * DM + 4 * lane + 256 * j) = w; } else *(f32x4*)(xdst + (m + r) * DM + 4 * lane + 256 * j) = x[r][j]; } }
;             if (hasnext) {
;                 float ss[2] = {0.f, 0.f};
; #pragma unroll
;                 for (int r = 0; r < 2; ++r)
; #pragma unroll
;                     for (int j = 0; j < 4; ++j) ss[r] += (x[r][j].x * x[r][j].x + x[r][j].y * x[r][j].y) + (x[r][j].z * x[r][j].z + x[r][j].w * x[r][j].w);
; #pragma unroll
;                 for (int off = 1; off < 64; off <<= 1) { ss[0] += __shfl_xor(ss[0], off); ss[1] += __shfl_xor(ss[1], off); }
; #pragma unroll
;                 for (int r = 0; r < 2; ++r) { const float rs = __builtin_amdgcn_rsqf(ss[r] * (1.f / DM) + EPS);
; #pragma unroll
;                     for (int j = 0; j < 4; ++j) { const f32x4 h = (x[r][j] * rs) * na[j] + ns[j]; u32x2 w; w.x = cvtpk(h.x, h.y); w.y = cvtpk(h.z, h.w); *(u32x2*)(H + (m + r) * DM + 4 * lane + 256 * j) = w; } }
	v_and_b32_e32 v203, 0xffff0000, v135
	v_pk_mul_f32 v[202:203], v[202:203], v[210:211] op_sel_hi:[1,0]
	v_pk_fma_f32 v[198:199], v[22:23], v[202:203], v[198:199]
	s_add_i32 s81, s80, 0
	s_add_i32 s81, s81, s82
	s_and_b32 s81, s81, 31
	s_lshl_b32 s83, s81, 11
	v_add_u32_e32 v2, s83, v1
	v_cvt_pk_bf16_f32 v128, v184, v185
	v_cvt_pk_bf16_f32 v129, v186, v187
	v_cvt_pk_bf16_f32 v130, v188, v189
	v_cvt_pk_bf16_f32 v131, v190, v191
	v_cvt_pk_bf16_f32 v132, v192, v193
	v_cvt_pk_bf16_f32 v133, v194, v195
	v_cvt_pk_bf16_f32 v134, v196, v197
	v_cvt_pk_bf16_f32 v135, v198, v199
	global_store_dwordx4 v2, v[128:131], s[76:77] nt
	global_store_dwordx4 v2, v[132:135], s[76:77] offset:1024 nt
	v_pk_mul_f32 v[204:205], v[184:185], v[184:185]
	v_pk_mul_f32 v[206:207], v[186:187], v[186:187]
	v_pk_fma_f32 v[204:205], v[188:189], v[188:189], v[204:205]
	v_pk_fma_f32 v[206:207], v[190:191], v[190:191], v[206:207]
	v_pk_fma_f32 v[204:205], v[192:193], v[192:193], v[204:205]
	v_pk_fma_f32 v[206:207], v[194:195], v[194:195], v[206:207]
	v_pk_fma_f32 v[204:205], v[196:197], v[196:197], v[204:205]
	v_pk_fma_f32 v[206:207], v[198:199], v[198:199], v[206:207]
	v_pk_add_f32 v[204:205], v[204:205], v[206:207]
	v_add_f32_e32 v208, v204, v205
	s_nop 0
	s_nop 0
	v_add_f32_dpp v208, v208, v208 quad_perm:[1,0,3,2] row_mask:0xf bank_mask:0xf
	s_nop 0
	s_nop 0
	v_add_f32_dpp v208, v208, v208 quad_perm:[2,3,0,1] row_mask:0xf bank_mask:0xf
	s_nop 0
	s_nop 0
	v_add_f32_dpp v208, v208, v208 row_half_mirror row_mask:0xf bank_mask:0xf
	s_nop 0
	s_nop 0
	v_add_f32_dpp v208, v208, v208 row_mirror row_mask:0xf bank_mask:0xf
	s_nop 0
	s_nop 0
	v_add_f32_dpp v208, v208, v208 row_bcast:15 row_mask:0xa bank_mask:0xf
	s_nop 0
	s_nop 0
	v_add_f32_dpp v208, v208, v208 row_bcast:31 row_mask:0xc bank_mask:0xf
	s_nop 0
	s_nop 0
	v_readlane_b32 s60, v208, 63
	s_nop 1
	v_mov_b32_e32 v210, s60
	v_fmaak_f32 v210, v210, v212, 0x358637bd
	v_rsq_f32_e32 v210, v210
	s_nop 0
	v_pk_mul_f32 v[200:201], v[184:185], v[210:211] op_sel_hi:[1,0]
	v_pk_fma_f32 v[200:201], v[200:201], v[24:25], v[40:41]
	v_cvt_pk_bf16_f32 v120, v200, v201
	v_pk_mul_f32 v[202:203], v[186:187], v[210:211] op_sel_hi:[1,0]
	v_pk_fma_f32 v[202:203], v[202:203], v[26:27], v[42:43]
	v_cvt_pk_bf16_f32 v121, v202, v203
	v_pk_mul_f32 v[200:201], v[188:189], v[210:211] op_sel_hi:[1,0]
	v_pk_fma_f32 v[200:201], v[200:201], v[28:29], v[44:45]
	v_cvt_pk_bf16_f32 v122, v200, v201
	v_pk_mul_f32 v[202:203], v[190:191], v[210:211] op_sel_hi:[1,0]
	v_pk_fma_f32 v[202:203], v[202:203], v[30:31], v[46:47]
	v_cvt_pk_bf16_f32 v123, v202, v203
	v_pk_mul_f32 v[200:201], v[192:193], v[210:211] op_sel_hi:[1,0]
	v_pk_fma_f32 v[200:201], v[200:201], v[32:33], v[48:49]
	v_cvt_pk_bf16_f32 v124, v200, v201
	v_pk_mul_f32 v[202:203], v[194:195], v[210:211] op_sel_hi:[1,0]
	v_pk_fma_f32 v[202:203], v[202:203], v[34:35], v[50:51]
	v_cvt_pk_bf16_f32 v125, v202, v203
	v_pk_mul_f32 v[200:201], v[196:197], v[210:211] op_sel_hi:[1,0]
	v_pk_fma_f32 v[200:201], v[200:201], v[36:37], v[52:53]
	v_cvt_pk_bf16_f32 v126, v200, v201
	v_pk_mul_f32 v[202:203], v[198:199], v[210:211] op_sel_hi:[1,0]
	v_pk_fma_f32 v[202:203], v[202:203], v[38:39], v[54:55]
	v_cvt_pk_bf16_f32 v127, v202, v203
	global_store_dwordx4 v2, v[120:123], s[78:79] nt
	global_store_dwordx4 v2, v[124:127], s[78:79] offset:1024 nt
	s_add_i32 s81, s82, 5
	s_cmp_lt_u32 s81, 32
	s_cbranch_scc0 .Lrw_MID_l1_d
	s_add_i32 s81, s80, 5
	s_add_i32 s81, s81, s82
	s_and_b32 s81, s81, 31
	s_lshl_b32 s83, s81, 11
	v_add_u32_e32 v2, s83, v1
	global_load_dwordx4 v[88:91], v2, s[72:73] nt
	global_load_dwordx4 v[92:95], v2, s[72:73] offset:1024 nt
	global_load_dwordx4 v[96:99], v2, s[74:75] nt
	global_load_dwordx4 v[100:103], v2, s[74:75] offset:1024 nt
	s_branch .Lrw_MID_l1_e

; __device__ __forceinline__ float bflo(unsigned u) { return __uint_as_float(u << 16); }
; __device__ __forceinline__ float bfhi(unsigned u) { return __uint_as_float(u & 0xffff0000u); }
; __device__ __forceinline__ void phase_rowwise(const void* xsrc_, bool sbf, void* xdst_, bool dbf, const bf16_t* Y, bf16_t* H, const float* mods, int lprev, int iprev, const float* lnpost, float resw, ...
;     ...
;             if (hasprev) {
;                 f32x4 y[2][4]; float ss[2] = {0.f, 0.f};
; #pragma unroll
;                 for (int r = 0; r < 2; ++r)
; #pragma unroll
;                     for (int j = 0; j < 4; ++j) { const u32x2 u = yr[r][j]; y[r][j] = (f32x4){bflo(u.x), bfhi(u.x), bflo(u.y), bfhi(u.y)};
;                         ss[r] += (y[r][j].x * y[r][j].x + y[r][j].y * y[r][j].y) + (y[r][j].z * y[r][j].z + y[r][j].w * y[r][j].w); }
; #pragma unroll
;                 for (int off = 1; off < 64; off <<= 1) { ss[0] += __shfl_xor(ss[0], off); ss[1] += __shfl_xor(ss[1], off); }
; #pragma unroll
;                 for (int r = 0; r < 2; ++r) { const float rs = __builtin_amdgcn_rsqf(ss[r] * (1.f / DM) + EPS);
; #pragma unroll
;                     for (int j = 0; j < 4; ++j) x[r][j] = x[r][j] + gp[j] * (y[r][j] * rs); }
.Lrw_MID_l1_e:
	s_waitcnt vmcnt(32)
	v_lshlrev_b32_e32 v200, 16, v144
	v_and_b32_e32 v201, 0xffff0000, v144
	v_pk_mul_f32 v[204:205], v[200:201], v[200:201]
	v_lshlrev_b32_e32 v202, 16, v145
	v_and_b32_e32 v203, 0xffff0000, v145
	v_pk_mul_f32 v[206:207], v[202:203], v[202:203]
	v_lshlrev_b32_e32 v200, 16, v146
	v_and_b32_e32 v201, 0xffff0000, v146
	v_pk_fma_f32 v[204:205], v[200:201], v[200:201], v[204:205]
	v_lshlrev_b32_e32 v202, 16, v147
	v_and_b32_e32 v203, 0xffff0000, v147
	v_pk_fma_f32 v[206:207], v[202:203], v[202:203], v[206:207]
	v_lshlrev_b32_e32 v200, 16, v148
	v_and_b32_e32 v201, 0xffff0000, v148
	v_pk_fma_f32 v[204:205], v[200:201], v[200:201], v[204:205]
	v_lshlrev_b32_e32 v202, 16, v149
	v_and_b32_e32 v203, 0xffff0000, v149
	v_pk_fma_f32 v[206:207], v[202:203], v[202:203], v[206:207]
	v_lshlrev_b32_e32 v200, 16, v150
	v_and_b32_e32 v201, 0xffff0000, v150
	v_pk_fma_f32 v[204:205], v[200:201], v[200:201], v[204:205]
	v_lshlrev_b32_e32 v202, 16, v151
	v_and_b32_e32 v203, 0xffff0000, v151
	v_pk_fma_f32 v[206:207], v[202:203], v[202:203], v[206:207]
	v_pk_add_f32 v[204:205], v[204:205], v[206:207]
	v_add_f32_e32 v208, v204, v205
	v_lshlrev_b32_e32 v184, 16, v136
	v_and_b32_e32 v185, 0xffff0000, v136
	v_add_f32_dpp v208, v208, v208 quad_perm:[1,0,3,2] row_mask:0xf bank_mask:0xf
	v_lshlrev_b32_e32 v186, 16, v137
	v_and_b32_e32 v187, 0xffff0000, v137
	v_add_f32_dpp v208, v208, v208 quad_perm:[2,3,0,1] row_mask:0xf bank_mask:0xf
	v_lshlrev_b32_e32 v188, 16, v138
	v_and_b32_e32 v189, 0xffff0000, v138
	v_add_f32_dpp v208, v208, v208 row_half_mirror row_mask:0xf bank_mask:0xf
	v_lshlrev_b32_e32 v190, 16, v139
	v_and_b32_e32 v191, 0xffff0000, v139
	v_add_f32_dpp v208, v208, v208 row_mirror row_mask:0xf bank_mask:0xf
	v_lshlrev_b32_e32 v192, 16, v140
	v_and_b32_e32 v193, 0xffff0000, v140
	v_add_f32_dpp v208, v208, v208 row_bcast:15 row_mask:0xa bank_mask:0xf
	v_lshlrev_b32_e32 v194, 16, v141
	v_and_b32_e32 v195, 0xffff0000, v141
	v_add_f32_dpp v208, v208, v208 row_bcast:31 row_mask:0xc bank_mask:0xf
	v_lshlrev_b32_e32 v196, 16, v142
	v_and_b32_e32 v197, 0xffff0000, v142
	v_readlane_b32 s60, v208, 63
	s_nop 1
	v_lshlrev_b32_e32 v198, 16, v143
	v_and_b32_e32 v199, 0xffff0000, v143
	v_mov_b32_e32 v210, s60
	v_fmaak_f32 v210, v210, v212, 0x358637bd
	v_rsq_f32_e32 v210, v210
	s_nop 0
	v_lshlrev_b32_e32 v200, 16, v144
	v_and_b32_e32 v201, 0xffff0000, v144
	v_pk_mul_f32 v[200:201], v[200:201], v[210:211] op_sel_hi:[1,0]
	v_pk_fma_f32 v[184:185], v[8:9], v[200:201], v[184:185]
	v_lshlrev_b32_e32 v202, 16, v145
	v_and_b32_e32 v203, 0xffff0000, v145
	v_pk_mul_f32 v[202:203], v[202:203], v[210:211] op_sel_hi:[1,0]
	v_pk_fma_f32 v[186:187], v[10:11], v[202:203], v[186:187]
	v_lshlrev_b32_e32 v200, 16, v146
	v_and_b32_e32 v201, 0xffff0000, v146
	v_pk_mul_f32 v[200:201], v[200:201], v[210:211] op_sel_hi:[1,0]
	v_pk_fma_f32 v[188:189], v[12:13], v[200:201], v[188:189]
	v_lshlrev_b32_e32 v202, 16, v147
	v_and_b32_e32 v203, 0xffff0000, v147
	v_pk_mul_f32 v[202:203], v[202:203], v[210:211] op_sel_hi:[1,0]
	v_pk_fma_f32 v[190:191], v[14:15], v[202:203], v[190:191]
	v_lshlrev_b32_e32 v200, 16, v148
	v_and_b32_e32 v201, 0xffff0000, v148
	v_pk_mul_f32 v[200:201], v[200:201], v[210:211] op_sel_hi:[1,0]
	v_pk_fma_f32 v[192:193], v[16:17], v[200:201], v[192:193]
	v_lshlrev_b32_e32 v202, 16, v149
	v_and_b32_e32 v203, 0xffff0000, v149
	v_pk_mul_f32 v[202:203], v[202:203], v[210:211] op_sel_hi:[1,0]
	v_pk_fma_f32 v[194:195], v[18:19], v[202:203], v[194:195]
	v_lshlrev_b32_e32 v200, 16, v150
	v_and_b32_e32 v201, 0xffff0000, v150
	v_pk_mul_f32 v[200:201], v[200:201], v[210:211] op_sel_hi:[1,0]
	v_pk_fma_f32 v[196:197], v[20:21], v[200:201], v[196:197]
	v_lshlrev_b32_e32 v202, 16, v151
; __device__ __forceinline__ unsigned cvtpk(float lo, float hi) { f32x2 v = {lo, hi}; bf16x2_t b = __builtin_convertvector(v, bf16x2_t); return __builtin_bit_cast(unsigned, b); }
; __device__ __forceinline__ void phase_rowwise(const void* xsrc_, bool sbf, void* xdst_, bool dbf, const bf16_t* Y, bf16_t* H, const float* mods, int lprev, int iprev, const float* lnpost, float resw, ...
;     ...
;             if (rr + 2 < 32) {
; #pragma unroll
;                 for (int r = 0; r < 2; ++r)
; #pragma unroll
;                     for (int j = 0; j < 4; ++j) { if (sbf) xnb[r][j] = *(const u32x2*)(xsrcb + (m + 2 + r) * DM + 4 * lane + 256 * j); else xn[r][j] = *(const f32x4*)(xsrc + (m + 2 + r) * DM + 4 * lane + 256 * j); if (hasprev) yn[r][j] = *(const u32x2*)(Y + (m + 2 + r) * DM + 4 * lane + 256 * j); } }
;     ...
;                     for (int j = 0; j < 4; ++j) x[r][j] = x[r][j] + gp[j] * (y[r][j] * rs); }
;             }
; #pragma unroll
;             for (int r = 0; r < 2; ++r)
; #pragma unroll
;                 for (int j = 0; j < 4; ++j) { if (hasprev) { if (dbf) { u32x2 w; w.x = cvtpk(x[r][j].x, x[r][j].y); w.y = cvtpk(x[r][j].z, x[r][j].w); *(u32x2*)(xdstb + (m + r) * DM + 4 * lane + 256 * j) = w; } else *(f32x4*)(xdst + (m + r) * DM + 4 * lane + 256 * j) = x[r][j]; } }
;             if (hasnext) {
;                 float ss[2] = {0.f, 0.f};
; #pragma unroll
;                 for (int r = 0; r < 2; ++r)
; #pragma unroll
;                     for (int j = 0; j < 4; ++j) ss[r] += (x[r][j].x * x[r][j].x + x[r][j].y * x[r][j].y) + (x[r][j].z * x[r][j].z + x[r][j].w * x[r][j].w);
; #pragma unroll
;                 for (int off = 1; off < 64; off <<= 1) { ss[0] += __shfl_xor(ss[0], off); ss[1] += __shfl_xor(ss[1], off); }
; #pragma unroll
;                 for (int r = 0; r < 2; ++r) { const float rs = __builtin_amdgcn_rsqf(ss[r] * (1.f / DM) + EPS);
; #pragma unroll
;                     for (int j = 0; j < 4; ++j) { const f32x4 h = (x[r][j] * rs) * na[j] + ns[j]; u32x2 w; w.x = cvtpk(h.x, h.y); w.y = cvtpk(h.z, h.w); *(u32x2*)(H + (m + r) * DM + 4 * lane + 256 * j) = w; } }
	v_and_b32_e32 v203, 0xffff0000, v151
	v_pk_mul_f32 v[202:203], v[202:203], v[210:211] op_sel_hi:[1,0]
	v_pk_fma_f32 v[198:199], v[22:23], v[202:203], v[198:199]
	s_add_i32 s81, s80, 1
	s_add_i32 s81, s81, s82
	s_and_b32 s81, s81, 31
	s_lshl_b32 s83, s81, 11
	v_add_u32_e32 v2, s83, v1
	v_cvt_pk_bf16_f32 v144, v184, v185
	v_cvt_pk_bf16_f32 v145, v186, v187
	v_cvt_pk_bf16_f32 v146, v188, v189
	v_cvt_pk_bf16_f32 v147, v190, v191
	v_cvt_pk_bf16_f32 v148, v192, v193
	v_cvt_pk_bf16_f32 v149, v194, v195
	v_cvt_pk_bf16_f32 v150, v196, v197
	v_cvt_pk_bf16_f32 v151, v198, v199
	global_store_dwordx4 v2, v[144:147], s[76:77] nt
	global_store_dwordx4 v2, v[148:151], s[76:77] offset:1024 nt
	v_pk_mul_f32 v[204:205], v[184:185], v[184:185]
	v_pk_mul_f32 v[206:207], v[186:187], v[186:187]
	v_pk_fma_f32 v[204:205], v[188:189], v[188:189], v[204:205]
	v_pk_fma_f32 v[206:207], v[190:191], v[190:191], v[206:207]
	v_pk_fma_f32 v[204:205], v[192:193], v[192:193], v[204:205]
	v_pk_fma_f32 v[206:207], v[194:195], v[194:195], v[206:207]
	v_pk_fma_f32 v[204:205], v[196:197], v[196:197], v[204:205]
	v_pk_fma_f32 v[206:207], v[198:199], v[198:199], v[206:207]
	v_pk_add_f32 v[204:205], v[204:205], v[206:207]
	v_add_f32_e32 v208, v204, v205
	s_nop 0
	s_nop 0
	v_add_f32_dpp v208, v208, v208 quad_perm:[1,0,3,2] row_mask:0xf bank_mask:0xf
	s_nop 0
	s_nop 0
	v_add_f32_dpp v208, v208, v208 quad_perm:[2,3,0,1] row_mask:0xf bank_mask:0xf
	s_nop 0
	s_nop 0
	v_add_f32_dpp v208, v208, v208 row_half_mirror row_mask:0xf bank_mask:0xf
	s_nop 0
	s_nop 0
	v_add_f32_dpp v208, v208, v208 row_mirror row_mask:0xf bank_mask:0xf
	s_nop 0
	s_nop 0
	v_add_f32_dpp v208, v208, v208 row_bcast:15 row_mask:0xa bank_mask:0xf
	s_nop 0
	s_nop 0
	v_add_f32_dpp v208, v208, v208 row_bcast:31 row_mask:0xc bank_mask:0xf
	s_nop 0
	s_nop 0
	v_readlane_b32 s60, v208, 63
	s_nop 1
	v_mov_b32_e32 v210, s60
	v_fmaak_f32 v210, v210, v212, 0x358637bd
	v_rsq_f32_e32 v210, v210
	s_nop 0
	v_pk_mul_f32 v[200:201], v[184:185], v[210:211] op_sel_hi:[1,0]
	v_pk_fma_f32 v[200:201], v[200:201], v[24:25], v[40:41]
	v_cvt_pk_bf16_f32 v136, v200, v201
	v_pk_mul_f32 v[202:203], v[186:187], v[210:211] op_sel_hi:[1,0]
	v_pk_fma_f32 v[202:203], v[202:203], v[26:27], v[42:43]
	v_cvt_pk_bf16_f32 v137, v202, v203
	v_pk_mul_f32 v[200:201], v[188:189], v[210:211] op_sel_hi:[1,0]
	v_pk_fma_f32 v[200:201], v[200:201], v[28:29], v[44:45]
	v_cvt_pk_bf16_f32 v138, v200, v201
	v_pk_mul_f32 v[202:203], v[190:191], v[210:211] op_sel_hi:[1,0]
	v_pk_fma_f32 v[202:203], v[202:203], v[30:31], v[46:47]
	v_cvt_pk_bf16_f32 v139, v202, v203
	v_pk_mul_f32 v[200:201], v[192:193], v[210:211] op_sel_hi:[1,0]
	v_pk_fma_f32 v[200:201], v[200:201], v[32:33], v[48:49]
	v_cvt_pk_bf16_f32 v140, v200, v201
	v_pk_mul_f32 v[202:203], v[194:195], v[210:211] op_sel_hi:[1,0]
	v_pk_fma_f32 v[202:203], v[202:203], v[34:35], v[50:51]
	v_cvt_pk_bf16_f32 v141, v202, v203
	v_pk_mul_f32 v[200:201], v[196:197], v[210:211] op_sel_hi:[1,0]
	v_pk_fma_f32 v[200:201], v[200:201], v[36:37], v[52:53]
	v_cvt_pk_bf16_f32 v142, v200, v201
	v_pk_mul_f32 v[202:203], v[198:199], v[210:211] op_sel_hi:[1,0]
	v_pk_fma_f32 v[202:203], v[202:203], v[38:39], v[54:55]
	v_cvt_pk_bf16_f32 v143, v202, v203
	global_store_dwordx4 v2, v[136:139], s[78:79] nt
	global_store_dwordx4 v2, v[140:143], s[78:79] offset:1024 nt
	s_add_i32 s81, s82, 6
	s_cmp_lt_u32 s81, 32
	s_cbranch_scc0 .Lrw_MID_l2_d
	s_add_i32 s81, s80, 6
	s_add_i32 s81, s81, s82
	s_and_b32 s81, s81, 31
	s_lshl_b32 s83, s81, 11
	v_add_u32_e32 v2, s83, v1
	global_load_dwordx4 v[104:107], v2, s[72:73] nt
	global_load_dwordx4 v[108:111], v2, s[72:73] offset:1024 nt
	global_load_dwordx4 v[112:115], v2, s[74:75] nt
	global_load_dwordx4 v[116:119], v2, s[74:75] offset:1024 nt
	s_branch .Lrw_MID_l2_e

; __device__ __forceinline__ float bflo(unsigned u) { return __uint_as_float(u << 16); }
; __device__ __forceinline__ float bfhi(unsigned u) { return __uint_as_float(u & 0xffff0000u); }
; __device__ __forceinline__ void phase_rowwise(const void* xsrc_, bool sbf, void* xdst_, bool dbf, const bf16_t* Y, bf16_t* H, const float* mods, int lprev, int iprev, const float* lnpost, float resw, ...
;     ...
;             if (hasprev) {
;                 f32x4 y[2][4]; float ss[2] = {0.f, 0.f};
; #pragma unroll
;                 for (int r = 0; r < 2; ++r)
; #pragma unroll
;                     for (int j = 0; j < 4; ++j) { const u32x2 u = yr[r][j]; y[r][j] = (f32x4){bflo(u.x), bfhi(u.x), bflo(u.y), bfhi(u.y)};
;                         ss[r] += (y[r][j].x * y[r][j].x + y[r][j].y * y[r][j].y) + (y[r][j].z * y[r][j].z + y[r][j].w * y[r][j].w); }
; #pragma unroll
;                 for (int off = 1; off < 64; off <<= 1) { ss[0] += __shfl_xor(ss[0], off); ss[1] += __shfl_xor(ss[1], off); }
; #pragma unroll
;                 for (int r = 0; r < 2; ++r) { const float rs = __builtin_amdgcn_rsqf(ss[r] * (1.f / DM) + EPS);
; #pragma unroll
;                     for (int j = 0; j < 4; ++j) x[r][j] = x[r][j] + gp[j] * (y[r][j] * rs); }
.Lrw_MID_l2_e:
	s_waitcnt vmcnt(32)
	v_lshlrev_b32_e32 v200, 16, v160
	v_and_b32_e32 v201, 0xffff0000, v160
	v_pk_mul_f32 v[204:205], v[200:201], v[200:201]
	v_lshlrev_b32_e32 v202, 16, v161
	v_and_b32_e32 v203, 0xffff0000, v161
	v_pk_mul_f32 v[206:207], v[202:203], v[202:203]
	v_lshlrev_b32_e32 v200, 16, v162
	v_and_b32_e32 v201, 0xffff0000, v162
	v_pk_fma_f32 v[204:205], v[200:201], v[200:201], v[204:205]
	v_lshlrev_b32_e32 v202, 16, v163
	v_and_b32_e32 v203, 0xffff0000, v163
	v_pk_fma_f32 v[206:207], v[202:203], v[202:203], v[206:207]
	v_lshlrev_b32_e32 v200, 16, v164
	v_and_b32_e32 v201, 0xffff0000, v164
	v_pk_fma_f32 v[204:205], v[200:201], v[200:201], v[204:205]
	v_lshlrev_b32_e32 v202, 16, v165
	v_and_b32_e32 v203, 0xffff0000, v165
	v_pk_fma_f32 v[206:207], v[202:203], v[202:203], v[206:207]
	v_lshlrev_b32_e32 v200, 16, v166
	v_and_b32_e32 v201, 0xffff0000, v166
	v_pk_fma_f32 v[204:205], v[200:201], v[200:201], v[204:205]
	v_lshlrev_b32_e32 v202, 16, v167
	v_and_b32_e32 v203, 0xffff0000, v167
	v_pk_fma_f32 v[206:207], v[202:203], v[202:203], v[206:207]
	v_pk_add_f32 v[204:205], v[204:205], v[206:207]
	v_add_f32_e32 v208, v204, v205
	v_lshlrev_b32_e32 v184, 16, v152
	v_and_b32_e32 v185, 0xffff0000, v152
	v_add_f32_dpp v208, v208, v208 quad_perm:[1,0,3,2] row_mask:0xf bank_mask:0xf
	v_lshlrev_b32_e32 v186, 16, v153
	v_and_b32_e32 v187, 0xffff0000, v153
	v_add_f32_dpp v208, v208, v208 quad_perm:[2,3,0,1] row_mask:0xf bank_mask:0xf
	v_lshlrev_b32_e32 v188, 16, v154
	v_and_b32_e32 v189, 0xffff0000, v154
	v_add_f32_dpp v208, v208, v208 row_half_mirror row_mask:0xf bank_mask:0xf
	v_lshlrev_b32_e32 v190, 16, v155
	v_and_b32_e32 v191, 0xffff0000, v155
	v_add_f32_dpp v208, v208, v208 row_mirror row_mask:0xf bank_mask:0xf
	v_lshlrev_b32_e32 v192, 16, v156
	v_and_b32_e32 v193, 0xffff0000, v156
	v_add_f32_dpp v208, v208, v208 row_bcast:15 row_mask:0xa bank_mask:0xf
	v_lshlrev_b32_e32 v194, 16, v157
	v_and_b32_e32 v195, 0xffff0000, v157
	v_add_f32_dpp v208, v208, v208 row_bcast:31 row_mask:0xc bank_mask:0xf
	v_lshlrev_b32_e32 v196, 16, v158
	v_and_b32_e32 v197, 0xffff0000, v158
	v_readlane_b32 s60, v208, 63
	s_nop 1
	v_lshlrev_b32_e32 v198, 16, v159
	v_and_b32_e32 v199, 0xffff0000, v159
	v_mov_b32_e32 v210, s60
	v_fmaak_f32 v210, v210, v212, 0x358637bd
	v_rsq_f32_e32 v210, v210
	s_nop 0
	v_lshlrev_b32_e32 v200, 16, v160
	v_and_b32_e32 v201, 0xffff0000, v160
	v_pk_mul_f32 v[200:201], v[200:201], v[210:211] op_sel_hi:[1,0]
	v_pk_fma_f32 v[184:185], v[8:9], v[200:201], v[184:185]
	v_lshlrev_b32_e32 v202, 16, v161
	v_and_b32_e32 v203, 0xffff0000, v161
	v_pk_mul_f32 v[202:203], v[202:203], v[210:211] op_sel_hi:[1,0]
	v_pk_fma_f32 v[186:187], v[10:11], v[202:203], v[186:187]
	v_lshlrev_b32_e32 v200, 16, v162
	v_and_b32_e32 v201, 0xffff0000, v162
	v_pk_mul_f32 v[200:201], v[200:201], v[210:211] op_sel_hi:[1,0]
	v_pk_fma_f32 v[188:189], v[12:13], v[200:201], v[188:189]
	v_lshlrev_b32_e32 v202, 16, v163
	v_and_b32_e32 v203, 0xffff0000, v163
	v_pk_mul_f32 v[202:203], v[202:203], v[210:211] op_sel_hi:[1,0]
	v_pk_fma_f32 v[190:191], v[14:15], v[202:203], v[190:191]
	v_lshlrev_b32_e32 v200, 16, v164
	v_and_b32_e32 v201, 0xffff0000, v164
	v_pk_mul_f32 v[200:201], v[200:201], v[210:211] op_sel_hi:[1,0]
	v_pk_fma_f32 v[192:193], v[16:17], v[200:201], v[192:193]
	v_lshlrev_b32_e32 v202, 16, v165
	v_and_b32_e32 v203, 0xffff0000, v165
	v_pk_mul_f32 v[202:203], v[202:203], v[210:211] op_sel_hi:[1,0]
	v_pk_fma_f32 v[194:195], v[18:19], v[202:203], v[194:195]
	v_lshlrev_b32_e32 v200, 16, v166
	v_and_b32_e32 v201, 0xffff0000, v166
	v_pk_mul_f32 v[200:201], v[200:201], v[210:211] op_sel_hi:[1,0]
	v_pk_fma_f32 v[196:197], v[20:21], v[200:201], v[196:197]
	v_lshlrev_b32_e32 v202, 16, v167
; __device__ __forceinline__ unsigned cvtpk(float lo, float hi) { f32x2 v = {lo, hi}; bf16x2_t b = __builtin_convertvector(v, bf16x2_t); return __builtin_bit_cast(unsigned, b); }
; __device__ __forceinline__ void phase_rowwise(const void* xsrc_, bool sbf, void* xdst_, bool dbf, const bf16_t* Y, bf16_t* H, const float* mods, int lprev, int iprev, const float* lnpost, float resw, ...
;     ...
;             if (rr + 2 < 32) {
; #pragma unroll
;                 for (int r = 0; r < 2; ++r)
; #pragma unroll
;                     for (int j = 0; j < 4; ++j) { if (sbf) xnb[r][j] = *(const u32x2*)(xsrcb + (m + 2 + r) * DM + 4 * lane + 256 * j); else xn[r][j] = *(const f32x4*)(xsrc + (m + 2 + r) * DM + 4 * lane + 256 * j); if (hasprev) yn[r][j] = *(const u32x2*)(Y + (m + 2 + r) * DM + 4 * lane + 256 * j); } }
;     ...
;                     for (int j = 0; j < 4; ++j) x[r][j] = x[r][j] + gp[j] * (y[r][j] * rs); }
;             }
; #pragma unroll
;             for (int r = 0; r < 2; ++r)
; #pragma unroll
;                 for (int j = 0; j < 4; ++j) { if (hasprev) { if (dbf) { u32x2 w; w.x = cvtpk(x[r][j].x, x[r][j].y); w.y = cvtpk(x[r][j].z, x[r][j].w); *(u32x2*)(xdstb + (m + r) * DM + 4 * lane + 256 * j) = w; } else *(f32x4*)(xdst + (m + r) * DM + 4 * lane + 256 * j) = x[r][j]; } }
;             if (hasnext) {
;                 float ss[2] = {0.f, 0.f};
; #pragma unroll
;                 for (int r = 0; r < 2; ++r)
; #pragma unroll
;                     for (int j = 0; j < 4; ++j) ss[r] += (x[r][j].x * x[r][j].x + x[r][j].y * x[r][j].y) + (x[r][j].z * x[r][j].z + x[r][j].w * x[r][j].w);
; #pragma unroll
;                 for (int off = 1; off < 64; off <<= 1) { ss[0] += __shfl_xor(ss[0], off); ss[1] += __shfl_xor(ss[1], off); }
; #pragma unroll
;                 for (int r = 0; r < 2; ++r) { const float rs = __builtin_amdgcn_rsqf(ss[r] * (1.f / DM) + EPS);
; #pragma unroll
;                     for (int j = 0; j < 4; ++j) { const f32x4 h = (x[r][j] * rs) * na[j] + ns[j]; u32x2 w; w.x = cvtpk(h.x, h.y); w.y = cvtpk(h.z, h.w); *(u32x2*)(H + (m + r) * DM + 4 * lane + 256 * j) = w; } }
	v_and_b32_e32 v203, 0xffff0000, v167
	v_pk_mul_f32 v[202:203], v[202:203], v[210:211] op_sel_hi:[1,0]
	v_pk_fma_f32 v[198:199], v[22:23], v[202:203], v[198:199]
	s_add_i32 s81, s80, 2
	s_add_i32 s81, s81, s82
	s_and_b32 s81, s81, 31
	s_lshl_b32 s83, s81, 11
	v_add_u32_e32 v2, s83, v1
	v_cvt_pk_bf16_f32 v160, v184, v185
	v_cvt_pk_bf16_f32 v161, v186, v187
	v_cvt_pk_bf16_f32 v162, v188, v189
	v_cvt_pk_bf16_f32 v163, v190, v191
	v_cvt_pk_bf16_f32 v164, v192, v193
	v_cvt_pk_bf16_f32 v165, v194, v195
	v_cvt_pk_bf16_f32 v166, v196, v197
	v_cvt_pk_bf16_f32 v167, v198, v199
	global_store_dwordx4 v2, v[160:163], s[76:77] nt
	global_store_dwordx4 v2, v[164:167], s[76:77] offset:1024 nt
	v_pk_mul_f32 v[204:205], v[184:185], v[184:185]
	v_pk_mul_f32 v[206:207], v[186:187], v[186:187]
	v_pk_fma_f32 v[204:205], v[188:189], v[188:189], v[204:205]
	v_pk_fma_f32 v[206:207], v[190:191], v[190:191], v[206:207]
	v_pk_fma_f32 v[204:205], v[192:193], v[192:193], v[204:205]
	v_pk_fma_f32 v[206:207], v[194:195], v[194:195], v[206:207]
	v_pk_fma_f32 v[204:205], v[196:197], v[196:197], v[204:205]
	v_pk_fma_f32 v[206:207], v[198:199], v[198:199], v[206:207]
	v_pk_add_f32 v[204:205], v[204:205], v[206:207]
	v_add_f32_e32 v208, v204, v205
	s_nop 0
	s_nop 0
	v_add_f32_dpp v208, v208, v208 quad_perm:[1,0,3,2] row_mask:0xf bank_mask:0xf
	s_nop 0
	s_nop 0
	v_add_f32_dpp v208, v208, v208 quad_perm:[2,3,0,1] row_mask:0xf bank_mask:0xf
	s_nop 0
	s_nop 0
	v_add_f32_dpp v208, v208, v208 row_half_mirror row_mask:0xf bank_mask:0xf
	s_nop 0
	s_nop 0
	v_add_f32_dpp v208, v208, v208 row_mirror row_mask:0xf bank_mask:0xf
	s_nop 0
	s_nop 0
	v_add_f32_dpp v208, v208, v208 row_bcast:15 row_mask:0xa bank_mask:0xf
	s_nop 0
	s_nop 0
	v_add_f32_dpp v208, v208, v208 row_bcast:31 row_mask:0xc bank_mask:0xf
	s_nop 0
	s_nop 0
	v_readlane_b32 s60, v208, 63
	s_nop 1
	v_mov_b32_e32 v210, s60
	v_fmaak_f32 v210, v210, v212, 0x358637bd
	v_rsq_f32_e32 v210, v210
	s_nop 0
	v_pk_mul_f32 v[200:201], v[184:185], v[210:211] op_sel_hi:[1,0]
	v_pk_fma_f32 v[200:201], v[200:201], v[24:25], v[40:41]
	v_cvt_pk_bf16_f32 v152, v200, v201
	v_pk_mul_f32 v[202:203], v[186:187], v[210:211] op_sel_hi:[1,0]
	v_pk_fma_f32 v[202:203], v[202:203], v[26:27], v[42:43]
	v_cvt_pk_bf16_f32 v153, v202, v203
	v_pk_mul_f32 v[200:201], v[188:189], v[210:211] op_sel_hi:[1,0]
	v_pk_fma_f32 v[200:201], v[200:201], v[28:29], v[44:45]
	v_cvt_pk_bf16_f32 v154, v200, v201
	v_pk_mul_f32 v[202:203], v[190:191], v[210:211] op_sel_hi:[1,0]
	v_pk_fma_f32 v[202:203], v[202:203], v[30:31], v[46:47]
	v_cvt_pk_bf16_f32 v155, v202, v203
	v_pk_mul_f32 v[200:201], v[192:193], v[210:211] op_sel_hi:[1,0]
	v_pk_fma_f32 v[200:201], v[200:201], v[32:33], v[48:49]
	v_cvt_pk_bf16_f32 v156, v200, v201
	v_pk_mul_f32 v[202:203], v[194:195], v[210:211] op_sel_hi:[1,0]
	v_pk_fma_f32 v[202:203], v[202:203], v[34:35], v[50:51]
	v_cvt_pk_bf16_f32 v157, v202, v203
	v_pk_mul_f32 v[200:201], v[196:197], v[210:211] op_sel_hi:[1,0]
	v_pk_fma_f32 v[200:201], v[200:201], v[36:37], v[52:53]
	v_cvt_pk_bf16_f32 v158, v200, v201
	v_pk_mul_f32 v[202:203], v[198:199], v[210:211] op_sel_hi:[1,0]
	v_pk_fma_f32 v[202:203], v[202:203], v[38:39], v[54:55]
	v_cvt_pk_bf16_f32 v159, v202, v203
	global_store_dwordx4 v2, v[152:155], s[78:79] nt
	global_store_dwordx4 v2, v[156:159], s[78:79] offset:1024 nt
	s_add_i32 s81, s82, 7
	s_cmp_lt_u32 s81, 32
	s_cbranch_scc0 .Lrw_MID_l3_d
	s_add_i32 s81, s80, 7
	s_add_i32 s81, s81, s82
	s_and_b32 s81, s81, 31
	s_lshl_b32 s83, s81, 11
	v_add_u32_e32 v2, s83, v1
	global_load_dwordx4 v[120:123], v2, s[72:73] nt
	global_load_dwordx4 v[124:127], v2, s[72:73] offset:1024 nt
	global_load_dwordx4 v[128:131], v2, s[74:75] nt
	global_load_dwordx4 v[132:135], v2, s[74:75] offset:1024 nt
	s_branch .Lrw_MID_l3_e

; __device__ __forceinline__ float bflo(unsigned u) { return __uint_as_float(u << 16); }
; __device__ __forceinline__ void phase_rowwise(const void* xsrc_, bool sbf, void* xdst_, bool dbf, const bf16_t* Y, bf16_t* H, const float* mods, int lprev, int iprev, const float* lnpost, float resw, ...
;     ...
;             if (hasprev) {
;                 f32x4 y[2][4]; float ss[2] = {0.f, 0.f};
; #pragma unroll
;                 for (int r = 0; r < 2; ++r)
; #pragma unroll
;                     for (int j = 0; j < 4; ++j) { const u32x2 u = yr[r][j]; y[r][j] = (f32x4){bflo(u.x), bfhi(u.x), bflo(u.y), bfhi(u.y)};
;                         ss[r] += (y[r][j].x * y[r][j].x + y[r][j].y * y[r][j].y) + (y[r][j].z * y[r][j].z + y[r][j].w * y[r][j].w); }
; #pragma unroll
;                 for (int off = 1; off < 64; off <<= 1) { ss[0] += __shfl_xor(ss[0], off); ss[1] += __shfl_xor(ss[1], off); }
; #pragma unroll
;                 for (int r = 0; r < 2; ++r) { const float rs = __builtin_amdgcn_rsqf(ss[r] * (1.f / DM) + EPS);
; #pragma unroll
;                     for (int j = 0; j < 4; ++j) x[r][j] = x[r][j] + gp[j] * (y[r][j] * rs); }
;             }
; #pragma unroll
;             for (int r = 0; r < 2; ++r)
; #pragma unroll
;                 for (int j = 0; j < 4; ++j) { if (hasprev) { if (dbf) { u32x2 w; w.x = cvtpk(x[r][j].x, x[r][j].y); w.y = cvtpk(x[r][j].z, x[r][j].w); *(u32x2*)(xdstb + (m + r) * DM + 4 * lane + 256 * j) = w; } else *(f32x4*)(xdst + (m + r) * DM + 4 * lane + 256 * j) = x[r][j]; } }
;             if (hasnext) {
;                 float ss[2] = {0.f, 0.f};
; #pragma unroll
;                 for (int r = 0; r < 2; ++r)
; #pragma unroll
;                     for (int j = 0; j < 4; ++j) ss[r] += (x[r][j].x * x[r][j].x + x[r][j].y * x[r][j].y) + (x[r][j].z * x[r][j].z + x[r][j].w * x[r][j].w);
; #pragma unroll
;                 for (int off = 1; off < 64; off <<= 1) { ss[0] += __shfl_xor(ss[0], off); ss[1] += __shfl_xor(ss[1], off); }
; #pragma unroll
;                 for (int r = 0; r < 2; ++r) { const float rs = __builtin_amdgcn_rsqf(ss[r] * (1.f / DM) + EPS);
; #pragma unroll
;                     for (int j = 0; j < 4; ++j) { const f32x4 h = (x[r][j] * rs) * na[j] + ns[j]; u32x2 w; w.x = cvtpk(h.x, h.y); w.y = cvtpk(h.z, h.w); *(u32x2*)(H + (m + r) * DM + 4 * lane + 256 * j) = w; } }
.Lrw_MID_l3_e:
	s_waitcnt vmcnt(32)
	v_lshlrev_b32_e32 v200, 16, v64
	v_and_b32_e32 v201, 0xffff0000, v64
	v_pk_mul_f32 v[204:205], v[200:201], v[200:201]
	v_lshlrev_b32_e32 v202, 16, v65
	v_and_b32_e32 v203, 0xffff0000, v65
	v_pk_mul_f32 v[206:207], v[202:203], v[202:203]
	v_lshlrev_b32_e32 v200, 16, v66
	v_and_b32_e32 v201, 0xffff0000, v66
	v_pk_fma_f32 v[204:205], v[200:201], v[200:201], v[204:205]
	v_lshlrev_b32_e32 v202, 16, v67
	v_and_b32_e32 v203, 0xffff0000, v67
	v_pk_fma_f32 v[206:207], v[202:203], v[202:203], v[206:207]
	v_lshlrev_b32_e32 v200, 16, v68
	v_and_b32_e32 v201, 0xffff0000, v68
	v_pk_fma_f32 v[204:205], v[200:201], v[200:201], v[204:205]
	v_lshlrev_b32_e32 v202, 16, v69
	v_and_b32_e32 v203, 0xffff0000, v69
	v_pk_fma_f32 v[206:207], v[202:203], v[202:203], v[206:207]
	v_lshlrev_b32_e32 v200, 16, v70
	v_and_b32_e32 v201, 0xffff0000, v70
	v_pk_fma_f32 v[204:205], v[200:201], v[200:201], v[204:205]
	v_lshlrev_b32_e32 v202, 16, v71
	v_and_b32_e32 v203, 0xffff0000, v71
	v_pk_fma_f32 v[206:207], v[202:203], v[202:203], v[206:207]
	v_pk_add_f32 v[204:205], v[204:205], v[206:207]
	v_add_f32_e32 v208, v204, v205
	v_lshlrev_b32_e32 v184, 16, v56
	v_and_b32_e32 v185, 0xffff0000, v56
	v_add_f32_dpp v208, v208, v208 quad_perm:[1,0,3,2] row_mask:0xf bank_mask:0xf
	v_lshlrev_b32_e32 v186, 16, v57
	v_and_b32_e32 v187, 0xffff0000, v57
	v_add_f32_dpp v208, v208, v208 quad_perm:[2,3,0,1] row_mask:0xf bank_mask:0xf
	v_lshlrev_b32_e32 v188, 16, v58
	v_and_b32_e32 v189, 0xffff0000, v58
	v_add_f32_dpp v208, v208, v208 row_half_mirror row_mask:0xf bank_mask:0xf
	v_lshlrev_b32_e32 v190, 16, v59
	v_and_b32_e32 v191, 0xffff0000, v59
	v_add_f32_dpp v208, v208, v208 row_mirror row_mask:0xf bank_mask:0xf
	v_lshlrev_b32_e32 v192, 16, v60
	v_and_b32_e32 v193, 0xffff0000, v60
	v_add_f32_dpp v208, v208, v208 row_bcast:15 row_mask:0xa bank_mask:0xf
	v_lshlrev_b32_e32 v194, 16, v61
	v_and_b32_e32 v195, 0xffff0000, v61
	v_add_f32_dpp v208, v208, v208 row_bcast:31 row_mask:0xc bank_mask:0xf
	v_lshlrev_b32_e32 v196, 16, v62
	v_and_b32_e32 v197, 0xffff0000, v62
	v_readlane_b32 s60, v208, 63
	s_nop 1
	v_lshlrev_b32_e32 v198, 16, v63
	v_and_b32_e32 v199, 0xffff0000, v63
	v_mov_b32_e32 v210, s60
	v_fmaak_f32 v210, v210, v212, 0x358637bd
	v_rsq_f32_e32 v210, v210
	s_nop 0
	v_lshlrev_b32_e32 v200, 16, v64
	v_and_b32_e32 v201, 0xffff0000, v64
	v_pk_mul_f32 v[200:201], v[200:201], v[210:211] op_sel_hi:[1,0]
	v_pk_fma_f32 v[184:185], v[8:9], v[200:201], v[184:185]
	v_lshlrev_b32_e32 v202, 16, v65
	v_and_b32_e32 v203, 0xffff0000, v65
	v_pk_mul_f32 v[202:203], v[202:203], v[210:211] op_sel_hi:[1,0]
	v_pk_fma_f32 v[186:187], v[10:11], v[202:203], v[186:187]
	v_lshlrev_b32_e32 v200, 16, v66
	v_and_b32_e32 v201, 0xffff0000, v66
	v_pk_mul_f32 v[200:201], v[200:201], v[210:211] op_sel_hi:[1,0]
	v_pk_fma_f32 v[188:189], v[12:13], v[200:201], v[188:189]
	v_lshlrev_b32_e32 v202, 16, v67
	v_and_b32_e32 v203, 0xffff0000, v67
	v_pk_mul_f32 v[202:203], v[202:203], v[210:211] op_sel_hi:[1,0]
	v_pk_fma_f32 v[190:191], v[14:15], v[202:203], v[190:191]
	v_lshlrev_b32_e32 v200, 16, v68
	v_and_b32_e32 v201, 0xffff0000, v68
	v_pk_mul_f32 v[200:201], v[200:201], v[210:211] op_sel_hi:[1,0]
	v_pk_fma_f32 v[192:193], v[16:17], v[200:201], v[192:193]
	v_lshlrev_b32_e32 v202, 16, v69
	v_and_b32_e32 v203, 0xffff0000, v69
	v_pk_mul_f32 v[202:203], v[202:203], v[210:211] op_sel_hi:[1,0]
	v_pk_fma_f32 v[194:195], v[18:19], v[202:203], v[194:195]
	v_lshlrev_b32_e32 v200, 16, v70
	v_and_b32_e32 v201, 0xffff0000, v70
	v_pk_mul_f32 v[200:201], v[200:201], v[210:211] op_sel_hi:[1,0]
	v_pk_fma_f32 v[196:197], v[20:21], v[200:201], v[196:197]
	v_lshlrev_b32_e32 v202, 16, v71
	v_and_b32_e32 v203, 0xffff0000, v71
	v_pk_mul_f32 v[202:203], v[202:203], v[210:211] op_sel_hi:[1,0]
	v_pk_fma_f32 v[198:199], v[22:23], v[202:203], v[198:199]
	s_add_i32 s81, s80, 3
	s_add_i32 s81, s81, s82
	s_and_b32 s81, s81, 31
	s_lshl_b32 s83, s81, 11
	v_add_u32_e32 v2, s83, v1
	v_cvt_pk_bf16_f32 v64, v184, v185
	v_cvt_pk_bf16_f32 v65, v186, v187
	v_cvt_pk_bf16_f32 v66, v188, v189
	v_cvt_pk_bf16_f32 v67, v190, v191
	v_cvt_pk_bf16_f32 v68, v192, v193
	v_cvt_pk_bf16_f32 v69, v194, v195
	v_cvt_pk_bf16_f32 v70, v196, v197
	v_cvt_pk_bf16_f32 v71, v198, v199
	global_store_dwordx4 v2, v[64:67], s[76:77] nt
	global_store_dwordx4 v2, v[68:71], s[76:77] offset:1024 nt
	v_pk_mul_f32 v[204:205], v[184:185], v[184:185]
	v_pk_mul_f32 v[206:207], v[186:187], v[186:187]
	v_pk_fma_f32 v[204:205], v[188:189], v[188:189], v[204:205]
	v_pk_fma_f32 v[206:207], v[190:191], v[190:191], v[206:207]
	v_pk_fma_f32 v[204:205], v[192:193], v[192:193], v[204:205]
	v_pk_fma_f32 v[206:207], v[194:195], v[194:195], v[206:207]
	v_pk_fma_f32 v[204:205], v[196:197], v[196:197], v[204:205]
	v_pk_fma_f32 v[206:207], v[198:199], v[198:199], v[206:207]
	v_pk_add_f32 v[204:205], v[204:205], v[206:207]
	v_add_f32_e32 v208, v204, v205
	s_nop 0
	s_nop 0
	v_add_f32_dpp v208, v208, v208 quad_perm:[1,0,3,2] row_mask:0xf bank_mask:0xf
	s_nop 0
	s_nop 0
	v_add_f32_dpp v208, v208, v208 quad_perm:[2,3,0,1] row_mask:0xf bank_mask:0xf
	s_nop 0
	s_nop 0
	v_add_f32_dpp v208, v208, v208 row_half_mirror row_mask:0xf bank_mask:0xf
	s_nop 0
	s_nop 0
	v_add_f32_dpp v208, v208, v208 row_mirror row_mask:0xf bank_mask:0xf
	s_nop 0
	s_nop 0
	v_add_f32_dpp v208, v208, v208 row_bcast:15 row_mask:0xa bank_mask:0xf
	s_nop 0
	s_nop 0
	v_add_f32_dpp v208, v208, v208 row_bcast:31 row_mask:0xc bank_mask:0xf
	s_nop 0
	s_nop 0
	v_readlane_b32 s60, v208, 63
	s_nop 1
	v_mov_b32_e32 v210, s60
	v_fmaak_f32 v210, v210, v212, 0x358637bd
	v_rsq_f32_e32 v210, v210
	s_nop 0
	v_pk_mul_f32 v[200:201], v[184:185], v[210:211] op_sel_hi:[1,0]
	v_pk_fma_f32 v[200:201], v[200:201], v[24:25], v[40:41]
	v_cvt_pk_bf16_f32 v56, v200, v201
	v_pk_mul_f32 v[202:203], v[186:187], v[210:211] op_sel_hi:[1,0]
	v_pk_fma_f32 v[202:203], v[202:203], v[26:27], v[42:43]
	v_cvt_pk_bf16_f32 v57, v202, v203
	v_pk_mul_f32 v[200:201], v[188:189], v[210:211] op_sel_hi:[1,0]
	v_pk_fma_f32 v[200:201], v[200:201], v[28:29], v[44:45]
	v_cvt_pk_bf16_f32 v58, v200, v201
	v_pk_mul_f32 v[202:203], v[190:191], v[210:211] op_sel_hi:[1,0]
	v_pk_fma_f32 v[202:203], v[202:203], v[30:31], v[46:47]
	v_cvt_pk_bf16_f32 v59, v202, v203
	v_pk_mul_f32 v[200:201], v[192:193], v[210:211] op_sel_hi:[1,0]
	v_pk_fma_f32 v[200:201], v[200:201], v[32:33], v[48:49]
	v_cvt_pk_bf16_f32 v60, v200, v201
	v_pk_mul_f32 v[202:203], v[194:195], v[210:211] op_sel_hi:[1,0]
	v_pk_fma_f32 v[202:203], v[202:203], v[34:35], v[50:51]
	v_cvt_pk_bf16_f32 v61, v202, v203
	v_pk_mul_f32 v[200:201], v[196:197], v[210:211] op_sel_hi:[1,0]
	v_pk_fma_f32 v[200:201], v[200:201], v[36:37], v[52:53]
	v_cvt_pk_bf16_f32 v62, v200, v201
	v_pk_mul_f32 v[202:203], v[198:199], v[210:211] op_sel_hi:[1,0]
	v_pk_fma_f32 v[202:203], v[202:203], v[38:39], v[54:55]
	v_cvt_pk_bf16_f32 v63, v202, v203
	global_store_dwordx4 v2, v[56:59], s[78:79] nt
	global_store_dwordx4 v2, v[60:63], s[78:79] offset:1024 nt
	s_add_i32 s81, s82, 8
	s_cmp_lt_u32 s81, 32
	s_cbranch_scc0 .Lrw_MID_l4_d
; __device__ __forceinline__ void phase_rowwise(const void* xsrc_, bool sbf, void* xdst_, bool dbf, const bf16_t* Y, bf16_t* H, const float* mods, int lprev, int iprev, const float* lnpost, float resw, ...
;     ...
;             if (rr + 2 < 32) {
; #pragma unroll
;                 for (int r = 0; r < 2; ++r)
; #pragma unroll
;                     for (int j = 0; j < 4; ++j) { if (sbf) xnb[r][j] = *(const u32x2*)(xsrcb + (m + 2 + r) * DM + 4 * lane + 256 * j); else xn[r][j] = *(const f32x4*)(xsrc + (m + 2 + r) * DM + 4 * lane + 256 * j); if (hasprev) yn[r][j] = *(const u32x2*)(Y + (m + 2 + r) * DM + 4 * lane + 256 * j); } }
	s_add_i32 s81, s80, 8
	s_add_i32 s81, s81, s82
	s_and_b32 s81, s81, 31
	s_lshl_b32 s83, s81, 11
	v_add_u32_e32 v2, s83, v1
	global_load_dwordx4 v[136:139], v2, s[72:73] nt
	global_load_dwordx4 v[140:143], v2, s[72:73] offset:1024 nt
	global_load_dwordx4 v[144:147], v2, s[74:75] nt
	global_load_dwordx4 v[148:151], v2, s[74:75] offset:1024 nt
	s_branch .Lrw_MID_l4_e

; __device__ __forceinline__ float bflo(unsigned u) { return __uint_as_float(u << 16); }
; __device__ __forceinline__ void phase_rowwise(const void* xsrc_, bool sbf, void* xdst_, bool dbf, const bf16_t* Y, bf16_t* H, const float* mods, int lprev, int iprev, const float* lnpost, float resw, ...
;     ...
;             if (hasprev) {
;                 f32x4 y[2][4]; float ss[2] = {0.f, 0.f};
; #pragma unroll
;                 for (int r = 0; r < 2; ++r)
; #pragma unroll
;                     for (int j = 0; j < 4; ++j) { const u32x2 u = yr[r][j]; y[r][j] = (f32x4){bflo(u.x), bfhi(u.x), bflo(u.y), bfhi(u.y)};
;                         ss[r] += (y[r][j].x * y[r][j].x + y[r][j].y * y[r][j].y) + (y[r][j].z * y[r][j].z + y[r][j].w * y[r][j].w); }
; #pragma unroll
;                 for (int off = 1; off < 64; off <<= 1) { ss[0] += __shfl_xor(ss[0], off); ss[1] += __shfl_xor(ss[1], off); }
; #pragma unroll
;                 for (int r = 0; r < 2; ++r) { const float rs = __builtin_amdgcn_rsqf(ss[r] * (1.f / DM) + EPS);
; #pragma unroll
;                     for (int j = 0; j < 4; ++j) x[r][j] = x[r][j] + gp[j] * (y[r][j] * rs); }
;             }
; #pragma unroll
;             for (int r = 0; r < 2; ++r)
; #pragma unroll
;                 for (int j = 0; j < 4; ++j) { if (hasprev) { if (dbf) { u32x2 w; w.x = cvtpk(x[r][j].x, x[r][j].y); w.y = cvtpk(x[r][j].z, x[r][j].w); *(u32x2*)(xdstb + (m + r) * DM + 4 * lane + 256 * j) = w; } else *(f32x4*)(xdst + (m + r) * DM + 4 * lane + 256 * j) = x[r][j]; } }
;             if (hasnext) {
;                 float ss[2] = {0.f, 0.f};
; #pragma unroll
;                 for (int r = 0; r < 2; ++r)
; #pragma unroll
;                     for (int j = 0; j < 4; ++j) ss[r] += (x[r][j].x * x[r][j].x + x[r][j].y * x[r][j].y) + (x[r][j].z * x[r][j].z + x[r][j].w * x[r][j].w);
; #pragma unroll
;                 for (int off = 1; off < 64; off <<= 1) { ss[0] += __shfl_xor(ss[0], off); ss[1] += __shfl_xor(ss[1], off); }
; #pragma unroll
;                 for (int r = 0; r < 2; ++r) { const float rs = __builtin_amdgcn_rsqf(ss[r] * (1.f / DM) + EPS);
; #pragma unroll
;                     for (int j = 0; j < 4; ++j) { const f32x4 h = (x[r][j] * rs) * na[j] + ns[j]; u32x2 w; w.x = cvtpk(h.x, h.y); w.y = cvtpk(h.z, h.w); *(u32x2*)(H + (m + r) * DM + 4 * lane + 256 * j) = w; } }
.Lrw_MID_l4_e:
	s_waitcnt vmcnt(32)
	v_lshlrev_b32_e32 v200, 16, v80
	v_and_b32_e32 v201, 0xffff0000, v80
	v_pk_mul_f32 v[204:205], v[200:201], v[200:201]
	v_lshlrev_b32_e32 v202, 16, v81
	v_and_b32_e32 v203, 0xffff0000, v81
	v_pk_mul_f32 v[206:207], v[202:203], v[202:203]
	v_lshlrev_b32_e32 v200, 16, v82
	v_and_b32_e32 v201, 0xffff0000, v82
	v_pk_fma_f32 v[204:205], v[200:201], v[200:201], v[204:205]
	v_lshlrev_b32_e32 v202, 16, v83
	v_and_b32_e32 v203, 0xffff0000, v83
	v_pk_fma_f32 v[206:207], v[202:203], v[202:203], v[206:207]
	v_lshlrev_b32_e32 v200, 16, v84
	v_and_b32_e32 v201, 0xffff0000, v84
	v_pk_fma_f32 v[204:205], v[200:201], v[200:201], v[204:205]
	v_lshlrev_b32_e32 v202, 16, v85
	v_and_b32_e32 v203, 0xffff0000, v85
	v_pk_fma_f32 v[206:207], v[202:203], v[202:203], v[206:207]
	v_lshlrev_b32_e32 v200, 16, v86
	v_and_b32_e32 v201, 0xffff0000, v86
	v_pk_fma_f32 v[204:205], v[200:201], v[200:201], v[204:205]
	v_lshlrev_b32_e32 v202, 16, v87
	v_and_b32_e32 v203, 0xffff0000, v87
	v_pk_fma_f32 v[206:207], v[202:203], v[202:203], v[206:207]
	v_pk_add_f32 v[204:205], v[204:205], v[206:207]
	v_add_f32_e32 v208, v204, v205
	v_lshlrev_b32_e32 v184, 16, v72
	v_and_b32_e32 v185, 0xffff0000, v72
	v_add_f32_dpp v208, v208, v208 quad_perm:[1,0,3,2] row_mask:0xf bank_mask:0xf
	v_lshlrev_b32_e32 v186, 16, v73
	v_and_b32_e32 v187, 0xffff0000, v73
	v_add_f32_dpp v208, v208, v208 quad_perm:[2,3,0,1] row_mask:0xf bank_mask:0xf
	v_lshlrev_b32_e32 v188, 16, v74
	v_and_b32_e32 v189, 0xffff0000, v74
	v_add_f32_dpp v208, v208, v208 row_half_mirror row_mask:0xf bank_mask:0xf
	v_lshlrev_b32_e32 v190, 16, v75
	v_and_b32_e32 v191, 0xffff0000, v75
	v_add_f32_dpp v208, v208, v208 row_mirror row_mask:0xf bank_mask:0xf
	v_lshlrev_b32_e32 v192, 16, v76
	v_and_b32_e32 v193, 0xffff0000, v76
	v_add_f32_dpp v208, v208, v208 row_bcast:15 row_mask:0xa bank_mask:0xf
	v_lshlrev_b32_e32 v194, 16, v77
	v_and_b32_e32 v195, 0xffff0000, v77
	v_add_f32_dpp v208, v208, v208 row_bcast:31 row_mask:0xc bank_mask:0xf
	v_lshlrev_b32_e32 v196, 16, v78
	v_and_b32_e32 v197, 0xffff0000, v78
	v_readlane_b32 s60, v208, 63
	s_nop 1
	v_lshlrev_b32_e32 v198, 16, v79
	v_and_b32_e32 v199, 0xffff0000, v79
	v_mov_b32_e32 v210, s60
	v_fmaak_f32 v210, v210, v212, 0x358637bd
	v_rsq_f32_e32 v210, v210
	s_nop 0
	v_lshlrev_b32_e32 v200, 16, v80
	v_and_b32_e32 v201, 0xffff0000, v80
	v_pk_mul_f32 v[200:201], v[200:201], v[210:211] op_sel_hi:[1,0]
	v_pk_fma_f32 v[184:185], v[8:9], v[200:201], v[184:185]
	v_lshlrev_b32_e32 v202, 16, v81
	v_and_b32_e32 v203, 0xffff0000, v81
	v_pk_mul_f32 v[202:203], v[202:203], v[210:211] op_sel_hi:[1,0]
	v_pk_fma_f32 v[186:187], v[10:11], v[202:203], v[186:187]
	v_lshlrev_b32_e32 v200, 16, v82
	v_and_b32_e32 v201, 0xffff0000, v82
	v_pk_mul_f32 v[200:201], v[200:201], v[210:211] op_sel_hi:[1,0]
	v_pk_fma_f32 v[188:189], v[12:13], v[200:201], v[188:189]
	v_lshlrev_b32_e32 v202, 16, v83
	v_and_b32_e32 v203, 0xffff0000, v83
	v_pk_mul_f32 v[202:203], v[202:203], v[210:211] op_sel_hi:[1,0]
	v_pk_fma_f32 v[190:191], v[14:15], v[202:203], v[190:191]
	v_lshlrev_b32_e32 v200, 16, v84
	v_and_b32_e32 v201, 0xffff0000, v84
	v_pk_mul_f32 v[200:201], v[200:201], v[210:211] op_sel_hi:[1,0]
	v_pk_fma_f32 v[192:193], v[16:17], v[200:201], v[192:193]
	v_lshlrev_b32_e32 v202, 16, v85
	v_and_b32_e32 v203, 0xffff0000, v85
	v_pk_mul_f32 v[202:203], v[202:203], v[210:211] op_sel_hi:[1,0]
	v_pk_fma_f32 v[194:195], v[18:19], v[202:203], v[194:195]
	v_lshlrev_b32_e32 v200, 16, v86
	v_and_b32_e32 v201, 0xffff0000, v86
	v_pk_mul_f32 v[200:201], v[200:201], v[210:211] op_sel_hi:[1,0]
	v_pk_fma_f32 v[196:197], v[20:21], v[200:201], v[196:197]
	v_lshlrev_b32_e32 v202, 16, v87
	v_and_b32_e32 v203, 0xffff0000, v87
	v_pk_mul_f32 v[202:203], v[202:203], v[210:211] op_sel_hi:[1,0]
	v_pk_fma_f32 v[198:199], v[22:23], v[202:203], v[198:199]
	s_add_i32 s81, s80, 4
	s_add_i32 s81, s81, s82
	s_and_b32 s81, s81, 31
	s_lshl_b32 s83, s81, 11
	v_add_u32_e32 v2, s83, v1
	v_cvt_pk_bf16_f32 v80, v184, v185
	v_cvt_pk_bf16_f32 v81, v186, v187
	v_cvt_pk_bf16_f32 v82, v188, v189
	v_cvt_pk_bf16_f32 v83, v190, v191
	v_cvt_pk_bf16_f32 v84, v192, v193
	v_cvt_pk_bf16_f32 v85, v194, v195
	v_cvt_pk_bf16_f32 v86, v196, v197
	v_cvt_pk_bf16_f32 v87, v198, v199
	global_store_dwordx4 v2, v[80:83], s[76:77] nt
	global_store_dwordx4 v2, v[84:87], s[76:77] offset:1024 nt
	v_pk_mul_f32 v[204:205], v[184:185], v[184:185]
	v_pk_mul_f32 v[206:207], v[186:187], v[186:187]
	v_pk_fma_f32 v[204:205], v[188:189], v[188:189], v[204:205]
	v_pk_fma_f32 v[206:207], v[190:191], v[190:191], v[206:207]
	v_pk_fma_f32 v[204:205], v[192:193], v[192:193], v[204:205]
	v_pk_fma_f32 v[206:207], v[194:195], v[194:195], v[206:207]
	v_pk_fma_f32 v[204:205], v[196:197], v[196:197], v[204:205]
	v_pk_fma_f32 v[206:207], v[198:199], v[198:199], v[206:207]
	v_pk_add_f32 v[204:205], v[204:205], v[206:207]
	v_add_f32_e32 v208, v204, v205
	s_nop 0
	s_nop 0
	v_add_f32_dpp v208, v208, v208 quad_perm:[1,0,3,2] row_mask:0xf bank_mask:0xf
	s_nop 0
	s_nop 0
	v_add_f32_dpp v208, v208, v208 quad_perm:[2,3,0,1] row_mask:0xf bank_mask:0xf
	s_nop 0
	s_nop 0
	v_add_f32_dpp v208, v208, v208 row_half_mirror row_mask:0xf bank_mask:0xf
	s_nop 0
	s_nop 0
	v_add_f32_dpp v208, v208, v208 row_mirror row_mask:0xf bank_mask:0xf
	s_nop 0
	s_nop 0
	v_add_f32_dpp v208, v208, v208 row_bcast:15 row_mask:0xa bank_mask:0xf
	s_nop 0
	s_nop 0
	v_add_f32_dpp v208, v208, v208 row_bcast:31 row_mask:0xc bank_mask:0xf
	s_nop 0
	s_nop 0
	v_readlane_b32 s60, v208, 63
	s_nop 1
	v_mov_b32_e32 v210, s60
	v_fmaak_f32 v210, v210, v212, 0x358637bd
	v_rsq_f32_e32 v210, v210
	s_nop 0
	v_pk_mul_f32 v[200:201], v[184:185], v[210:211] op_sel_hi:[1,0]
	v_pk_fma_f32 v[200:201], v[200:201], v[24:25], v[40:41]
	v_cvt_pk_bf16_f32 v72, v200, v201
	v_pk_mul_f32 v[202:203], v[186:187], v[210:211] op_sel_hi:[1,0]
	v_pk_fma_f32 v[202:203], v[202:203], v[26:27], v[42:43]
	v_cvt_pk_bf16_f32 v73, v202, v203
	v_pk_mul_f32 v[200:201], v[188:189], v[210:211] op_sel_hi:[1,0]
	v_pk_fma_f32 v[200:201], v[200:201], v[28:29], v[44:45]
	v_cvt_pk_bf16_f32 v74, v200, v201
	v_pk_mul_f32 v[202:203], v[190:191], v[210:211] op_sel_hi:[1,0]
	v_pk_fma_f32 v[202:203], v[202:203], v[30:31], v[46:47]
	v_cvt_pk_bf16_f32 v75, v202, v203
	v_pk_mul_f32 v[200:201], v[192:193], v[210:211] op_sel_hi:[1,0]
	v_pk_fma_f32 v[200:201], v[200:201], v[32:33], v[48:49]
	v_cvt_pk_bf16_f32 v76, v200, v201
	v_pk_mul_f32 v[202:203], v[194:195], v[210:211] op_sel_hi:[1,0]
	v_pk_fma_f32 v[202:203], v[202:203], v[34:35], v[50:51]
	v_cvt_pk_bf16_f32 v77, v202, v203
	v_pk_mul_f32 v[200:201], v[196:197], v[210:211] op_sel_hi:[1,0]
	v_pk_fma_f32 v[200:201], v[200:201], v[36:37], v[52:53]
	v_cvt_pk_bf16_f32 v78, v200, v201
	v_pk_mul_f32 v[202:203], v[198:199], v[210:211] op_sel_hi:[1,0]
	v_pk_fma_f32 v[202:203], v[202:203], v[38:39], v[54:55]
	v_cvt_pk_bf16_f32 v79, v202, v203
	global_store_dwordx4 v2, v[72:75], s[78:79] nt
	global_store_dwordx4 v2, v[76:79], s[78:79] offset:1024 nt
	s_add_i32 s81, s82, 9
	s_cmp_lt_u32 s81, 32
	s_cbranch_scc0 .Lrw_MID_l5_d
; __device__ __forceinline__ void phase_rowwise(const void* xsrc_, bool sbf, void* xdst_, bool dbf, const bf16_t* Y, bf16_t* H, const float* mods, int lprev, int iprev, const float* lnpost, float resw, ...
;     ...
;             if (rr + 2 < 32) {
; #pragma unroll
;                 for (int r = 0; r < 2; ++r)
; #pragma unroll
;                     for (int j = 0; j < 4; ++j) { if (sbf) xnb[r][j] = *(const u32x2*)(xsrcb + (m + 2 + r) * DM + 4 * lane + 256 * j); else xn[r][j] = *(const f32x4*)(xsrc + (m + 2 + r) * DM + 4 * lane + 256 * j); if (hasprev) yn[r][j] = *(const u32x2*)(Y + (m + 2 + r) * DM + 4 * lane + 256 * j); } }
	s_add_i32 s81, s80, 9
	s_add_i32 s81, s81, s82
	s_and_b32 s81, s81, 31
	s_lshl_b32 s83, s81, 11
	v_add_u32_e32 v2, s83, v1
	global_load_dwordx4 v[152:155], v2, s[72:73] nt
	global_load_dwordx4 v[156:159], v2, s[72:73] offset:1024 nt
	global_load_dwordx4 v[160:163], v2, s[74:75] nt
	global_load_dwordx4 v[164:167], v2, s[74:75] offset:1024 nt
	s_branch .Lrw_MID_l5_e

; __device__ __forceinline__ float bflo(unsigned u) { return __uint_as_float(u << 16); }
; __device__ __forceinline__ float bfhi(unsigned u) { return __uint_as_float(u & 0xffff0000u); }
; __device__ __forceinline__ void phase_rowwise(const void* xsrc_, bool sbf, void* xdst_, bool dbf, const bf16_t* Y, bf16_t* H, const float* mods, int lprev, int iprev, const float* lnpost, float resw, ...
;     ...
;             if (hasprev) {
;                 f32x4 y[2][4]; float ss[2] = {0.f, 0.f};
; #pragma unroll
;                 for (int r = 0; r < 2; ++r)
; #pragma unroll
;                     for (int j = 0; j < 4; ++j) { const u32x2 u = yr[r][j]; y[r][j] = (f32x4){bflo(u.x), bfhi(u.x), bflo(u.y), bfhi(u.y)};
;                         ss[r] += (y[r][j].x * y[r][j].x + y[r][j].y * y[r][j].y) + (y[r][j].z * y[r][j].z + y[r][j].w * y[r][j].w); }
; #pragma unroll
;                 for (int off = 1; off < 64; off <<= 1) { ss[0] += __shfl_xor(ss[0], off); ss[1] += __shfl_xor(ss[1], off); }
; #pragma unroll
;                 for (int r = 0; r < 2; ++r) { const float rs = __builtin_amdgcn_rsqf(ss[r] * (1.f / DM) + EPS);
; #pragma unroll
;                     for (int j = 0; j < 4; ++j) x[r][j] = x[r][j] + gp[j] * (y[r][j] * rs); }
.Lrw_MID_l5_e:
	s_waitcnt vmcnt(32)
	v_lshlrev_b32_e32 v200, 16, v96
	v_and_b32_e32 v201, 0xffff0000, v96
	v_pk_mul_f32 v[204:205], v[200:201], v[200:201]
	v_lshlrev_b32_e32 v202, 16, v97
	v_and_b32_e32 v203, 0xffff0000, v97
	v_pk_mul_f32 v[206:207], v[202:203], v[202:203]
	v_lshlrev_b32_e32 v200, 16, v98
	v_and_b32_e32 v201, 0xffff0000, v98
	v_pk_fma_f32 v[204:205], v[200:201], v[200:201], v[204:205]
	v_lshlrev_b32_e32 v202, 16, v99
	v_and_b32_e32 v203, 0xffff0000, v99
	v_pk_fma_f32 v[206:207], v[202:203], v[202:203], v[206:207]
	v_lshlrev_b32_e32 v200, 16, v100
	v_and_b32_e32 v201, 0xffff0000, v100
	v_pk_fma_f32 v[204:205], v[200:201], v[200:201], v[204:205]
	v_lshlrev_b32_e32 v202, 16, v101
	v_and_b32_e32 v203, 0xffff0000, v101
	v_pk_fma_f32 v[206:207], v[202:203], v[202:203], v[206:207]
	v_lshlrev_b32_e32 v200, 16, v102
	v_and_b32_e32 v201, 0xffff0000, v102
	v_pk_fma_f32 v[204:205], v[200:201], v[200:201], v[204:205]
	v_lshlrev_b32_e32 v202, 16, v103
	v_and_b32_e32 v203, 0xffff0000, v103
	v_pk_fma_f32 v[206:207], v[202:203], v[202:203], v[206:207]
	v_pk_add_f32 v[204:205], v[204:205], v[206:207]
	v_add_f32_e32 v208, v204, v205
	v_lshlrev_b32_e32 v184, 16, v88
	v_and_b32_e32 v185, 0xffff0000, v88
	v_add_f32_dpp v208, v208, v208 quad_perm:[1,0,3,2] row_mask:0xf bank_mask:0xf
	v_lshlrev_b32_e32 v186, 16, v89
	v_and_b32_e32 v187, 0xffff0000, v89
	v_add_f32_dpp v208, v208, v208 quad_perm:[2,3,0,1] row_mask:0xf bank_mask:0xf
	v_lshlrev_b32_e32 v188, 16, v90
	v_and_b32_e32 v189, 0xffff0000, v90
	v_add_f32_dpp v208, v208, v208 row_half_mirror row_mask:0xf bank_mask:0xf
	v_lshlrev_b32_e32 v190, 16, v91
	v_and_b32_e32 v191, 0xffff0000, v91
	v_add_f32_dpp v208, v208, v208 row_mirror row_mask:0xf bank_mask:0xf
	v_lshlrev_b32_e32 v192, 16, v92
	v_and_b32_e32 v193, 0xffff0000, v92
	v_add_f32_dpp v208, v208, v208 row_bcast:15 row_mask:0xa bank_mask:0xf
	v_lshlrev_b32_e32 v194, 16, v93
	v_and_b32_e32 v195, 0xffff0000, v93
	v_add_f32_dpp v208, v208, v208 row_bcast:31 row_mask:0xc bank_mask:0xf
	v_lshlrev_b32_e32 v196, 16, v94
	v_and_b32_e32 v197, 0xffff0000, v94
	v_readlane_b32 s60, v208, 63
	s_nop 1
	v_lshlrev_b32_e32 v198, 16, v95
	v_and_b32_e32 v199, 0xffff0000, v95
	v_mov_b32_e32 v210, s60
	v_fmaak_f32 v210, v210, v212, 0x358637bd
	v_rsq_f32_e32 v210, v210
	s_nop 0
	v_lshlrev_b32_e32 v200, 16, v96
	v_and_b32_e32 v201, 0xffff0000, v96
	v_pk_mul_f32 v[200:201], v[200:201], v[210:211] op_sel_hi:[1,0]
	v_pk_fma_f32 v[184:185], v[8:9], v[200:201], v[184:185]
	v_lshlrev_b32_e32 v202, 16, v97
	v_and_b32_e32 v203, 0xffff0000, v97
	v_pk_mul_f32 v[202:203], v[202:203], v[210:211] op_sel_hi:[1,0]
	v_pk_fma_f32 v[186:187], v[10:11], v[202:203], v[186:187]
	v_lshlrev_b32_e32 v200, 16, v98
	v_and_b32_e32 v201, 0xffff0000, v98
	v_pk_mul_f32 v[200:201], v[200:201], v[210:211] op_sel_hi:[1,0]
	v_pk_fma_f32 v[188:189], v[12:13], v[200:201], v[188:189]
	v_lshlrev_b32_e32 v202, 16, v99
	v_and_b32_e32 v203, 0xffff0000, v99
	v_pk_mul_f32 v[202:203], v[202:203], v[210:211] op_sel_hi:[1,0]
	v_pk_fma_f32 v[190:191], v[14:15], v[202:203], v[190:191]
	v_lshlrev_b32_e32 v200, 16, v100
	v_and_b32_e32 v201, 0xffff0000, v100
	v_pk_mul_f32 v[200:201], v[200:201], v[210:211] op_sel_hi:[1,0]
	v_pk_fma_f32 v[192:193], v[16:17], v[200:201], v[192:193]
	v_lshlrev_b32_e32 v202, 16, v101
	v_and_b32_e32 v203, 0xffff0000, v101
	v_pk_mul_f32 v[202:203], v[202:203], v[210:211] op_sel_hi:[1,0]
	v_pk_fma_f32 v[194:195], v[18:19], v[202:203], v[194:195]
	v_lshlrev_b32_e32 v200, 16, v102
	v_and_b32_e32 v201, 0xffff0000, v102
	v_pk_mul_f32 v[200:201], v[200:201], v[210:211] op_sel_hi:[1,0]
	v_pk_fma_f32 v[196:197], v[20:21], v[200:201], v[196:197]
	v_lshlrev_b32_e32 v202, 16, v103
	v_and_b32_e32 v203, 0xffff0000, v103
; __device__ __forceinline__ unsigned cvtpk(float lo, float hi) { f32x2 v = {lo, hi}; bf16x2_t b = __builtin_convertvector(v, bf16x2_t); return __builtin_bit_cast(unsigned, b); }
; __device__ __forceinline__ void phase_rowwise(const void* xsrc_, bool sbf, void* xdst_, bool dbf, const bf16_t* Y, bf16_t* H, const float* mods, int lprev, int iprev, const float* lnpost, float resw, ...
;     ...
;             if (rr + 2 < 32) {
; #pragma unroll
;                 for (int r = 0; r < 2; ++r)
; #pragma unroll
;                     for (int j = 0; j < 4; ++j) { if (sbf) xnb[r][j] = *(const u32x2*)(xsrcb + (m + 2 + r) * DM + 4 * lane + 256 * j); else xn[r][j] = *(const f32x4*)(xsrc + (m + 2 + r) * DM + 4 * lane + 256 * j); if (hasprev) yn[r][j] = *(const u32x2*)(Y + (m + 2 + r) * DM + 4 * lane + 256 * j); } }
;     ...
;                     for (int j = 0; j < 4; ++j) x[r][j] = x[r][j] + gp[j] * (y[r][j] * rs); }
;             }
; #pragma unroll
;             for (int r = 0; r < 2; ++r)
; #pragma unroll
;                 for (int j = 0; j < 4; ++j) { if (hasprev) { if (dbf) { u32x2 w; w.x = cvtpk(x[r][j].x, x[r][j].y); w.y = cvtpk(x[r][j].z, x[r][j].w); *(u32x2*)(xdstb + (m + r) * DM + 4 * lane + 256 * j) = w; } else *(f32x4*)(xdst + (m + r) * DM + 4 * lane + 256 * j) = x[r][j]; } }
;             if (hasnext) {
;                 float ss[2] = {0.f, 0.f};
; #pragma unroll
;                 for (int r = 0; r < 2; ++r)
; #pragma unroll
;                     for (int j = 0; j < 4; ++j) ss[r] += (x[r][j].x * x[r][j].x + x[r][j].y * x[r][j].y) + (x[r][j].z * x[r][j].z + x[r][j].w * x[r][j].w);
; #pragma unroll
;                 for (int off = 1; off < 64; off <<= 1) { ss[0] += __shfl_xor(ss[0], off); ss[1] += __shfl_xor(ss[1], off); }
; #pragma unroll
;                 for (int r = 0; r < 2; ++r) { const float rs = __builtin_amdgcn_rsqf(ss[r] * (1.f / DM) + EPS);
; #pragma unroll
;                     for (int j = 0; j < 4; ++j) { const f32x4 h = (x[r][j] * rs) * na[j] + ns[j]; u32x2 w; w.x = cvtpk(h.x, h.y); w.y = cvtpk(h.z, h.w); *(u32x2*)(H + (m + r) * DM + 4 * lane + 256 * j) = w; } }
	v_pk_mul_f32 v[202:203], v[202:203], v[210:211] op_sel_hi:[1,0]
	v_pk_fma_f32 v[198:199], v[22:23], v[202:203], v[198:199]
	s_add_i32 s81, s80, 5
	s_add_i32 s81, s81, s82
	s_and_b32 s81, s81, 31
	s_lshl_b32 s83, s81, 11
	v_add_u32_e32 v2, s83, v1
	v_cvt_pk_bf16_f32 v96, v184, v185
	v_cvt_pk_bf16_f32 v97, v186, v187
	v_cvt_pk_bf16_f32 v98, v188, v189
	v_cvt_pk_bf16_f32 v99, v190, v191
	v_cvt_pk_bf16_f32 v100, v192, v193
	v_cvt_pk_bf16_f32 v101, v194, v195
	v_cvt_pk_bf16_f32 v102, v196, v197
	v_cvt_pk_bf16_f32 v103, v198, v199
	global_store_dwordx4 v2, v[96:99], s[76:77] nt
	global_store_dwordx4 v2, v[100:103], s[76:77] offset:1024 nt
	v_pk_mul_f32 v[204:205], v[184:185], v[184:185]
	v_pk_mul_f32 v[206:207], v[186:187], v[186:187]
	v_pk_fma_f32 v[204:205], v[188:189], v[188:189], v[204:205]
	v_pk_fma_f32 v[206:207], v[190:191], v[190:191], v[206:207]
	v_pk_fma_f32 v[204:205], v[192:193], v[192:193], v[204:205]
	v_pk_fma_f32 v[206:207], v[194:195], v[194:195], v[206:207]
	v_pk_fma_f32 v[204:205], v[196:197], v[196:197], v[204:205]
	v_pk_fma_f32 v[206:207], v[198:199], v[198:199], v[206:207]
	v_pk_add_f32 v[204:205], v[204:205], v[206:207]
	v_add_f32_e32 v208, v204, v205
	s_nop 0
	s_nop 0
	v_add_f32_dpp v208, v208, v208 quad_perm:[1,0,3,2] row_mask:0xf bank_mask:0xf
	s_nop 0
	s_nop 0
	v_add_f32_dpp v208, v208, v208 quad_perm:[2,3,0,1] row_mask:0xf bank_mask:0xf
	s_nop 0
	s_nop 0
	v_add_f32_dpp v208, v208, v208 row_half_mirror row_mask:0xf bank_mask:0xf
	s_nop 0
	s_nop 0
	v_add_f32_dpp v208, v208, v208 row_mirror row_mask:0xf bank_mask:0xf
	s_nop 0
	s_nop 0
	v_add_f32_dpp v208, v208, v208 row_bcast:15 row_mask:0xa bank_mask:0xf
	s_nop 0
	s_nop 0
	v_add_f32_dpp v208, v208, v208 row_bcast:31 row_mask:0xc bank_mask:0xf
	s_nop 0
	s_nop 0
	v_readlane_b32 s60, v208, 63
	s_nop 1
	v_mov_b32_e32 v210, s60
	v_fmaak_f32 v210, v210, v212, 0x358637bd
	v_rsq_f32_e32 v210, v210
	s_nop 0
	v_pk_mul_f32 v[200:201], v[184:185], v[210:211] op_sel_hi:[1,0]
	v_pk_fma_f32 v[200:201], v[200:201], v[24:25], v[40:41]
	v_cvt_pk_bf16_f32 v88, v200, v201
	v_pk_mul_f32 v[202:203], v[186:187], v[210:211] op_sel_hi:[1,0]
	v_pk_fma_f32 v[202:203], v[202:203], v[26:27], v[42:43]
	v_cvt_pk_bf16_f32 v89, v202, v203
	v_pk_mul_f32 v[200:201], v[188:189], v[210:211] op_sel_hi:[1,0]
	v_pk_fma_f32 v[200:201], v[200:201], v[28:29], v[44:45]
	v_cvt_pk_bf16_f32 v90, v200, v201
	v_pk_mul_f32 v[202:203], v[190:191], v[210:211] op_sel_hi:[1,0]
	v_pk_fma_f32 v[202:203], v[202:203], v[30:31], v[46:47]
	v_cvt_pk_bf16_f32 v91, v202, v203
	v_pk_mul_f32 v[200:201], v[192:193], v[210:211] op_sel_hi:[1,0]
	v_pk_fma_f32 v[200:201], v[200:201], v[32:33], v[48:49]
	v_cvt_pk_bf16_f32 v92, v200, v201
	v_pk_mul_f32 v[202:203], v[194:195], v[210:211] op_sel_hi:[1,0]
	v_pk_fma_f32 v[202:203], v[202:203], v[34:35], v[50:51]
	v_cvt_pk_bf16_f32 v93, v202, v203
	v_pk_mul_f32 v[200:201], v[196:197], v[210:211] op_sel_hi:[1,0]
	v_pk_fma_f32 v[200:201], v[200:201], v[36:37], v[52:53]
	v_cvt_pk_bf16_f32 v94, v200, v201
	v_pk_mul_f32 v[202:203], v[198:199], v[210:211] op_sel_hi:[1,0]
	v_pk_fma_f32 v[202:203], v[202:203], v[38:39], v[54:55]
	v_cvt_pk_bf16_f32 v95, v202, v203
	global_store_dwordx4 v2, v[88:91], s[78:79] nt
	global_store_dwordx4 v2, v[92:95], s[78:79] offset:1024 nt
	s_add_i32 s81, s82, 10
	s_cmp_lt_u32 s81, 32
	s_cbranch_scc0 .Lrw_MID_l6_d
	s_add_i32 s81, s80, 10
	s_add_i32 s81, s81, s82
	s_and_b32 s81, s81, 31
	s_lshl_b32 s83, s81, 11
	v_add_u32_e32 v2, s83, v1
	global_load_dwordx4 v[56:59], v2, s[72:73] nt
	global_load_dwordx4 v[60:63], v2, s[72:73] offset:1024 nt
	global_load_dwordx4 v[64:67], v2, s[74:75] nt
	global_load_dwordx4 v[68:71], v2, s[74:75] offset:1024 nt
	s_branch .Lrw_MID_l6_e

; __device__ __forceinline__ unsigned cvtpk(float lo, float hi) { f32x2 v = {lo, hi}; bf16x2_t b = __builtin_convertvector(v, bf16x2_t); return __builtin_bit_cast(unsigned, b); }
; __device__ __forceinline__ float bflo(unsigned u) { return __uint_as_float(u << 16); }
; __device__ __forceinline__ float bfhi(unsigned u) { return __uint_as_float(u & 0xffff0000u); }
; __device__ __forceinline__ void phase_rowwise(const void* xsrc_, bool sbf, void* xdst_, bool dbf, const bf16_t* Y, bf16_t* H, const float* mods, int lprev, int iprev, const float* lnpost, float resw, ...
;     ...
;             if (hasprev) {
;                 f32x4 y[2][4]; float ss[2] = {0.f, 0.f};
; #pragma unroll
;                 for (int r = 0; r < 2; ++r)
; #pragma unroll
;                     for (int j = 0; j < 4; ++j) { const u32x2 u = yr[r][j]; y[r][j] = (f32x4){bflo(u.x), bfhi(u.x), bflo(u.y), bfhi(u.y)};
;                         ss[r] += (y[r][j].x * y[r][j].x + y[r][j].y * y[r][j].y) + (y[r][j].z * y[r][j].z + y[r][j].w * y[r][j].w); }
; #pragma unroll
;                 for (int off = 1; off < 64; off <<= 1) { ss[0] += __shfl_xor(ss[0], off); ss[1] += __shfl_xor(ss[1], off); }
; #pragma unroll
;                 for (int r = 0; r < 2; ++r) { const float rs = __builtin_amdgcn_rsqf(ss[r] * (1.f / DM) + EPS);
; #pragma unroll
;                     for (int j = 0; j < 4; ++j) x[r][j] = x[r][j] + gp[j] * (y[r][j] * rs); }
;             }
; #pragma unroll
;             for (int r = 0; r < 2; ++r)
; #pragma unroll
;                 for (int j = 0; j < 4; ++j) { if (hasprev) { if (dbf) { u32x2 w; w.x = cvtpk(x[r][j].x, x[r][j].y); w.y = cvtpk(x[r][j].z, x[r][j].w); *(u32x2*)(xdstb + (m + r) * DM + 4 * lane + 256 * j) = w; } else *(f32x4*)(xdst + (m + r) * DM + 4 * lane + 256 * j) = x[r][j]; } }
;             if (hasnext) {
;                 float ss[2] = {0.f, 0.f};
; #pragma unroll
;                 for (int r = 0; r < 2; ++r)
; #pragma unroll
;                     for (int j = 0; j < 4; ++j) ss[r] += (x[r][j].x * x[r][j].x + x[r][j].y * x[r][j].y) + (x[r][j].z * x[r][j].z + x[r][j].w * x[r][j].w);
; #pragma unroll
;                 for (int off = 1; off < 64; off <<= 1) { ss[0] += __shfl_xor(ss[0], off); ss[1] += __shfl_xor(ss[1], off); }
.Lrw_MID_l6_e:
	s_waitcnt vmcnt(32)
	v_lshlrev_b32_e32 v200, 16, v112
	v_and_b32_e32 v201, 0xffff0000, v112
	v_pk_mul_f32 v[204:205], v[200:201], v[200:201]
	v_lshlrev_b32_e32 v202, 16, v113
	v_and_b32_e32 v203, 0xffff0000, v113
	v_pk_mul_f32 v[206:207], v[202:203], v[202:203]
	v_lshlrev_b32_e32 v200, 16, v114
	v_and_b32_e32 v201, 0xffff0000, v114
	v_pk_fma_f32 v[204:205], v[200:201], v[200:201], v[204:205]
	v_lshlrev_b32_e32 v202, 16, v115
	v_and_b32_e32 v203, 0xffff0000, v115
	v_pk_fma_f32 v[206:207], v[202:203], v[202:203], v[206:207]
	v_lshlrev_b32_e32 v200, 16, v116
	v_and_b32_e32 v201, 0xffff0000, v116
	v_pk_fma_f32 v[204:205], v[200:201], v[200:201], v[204:205]
	v_lshlrev_b32_e32 v202, 16, v117
	v_and_b32_e32 v203, 0xffff0000, v117
	v_pk_fma_f32 v[206:207], v[202:203], v[202:203], v[206:207]
	v_lshlrev_b32_e32 v200, 16, v118
	v_and_b32_e32 v201, 0xffff0000, v118
	v_pk_fma_f32 v[204:205], v[200:201], v[200:201], v[204:205]
	v_lshlrev_b32_e32 v202, 16, v119
	v_and_b32_e32 v203, 0xffff0000, v119
	v_pk_fma_f32 v[206:207], v[202:203], v[202:203], v[206:207]
	v_pk_add_f32 v[204:205], v[204:205], v[206:207]
	v_add_f32_e32 v208, v204, v205
	v_lshlrev_b32_e32 v184, 16, v104
	v_and_b32_e32 v185, 0xffff0000, v104
	v_add_f32_dpp v208, v208, v208 quad_perm:[1,0,3,2] row_mask:0xf bank_mask:0xf
	v_lshlrev_b32_e32 v186, 16, v105
	v_and_b32_e32 v187, 0xffff0000, v105
	v_add_f32_dpp v208, v208, v208 quad_perm:[2,3,0,1] row_mask:0xf bank_mask:0xf
	v_lshlrev_b32_e32 v188, 16, v106
	v_and_b32_e32 v189, 0xffff0000, v106
	v_add_f32_dpp v208, v208, v208 row_half_mirror row_mask:0xf bank_mask:0xf
	v_lshlrev_b32_e32 v190, 16, v107
	v_and_b32_e32 v191, 0xffff0000, v107
	v_add_f32_dpp v208, v208, v208 row_mirror row_mask:0xf bank_mask:0xf
	v_lshlrev_b32_e32 v192, 16, v108
	v_and_b32_e32 v193, 0xffff0000, v108
	v_add_f32_dpp v208, v208, v208 row_bcast:15 row_mask:0xa bank_mask:0xf
	v_lshlrev_b32_e32 v194, 16, v109
	v_and_b32_e32 v195, 0xffff0000, v109
	v_add_f32_dpp v208, v208, v208 row_bcast:31 row_mask:0xc bank_mask:0xf
	v_lshlrev_b32_e32 v196, 16, v110
	v_and_b32_e32 v197, 0xffff0000, v110
	v_readlane_b32 s60, v208, 63
	s_nop 1
	v_lshlrev_b32_e32 v198, 16, v111
	v_and_b32_e32 v199, 0xffff0000, v111
	v_mov_b32_e32 v210, s60
	v_fmaak_f32 v210, v210, v212, 0x358637bd
	v_rsq_f32_e32 v210, v210
	s_nop 0
	v_lshlrev_b32_e32 v200, 16, v112
	v_and_b32_e32 v201, 0xffff0000, v112
	v_pk_mul_f32 v[200:201], v[200:201], v[210:211] op_sel_hi:[1,0]
	v_pk_fma_f32 v[184:185], v[8:9], v[200:201], v[184:185]
	v_lshlrev_b32_e32 v202, 16, v113
	v_and_b32_e32 v203, 0xffff0000, v113
	v_pk_mul_f32 v[202:203], v[202:203], v[210:211] op_sel_hi:[1,0]
	v_pk_fma_f32 v[186:187], v[10:11], v[202:203], v[186:187]
	v_lshlrev_b32_e32 v200, 16, v114
	v_and_b32_e32 v201, 0xffff0000, v114
	v_pk_mul_f32 v[200:201], v[200:201], v[210:211] op_sel_hi:[1,0]
	v_pk_fma_f32 v[188:189], v[12:13], v[200:201], v[188:189]
	v_lshlrev_b32_e32 v202, 16, v115
	v_and_b32_e32 v203, 0xffff0000, v115
	v_pk_mul_f32 v[202:203], v[202:203], v[210:211] op_sel_hi:[1,0]
	v_pk_fma_f32 v[190:191], v[14:15], v[202:203], v[190:191]
	v_lshlrev_b32_e32 v200, 16, v116
	v_and_b32_e32 v201, 0xffff0000, v116
	v_pk_mul_f32 v[200:201], v[200:201], v[210:211] op_sel_hi:[1,0]
	v_pk_fma_f32 v[192:193], v[16:17], v[200:201], v[192:193]
	v_lshlrev_b32_e32 v202, 16, v117
	v_and_b32_e32 v203, 0xffff0000, v117
	v_pk_mul_f32 v[202:203], v[202:203], v[210:211] op_sel_hi:[1,0]
	v_pk_fma_f32 v[194:195], v[18:19], v[202:203], v[194:195]
	v_lshlrev_b32_e32 v200, 16, v118
	v_and_b32_e32 v201, 0xffff0000, v118
	v_pk_mul_f32 v[200:201], v[200:201], v[210:211] op_sel_hi:[1,0]
	v_pk_fma_f32 v[196:197], v[20:21], v[200:201], v[196:197]
	v_lshlrev_b32_e32 v202, 16, v119
	v_and_b32_e32 v203, 0xffff0000, v119
	v_pk_mul_f32 v[202:203], v[202:203], v[210:211] op_sel_hi:[1,0]
	v_pk_fma_f32 v[198:199], v[22:23], v[202:203], v[198:199]
	s_add_i32 s81, s80, 6
	s_add_i32 s81, s81, s82
	s_and_b32 s81, s81, 31
	s_lshl_b32 s83, s81, 11
	v_add_u32_e32 v2, s83, v1
	v_cvt_pk_bf16_f32 v112, v184, v185
	v_cvt_pk_bf16_f32 v113, v186, v187
	v_cvt_pk_bf16_f32 v114, v188, v189
	v_cvt_pk_bf16_f32 v115, v190, v191
	v_cvt_pk_bf16_f32 v116, v192, v193
	v_cvt_pk_bf16_f32 v117, v194, v195
	v_cvt_pk_bf16_f32 v118, v196, v197
	v_cvt_pk_bf16_f32 v119, v198, v199
	global_store_dwordx4 v2, v[112:115], s[76:77] nt
	global_store_dwordx4 v2, v[116:119], s[76:77] offset:1024 nt
	v_pk_mul_f32 v[204:205], v[184:185], v[184:185]
	v_pk_mul_f32 v[206:207], v[186:187], v[186:187]
	v_pk_fma_f32 v[204:205], v[188:189], v[188:189], v[204:205]
	v_pk_fma_f32 v[206:207], v[190:191], v[190:191], v[206:207]
	v_pk_fma_f32 v[204:205], v[192:193], v[192:193], v[204:205]
	v_pk_fma_f32 v[206:207], v[194:195], v[194:195], v[206:207]
	v_pk_fma_f32 v[204:205], v[196:197], v[196:197], v[204:205]
	v_pk_fma_f32 v[206:207], v[198:199], v[198:199], v[206:207]
	v_pk_add_f32 v[204:205], v[204:205], v[206:207]
	v_add_f32_e32 v208, v204, v205
	s_nop 0
	s_nop 0
	v_add_f32_dpp v208, v208, v208 quad_perm:[1,0,3,2] row_mask:0xf bank_mask:0xf
	s_nop 0
	s_nop 0
	v_add_f32_dpp v208, v208, v208 quad_perm:[2,3,0,1] row_mask:0xf bank_mask:0xf
	s_nop 0
	s_nop 0
	v_add_f32_dpp v208, v208, v208 row_half_mirror row_mask:0xf bank_mask:0xf
	s_nop 0
	s_nop 0
	v_add_f32_dpp v208, v208, v208 row_mirror row_mask:0xf bank_mask:0xf
	s_nop 0
	s_nop 0
	v_add_f32_dpp v208, v208, v208 row_bcast:15 row_mask:0xa bank_mask:0xf
	s_nop 0
	s_nop 0
	v_add_f32_dpp v208, v208, v208 row_bcast:31 row_mask:0xc bank_mask:0xf
	s_nop 0
	s_nop 0
	v_readlane_b32 s60, v208, 63
	s_nop 1
	v_mov_b32_e32 v210, s60
	v_fmaak_f32 v210, v210, v212, 0x358637bd
; __device__ __forceinline__ unsigned cvtpk(float lo, float hi) { f32x2 v = {lo, hi}; bf16x2_t b = __builtin_convertvector(v, bf16x2_t); return __builtin_bit_cast(unsigned, b); }
; __device__ __forceinline__ void phase_rowwise(const void* xsrc_, bool sbf, void* xdst_, bool dbf, const bf16_t* Y, bf16_t* H, const float* mods, int lprev, int iprev, const float* lnpost, float resw, ...
;     ...
;     for (int ch = gw; ch < M / 32; ch += NGW) {
;         const int b = ch >> 6;
;         f32x4 gp[4], na[4], ns[4];
; #pragma unroll
;         for (int j = 0; j < 4; ++j) { const int c = 4 * lane + 256 * j;
;             if (hasprev) { const f32x4 g = *(const f32x4*)(mods + ((size_t)lprev * 32 + b) * 9216 + iprev * 3072 + 2048 + c); const f32x4 lp = *(const f32x4*)(lnpost + c); gp[j] = g * lp * resw; }
;             else gp[j] = (f32x4){0.f, 0.f, 0.f, 0.f};
;             if (hasnext) { const f32x4 sh = *(const f32x4*)(mods + ((size_t)lnext * 32 + b) * 9216 + inext * 3072 + c); const f32x4 scl = *(const f32x4*)(mods + ((size_t)lnext * 32 + b) * 9216 + inext * 3072 + 1024 + c);
;                 const f32x4 lp = *(const f32x4*)(lnpre + c); na[j] = lp * (scl + 1.0f); ns[j] = sh; }
;             else { na[j] = (f32x4){0.f, 0.f, 0.f, 0.f}; ns[j] = na[j]; } }
;         f32x4 xn[2][4]; u32x2 xnb[2][4]; u32x2 yn[2][4];
;         { const size_t m0 = (size_t)ch * 32;
; #pragma unroll
;           for (int r = 0; r < 2; ++r)
; #pragma unroll
;             for (int j = 0; j < 4; ++j) { if (sbf) { xnb[r][j] = *(const u32x2*)(xsrcb + (m0 + r) * DM + 4 * lane + 256 * j); xn[r][j] = (f32x4){0.f, 0.f, 0.f, 0.f}; } else { xn[r][j] = *(const f32x4*)(xsrc + (m0 + r) * DM + 4 * lane + 256 * j); xnb[r][j] = (u32x2){0u, 0u}; }
;                 yn[r][j] = hasprev ? *(const u32x2*)(Y + (m0 + r) * DM + 4 * lane + 256 * j) : (u32x2){0u, 0u}; } }
;     ...
;                 for (int r = 0; r < 2; ++r) { const float rs = __builtin_amdgcn_rsqf(ss[r] * (1.f / DM) + EPS);
; #pragma unroll
;                     for (int j = 0; j < 4; ++j) { const f32x4 h = (x[r][j] * rs) * na[j] + ns[j]; u32x2 w; w.x = cvtpk(h.x, h.y); w.y = cvtpk(h.z, h.w); *(u32x2*)(H + (m + r) * DM + 4 * lane + 256 * j) = w; } }
	v_rsq_f32_e32 v210, v210
	s_nop 0
	v_pk_mul_f32 v[200:201], v[184:185], v[210:211] op_sel_hi:[1,0]
	v_pk_fma_f32 v[200:201], v[200:201], v[24:25], v[40:41]
	v_cvt_pk_bf16_f32 v104, v200, v201
	v_pk_mul_f32 v[202:203], v[186:187], v[210:211] op_sel_hi:[1,0]
	v_pk_fma_f32 v[202:203], v[202:203], v[26:27], v[42:43]
	v_cvt_pk_bf16_f32 v105, v202, v203
	v_pk_mul_f32 v[200:201], v[188:189], v[210:211] op_sel_hi:[1,0]
	v_pk_fma_f32 v[200:201], v[200:201], v[28:29], v[44:45]
	v_cvt_pk_bf16_f32 v106, v200, v201
	v_pk_mul_f32 v[202:203], v[190:191], v[210:211] op_sel_hi:[1,0]
	v_pk_fma_f32 v[202:203], v[202:203], v[30:31], v[46:47]
	v_cvt_pk_bf16_f32 v107, v202, v203
	v_pk_mul_f32 v[200:201], v[192:193], v[210:211] op_sel_hi:[1,0]
	v_pk_fma_f32 v[200:201], v[200:201], v[32:33], v[48:49]
	v_cvt_pk_bf16_f32 v108, v200, v201
	v_pk_mul_f32 v[202:203], v[194:195], v[210:211] op_sel_hi:[1,0]
	v_pk_fma_f32 v[202:203], v[202:203], v[34:35], v[50:51]
	v_cvt_pk_bf16_f32 v109, v202, v203
	v_pk_mul_f32 v[200:201], v[196:197], v[210:211] op_sel_hi:[1,0]
	v_pk_fma_f32 v[200:201], v[200:201], v[36:37], v[52:53]
	v_cvt_pk_bf16_f32 v110, v200, v201
	v_pk_mul_f32 v[202:203], v[198:199], v[210:211] op_sel_hi:[1,0]
	v_pk_fma_f32 v[202:203], v[202:203], v[38:39], v[54:55]
	v_cvt_pk_bf16_f32 v111, v202, v203
	global_store_dwordx4 v2, v[104:107], s[78:79] nt
	global_store_dwordx4 v2, v[108:111], s[78:79] offset:1024 nt
	s_add_i32 s82, s82, 7
	s_cmp_lt_u32 s82, 32
	s_cbranch_scc1 .Lrw_MID_loop
	s_branch .LBB0_1024
.Lrw_INIT:
	v_readfirstlane_b32 s40, v214
	v_readlane_b32 s41, v254, 46
	s_lshr_b32 s40, s40, 6
	s_add_i32 s40, s40, s41
	s_lshr_b32 s41, s40, 6
	v_and_b32_e32 v1, 63, v214
	v_lshlrev_b32_e32 v3, 5, v1
	v_lshlrev_b32_e32 v1, 4, v1
	v_mov_b32_e32 v212, 0x3a800000
	s_mov_b32 s42, 0
	s_mov_b32 s43, 0
	v_readlane_b32 s44, v255, 22
	v_readlane_b32 s45, v255, 23
	s_lshl_b32 s46, s42, 5
	s_add_i32 s46, s46, s41
	s_mul_i32 s46, s46, 0x9000
	s_mul_i32 s47, s43, 0x3000
	s_add_i32 s46, s46, s47
	s_add_u32 s50, s44, s46
	s_addc_u32 s51, s45, 0
	s_add_u32 s56, s50, 0x1000
	s_addc_u32 s57, s51, 0
	v_readlane_b32 s54, v255, 14
	v_readlane_b32 s55, v255, 15
	s_mul_i32 s46, s42, 3
	s_add_i32 s46, s46, s43
	s_lshl_b32 s46, s46, 12
	s_add_u32 s54, s54, s46
	s_addc_u32 s55, s55, 0
	global_load_dwordx4 v[24:27], v3, s[56:57]
	global_load_dwordx4 v[28:31], v3, s[56:57] offset:16
	global_load_dwordx4 v[32:35], v3, s[56:57] offset:2048
	global_load_dwordx4 v[36:39], v3, s[56:57] offset:2064
	global_load_dwordx4 v[72:75], v3, s[54:55]
	global_load_dwordx4 v[76:79], v3, s[54:55] offset:16
	global_load_dwordx4 v[80:83], v3, s[54:55] offset:2048
	global_load_dwordx4 v[84:87], v3, s[54:55] offset:2064
	global_load_dwordx4 v[40:43], v3, s[50:51]
	global_load_dwordx4 v[44:47], v3, s[50:51] offset:16
	global_load_dwordx4 v[48:51], v3, s[50:51] offset:2048
	global_load_dwordx4 v[52:55], v3, s[50:51] offset:2064
	s_lshl_b32 s46, s40, 16
	s_lshl_b32 s47, s40, 17
	v_readlane_b32 s72, v255, 4
	v_readlane_b32 s73, v255, 5
	s_add_u32 s72, s72, s47
	s_addc_u32 s73, s73, 0
	v_readlane_b32 s78, v252, 20
	v_readlane_b32 s79, v252, 21
	s_add_u32 s78, s78, s46
	s_addc_u32 s79, s79, 0
	s_and_b32 s80, s40, 15
	s_lshl_b32 s80, s80, 1
	s_waitcnt vmcnt(4)
	v_pk_add_f32 v[24:25], v[24:25], 1.0 op_sel_hi:[1,0]
	v_pk_add_f32 v[26:27], v[26:27], 1.0 op_sel_hi:[1,0]
	v_pk_add_f32 v[28:29], v[28:29], 1.0 op_sel_hi:[1,0]
	v_pk_add_f32 v[30:31], v[30:31], 1.0 op_sel_hi:[1,0]
	v_pk_add_f32 v[32:33], v[32:33], 1.0 op_sel_hi:[1,0]
	v_pk_add_f32 v[34:35], v[34:35], 1.0 op_sel_hi:[1,0]
	v_pk_add_f32 v[36:37], v[36:37], 1.0 op_sel_hi:[1,0]
	v_pk_add_f32 v[38:39], v[38:39], 1.0 op_sel_hi:[1,0]
	v_pk_mul_f32 v[24:25], v[72:73], v[24:25]
	v_pk_mul_f32 v[26:27], v[74:75], v[26:27]
	v_pk_mul_f32 v[28:29], v[76:77], v[28:29]
	v_pk_mul_f32 v[30:31], v[78:79], v[30:31]
	v_pk_mul_f32 v[32:33], v[80:81], v[32:33]
	v_pk_mul_f32 v[34:35], v[82:83], v[34:35]
	v_pk_mul_f32 v[36:37], v[84:85], v[36:37]
	v_pk_mul_f32 v[38:39], v[86:87], v[38:39]
	s_waitcnt vmcnt(0)
	s_mov_b32 s82, 0
	s_add_i32 s81, s80, 0
	s_add_i32 s81, s81, s82
	s_and_b32 s81, s81, 31
	s_lshl_b32 s83, s81, 12
	v_add_u32_e32 v213, s83, v3
	global_load_dwordx4 v[56:59], v213, s[72:73] nt
	global_load_dwordx4 v[60:63], v213, s[72:73] offset:16 nt
	global_load_dwordx4 v[64:67], v213, s[72:73] offset:2048 nt
	global_load_dwordx4 v[68:71], v213, s[72:73] offset:2064 nt
	s_add_i32 s81, s80, 1
	s_add_i32 s81, s81, s82
	s_and_b32 s81, s81, 31
	s_lshl_b32 s83, s81, 12
	v_add_u32_e32 v213, s83, v3
	global_load_dwordx4 v[72:75], v213, s[72:73] nt
	global_load_dwordx4 v[76:79], v213, s[72:73] offset:16 nt
	global_load_dwordx4 v[80:83], v213, s[72:73] offset:2048 nt
	global_load_dwordx4 v[84:87], v213, s[72:73] offset:2064 nt
	s_add_i32 s81, s80, 2
	s_add_i32 s81, s81, s82
	s_and_b32 s81, s81, 31
	s_lshl_b32 s83, s81, 12
	v_add_u32_e32 v213, s83, v3
	global_load_dwordx4 v[88:91], v213, s[72:73] nt
	global_load_dwordx4 v[92:95], v213, s[72:73] offset:16 nt
	global_load_dwordx4 v[96:99], v213, s[72:73] offset:2048 nt
	global_load_dwordx4 v[100:103], v213, s[72:73] offset:2064 nt
	s_add_i32 s81, s80, 3
	s_add_i32 s81, s81, s82
	s_and_b32 s81, s81, 31
	s_lshl_b32 s83, s81, 12
	v_add_u32_e32 v213, s83, v3
	global_load_dwordx4 v[104:107], v213, s[72:73] nt
	global_load_dwordx4 v[108:111], v213, s[72:73] offset:16 nt
	global_load_dwordx4 v[112:115], v213, s[72:73] offset:2048 nt
	global_load_dwordx4 v[116:119], v213, s[72:73] offset:2064 nt
	s_add_i32 s81, s80, 4
	s_add_i32 s81, s81, s82
	s_and_b32 s81, s81, 31
	s_lshl_b32 s83, s81, 12
	v_add_u32_e32 v213, s83, v3
	global_load_dwordx4 v[120:123], v213, s[72:73] nt
	global_load_dwordx4 v[124:127], v213, s[72:73] offset:16 nt
	global_load_dwordx4 v[128:131], v213, s[72:73] offset:2048 nt
	global_load_dwordx4 v[132:135], v213, s[72:73] offset:2064 nt
	s_waitcnt vmcnt(16)
; __device__ __forceinline__ unsigned cvtpk(float lo, float hi) { f32x2 v = {lo, hi}; bf16x2_t b = __builtin_convertvector(v, bf16x2_t); return __builtin_bit_cast(unsigned, b); }
; __device__ __forceinline__ void phase_rowwise(const void* xsrc_, bool sbf, void* xdst_, bool dbf, const bf16_t* Y, bf16_t* H, const float* mods, int lprev, int iprev, const float* lnpost, float resw, ...
;     ...
;             if (rr + 2 < 32) {
; #pragma unroll
;                 for (int r = 0; r < 2; ++r)
; #pragma unroll
;                     for (int j = 0; j < 4; ++j) { if (sbf) xnb[r][j] = *(const u32x2*)(xsrcb + (m + 2 + r) * DM + 4 * lane + 256 * j); else xn[r][j] = *(const f32x4*)(xsrc + (m + 2 + r) * DM + 4 * lane + 256 * j); if (hasprev) yn[r][j] = *(const u32x2*)(Y + (m + 2 + r) * DM + 4 * lane + 256 * j); } }
;     ...
;             if (hasnext) {
;                 float ss[2] = {0.f, 0.f};
; #pragma unroll
;                 for (int r = 0; r < 2; ++r)
; #pragma unroll
;                     for (int j = 0; j < 4; ++j) ss[r] += (x[r][j].x * x[r][j].x + x[r][j].y * x[r][j].y) + (x[r][j].z * x[r][j].z + x[r][j].w * x[r][j].w);
; #pragma unroll
;                 for (int off = 1; off < 64; off <<= 1) { ss[0] += __shfl_xor(ss[0], off); ss[1] += __shfl_xor(ss[1], off); }
; #pragma unroll
;                 for (int r = 0; r < 2; ++r) { const float rs = __builtin_amdgcn_rsqf(ss[r] * (1.f / DM) + EPS);
; #pragma unroll
;                     for (int j = 0; j < 4; ++j) { const f32x4 h = (x[r][j] * rs) * na[j] + ns[j]; u32x2 w; w.x = cvtpk(h.x, h.y); w.y = cvtpk(h.z, h.w); *(u32x2*)(H + (m + r) * DM + 4 * lane + 256 * j) = w; } }
	s_add_i32 s81, s80, 0
	s_add_i32 s81, s81, s82
	s_and_b32 s81, s81, 31
	s_lshl_b32 s83, s81, 11
	v_add_u32_e32 v2, s83, v1
	v_pk_mul_f32 v[204:205], v[56:57], v[56:57]
	v_pk_mul_f32 v[206:207], v[58:59], v[58:59]
	v_pk_fma_f32 v[204:205], v[60:61], v[60:61], v[204:205]
	v_pk_fma_f32 v[206:207], v[62:63], v[62:63], v[206:207]
	v_pk_fma_f32 v[204:205], v[64:65], v[64:65], v[204:205]
	v_pk_fma_f32 v[206:207], v[66:67], v[66:67], v[206:207]
	v_pk_fma_f32 v[204:205], v[68:69], v[68:69], v[204:205]
	v_pk_fma_f32 v[206:207], v[70:71], v[70:71], v[206:207]
	v_pk_add_f32 v[204:205], v[204:205], v[206:207]
	v_add_f32_e32 v208, v204, v205
	s_nop 0
	s_nop 0
	v_add_f32_dpp v208, v208, v208 quad_perm:[1,0,3,2] row_mask:0xf bank_mask:0xf
	s_nop 0
	s_nop 0
	v_add_f32_dpp v208, v208, v208 quad_perm:[2,3,0,1] row_mask:0xf bank_mask:0xf
	s_nop 0
	s_nop 0
	v_add_f32_dpp v208, v208, v208 row_half_mirror row_mask:0xf bank_mask:0xf
	s_nop 0
	s_nop 0
	v_add_f32_dpp v208, v208, v208 row_mirror row_mask:0xf bank_mask:0xf
	s_nop 0
	s_nop 0
	v_add_f32_dpp v208, v208, v208 row_bcast:15 row_mask:0xa bank_mask:0xf
	s_nop 0
	s_nop 0
	v_add_f32_dpp v208, v208, v208 row_bcast:31 row_mask:0xc bank_mask:0xf
	s_nop 0
	s_nop 0
	v_readlane_b32 s60, v208, 63
	s_nop 1
	v_mov_b32_e32 v210, s60
	v_fmaak_f32 v210, v210, v212, 0x358637bd
	v_rsq_f32_e32 v210, v210
	s_nop 0
	v_pk_mul_f32 v[200:201], v[56:57], v[210:211] op_sel_hi:[1,0]
	v_pk_fma_f32 v[200:201], v[200:201], v[24:25], v[40:41]
	v_cvt_pk_bf16_f32 v184, v200, v201
	v_pk_mul_f32 v[202:203], v[58:59], v[210:211] op_sel_hi:[1,0]
	v_pk_fma_f32 v[202:203], v[202:203], v[26:27], v[42:43]
	v_cvt_pk_bf16_f32 v185, v202, v203
	v_pk_mul_f32 v[200:201], v[60:61], v[210:211] op_sel_hi:[1,0]
	v_pk_fma_f32 v[200:201], v[200:201], v[28:29], v[44:45]
	v_cvt_pk_bf16_f32 v186, v200, v201
	v_pk_mul_f32 v[202:203], v[62:63], v[210:211] op_sel_hi:[1,0]
	v_pk_fma_f32 v[202:203], v[202:203], v[30:31], v[46:47]
	v_cvt_pk_bf16_f32 v187, v202, v203
	v_pk_mul_f32 v[200:201], v[64:65], v[210:211] op_sel_hi:[1,0]
	v_pk_fma_f32 v[200:201], v[200:201], v[32:33], v[48:49]
	v_cvt_pk_bf16_f32 v188, v200, v201
	v_pk_mul_f32 v[202:203], v[66:67], v[210:211] op_sel_hi:[1,0]
	v_pk_fma_f32 v[202:203], v[202:203], v[34:35], v[50:51]
	v_cvt_pk_bf16_f32 v189, v202, v203
	v_pk_mul_f32 v[200:201], v[68:69], v[210:211] op_sel_hi:[1,0]
	v_pk_fma_f32 v[200:201], v[200:201], v[36:37], v[52:53]
	v_cvt_pk_bf16_f32 v190, v200, v201
	v_pk_mul_f32 v[202:203], v[70:71], v[210:211] op_sel_hi:[1,0]
	v_pk_fma_f32 v[202:203], v[202:203], v[38:39], v[54:55]
	v_cvt_pk_bf16_f32 v191, v202, v203
	global_store_dwordx4 v2, v[184:187], s[78:79] nt
	global_store_dwordx4 v2, v[188:191], s[78:79] offset:1024 nt
	s_add_i32 s81, s80, 5
	s_add_i32 s81, s81, s82
	s_and_b32 s81, s81, 31
	s_lshl_b32 s83, s81, 12
	v_add_u32_e32 v213, s83, v3
	global_load_dwordx4 v[136:139], v213, s[72:73] nt
	global_load_dwordx4 v[140:143], v213, s[72:73] offset:16 nt
	global_load_dwordx4 v[144:147], v213, s[72:73] offset:2048 nt
	global_load_dwordx4 v[148:151], v213, s[72:73] offset:2064 nt
	s_waitcnt vmcnt(18)
	s_add_i32 s81, s80, 1
	s_add_i32 s81, s81, s82
	s_and_b32 s81, s81, 31
	s_lshl_b32 s83, s81, 11
	v_add_u32_e32 v2, s83, v1
	v_pk_mul_f32 v[204:205], v[72:73], v[72:73]
	v_pk_mul_f32 v[206:207], v[74:75], v[74:75]
	v_pk_fma_f32 v[204:205], v[76:77], v[76:77], v[204:205]
	v_pk_fma_f32 v[206:207], v[78:79], v[78:79], v[206:207]
	v_pk_fma_f32 v[204:205], v[80:81], v[80:81], v[204:205]
	v_pk_fma_f32 v[206:207], v[82:83], v[82:83], v[206:207]
	v_pk_fma_f32 v[204:205], v[84:85], v[84:85], v[204:205]
	v_pk_fma_f32 v[206:207], v[86:87], v[86:87], v[206:207]
	v_pk_add_f32 v[204:205], v[204:205], v[206:207]
	v_add_f32_e32 v208, v204, v205
	s_nop 0
	s_nop 0
	v_add_f32_dpp v208, v208, v208 quad_perm:[1,0,3,2] row_mask:0xf bank_mask:0xf
	s_nop 0
	s_nop 0
	v_add_f32_dpp v208, v208, v208 quad_perm:[2,3,0,1] row_mask:0xf bank_mask:0xf
	s_nop 0
	s_nop 0
	v_add_f32_dpp v208, v208, v208 row_half_mirror row_mask:0xf bank_mask:0xf
	s_nop 0
	s_nop 0
	v_add_f32_dpp v208, v208, v208 row_mirror row_mask:0xf bank_mask:0xf
	s_nop 0
	s_nop 0
	v_add_f32_dpp v208, v208, v208 row_bcast:15 row_mask:0xa bank_mask:0xf
	s_nop 0
	s_nop 0
	v_add_f32_dpp v208, v208, v208 row_bcast:31 row_mask:0xc bank_mask:0xf
	s_nop 0
	s_nop 0
	v_readlane_b32 s60, v208, 63
	s_nop 1
	v_mov_b32_e32 v210, s60
	v_fmaak_f32 v210, v210, v212, 0x358637bd
	v_rsq_f32_e32 v210, v210
	s_nop 0
	v_pk_mul_f32 v[200:201], v[72:73], v[210:211] op_sel_hi:[1,0]
	v_pk_fma_f32 v[200:201], v[200:201], v[24:25], v[40:41]
	v_cvt_pk_bf16_f32 v184, v200, v201
	v_pk_mul_f32 v[202:203], v[74:75], v[210:211] op_sel_hi:[1,0]
	v_pk_fma_f32 v[202:203], v[202:203], v[26:27], v[42:43]
	v_cvt_pk_bf16_f32 v185, v202, v203
	v_pk_mul_f32 v[200:201], v[76:77], v[210:211] op_sel_hi:[1,0]
	v_pk_fma_f32 v[200:201], v[200:201], v[28:29], v[44:45]
	v_cvt_pk_bf16_f32 v186, v200, v201
	v_pk_mul_f32 v[202:203], v[78:79], v[210:211] op_sel_hi:[1,0]
	v_pk_fma_f32 v[202:203], v[202:203], v[30:31], v[46:47]
	v_cvt_pk_bf16_f32 v187, v202, v203
	v_pk_mul_f32 v[200:201], v[80:81], v[210:211] op_sel_hi:[1,0]
	v_pk_fma_f32 v[200:201], v[200:201], v[32:33], v[48:49]
	v_cvt_pk_bf16_f32 v188, v200, v201
	v_pk_mul_f32 v[202:203], v[82:83], v[210:211] op_sel_hi:[1,0]
	v_pk_fma_f32 v[202:203], v[202:203], v[34:35], v[50:51]
	v_cvt_pk_bf16_f32 v189, v202, v203
	v_pk_mul_f32 v[200:201], v[84:85], v[210:211] op_sel_hi:[1,0]
	v_pk_fma_f32 v[200:201], v[200:201], v[36:37], v[52:53]
	v_cvt_pk_bf16_f32 v190, v200, v201
	v_pk_mul_f32 v[202:203], v[86:87], v[210:211] op_sel_hi:[1,0]
	v_pk_fma_f32 v[202:203], v[202:203], v[38:39], v[54:55]
	v_cvt_pk_bf16_f32 v191, v202, v203
	global_store_dwordx4 v2, v[184:187], s[78:79] nt
	global_store_dwordx4 v2, v[188:191], s[78:79] offset:1024 nt
	s_add_i32 s81, s80, 6
	s_add_i32 s81, s81, s82
	s_and_b32 s81, s81, 31
	s_lshl_b32 s83, s81, 12
	v_add_u32_e32 v213, s83, v3
	global_load_dwordx4 v[152:155], v213, s[72:73] nt
	global_load_dwordx4 v[156:159], v213, s[72:73] offset:16 nt
	global_load_dwordx4 v[160:163], v213, s[72:73] offset:2048 nt
	global_load_dwordx4 v[164:167], v213, s[72:73] offset:2064 nt
	s_waitcnt vmcnt(20)
; __device__ __forceinline__ unsigned cvtpk(float lo, float hi) { f32x2 v = {lo, hi}; bf16x2_t b = __builtin_convertvector(v, bf16x2_t); return __builtin_bit_cast(unsigned, b); }
; __device__ __forceinline__ void phase_rowwise(const void* xsrc_, bool sbf, void* xdst_, bool dbf, const bf16_t* Y, bf16_t* H, const float* mods, int lprev, int iprev, const float* lnpost, float resw, ...
;     ...
;             if (rr + 2 < 32) {
; #pragma unroll
;                 for (int r = 0; r < 2; ++r)
; #pragma unroll
;                     for (int j = 0; j < 4; ++j) { if (sbf) xnb[r][j] = *(const u32x2*)(xsrcb + (m + 2 + r) * DM + 4 * lane + 256 * j); else xn[r][j] = *(const f32x4*)(xsrc + (m + 2 + r) * DM + 4 * lane + 256 * j); if (hasprev) yn[r][j] = *(const u32x2*)(Y + (m + 2 + r) * DM + 4 * lane + 256 * j); } }
;     ...
;             if (hasnext) {
;                 float ss[2] = {0.f, 0.f};
; #pragma unroll
;                 for (int r = 0; r < 2; ++r)
; #pragma unroll
;                     for (int j = 0; j < 4; ++j) ss[r] += (x[r][j].x * x[r][j].x + x[r][j].y * x[r][j].y) + (x[r][j].z * x[r][j].z + x[r][j].w * x[r][j].w);
; #pragma unroll
;                 for (int off = 1; off < 64; off <<= 1) { ss[0] += __shfl_xor(ss[0], off); ss[1] += __shfl_xor(ss[1], off); }
; #pragma unroll
;                 for (int r = 0; r < 2; ++r) { const float rs = __builtin_amdgcn_rsqf(ss[r] * (1.f / DM) + EPS);
; #pragma unroll
;                     for (int j = 0; j < 4; ++j) { const f32x4 h = (x[r][j] * rs) * na[j] + ns[j]; u32x2 w; w.x = cvtpk(h.x, h.y); w.y = cvtpk(h.z, h.w); *(u32x2*)(H + (m + r) * DM + 4 * lane + 256 * j) = w; } }
	s_add_i32 s81, s80, 2
	s_add_i32 s81, s81, s82
	s_and_b32 s81, s81, 31
	s_lshl_b32 s83, s81, 11
	v_add_u32_e32 v2, s83, v1
	v_pk_mul_f32 v[204:205], v[88:89], v[88:89]
	v_pk_mul_f32 v[206:207], v[90:91], v[90:91]
	v_pk_fma_f32 v[204:205], v[92:93], v[92:93], v[204:205]
	v_pk_fma_f32 v[206:207], v[94:95], v[94:95], v[206:207]
	v_pk_fma_f32 v[204:205], v[96:97], v[96:97], v[204:205]
	v_pk_fma_f32 v[206:207], v[98:99], v[98:99], v[206:207]
	v_pk_fma_f32 v[204:205], v[100:101], v[100:101], v[204:205]
	v_pk_fma_f32 v[206:207], v[102:103], v[102:103], v[206:207]
	v_pk_add_f32 v[204:205], v[204:205], v[206:207]
	v_add_f32_e32 v208, v204, v205
	s_nop 0
	s_nop 0
	v_add_f32_dpp v208, v208, v208 quad_perm:[1,0,3,2] row_mask:0xf bank_mask:0xf
	s_nop 0
	s_nop 0
	v_add_f32_dpp v208, v208, v208 quad_perm:[2,3,0,1] row_mask:0xf bank_mask:0xf
	s_nop 0
	s_nop 0
	v_add_f32_dpp v208, v208, v208 row_half_mirror row_mask:0xf bank_mask:0xf
	s_nop 0
	s_nop 0
	v_add_f32_dpp v208, v208, v208 row_mirror row_mask:0xf bank_mask:0xf
	s_nop 0
	s_nop 0
	v_add_f32_dpp v208, v208, v208 row_bcast:15 row_mask:0xa bank_mask:0xf
	s_nop 0
	s_nop 0
	v_add_f32_dpp v208, v208, v208 row_bcast:31 row_mask:0xc bank_mask:0xf
	s_nop 0
	s_nop 0
	v_readlane_b32 s60, v208, 63
	s_nop 1
	v_mov_b32_e32 v210, s60
	v_fmaak_f32 v210, v210, v212, 0x358637bd
	v_rsq_f32_e32 v210, v210
	s_nop 0
	v_pk_mul_f32 v[200:201], v[88:89], v[210:211] op_sel_hi:[1,0]
	v_pk_fma_f32 v[200:201], v[200:201], v[24:25], v[40:41]
	v_cvt_pk_bf16_f32 v184, v200, v201
	v_pk_mul_f32 v[202:203], v[90:91], v[210:211] op_sel_hi:[1,0]
	v_pk_fma_f32 v[202:203], v[202:203], v[26:27], v[42:43]
	v_cvt_pk_bf16_f32 v185, v202, v203
	v_pk_mul_f32 v[200:201], v[92:93], v[210:211] op_sel_hi:[1,0]
	v_pk_fma_f32 v[200:201], v[200:201], v[28:29], v[44:45]
	v_cvt_pk_bf16_f32 v186, v200, v201
	v_pk_mul_f32 v[202:203], v[94:95], v[210:211] op_sel_hi:[1,0]
	v_pk_fma_f32 v[202:203], v[202:203], v[30:31], v[46:47]
	v_cvt_pk_bf16_f32 v187, v202, v203
	v_pk_mul_f32 v[200:201], v[96:97], v[210:211] op_sel_hi:[1,0]
	v_pk_fma_f32 v[200:201], v[200:201], v[32:33], v[48:49]
	v_cvt_pk_bf16_f32 v188, v200, v201
	v_pk_mul_f32 v[202:203], v[98:99], v[210:211] op_sel_hi:[1,0]
	v_pk_fma_f32 v[202:203], v[202:203], v[34:35], v[50:51]
	v_cvt_pk_bf16_f32 v189, v202, v203
	v_pk_mul_f32 v[200:201], v[100:101], v[210:211] op_sel_hi:[1,0]
	v_pk_fma_f32 v[200:201], v[200:201], v[36:37], v[52:53]
	v_cvt_pk_bf16_f32 v190, v200, v201
	v_pk_mul_f32 v[202:203], v[102:103], v[210:211] op_sel_hi:[1,0]
	v_pk_fma_f32 v[202:203], v[202:203], v[38:39], v[54:55]
	v_cvt_pk_bf16_f32 v191, v202, v203
	global_store_dwordx4 v2, v[184:187], s[78:79] nt
	global_store_dwordx4 v2, v[188:191], s[78:79] offset:1024 nt
	s_add_i32 s81, s80, 7
	s_add_i32 s81, s81, s82
	s_and_b32 s81, s81, 31
	s_lshl_b32 s83, s81, 12
	v_add_u32_e32 v213, s83, v3
	global_load_dwordx4 v[56:59], v213, s[72:73] nt
	global_load_dwordx4 v[60:63], v213, s[72:73] offset:16 nt
	global_load_dwordx4 v[64:67], v213, s[72:73] offset:2048 nt
	global_load_dwordx4 v[68:71], v213, s[72:73] offset:2064 nt
	s_waitcnt vmcnt(22)
	s_add_i32 s81, s80, 3
	s_add_i32 s81, s81, s82
	s_and_b32 s81, s81, 31
	s_lshl_b32 s83, s81, 11
	v_add_u32_e32 v2, s83, v1
	v_pk_mul_f32 v[204:205], v[104:105], v[104:105]
	v_pk_mul_f32 v[206:207], v[106:107], v[106:107]
	v_pk_fma_f32 v[204:205], v[108:109], v[108:109], v[204:205]
	v_pk_fma_f32 v[206:207], v[110:111], v[110:111], v[206:207]
	v_pk_fma_f32 v[204:205], v[112:113], v[112:113], v[204:205]
	v_pk_fma_f32 v[206:207], v[114:115], v[114:115], v[206:207]
	v_pk_fma_f32 v[204:205], v[116:117], v[116:117], v[204:205]
	v_pk_fma_f32 v[206:207], v[118:119], v[118:119], v[206:207]
	v_pk_add_f32 v[204:205], v[204:205], v[206:207]
	v_add_f32_e32 v208, v204, v205
	s_nop 0
	s_nop 0
	v_add_f32_dpp v208, v208, v208 quad_perm:[1,0,3,2] row_mask:0xf bank_mask:0xf
	s_nop 0
	s_nop 0
	v_add_f32_dpp v208, v208, v208 quad_perm:[2,3,0,1] row_mask:0xf bank_mask:0xf
	s_nop 0
	s_nop 0
	v_add_f32_dpp v208, v208, v208 row_half_mirror row_mask:0xf bank_mask:0xf
	s_nop 0
	s_nop 0
	v_add_f32_dpp v208, v208, v208 row_mirror row_mask:0xf bank_mask:0xf
	s_nop 0
	s_nop 0
	v_add_f32_dpp v208, v208, v208 row_bcast:15 row_mask:0xa bank_mask:0xf
	s_nop 0
	s_nop 0
	v_add_f32_dpp v208, v208, v208 row_bcast:31 row_mask:0xc bank_mask:0xf
	s_nop 0
	s_nop 0
	v_readlane_b32 s60, v208, 63
	s_nop 1
	v_mov_b32_e32 v210, s60
	v_fmaak_f32 v210, v210, v212, 0x358637bd
	v_rsq_f32_e32 v210, v210
	s_nop 0
	v_pk_mul_f32 v[200:201], v[104:105], v[210:211] op_sel_hi:[1,0]
	v_pk_fma_f32 v[200:201], v[200:201], v[24:25], v[40:41]
	v_cvt_pk_bf16_f32 v184, v200, v201
	v_pk_mul_f32 v[202:203], v[106:107], v[210:211] op_sel_hi:[1,0]
	v_pk_fma_f32 v[202:203], v[202:203], v[26:27], v[42:43]
	v_cvt_pk_bf16_f32 v185, v202, v203
	v_pk_mul_f32 v[200:201], v[108:109], v[210:211] op_sel_hi:[1,0]
	v_pk_fma_f32 v[200:201], v[200:201], v[28:29], v[44:45]
	v_cvt_pk_bf16_f32 v186, v200, v201
	v_pk_mul_f32 v[202:203], v[110:111], v[210:211] op_sel_hi:[1,0]
	v_pk_fma_f32 v[202:203], v[202:203], v[30:31], v[46:47]
	v_cvt_pk_bf16_f32 v187, v202, v203
	v_pk_mul_f32 v[200:201], v[112:113], v[210:211] op_sel_hi:[1,0]
	v_pk_fma_f32 v[200:201], v[200:201], v[32:33], v[48:49]
	v_cvt_pk_bf16_f32 v188, v200, v201
	v_pk_mul_f32 v[202:203], v[114:115], v[210:211] op_sel_hi:[1,0]
	v_pk_fma_f32 v[202:203], v[202:203], v[34:35], v[50:51]
	v_cvt_pk_bf16_f32 v189, v202, v203
	v_pk_mul_f32 v[200:201], v[116:117], v[210:211] op_sel_hi:[1,0]
	v_pk_fma_f32 v[200:201], v[200:201], v[36:37], v[52:53]
	v_cvt_pk_bf16_f32 v190, v200, v201
	v_pk_mul_f32 v[202:203], v[118:119], v[210:211] op_sel_hi:[1,0]
	v_pk_fma_f32 v[202:203], v[202:203], v[38:39], v[54:55]
	v_cvt_pk_bf16_f32 v191, v202, v203
	global_store_dwordx4 v2, v[184:187], s[78:79] nt
	global_store_dwordx4 v2, v[188:191], s[78:79] offset:1024 nt
	s_mov_b32 s82, 4
.Lrw_INIT_loop:
	s_add_i32 s81, s82, 4
	s_cmp_lt_u32 s81, 32
	s_cbranch_scc0 .Lrw_INIT_l0_d
	s_add_i32 s81, s80, 4
	s_add_i32 s81, s81, s82
	s_and_b32 s81, s81, 31
	s_lshl_b32 s83, s81, 12
	v_add_u32_e32 v213, s83, v3
	global_load_dwordx4 v[72:75], v213, s[72:73] nt
	global_load_dwordx4 v[76:79], v213, s[72:73] offset:16 nt
	global_load_dwordx4 v[80:83], v213, s[72:73] offset:2048 nt
	global_load_dwordx4 v[84:87], v213, s[72:73] offset:2064 nt
	s_branch .Lrw_INIT_l0_e

; __device__ __forceinline__ unsigned cvtpk(float lo, float hi) { f32x2 v = {lo, hi}; bf16x2_t b = __builtin_convertvector(v, bf16x2_t); return __builtin_bit_cast(unsigned, b); }
; __device__ __forceinline__ void phase_rowwise(const void* xsrc_, bool sbf, void* xdst_, bool dbf, const bf16_t* Y, bf16_t* H, const float* mods, int lprev, int iprev, const float* lnpost, float resw, ...
;     ...
;             if (rr + 2 < 32) {
; #pragma unroll
;                 for (int r = 0; r < 2; ++r)
; #pragma unroll
;                     for (int j = 0; j < 4; ++j) { if (sbf) xnb[r][j] = *(const u32x2*)(xsrcb + (m + 2 + r) * DM + 4 * lane + 256 * j); else xn[r][j] = *(const f32x4*)(xsrc + (m + 2 + r) * DM + 4 * lane + 256 * j); if (hasprev) yn[r][j] = *(const u32x2*)(Y + (m + 2 + r) * DM + 4 * lane + 256 * j); } }
;     ...
;             if (hasnext) {
;                 float ss[2] = {0.f, 0.f};
; #pragma unroll
;                 for (int r = 0; r < 2; ++r)
; #pragma unroll
;                     for (int j = 0; j < 4; ++j) ss[r] += (x[r][j].x * x[r][j].x + x[r][j].y * x[r][j].y) + (x[r][j].z * x[r][j].z + x[r][j].w * x[r][j].w);
; #pragma unroll
;                 for (int off = 1; off < 64; off <<= 1) { ss[0] += __shfl_xor(ss[0], off); ss[1] += __shfl_xor(ss[1], off); }
; #pragma unroll
;                 for (int r = 0; r < 2; ++r) { const float rs = __builtin_amdgcn_rsqf(ss[r] * (1.f / DM) + EPS);
; #pragma unroll
;                     for (int j = 0; j < 4; ++j) { const f32x4 h = (x[r][j] * rs) * na[j] + ns[j]; u32x2 w; w.x = cvtpk(h.x, h.y); w.y = cvtpk(h.z, h.w); *(u32x2*)(H + (m + r) * DM + 4 * lane + 256 * j) = w; } }
.Lrw_INIT_l0_e:
	s_waitcnt vmcnt(24)
	s_add_i32 s81, s80, 0
	s_add_i32 s81, s81, s82
	s_and_b32 s81, s81, 31
	s_lshl_b32 s83, s81, 11
	v_add_u32_e32 v2, s83, v1
	v_pk_mul_f32 v[204:205], v[120:121], v[120:121]
	v_pk_mul_f32 v[206:207], v[122:123], v[122:123]
	v_pk_fma_f32 v[204:205], v[124:125], v[124:125], v[204:205]
	v_pk_fma_f32 v[206:207], v[126:127], v[126:127], v[206:207]
	v_pk_fma_f32 v[204:205], v[128:129], v[128:129], v[204:205]
	v_pk_fma_f32 v[206:207], v[130:131], v[130:131], v[206:207]
	v_pk_fma_f32 v[204:205], v[132:133], v[132:133], v[204:205]
	v_pk_fma_f32 v[206:207], v[134:135], v[134:135], v[206:207]
	v_pk_add_f32 v[204:205], v[204:205], v[206:207]
	v_add_f32_e32 v208, v204, v205
	s_nop 0
	s_nop 0
	v_add_f32_dpp v208, v208, v208 quad_perm:[1,0,3,2] row_mask:0xf bank_mask:0xf
	s_nop 0
	s_nop 0
	v_add_f32_dpp v208, v208, v208 quad_perm:[2,3,0,1] row_mask:0xf bank_mask:0xf
	s_nop 0
	s_nop 0
	v_add_f32_dpp v208, v208, v208 row_half_mirror row_mask:0xf bank_mask:0xf
	s_nop 0
	s_nop 0
	v_add_f32_dpp v208, v208, v208 row_mirror row_mask:0xf bank_mask:0xf
	s_nop 0
	s_nop 0
	v_add_f32_dpp v208, v208, v208 row_bcast:15 row_mask:0xa bank_mask:0xf
	s_nop 0
	s_nop 0
	v_add_f32_dpp v208, v208, v208 row_bcast:31 row_mask:0xc bank_mask:0xf
	s_nop 0
	s_nop 0
	v_readlane_b32 s60, v208, 63
	s_nop 1
	v_mov_b32_e32 v210, s60
	v_fmaak_f32 v210, v210, v212, 0x358637bd
	v_rsq_f32_e32 v210, v210
	s_nop 0
	v_pk_mul_f32 v[200:201], v[120:121], v[210:211] op_sel_hi:[1,0]
	v_pk_fma_f32 v[200:201], v[200:201], v[24:25], v[40:41]
	v_cvt_pk_bf16_f32 v184, v200, v201
	v_pk_mul_f32 v[202:203], v[122:123], v[210:211] op_sel_hi:[1,0]
	v_pk_fma_f32 v[202:203], v[202:203], v[26:27], v[42:43]
	v_cvt_pk_bf16_f32 v185, v202, v203
	v_pk_mul_f32 v[200:201], v[124:125], v[210:211] op_sel_hi:[1,0]
	v_pk_fma_f32 v[200:201], v[200:201], v[28:29], v[44:45]
	v_cvt_pk_bf16_f32 v186, v200, v201
	v_pk_mul_f32 v[202:203], v[126:127], v[210:211] op_sel_hi:[1,0]
	v_pk_fma_f32 v[202:203], v[202:203], v[30:31], v[46:47]
	v_cvt_pk_bf16_f32 v187, v202, v203
	v_pk_mul_f32 v[200:201], v[128:129], v[210:211] op_sel_hi:[1,0]
	v_pk_fma_f32 v[200:201], v[200:201], v[32:33], v[48:49]
	v_cvt_pk_bf16_f32 v188, v200, v201
	v_pk_mul_f32 v[202:203], v[130:131], v[210:211] op_sel_hi:[1,0]
	v_pk_fma_f32 v[202:203], v[202:203], v[34:35], v[50:51]
	v_cvt_pk_bf16_f32 v189, v202, v203
	v_pk_mul_f32 v[200:201], v[132:133], v[210:211] op_sel_hi:[1,0]
	v_pk_fma_f32 v[200:201], v[200:201], v[36:37], v[52:53]
	v_cvt_pk_bf16_f32 v190, v200, v201
	v_pk_mul_f32 v[202:203], v[134:135], v[210:211] op_sel_hi:[1,0]
	v_pk_fma_f32 v[202:203], v[202:203], v[38:39], v[54:55]
	v_cvt_pk_bf16_f32 v191, v202, v203
	global_store_dwordx4 v2, v[184:187], s[78:79] nt
	global_store_dwordx4 v2, v[188:191], s[78:79] offset:1024 nt
	s_add_i32 s81, s82, 5
	s_cmp_lt_u32 s81, 32
	s_cbranch_scc0 .Lrw_INIT_l1_d
	s_add_i32 s81, s80, 5
	s_add_i32 s81, s81, s82
	s_and_b32 s81, s81, 31
	s_lshl_b32 s83, s81, 12
	v_add_u32_e32 v213, s83, v3
	global_load_dwordx4 v[88:91], v213, s[72:73] nt
	global_load_dwordx4 v[92:95], v213, s[72:73] offset:16 nt
	global_load_dwordx4 v[96:99], v213, s[72:73] offset:2048 nt
	global_load_dwordx4 v[100:103], v213, s[72:73] offset:2064 nt
	s_branch .Lrw_INIT_l1_e

; __device__ __forceinline__ unsigned cvtpk(float lo, float hi) { f32x2 v = {lo, hi}; bf16x2_t b = __builtin_convertvector(v, bf16x2_t); return __builtin_bit_cast(unsigned, b); }
; __device__ __forceinline__ void phase_rowwise(const void* xsrc_, bool sbf, void* xdst_, bool dbf, const bf16_t* Y, bf16_t* H, const float* mods, int lprev, int iprev, const float* lnpost, float resw, ...
;     ...
;             if (rr + 2 < 32) {
; #pragma unroll
;                 for (int r = 0; r < 2; ++r)
; #pragma unroll
;                     for (int j = 0; j < 4; ++j) { if (sbf) xnb[r][j] = *(const u32x2*)(xsrcb + (m + 2 + r) * DM + 4 * lane + 256 * j); else xn[r][j] = *(const f32x4*)(xsrc + (m + 2 + r) * DM + 4 * lane + 256 * j); if (hasprev) yn[r][j] = *(const u32x2*)(Y + (m + 2 + r) * DM + 4 * lane + 256 * j); } }
;     ...
;             if (hasnext) {
;                 float ss[2] = {0.f, 0.f};
; #pragma unroll
;                 for (int r = 0; r < 2; ++r)
; #pragma unroll
;                     for (int j = 0; j < 4; ++j) ss[r] += (x[r][j].x * x[r][j].x + x[r][j].y * x[r][j].y) + (x[r][j].z * x[r][j].z + x[r][j].w * x[r][j].w);
; #pragma unroll
;                 for (int off = 1; off < 64; off <<= 1) { ss[0] += __shfl_xor(ss[0], off); ss[1] += __shfl_xor(ss[1], off); }
; #pragma unroll
;                 for (int r = 0; r < 2; ++r) { const float rs = __builtin_amdgcn_rsqf(ss[r] * (1.f / DM) + EPS);
; #pragma unroll
;                     for (int j = 0; j < 4; ++j) { const f32x4 h = (x[r][j] * rs) * na[j] + ns[j]; u32x2 w; w.x = cvtpk(h.x, h.y); w.y = cvtpk(h.z, h.w); *(u32x2*)(H + (m + r) * DM + 4 * lane + 256 * j) = w; } }
.Lrw_INIT_l1_e:
	s_waitcnt vmcnt(24)
	s_add_i32 s81, s80, 1
	s_add_i32 s81, s81, s82
	s_and_b32 s81, s81, 31
	s_lshl_b32 s83, s81, 11
	v_add_u32_e32 v2, s83, v1
	v_pk_mul_f32 v[204:205], v[136:137], v[136:137]
	v_pk_mul_f32 v[206:207], v[138:139], v[138:139]
	v_pk_fma_f32 v[204:205], v[140:141], v[140:141], v[204:205]
	v_pk_fma_f32 v[206:207], v[142:143], v[142:143], v[206:207]
	v_pk_fma_f32 v[204:205], v[144:145], v[144:145], v[204:205]
	v_pk_fma_f32 v[206:207], v[146:147], v[146:147], v[206:207]
	v_pk_fma_f32 v[204:205], v[148:149], v[148:149], v[204:205]
	v_pk_fma_f32 v[206:207], v[150:151], v[150:151], v[206:207]
	v_pk_add_f32 v[204:205], v[204:205], v[206:207]
	v_add_f32_e32 v208, v204, v205
	s_nop 0
	s_nop 0
	v_add_f32_dpp v208, v208, v208 quad_perm:[1,0,3,2] row_mask:0xf bank_mask:0xf
	s_nop 0
	s_nop 0
	v_add_f32_dpp v208, v208, v208 quad_perm:[2,3,0,1] row_mask:0xf bank_mask:0xf
	s_nop 0
	s_nop 0
	v_add_f32_dpp v208, v208, v208 row_half_mirror row_mask:0xf bank_mask:0xf
	s_nop 0
	s_nop 0
	v_add_f32_dpp v208, v208, v208 row_mirror row_mask:0xf bank_mask:0xf
	s_nop 0
	s_nop 0
	v_add_f32_dpp v208, v208, v208 row_bcast:15 row_mask:0xa bank_mask:0xf
	s_nop 0
	s_nop 0
	v_add_f32_dpp v208, v208, v208 row_bcast:31 row_mask:0xc bank_mask:0xf
	s_nop 0
	s_nop 0
	v_readlane_b32 s60, v208, 63
	s_nop 1
	v_mov_b32_e32 v210, s60
	v_fmaak_f32 v210, v210, v212, 0x358637bd
	v_rsq_f32_e32 v210, v210
	s_nop 0
	v_pk_mul_f32 v[200:201], v[136:137], v[210:211] op_sel_hi:[1,0]
	v_pk_fma_f32 v[200:201], v[200:201], v[24:25], v[40:41]
	v_cvt_pk_bf16_f32 v184, v200, v201
	v_pk_mul_f32 v[202:203], v[138:139], v[210:211] op_sel_hi:[1,0]
	v_pk_fma_f32 v[202:203], v[202:203], v[26:27], v[42:43]
	v_cvt_pk_bf16_f32 v185, v202, v203
	v_pk_mul_f32 v[200:201], v[140:141], v[210:211] op_sel_hi:[1,0]
	v_pk_fma_f32 v[200:201], v[200:201], v[28:29], v[44:45]
	v_cvt_pk_bf16_f32 v186, v200, v201
	v_pk_mul_f32 v[202:203], v[142:143], v[210:211] op_sel_hi:[1,0]
	v_pk_fma_f32 v[202:203], v[202:203], v[30:31], v[46:47]
	v_cvt_pk_bf16_f32 v187, v202, v203
	v_pk_mul_f32 v[200:201], v[144:145], v[210:211] op_sel_hi:[1,0]
	v_pk_fma_f32 v[200:201], v[200:201], v[32:33], v[48:49]
	v_cvt_pk_bf16_f32 v188, v200, v201
	v_pk_mul_f32 v[202:203], v[146:147], v[210:211] op_sel_hi:[1,0]
	v_pk_fma_f32 v[202:203], v[202:203], v[34:35], v[50:51]
	v_cvt_pk_bf16_f32 v189, v202, v203
	v_pk_mul_f32 v[200:201], v[148:149], v[210:211] op_sel_hi:[1,0]
	v_pk_fma_f32 v[200:201], v[200:201], v[36:37], v[52:53]
	v_cvt_pk_bf16_f32 v190, v200, v201
	v_pk_mul_f32 v[202:203], v[150:151], v[210:211] op_sel_hi:[1,0]
	v_pk_fma_f32 v[202:203], v[202:203], v[38:39], v[54:55]
	v_cvt_pk_bf16_f32 v191, v202, v203
	global_store_dwordx4 v2, v[184:187], s[78:79] nt
	global_store_dwordx4 v2, v[188:191], s[78:79] offset:1024 nt
	s_add_i32 s81, s82, 6
	s_cmp_lt_u32 s81, 32
	s_cbranch_scc0 .Lrw_INIT_l2_d
	s_add_i32 s81, s80, 6
	s_add_i32 s81, s81, s82
	s_and_b32 s81, s81, 31
	s_lshl_b32 s83, s81, 12
	v_add_u32_e32 v213, s83, v3
	global_load_dwordx4 v[104:107], v213, s[72:73] nt
	global_load_dwordx4 v[108:111], v213, s[72:73] offset:16 nt
	global_load_dwordx4 v[112:115], v213, s[72:73] offset:2048 nt
	global_load_dwordx4 v[116:119], v213, s[72:73] offset:2064 nt
	s_branch .Lrw_INIT_l2_e

; __device__ __forceinline__ unsigned cvtpk(float lo, float hi) { f32x2 v = {lo, hi}; bf16x2_t b = __builtin_convertvector(v, bf16x2_t); return __builtin_bit_cast(unsigned, b); }
; __device__ __forceinline__ void phase_rowwise(const void* xsrc_, bool sbf, void* xdst_, bool dbf, const bf16_t* Y, bf16_t* H, const float* mods, int lprev, int iprev, const float* lnpost, float resw, ...
;     ...
;             if (rr + 2 < 32) {
; #pragma unroll
;                 for (int r = 0; r < 2; ++r)
; #pragma unroll
;                     for (int j = 0; j < 4; ++j) { if (sbf) xnb[r][j] = *(const u32x2*)(xsrcb + (m + 2 + r) * DM + 4 * lane + 256 * j); else xn[r][j] = *(const f32x4*)(xsrc + (m + 2 + r) * DM + 4 * lane + 256 * j); if (hasprev) yn[r][j] = *(const u32x2*)(Y + (m + 2 + r) * DM + 4 * lane + 256 * j); } }
;     ...
;             if (hasnext) {
;                 float ss[2] = {0.f, 0.f};
; #pragma unroll
;                 for (int r = 0; r < 2; ++r)
; #pragma unroll
;                     for (int j = 0; j < 4; ++j) ss[r] += (x[r][j].x * x[r][j].x + x[r][j].y * x[r][j].y) + (x[r][j].z * x[r][j].z + x[r][j].w * x[r][j].w);
; #pragma unroll
;                 for (int off = 1; off < 64; off <<= 1) { ss[0] += __shfl_xor(ss[0], off); ss[1] += __shfl_xor(ss[1], off); }
; #pragma unroll
;                 for (int r = 0; r < 2; ++r) { const float rs = __builtin_amdgcn_rsqf(ss[r] * (1.f / DM) + EPS);
; #pragma unroll
;                     for (int j = 0; j < 4; ++j) { const f32x4 h = (x[r][j] * rs) * na[j] + ns[j]; u32x2 w; w.x = cvtpk(h.x, h.y); w.y = cvtpk(h.z, h.w); *(u32x2*)(H + (m + r) * DM + 4 * lane + 256 * j) = w; } }
.Lrw_INIT_l2_e:
	s_waitcnt vmcnt(24)
	s_add_i32 s81, s80, 2
	s_add_i32 s81, s81, s82
	s_and_b32 s81, s81, 31
	s_lshl_b32 s83, s81, 11
	v_add_u32_e32 v2, s83, v1
	v_pk_mul_f32 v[204:205], v[152:153], v[152:153]
	v_pk_mul_f32 v[206:207], v[154:155], v[154:155]
	v_pk_fma_f32 v[204:205], v[156:157], v[156:157], v[204:205]
	v_pk_fma_f32 v[206:207], v[158:159], v[158:159], v[206:207]
	v_pk_fma_f32 v[204:205], v[160:161], v[160:161], v[204:205]
	v_pk_fma_f32 v[206:207], v[162:163], v[162:163], v[206:207]
	v_pk_fma_f32 v[204:205], v[164:165], v[164:165], v[204:205]
	v_pk_fma_f32 v[206:207], v[166:167], v[166:167], v[206:207]
	v_pk_add_f32 v[204:205], v[204:205], v[206:207]
	v_add_f32_e32 v208, v204, v205
	s_nop 0
	s_nop 0
	v_add_f32_dpp v208, v208, v208 quad_perm:[1,0,3,2] row_mask:0xf bank_mask:0xf
	s_nop 0
	s_nop 0
	v_add_f32_dpp v208, v208, v208 quad_perm:[2,3,0,1] row_mask:0xf bank_mask:0xf
	s_nop 0
	s_nop 0
	v_add_f32_dpp v208, v208, v208 row_half_mirror row_mask:0xf bank_mask:0xf
	s_nop 0
	s_nop 0
	v_add_f32_dpp v208, v208, v208 row_mirror row_mask:0xf bank_mask:0xf
	s_nop 0
	s_nop 0
	v_add_f32_dpp v208, v208, v208 row_bcast:15 row_mask:0xa bank_mask:0xf
	s_nop 0
	s_nop 0
	v_add_f32_dpp v208, v208, v208 row_bcast:31 row_mask:0xc bank_mask:0xf
	s_nop 0
	s_nop 0
	v_readlane_b32 s60, v208, 63
	s_nop 1
	v_mov_b32_e32 v210, s60
	v_fmaak_f32 v210, v210, v212, 0x358637bd
	v_rsq_f32_e32 v210, v210
	s_nop 0
	v_pk_mul_f32 v[200:201], v[152:153], v[210:211] op_sel_hi:[1,0]
	v_pk_fma_f32 v[200:201], v[200:201], v[24:25], v[40:41]
	v_cvt_pk_bf16_f32 v184, v200, v201
	v_pk_mul_f32 v[202:203], v[154:155], v[210:211] op_sel_hi:[1,0]
	v_pk_fma_f32 v[202:203], v[202:203], v[26:27], v[42:43]
	v_cvt_pk_bf16_f32 v185, v202, v203
	v_pk_mul_f32 v[200:201], v[156:157], v[210:211] op_sel_hi:[1,0]
	v_pk_fma_f32 v[200:201], v[200:201], v[28:29], v[44:45]
	v_cvt_pk_bf16_f32 v186, v200, v201
	v_pk_mul_f32 v[202:203], v[158:159], v[210:211] op_sel_hi:[1,0]
	v_pk_fma_f32 v[202:203], v[202:203], v[30:31], v[46:47]
	v_cvt_pk_bf16_f32 v187, v202, v203
	v_pk_mul_f32 v[200:201], v[160:161], v[210:211] op_sel_hi:[1,0]
	v_pk_fma_f32 v[200:201], v[200:201], v[32:33], v[48:49]
	v_cvt_pk_bf16_f32 v188, v200, v201
	v_pk_mul_f32 v[202:203], v[162:163], v[210:211] op_sel_hi:[1,0]
	v_pk_fma_f32 v[202:203], v[202:203], v[34:35], v[50:51]
	v_cvt_pk_bf16_f32 v189, v202, v203
	v_pk_mul_f32 v[200:201], v[164:165], v[210:211] op_sel_hi:[1,0]
	v_pk_fma_f32 v[200:201], v[200:201], v[36:37], v[52:53]
	v_cvt_pk_bf16_f32 v190, v200, v201
	v_pk_mul_f32 v[202:203], v[166:167], v[210:211] op_sel_hi:[1,0]
	v_pk_fma_f32 v[202:203], v[202:203], v[38:39], v[54:55]
	v_cvt_pk_bf16_f32 v191, v202, v203
	global_store_dwordx4 v2, v[184:187], s[78:79] nt
	global_store_dwordx4 v2, v[188:191], s[78:79] offset:1024 nt
	s_add_i32 s81, s82, 7
	s_cmp_lt_u32 s81, 32
	s_cbranch_scc0 .Lrw_INIT_l3_d
	s_add_i32 s81, s80, 7
	s_add_i32 s81, s81, s82
	s_and_b32 s81, s81, 31
	s_lshl_b32 s83, s81, 12
	v_add_u32_e32 v213, s83, v3
	global_load_dwordx4 v[120:123], v213, s[72:73] nt
	global_load_dwordx4 v[124:127], v213, s[72:73] offset:16 nt
	global_load_dwordx4 v[128:131], v213, s[72:73] offset:2048 nt
	global_load_dwordx4 v[132:135], v213, s[72:73] offset:2064 nt
	s_branch .Lrw_INIT_l3_e

; __device__ __forceinline__ unsigned cvtpk(float lo, float hi) { f32x2 v = {lo, hi}; bf16x2_t b = __builtin_convertvector(v, bf16x2_t); return __builtin_bit_cast(unsigned, b); }
; __device__ __forceinline__ void phase_rowwise(const void* xsrc_, bool sbf, void* xdst_, bool dbf, const bf16_t* Y, bf16_t* H, const float* mods, int lprev, int iprev, const float* lnpost, float resw, ...
;     ...
;             if (rr + 2 < 32) {
; #pragma unroll
;                 for (int r = 0; r < 2; ++r)
; #pragma unroll
;                     for (int j = 0; j < 4; ++j) { if (sbf) xnb[r][j] = *(const u32x2*)(xsrcb + (m + 2 + r) * DM + 4 * lane + 256 * j); else xn[r][j] = *(const f32x4*)(xsrc + (m + 2 + r) * DM + 4 * lane + 256 * j); if (hasprev) yn[r][j] = *(const u32x2*)(Y + (m + 2 + r) * DM + 4 * lane + 256 * j); } }
;     ...
;             if (hasnext) {
;                 float ss[2] = {0.f, 0.f};
; #pragma unroll
;                 for (int r = 0; r < 2; ++r)
; #pragma unroll
;                     for (int j = 0; j < 4; ++j) ss[r] += (x[r][j].x * x[r][j].x + x[r][j].y * x[r][j].y) + (x[r][j].z * x[r][j].z + x[r][j].w * x[r][j].w);
; #pragma unroll
;                 for (int off = 1; off < 64; off <<= 1) { ss[0] += __shfl_xor(ss[0], off); ss[1] += __shfl_xor(ss[1], off); }
; #pragma unroll
;                 for (int r = 0; r < 2; ++r) { const float rs = __builtin_amdgcn_rsqf(ss[r] * (1.f / DM) + EPS);
; #pragma unroll
;                     for (int j = 0; j < 4; ++j) { const f32x4 h = (x[r][j] * rs) * na[j] + ns[j]; u32x2 w; w.x = cvtpk(h.x, h.y); w.y = cvtpk(h.z, h.w); *(u32x2*)(H + (m + r) * DM + 4 * lane + 256 * j) = w; } }
.Lrw_INIT_l3_e:
	s_waitcnt vmcnt(24)
	s_add_i32 s81, s80, 3
	s_add_i32 s81, s81, s82
	s_and_b32 s81, s81, 31
	s_lshl_b32 s83, s81, 11
	v_add_u32_e32 v2, s83, v1
	v_pk_mul_f32 v[204:205], v[56:57], v[56:57]
	v_pk_mul_f32 v[206:207], v[58:59], v[58:59]
	v_pk_fma_f32 v[204:205], v[60:61], v[60:61], v[204:205]
	v_pk_fma_f32 v[206:207], v[62:63], v[62:63], v[206:207]
	v_pk_fma_f32 v[204:205], v[64:65], v[64:65], v[204:205]
	v_pk_fma_f32 v[206:207], v[66:67], v[66:67], v[206:207]
	v_pk_fma_f32 v[204:205], v[68:69], v[68:69], v[204:205]
	v_pk_fma_f32 v[206:207], v[70:71], v[70:71], v[206:207]
	v_pk_add_f32 v[204:205], v[204:205], v[206:207]
	v_add_f32_e32 v208, v204, v205
	s_nop 0
	s_nop 0
	v_add_f32_dpp v208, v208, v208 quad_perm:[1,0,3,2] row_mask:0xf bank_mask:0xf
	s_nop 0
	s_nop 0
	v_add_f32_dpp v208, v208, v208 quad_perm:[2,3,0,1] row_mask:0xf bank_mask:0xf
	s_nop 0
	s_nop 0
	v_add_f32_dpp v208, v208, v208 row_half_mirror row_mask:0xf bank_mask:0xf
	s_nop 0
	s_nop 0
	v_add_f32_dpp v208, v208, v208 row_mirror row_mask:0xf bank_mask:0xf
	s_nop 0
	s_nop 0
	v_add_f32_dpp v208, v208, v208 row_bcast:15 row_mask:0xa bank_mask:0xf
	s_nop 0
	s_nop 0
	v_add_f32_dpp v208, v208, v208 row_bcast:31 row_mask:0xc bank_mask:0xf
	s_nop 0
	s_nop 0
	v_readlane_b32 s60, v208, 63
	s_nop 1
	v_mov_b32_e32 v210, s60
	v_fmaak_f32 v210, v210, v212, 0x358637bd
	v_rsq_f32_e32 v210, v210
	s_nop 0
	v_pk_mul_f32 v[200:201], v[56:57], v[210:211] op_sel_hi:[1,0]
	v_pk_fma_f32 v[200:201], v[200:201], v[24:25], v[40:41]
	v_cvt_pk_bf16_f32 v184, v200, v201
	v_pk_mul_f32 v[202:203], v[58:59], v[210:211] op_sel_hi:[1,0]
	v_pk_fma_f32 v[202:203], v[202:203], v[26:27], v[42:43]
	v_cvt_pk_bf16_f32 v185, v202, v203
	v_pk_mul_f32 v[200:201], v[60:61], v[210:211] op_sel_hi:[1,0]
	v_pk_fma_f32 v[200:201], v[200:201], v[28:29], v[44:45]
	v_cvt_pk_bf16_f32 v186, v200, v201
	v_pk_mul_f32 v[202:203], v[62:63], v[210:211] op_sel_hi:[1,0]
	v_pk_fma_f32 v[202:203], v[202:203], v[30:31], v[46:47]
	v_cvt_pk_bf16_f32 v187, v202, v203
	v_pk_mul_f32 v[200:201], v[64:65], v[210:211] op_sel_hi:[1,0]
	v_pk_fma_f32 v[200:201], v[200:201], v[32:33], v[48:49]
	v_cvt_pk_bf16_f32 v188, v200, v201
	v_pk_mul_f32 v[202:203], v[66:67], v[210:211] op_sel_hi:[1,0]
	v_pk_fma_f32 v[202:203], v[202:203], v[34:35], v[50:51]
	v_cvt_pk_bf16_f32 v189, v202, v203
	v_pk_mul_f32 v[200:201], v[68:69], v[210:211] op_sel_hi:[1,0]
	v_pk_fma_f32 v[200:201], v[200:201], v[36:37], v[52:53]
	v_cvt_pk_bf16_f32 v190, v200, v201
	v_pk_mul_f32 v[202:203], v[70:71], v[210:211] op_sel_hi:[1,0]
	v_pk_fma_f32 v[202:203], v[202:203], v[38:39], v[54:55]
	v_cvt_pk_bf16_f32 v191, v202, v203
	global_store_dwordx4 v2, v[184:187], s[78:79] nt
	global_store_dwordx4 v2, v[188:191], s[78:79] offset:1024 nt
	s_add_i32 s81, s82, 8
	s_cmp_lt_u32 s81, 32
	s_cbranch_scc0 .Lrw_INIT_l4_d
	s_add_i32 s81, s80, 8
	s_add_i32 s81, s81, s82
	s_and_b32 s81, s81, 31
	s_lshl_b32 s83, s81, 12
	v_add_u32_e32 v213, s83, v3
	global_load_dwordx4 v[136:139], v213, s[72:73] nt
	global_load_dwordx4 v[140:143], v213, s[72:73] offset:16 nt
	global_load_dwordx4 v[144:147], v213, s[72:73] offset:2048 nt
	global_load_dwordx4 v[148:151], v213, s[72:73] offset:2064 nt
	s_branch .Lrw_INIT_l4_e

; __device__ __forceinline__ unsigned cvtpk(float lo, float hi) { f32x2 v = {lo, hi}; bf16x2_t b = __builtin_convertvector(v, bf16x2_t); return __builtin_bit_cast(unsigned, b); }
; __device__ __forceinline__ void phase_rowwise(const void* xsrc_, bool sbf, void* xdst_, bool dbf, const bf16_t* Y, bf16_t* H, const float* mods, int lprev, int iprev, const float* lnpost, float resw, ...
;     ...
;             if (rr + 2 < 32) {
; #pragma unroll
;                 for (int r = 0; r < 2; ++r)
; #pragma unroll
;                     for (int j = 0; j < 4; ++j) { if (sbf) xnb[r][j] = *(const u32x2*)(xsrcb + (m + 2 + r) * DM + 4 * lane + 256 * j); else xn[r][j] = *(const f32x4*)(xsrc + (m + 2 + r) * DM + 4 * lane + 256 * j); if (hasprev) yn[r][j] = *(const u32x2*)(Y + (m + 2 + r) * DM + 4 * lane + 256 * j); } }
;     ...
;             if (hasnext) {
;                 float ss[2] = {0.f, 0.f};
; #pragma unroll
;                 for (int r = 0; r < 2; ++r)
; #pragma unroll
;                     for (int j = 0; j < 4; ++j) ss[r] += (x[r][j].x * x[r][j].x + x[r][j].y * x[r][j].y) + (x[r][j].z * x[r][j].z + x[r][j].w * x[r][j].w);
; #pragma unroll
;                 for (int off = 1; off < 64; off <<= 1) { ss[0] += __shfl_xor(ss[0], off); ss[1] += __shfl_xor(ss[1], off); }
; #pragma unroll
;                 for (int r = 0; r < 2; ++r) { const float rs = __builtin_amdgcn_rsqf(ss[r] * (1.f / DM) + EPS);
; #pragma unroll
;                     for (int j = 0; j < 4; ++j) { const f32x4 h = (x[r][j] * rs) * na[j] + ns[j]; u32x2 w; w.x = cvtpk(h.x, h.y); w.y = cvtpk(h.z, h.w); *(u32x2*)(H + (m + r) * DM + 4 * lane + 256 * j) = w; } }
.Lrw_INIT_l4_e:
	s_waitcnt vmcnt(24)
	s_add_i32 s81, s80, 4
	s_add_i32 s81, s81, s82
	s_and_b32 s81, s81, 31
	s_lshl_b32 s83, s81, 11
	v_add_u32_e32 v2, s83, v1
	v_pk_mul_f32 v[204:205], v[72:73], v[72:73]
	v_pk_mul_f32 v[206:207], v[74:75], v[74:75]
	v_pk_fma_f32 v[204:205], v[76:77], v[76:77], v[204:205]
	v_pk_fma_f32 v[206:207], v[78:79], v[78:79], v[206:207]
	v_pk_fma_f32 v[204:205], v[80:81], v[80:81], v[204:205]
	v_pk_fma_f32 v[206:207], v[82:83], v[82:83], v[206:207]
	v_pk_fma_f32 v[204:205], v[84:85], v[84:85], v[204:205]
	v_pk_fma_f32 v[206:207], v[86:87], v[86:87], v[206:207]
	v_pk_add_f32 v[204:205], v[204:205], v[206:207]
	v_add_f32_e32 v208, v204, v205
	s_nop 0
	s_nop 0
	v_add_f32_dpp v208, v208, v208 quad_perm:[1,0,3,2] row_mask:0xf bank_mask:0xf
	s_nop 0
	s_nop 0
	v_add_f32_dpp v208, v208, v208 quad_perm:[2,3,0,1] row_mask:0xf bank_mask:0xf
	s_nop 0
	s_nop 0
	v_add_f32_dpp v208, v208, v208 row_half_mirror row_mask:0xf bank_mask:0xf
	s_nop 0
	s_nop 0
	v_add_f32_dpp v208, v208, v208 row_mirror row_mask:0xf bank_mask:0xf
	s_nop 0
	s_nop 0
	v_add_f32_dpp v208, v208, v208 row_bcast:15 row_mask:0xa bank_mask:0xf
	s_nop 0
	s_nop 0
	v_add_f32_dpp v208, v208, v208 row_bcast:31 row_mask:0xc bank_mask:0xf
	s_nop 0
	s_nop 0
	v_readlane_b32 s60, v208, 63
	s_nop 1
	v_mov_b32_e32 v210, s60
	v_fmaak_f32 v210, v210, v212, 0x358637bd
	v_rsq_f32_e32 v210, v210
	s_nop 0
	v_pk_mul_f32 v[200:201], v[72:73], v[210:211] op_sel_hi:[1,0]
	v_pk_fma_f32 v[200:201], v[200:201], v[24:25], v[40:41]
	v_cvt_pk_bf16_f32 v184, v200, v201
	v_pk_mul_f32 v[202:203], v[74:75], v[210:211] op_sel_hi:[1,0]
	v_pk_fma_f32 v[202:203], v[202:203], v[26:27], v[42:43]
	v_cvt_pk_bf16_f32 v185, v202, v203
	v_pk_mul_f32 v[200:201], v[76:77], v[210:211] op_sel_hi:[1,0]
	v_pk_fma_f32 v[200:201], v[200:201], v[28:29], v[44:45]
	v_cvt_pk_bf16_f32 v186, v200, v201
	v_pk_mul_f32 v[202:203], v[78:79], v[210:211] op_sel_hi:[1,0]
	v_pk_fma_f32 v[202:203], v[202:203], v[30:31], v[46:47]
	v_cvt_pk_bf16_f32 v187, v202, v203
	v_pk_mul_f32 v[200:201], v[80:81], v[210:211] op_sel_hi:[1,0]
	v_pk_fma_f32 v[200:201], v[200:201], v[32:33], v[48:49]
	v_cvt_pk_bf16_f32 v188, v200, v201
	v_pk_mul_f32 v[202:203], v[82:83], v[210:211] op_sel_hi:[1,0]
	v_pk_fma_f32 v[202:203], v[202:203], v[34:35], v[50:51]
	v_cvt_pk_bf16_f32 v189, v202, v203
	v_pk_mul_f32 v[200:201], v[84:85], v[210:211] op_sel_hi:[1,0]
	v_pk_fma_f32 v[200:201], v[200:201], v[36:37], v[52:53]
	v_cvt_pk_bf16_f32 v190, v200, v201
	v_pk_mul_f32 v[202:203], v[86:87], v[210:211] op_sel_hi:[1,0]
	v_pk_fma_f32 v[202:203], v[202:203], v[38:39], v[54:55]
	v_cvt_pk_bf16_f32 v191, v202, v203
	global_store_dwordx4 v2, v[184:187], s[78:79] nt
	global_store_dwordx4 v2, v[188:191], s[78:79] offset:1024 nt
	s_add_i32 s81, s82, 9
	s_cmp_lt_u32 s81, 32
	s_cbranch_scc0 .Lrw_INIT_l5_d
	s_add_i32 s81, s80, 9
	s_add_i32 s81, s81, s82
	s_and_b32 s81, s81, 31
	s_lshl_b32 s83, s81, 12
	v_add_u32_e32 v213, s83, v3
	global_load_dwordx4 v[152:155], v213, s[72:73] nt
	global_load_dwordx4 v[156:159], v213, s[72:73] offset:16 nt
	global_load_dwordx4 v[160:163], v213, s[72:73] offset:2048 nt
	global_load_dwordx4 v[164:167], v213, s[72:73] offset:2064 nt
	s_branch .Lrw_INIT_l5_e

; __device__ __forceinline__ unsigned cvtpk(float lo, float hi) { f32x2 v = {lo, hi}; bf16x2_t b = __builtin_convertvector(v, bf16x2_t); return __builtin_bit_cast(unsigned, b); }
; __device__ __forceinline__ void phase_rowwise(const void* xsrc_, bool sbf, void* xdst_, bool dbf, const bf16_t* Y, bf16_t* H, const float* mods, int lprev, int iprev, const float* lnpost, float resw, ...
;     ...
;             if (rr + 2 < 32) {
; #pragma unroll
;                 for (int r = 0; r < 2; ++r)
; #pragma unroll
;                     for (int j = 0; j < 4; ++j) { if (sbf) xnb[r][j] = *(const u32x2*)(xsrcb + (m + 2 + r) * DM + 4 * lane + 256 * j); else xn[r][j] = *(const f32x4*)(xsrc + (m + 2 + r) * DM + 4 * lane + 256 * j); if (hasprev) yn[r][j] = *(const u32x2*)(Y + (m + 2 + r) * DM + 4 * lane + 256 * j); } }
;     ...
;             if (hasnext) {
;                 float ss[2] = {0.f, 0.f};
; #pragma unroll
;                 for (int r = 0; r < 2; ++r)
; #pragma unroll
;                     for (int j = 0; j < 4; ++j) ss[r] += (x[r][j].x * x[r][j].x + x[r][j].y * x[r][j].y) + (x[r][j].z * x[r][j].z + x[r][j].w * x[r][j].w);
; #pragma unroll
;                 for (int off = 1; off < 64; off <<= 1) { ss[0] += __shfl_xor(ss[0], off); ss[1] += __shfl_xor(ss[1], off); }
; #pragma unroll
;                 for (int r = 0; r < 2; ++r) { const float rs = __builtin_amdgcn_rsqf(ss[r] * (1.f / DM) + EPS);
; #pragma unroll
;                     for (int j = 0; j < 4; ++j) { const f32x4 h = (x[r][j] * rs) * na[j] + ns[j]; u32x2 w; w.x = cvtpk(h.x, h.y); w.y = cvtpk(h.z, h.w); *(u32x2*)(H + (m + r) * DM + 4 * lane + 256 * j) = w; } }
.Lrw_INIT_l5_e:
	s_waitcnt vmcnt(24)
	s_add_i32 s81, s80, 5
	s_add_i32 s81, s81, s82
	s_and_b32 s81, s81, 31
	s_lshl_b32 s83, s81, 11
	v_add_u32_e32 v2, s83, v1
	v_pk_mul_f32 v[204:205], v[88:89], v[88:89]
	v_pk_mul_f32 v[206:207], v[90:91], v[90:91]
	v_pk_fma_f32 v[204:205], v[92:93], v[92:93], v[204:205]
	v_pk_fma_f32 v[206:207], v[94:95], v[94:95], v[206:207]
	v_pk_fma_f32 v[204:205], v[96:97], v[96:97], v[204:205]
	v_pk_fma_f32 v[206:207], v[98:99], v[98:99], v[206:207]
	v_pk_fma_f32 v[204:205], v[100:101], v[100:101], v[204:205]
	v_pk_fma_f32 v[206:207], v[102:103], v[102:103], v[206:207]
	v_pk_add_f32 v[204:205], v[204:205], v[206:207]
	v_add_f32_e32 v208, v204, v205
	s_nop 0
	s_nop 0
	v_add_f32_dpp v208, v208, v208 quad_perm:[1,0,3,2] row_mask:0xf bank_mask:0xf
	s_nop 0
	s_nop 0
	v_add_f32_dpp v208, v208, v208 quad_perm:[2,3,0,1] row_mask:0xf bank_mask:0xf
	s_nop 0
	s_nop 0
	v_add_f32_dpp v208, v208, v208 row_half_mirror row_mask:0xf bank_mask:0xf
	s_nop 0
	s_nop 0
	v_add_f32_dpp v208, v208, v208 row_mirror row_mask:0xf bank_mask:0xf
	s_nop 0
	s_nop 0
	v_add_f32_dpp v208, v208, v208 row_bcast:15 row_mask:0xa bank_mask:0xf
	s_nop 0
	s_nop 0
	v_add_f32_dpp v208, v208, v208 row_bcast:31 row_mask:0xc bank_mask:0xf
	s_nop 0
	s_nop 0
	v_readlane_b32 s60, v208, 63
	s_nop 1
	v_mov_b32_e32 v210, s60
	v_fmaak_f32 v210, v210, v212, 0x358637bd
	v_rsq_f32_e32 v210, v210
	s_nop 0
	v_pk_mul_f32 v[200:201], v[88:89], v[210:211] op_sel_hi:[1,0]
	v_pk_fma_f32 v[200:201], v[200:201], v[24:25], v[40:41]
	v_cvt_pk_bf16_f32 v184, v200, v201
	v_pk_mul_f32 v[202:203], v[90:91], v[210:211] op_sel_hi:[1,0]
	v_pk_fma_f32 v[202:203], v[202:203], v[26:27], v[42:43]
	v_cvt_pk_bf16_f32 v185, v202, v203
	v_pk_mul_f32 v[200:201], v[92:93], v[210:211] op_sel_hi:[1,0]
	v_pk_fma_f32 v[200:201], v[200:201], v[28:29], v[44:45]
	v_cvt_pk_bf16_f32 v186, v200, v201
	v_pk_mul_f32 v[202:203], v[94:95], v[210:211] op_sel_hi:[1,0]
	v_pk_fma_f32 v[202:203], v[202:203], v[30:31], v[46:47]
	v_cvt_pk_bf16_f32 v187, v202, v203
	v_pk_mul_f32 v[200:201], v[96:97], v[210:211] op_sel_hi:[1,0]
	v_pk_fma_f32 v[200:201], v[200:201], v[32:33], v[48:49]
	v_cvt_pk_bf16_f32 v188, v200, v201
	v_pk_mul_f32 v[202:203], v[98:99], v[210:211] op_sel_hi:[1,0]
	v_pk_fma_f32 v[202:203], v[202:203], v[34:35], v[50:51]
	v_cvt_pk_bf16_f32 v189, v202, v203
	v_pk_mul_f32 v[200:201], v[100:101], v[210:211] op_sel_hi:[1,0]
	v_pk_fma_f32 v[200:201], v[200:201], v[36:37], v[52:53]
	v_cvt_pk_bf16_f32 v190, v200, v201
	v_pk_mul_f32 v[202:203], v[102:103], v[210:211] op_sel_hi:[1,0]
	v_pk_fma_f32 v[202:203], v[202:203], v[38:39], v[54:55]
	v_cvt_pk_bf16_f32 v191, v202, v203
	global_store_dwordx4 v2, v[184:187], s[78:79] nt
	global_store_dwordx4 v2, v[188:191], s[78:79] offset:1024 nt
	s_add_i32 s81, s82, 10
	s_cmp_lt_u32 s81, 32
	s_cbranch_scc0 .Lrw_INIT_l6_d
	s_add_i32 s81, s80, 10
	s_add_i32 s81, s81, s82
	s_and_b32 s81, s81, 31
	s_lshl_b32 s83, s81, 12
	v_add_u32_e32 v213, s83, v3
	global_load_dwordx4 v[56:59], v213, s[72:73] nt
	global_load_dwordx4 v[60:63], v213, s[72:73] offset:16 nt
	global_load_dwordx4 v[64:67], v213, s[72:73] offset:2048 nt
	global_load_dwordx4 v[68:71], v213, s[72:73] offset:2064 nt
	s_branch .Lrw_INIT_l6_e

; __device__ __forceinline__ unsigned cvtpk(float lo, float hi) { f32x2 v = {lo, hi}; bf16x2_t b = __builtin_convertvector(v, bf16x2_t); return __builtin_bit_cast(unsigned, b); }
; __device__ __forceinline__ void phase_rowwise(const void* xsrc_, bool sbf, void* xdst_, bool dbf, const bf16_t* Y, bf16_t* H, const float* mods, int lprev, int iprev, const float* lnpost, float resw, ...
;     ...
;     for (int ch = gw; ch < M / 32; ch += NGW) {
;         const int b = ch >> 6;
;         f32x4 gp[4], na[4], ns[4];
; #pragma unroll
;         for (int j = 0; j < 4; ++j) { const int c = 4 * lane + 256 * j;
;             if (hasprev) { const f32x4 g = *(const f32x4*)(mods + ((size_t)lprev * 32 + b) * 9216 + iprev * 3072 + 2048 + c); const f32x4 lp = *(const f32x4*)(lnpost + c); gp[j] = g * lp * resw; }
;             else gp[j] = (f32x4){0.f, 0.f, 0.f, 0.f};
;             if (hasnext) { const f32x4 sh = *(const f32x4*)(mods + ((size_t)lnext * 32 + b) * 9216 + inext * 3072 + c); const f32x4 scl = *(const f32x4*)(mods + ((size_t)lnext * 32 + b) * 9216 + inext * 3072 + 1024 + c);
;                 const f32x4 lp = *(const f32x4*)(lnpre + c); na[j] = lp * (scl + 1.0f); ns[j] = sh; }
;             else { na[j] = (f32x4){0.f, 0.f, 0.f, 0.f}; ns[j] = na[j]; } }
;     ...
;             if (hasnext) {
;                 float ss[2] = {0.f, 0.f};
; #pragma unroll
;                 for (int r = 0; r < 2; ++r)
; #pragma unroll
;                     for (int j = 0; j < 4; ++j) ss[r] += (x[r][j].x * x[r][j].x + x[r][j].y * x[r][j].y) + (x[r][j].z * x[r][j].z + x[r][j].w * x[r][j].w);
; #pragma unroll
;                 for (int off = 1; off < 64; off <<= 1) { ss[0] += __shfl_xor(ss[0], off); ss[1] += __shfl_xor(ss[1], off); }
; #pragma unroll
;                 for (int r = 0; r < 2; ++r) { const float rs = __builtin_amdgcn_rsqf(ss[r] * (1.f / DM) + EPS);
; #pragma unroll
;                     for (int j = 0; j < 4; ++j) { const f32x4 h = (x[r][j] * rs) * na[j] + ns[j]; u32x2 w; w.x = cvtpk(h.x, h.y); w.y = cvtpk(h.z, h.w); *(u32x2*)(H + (m + r) * DM + 4 * lane + 256 * j) = w; } }
.Lrw_INIT_l6_e:
	s_waitcnt vmcnt(24)
	s_add_i32 s81, s80, 6
	s_add_i32 s81, s81, s82
	s_and_b32 s81, s81, 31
	s_lshl_b32 s83, s81, 11
	v_add_u32_e32 v2, s83, v1
	v_pk_mul_f32 v[204:205], v[104:105], v[104:105]
	v_pk_mul_f32 v[206:207], v[106:107], v[106:107]
	v_pk_fma_f32 v[204:205], v[108:109], v[108:109], v[204:205]
	v_pk_fma_f32 v[206:207], v[110:111], v[110:111], v[206:207]
	v_pk_fma_f32 v[204:205], v[112:113], v[112:113], v[204:205]
	v_pk_fma_f32 v[206:207], v[114:115], v[114:115], v[206:207]
	v_pk_fma_f32 v[204:205], v[116:117], v[116:117], v[204:205]
	v_pk_fma_f32 v[206:207], v[118:119], v[118:119], v[206:207]
	v_pk_add_f32 v[204:205], v[204:205], v[206:207]
	v_add_f32_e32 v208, v204, v205
	s_nop 0
	s_nop 0
	v_add_f32_dpp v208, v208, v208 quad_perm:[1,0,3,2] row_mask:0xf bank_mask:0xf
	s_nop 0
	s_nop 0
	v_add_f32_dpp v208, v208, v208 quad_perm:[2,3,0,1] row_mask:0xf bank_mask:0xf
	s_nop 0
	s_nop 0
	v_add_f32_dpp v208, v208, v208 row_half_mirror row_mask:0xf bank_mask:0xf
	s_nop 0
	s_nop 0
	v_add_f32_dpp v208, v208, v208 row_mirror row_mask:0xf bank_mask:0xf
	s_nop 0
	s_nop 0
	v_add_f32_dpp v208, v208, v208 row_bcast:15 row_mask:0xa bank_mask:0xf
	s_nop 0
	s_nop 0
	v_add_f32_dpp v208, v208, v208 row_bcast:31 row_mask:0xc bank_mask:0xf
	s_nop 0
	s_nop 0
	v_readlane_b32 s60, v208, 63
	s_nop 1
	v_mov_b32_e32 v210, s60
	v_fmaak_f32 v210, v210, v212, 0x358637bd
	v_rsq_f32_e32 v210, v210
	s_nop 0
	v_pk_mul_f32 v[200:201], v[104:105], v[210:211] op_sel_hi:[1,0]
	v_pk_fma_f32 v[200:201], v[200:201], v[24:25], v[40:41]
	v_cvt_pk_bf16_f32 v184, v200, v201
	v_pk_mul_f32 v[202:203], v[106:107], v[210:211] op_sel_hi:[1,0]
	v_pk_fma_f32 v[202:203], v[202:203], v[26:27], v[42:43]
	v_cvt_pk_bf16_f32 v185, v202, v203
	v_pk_mul_f32 v[200:201], v[108:109], v[210:211] op_sel_hi:[1,0]
	v_pk_fma_f32 v[200:201], v[200:201], v[28:29], v[44:45]
	v_cvt_pk_bf16_f32 v186, v200, v201
	v_pk_mul_f32 v[202:203], v[110:111], v[210:211] op_sel_hi:[1,0]
	v_pk_fma_f32 v[202:203], v[202:203], v[30:31], v[46:47]
	v_cvt_pk_bf16_f32 v187, v202, v203
	v_pk_mul_f32 v[200:201], v[112:113], v[210:211] op_sel_hi:[1,0]
	v_pk_fma_f32 v[200:201], v[200:201], v[32:33], v[48:49]
	v_cvt_pk_bf16_f32 v188, v200, v201
	v_pk_mul_f32 v[202:203], v[114:115], v[210:211] op_sel_hi:[1,0]
	v_pk_fma_f32 v[202:203], v[202:203], v[34:35], v[50:51]
	v_cvt_pk_bf16_f32 v189, v202, v203
	v_pk_mul_f32 v[200:201], v[116:117], v[210:211] op_sel_hi:[1,0]
	v_pk_fma_f32 v[200:201], v[200:201], v[36:37], v[52:53]
	v_cvt_pk_bf16_f32 v190, v200, v201
	v_pk_mul_f32 v[202:203], v[118:119], v[210:211] op_sel_hi:[1,0]
	v_pk_fma_f32 v[202:203], v[202:203], v[38:39], v[54:55]
	v_cvt_pk_bf16_f32 v191, v202, v203
	global_store_dwordx4 v2, v[184:187], s[78:79] nt
	global_store_dwordx4 v2, v[188:191], s[78:79] offset:1024 nt
	s_add_i32 s82, s82, 7
	s_cmp_lt_u32 s82, 32
	s_cbranch_scc1 .Lrw_INIT_loop
	s_branch .LBB0_1024
.Lrw_FIRST:
	v_readfirstlane_b32 s40, v214
	v_readlane_b32 s41, v254, 46
	s_lshr_b32 s40, s40, 6
	s_add_i32 s40, s40, s41
	s_lshr_b32 s41, s40, 6
	v_and_b32_e32 v1, 63, v214
	v_lshlrev_b32_e32 v3, 5, v1
	v_lshlrev_b32_e32 v1, 4, v1
	v_mov_b32_e32 v212, 0x3a800000
	s_cmp_eq_u32 s74, 2
	s_cselect_b32 s42, 1, 0
	s_add_i32 s42, s73, s42
	s_add_i32 s43, s74, 1
	s_cmp_eq_u32 s74, 2
	s_cselect_b32 s43, 0, s43
	s_cmp_eq_u32 s74, 1
	s_cselect_b32 s90, 1.0, 0.5
	s_mov_b32 s91, s90
	v_readlane_b32 s44, v255, 22
	v_readlane_b32 s45, v255, 23
	s_lshl_b32 s46, s73, 5
	s_add_i32 s46, s46, s41
	s_mul_i32 s46, s46, 0x9000
	s_mul_i32 s47, s74, 0x3000
	s_add_i32 s46, s46, s47
	s_add_i32 s46, s46, 0x2000
	s_add_u32 s48, s44, s46
	s_addc_u32 s49, s45, 0
	v_readlane_b32 s52, v255, 16
	v_readlane_b32 s53, v255, 17
	s_mul_i32 s46, s73, 3
	s_add_i32 s46, s46, s74
	s_lshl_b32 s46, s46, 12
	s_add_u32 s52, s52, s46
	s_addc_u32 s53, s53, 0
	global_load_dwordx4 v[8:11], v3, s[48:49]
	global_load_dwordx4 v[12:15], v3, s[48:49] offset:16
	global_load_dwordx4 v[16:19], v3, s[48:49] offset:2048
	global_load_dwordx4 v[20:23], v3, s[48:49] offset:2064
	global_load_dwordx4 v[56:59], v3, s[52:53]
	global_load_dwordx4 v[60:63], v3, s[52:53] offset:16
	global_load_dwordx4 v[64:67], v3, s[52:53] offset:2048
	global_load_dwordx4 v[68:71], v3, s[52:53] offset:2064
	s_lshl_b32 s46, s42, 5
	s_add_i32 s46, s46, s41
	s_mul_i32 s46, s46, 0x9000
	s_mul_i32 s47, s43, 0x3000
	s_add_i32 s46, s46, s47
	s_add_u32 s50, s44, s46
	s_addc_u32 s51, s45, 0
	s_add_u32 s56, s50, 0x1000
	s_addc_u32 s57, s51, 0
	v_readlane_b32 s54, v255, 14
	v_readlane_b32 s55, v255, 15
	s_mul_i32 s46, s42, 3
	s_add_i32 s46, s46, s43
	s_lshl_b32 s46, s46, 12
	s_add_u32 s54, s54, s46
	s_addc_u32 s55, s55, 0
	global_load_dwordx4 v[24:27], v3, s[56:57]
	global_load_dwordx4 v[28:31], v3, s[56:57] offset:16
	global_load_dwordx4 v[32:35], v3, s[56:57] offset:2048
	global_load_dwordx4 v[36:39], v3, s[56:57] offset:2064
	global_load_dwordx4 v[72:75], v3, s[54:55]
	global_load_dwordx4 v[76:79], v3, s[54:55] offset:16
	global_load_dwordx4 v[80:83], v3, s[54:55] offset:2048
	global_load_dwordx4 v[84:87], v3, s[54:55] offset:2064
	global_load_dwordx4 v[40:43], v3, s[50:51]
	global_load_dwordx4 v[44:47], v3, s[50:51] offset:16
	global_load_dwordx4 v[48:51], v3, s[50:51] offset:2048
	global_load_dwordx4 v[52:55], v3, s[50:51] offset:2064
	s_lshl_b32 s46, s40, 16
	s_lshl_b32 s47, s40, 17
	v_readlane_b32 s72, v255, 4
	v_readlane_b32 s73, v255, 5
	s_add_u32 s72, s72, s47
	s_addc_u32 s73, s73, 0
	v_readlane_b32 s74, v252, 22
	v_readlane_b32 s75, v252, 23
	s_add_u32 s74, s74, s46
	s_addc_u32 s75, s75, 0
	v_readlane_b32 s76, v252, 6
	v_readlane_b32 s77, v252, 7
	s_add_u32 s76, s76, s46
	s_addc_u32 s77, s77, 0
	v_readlane_b32 s78, v252, 20
	v_readlane_b32 s79, v252, 21
	s_add_u32 s78, s78, s46
	s_addc_u32 s79, s79, 0
	s_and_b32 s80, s40, 15
	s_lshl_b32 s80, s80, 1
	s_waitcnt vmcnt(12)
; __device__ __forceinline__ void phase_rowwise(const void* xsrc_, bool sbf, void* xdst_, bool dbf, const bf16_t* Y, bf16_t* H, const float* mods, int lprev, int iprev, const float* lnpost, float resw, ...
;     ...
;         for (int j = 0; j < 4; ++j) { const int c = 4 * lane + 256 * j;
;             if (hasprev) { const f32x4 g = *(const f32x4*)(mods + ((size_t)lprev * 32 + b) * 9216 + iprev * 3072 + 2048 + c); const f32x4 lp = *(const f32x4*)(lnpost + c); gp[j] = g * lp * resw; }
;             else gp[j] = (f32x4){0.f, 0.f, 0.f, 0.f};
;             if (hasnext) { const f32x4 sh = *(const f32x4*)(mods + ((size_t)lnext * 32 + b) * 9216 + inext * 3072 + c); const f32x4 scl = *(const f32x4*)(mods + ((size_t)lnext * 32 + b) * 9216 + inext * 3072 + 1024 + c);
;                 const f32x4 lp = *(const f32x4*)(lnpre + c); na[j] = lp * (scl + 1.0f); ns[j] = sh; }
;             else { na[j] = (f32x4){0.f, 0.f, 0.f, 0.f}; ns[j] = na[j]; } }
;         f32x4 xn[2][4]; u32x2 xnb[2][4]; u32x2 yn[2][4];
;         { const size_t m0 = (size_t)ch * 32;
; #pragma unroll
;           for (int r = 0; r < 2; ++r)
; #pragma unroll
;             for (int j = 0; j < 4; ++j) { if (sbf) { xnb[r][j] = *(const u32x2*)(xsrcb + (m0 + r) * DM + 4 * lane + 256 * j); xn[r][j] = (f32x4){0.f, 0.f, 0.f, 0.f}; } else { xn[r][j] = *(const f32x4*)(xsrc + (m0 + r) * DM + 4 * lane + 256 * j); xnb[r][j] = (u32x2){0u, 0u}; }
;                 yn[r][j] = hasprev ? *(const u32x2*)(Y + (m0 + r) * DM + 4 * lane + 256 * j) : (u32x2){0u, 0u}; } }
;     ...
;             if (hasprev) {
;                 f32x4 y[2][4]; float ss[2] = {0.f, 0.f};
; #pragma unroll
;                 for (int r = 0; r < 2; ++r)
; #pragma unroll
;                     for (int j = 0; j < 4; ++j) { const u32x2 u = yr[r][j]; y[r][j] = (f32x4){bflo(u.x), bfhi(u.x), bflo(u.y), bfhi(u.y)};
;                         ss[r] += (y[r][j].x * y[r][j].x + y[r][j].y * y[r][j].y) + (y[r][j].z * y[r][j].z + y[r][j].w * y[r][j].w); }
; #pragma unroll
;                 for (int off = 1; off < 64; off <<= 1) { ss[0] += __shfl_xor(ss[0], off); ss[1] += __shfl_xor(ss[1], off); }
; #pragma unroll
;                 for (int r = 0; r < 2; ++r) { const float rs = __builtin_amdgcn_rsqf(ss[r] * (1.f / DM) + EPS);
; #pragma unroll
;                     for (int j = 0; j < 4; ++j) x[r][j] = x[r][j] + gp[j] * (y[r][j] * rs); }
	v_pk_mul_f32 v[8:9], v[8:9], v[56:57]
	v_pk_mul_f32 v[10:11], v[10:11], v[58:59]
	v_pk_mul_f32 v[12:13], v[12:13], v[60:61]
	v_pk_mul_f32 v[14:15], v[14:15], v[62:63]
	v_pk_mul_f32 v[16:17], v[16:17], v[64:65]
	v_pk_mul_f32 v[18:19], v[18:19], v[66:67]
	v_pk_mul_f32 v[20:21], v[20:21], v[68:69]
	v_pk_mul_f32 v[22:23], v[22:23], v[70:71]
	v_pk_mul_f32 v[8:9], v[8:9], s[90:91]
	v_pk_mul_f32 v[10:11], v[10:11], s[90:91]
	v_pk_mul_f32 v[12:13], v[12:13], s[90:91]
	v_pk_mul_f32 v[14:15], v[14:15], s[90:91]
	v_pk_mul_f32 v[16:17], v[16:17], s[90:91]
	v_pk_mul_f32 v[18:19], v[18:19], s[90:91]
	v_pk_mul_f32 v[20:21], v[20:21], s[90:91]
	v_pk_mul_f32 v[22:23], v[22:23], s[90:91]
	s_waitcnt vmcnt(4)
	v_pk_add_f32 v[24:25], v[24:25], 1.0 op_sel_hi:[1,0]
	v_pk_add_f32 v[26:27], v[26:27], 1.0 op_sel_hi:[1,0]
	v_pk_add_f32 v[28:29], v[28:29], 1.0 op_sel_hi:[1,0]
	v_pk_add_f32 v[30:31], v[30:31], 1.0 op_sel_hi:[1,0]
	v_pk_add_f32 v[32:33], v[32:33], 1.0 op_sel_hi:[1,0]
	v_pk_add_f32 v[34:35], v[34:35], 1.0 op_sel_hi:[1,0]
	v_pk_add_f32 v[36:37], v[36:37], 1.0 op_sel_hi:[1,0]
	v_pk_add_f32 v[38:39], v[38:39], 1.0 op_sel_hi:[1,0]
	v_pk_mul_f32 v[24:25], v[72:73], v[24:25]
	v_pk_mul_f32 v[26:27], v[74:75], v[26:27]
	v_pk_mul_f32 v[28:29], v[76:77], v[28:29]
	v_pk_mul_f32 v[30:31], v[78:79], v[30:31]
	v_pk_mul_f32 v[32:33], v[80:81], v[32:33]
	v_pk_mul_f32 v[34:35], v[82:83], v[34:35]
	v_pk_mul_f32 v[36:37], v[84:85], v[36:37]
	v_pk_mul_f32 v[38:39], v[86:87], v[38:39]
	s_waitcnt vmcnt(0)
	s_mov_b32 s82, 0
	s_add_i32 s81, s80, 0
	s_add_i32 s81, s81, s82
	s_and_b32 s81, s81, 31
	s_lshl_b32 s83, s81, 11
	v_add_u32_e32 v2, s83, v1
	s_lshl_b32 s83, s81, 12
	v_add_u32_e32 v213, s83, v3
	global_load_dwordx4 v[56:59], v213, s[72:73] nt
	global_load_dwordx4 v[60:63], v213, s[72:73] offset:16 nt
	global_load_dwordx4 v[64:67], v213, s[72:73] offset:2048 nt
	global_load_dwordx4 v[68:71], v213, s[72:73] offset:2064 nt
	global_load_dwordx4 v[72:75], v2, s[74:75] nt
	global_load_dwordx4 v[76:79], v2, s[74:75] offset:1024 nt
	s_add_i32 s81, s80, 1
	s_add_i32 s81, s81, s82
	s_and_b32 s81, s81, 31
	s_lshl_b32 s83, s81, 11
	v_add_u32_e32 v2, s83, v1
	s_lshl_b32 s83, s81, 12
	v_add_u32_e32 v213, s83, v3
	global_load_dwordx4 v[80:83], v213, s[72:73] nt
	global_load_dwordx4 v[84:87], v213, s[72:73] offset:16 nt
	global_load_dwordx4 v[88:91], v213, s[72:73] offset:2048 nt
	global_load_dwordx4 v[92:95], v213, s[72:73] offset:2064 nt
	global_load_dwordx4 v[96:99], v2, s[74:75] nt
	global_load_dwordx4 v[100:103], v2, s[74:75] offset:1024 nt
	s_add_i32 s81, s80, 2
	s_add_i32 s81, s81, s82
	s_and_b32 s81, s81, 31
	s_lshl_b32 s83, s81, 11
	v_add_u32_e32 v2, s83, v1
	s_lshl_b32 s83, s81, 12
	v_add_u32_e32 v213, s83, v3
	global_load_dwordx4 v[104:107], v213, s[72:73] nt
	global_load_dwordx4 v[108:111], v213, s[72:73] offset:16 nt
	global_load_dwordx4 v[112:115], v213, s[72:73] offset:2048 nt
	global_load_dwordx4 v[116:119], v213, s[72:73] offset:2064 nt
	global_load_dwordx4 v[120:123], v2, s[74:75] nt
	global_load_dwordx4 v[124:127], v2, s[74:75] offset:1024 nt
	s_waitcnt vmcnt(12)
	v_lshlrev_b32_e32 v200, 16, v72
	v_and_b32_e32 v201, 0xffff0000, v72
	v_pk_mul_f32 v[204:205], v[200:201], v[200:201]
	v_lshlrev_b32_e32 v202, 16, v73
	v_and_b32_e32 v203, 0xffff0000, v73
	v_pk_mul_f32 v[206:207], v[202:203], v[202:203]
	v_lshlrev_b32_e32 v200, 16, v74
	v_and_b32_e32 v201, 0xffff0000, v74
	v_pk_fma_f32 v[204:205], v[200:201], v[200:201], v[204:205]
	v_lshlrev_b32_e32 v202, 16, v75
	v_and_b32_e32 v203, 0xffff0000, v75
	v_pk_fma_f32 v[206:207], v[202:203], v[202:203], v[206:207]
	v_lshlrev_b32_e32 v200, 16, v76
	v_and_b32_e32 v201, 0xffff0000, v76
	v_pk_fma_f32 v[204:205], v[200:201], v[200:201], v[204:205]
	v_lshlrev_b32_e32 v202, 16, v77
	v_and_b32_e32 v203, 0xffff0000, v77
	v_pk_fma_f32 v[206:207], v[202:203], v[202:203], v[206:207]
	v_lshlrev_b32_e32 v200, 16, v78
	v_and_b32_e32 v201, 0xffff0000, v78
	v_pk_fma_f32 v[204:205], v[200:201], v[200:201], v[204:205]
	v_lshlrev_b32_e32 v202, 16, v79
	v_and_b32_e32 v203, 0xffff0000, v79
	v_pk_fma_f32 v[206:207], v[202:203], v[202:203], v[206:207]
	v_pk_add_f32 v[204:205], v[204:205], v[206:207]
	v_add_f32_e32 v208, v204, v205
	s_nop 0
	s_nop 0
	v_add_f32_dpp v208, v208, v208 quad_perm:[1,0,3,2] row_mask:0xf bank_mask:0xf
	s_nop 0
	s_nop 0
	v_add_f32_dpp v208, v208, v208 quad_perm:[2,3,0,1] row_mask:0xf bank_mask:0xf
	s_nop 0
	s_nop 0
	v_add_f32_dpp v208, v208, v208 row_half_mirror row_mask:0xf bank_mask:0xf
	s_nop 0
	s_nop 0
	v_add_f32_dpp v208, v208, v208 row_mirror row_mask:0xf bank_mask:0xf
	s_nop 0
	s_nop 0
	v_add_f32_dpp v208, v208, v208 row_bcast:15 row_mask:0xa bank_mask:0xf
	s_nop 0
	s_nop 0
	v_add_f32_dpp v208, v208, v208 row_bcast:31 row_mask:0xc bank_mask:0xf
	s_nop 0
	s_nop 0
	v_readlane_b32 s60, v208, 63
	s_nop 1
	v_mov_b32_e32 v210, s60
	v_fmaak_f32 v210, v210, v212, 0x358637bd
	v_rsq_f32_e32 v210, v210
	s_nop 0
	v_lshlrev_b32_e32 v200, 16, v72
	v_and_b32_e32 v201, 0xffff0000, v72
	v_pk_mul_f32 v[200:201], v[200:201], v[210:211] op_sel_hi:[1,0]
	v_pk_fma_f32 v[56:57], v[8:9], v[200:201], v[56:57]
	v_lshlrev_b32_e32 v202, 16, v73
	v_and_b32_e32 v203, 0xffff0000, v73
	v_pk_mul_f32 v[202:203], v[202:203], v[210:211] op_sel_hi:[1,0]
	v_pk_fma_f32 v[58:59], v[10:11], v[202:203], v[58:59]
	v_lshlrev_b32_e32 v200, 16, v74
	v_and_b32_e32 v201, 0xffff0000, v74
	v_pk_mul_f32 v[200:201], v[200:201], v[210:211] op_sel_hi:[1,0]
	v_pk_fma_f32 v[60:61], v[12:13], v[200:201], v[60:61]
	v_lshlrev_b32_e32 v202, 16, v75
	v_and_b32_e32 v203, 0xffff0000, v75
	v_pk_mul_f32 v[202:203], v[202:203], v[210:211] op_sel_hi:[1,0]
; __device__ __forceinline__ unsigned cvtpk(float lo, float hi) { f32x2 v = {lo, hi}; bf16x2_t b = __builtin_convertvector(v, bf16x2_t); return __builtin_bit_cast(unsigned, b); }
; __device__ __forceinline__ void phase_rowwise(const void* xsrc_, bool sbf, void* xdst_, bool dbf, const bf16_t* Y, bf16_t* H, const float* mods, int lprev, int iprev, const float* lnpost, float resw, ...
;     ...
;             if (rr + 2 < 32) {
; #pragma unroll
;                 for (int r = 0; r < 2; ++r)
; #pragma unroll
;                     for (int j = 0; j < 4; ++j) { if (sbf) xnb[r][j] = *(const u32x2*)(xsrcb + (m + 2 + r) * DM + 4 * lane + 256 * j); else xn[r][j] = *(const f32x4*)(xsrc + (m + 2 + r) * DM + 4 * lane + 256 * j); if (hasprev) yn[r][j] = *(const u32x2*)(Y + (m + 2 + r) * DM + 4 * lane + 256 * j); } }
;     ...
;                     for (int j = 0; j < 4; ++j) x[r][j] = x[r][j] + gp[j] * (y[r][j] * rs); }
;             }
; #pragma unroll
;             for (int r = 0; r < 2; ++r)
; #pragma unroll
;                 for (int j = 0; j < 4; ++j) { if (hasprev) { if (dbf) { u32x2 w; w.x = cvtpk(x[r][j].x, x[r][j].y); w.y = cvtpk(x[r][j].z, x[r][j].w); *(u32x2*)(xdstb + (m + r) * DM + 4 * lane + 256 * j) = w; } else *(f32x4*)(xdst + (m + r) * DM + 4 * lane + 256 * j) = x[r][j]; } }
;             if (hasnext) {
;                 float ss[2] = {0.f, 0.f};
; #pragma unroll
;                 for (int r = 0; r < 2; ++r)
; #pragma unroll
;                     for (int j = 0; j < 4; ++j) ss[r] += (x[r][j].x * x[r][j].x + x[r][j].y * x[r][j].y) + (x[r][j].z * x[r][j].z + x[r][j].w * x[r][j].w);
; #pragma unroll
;                 for (int off = 1; off < 64; off <<= 1) { ss[0] += __shfl_xor(ss[0], off); ss[1] += __shfl_xor(ss[1], off); }
; #pragma unroll
;                 for (int r = 0; r < 2; ++r) { const float rs = __builtin_amdgcn_rsqf(ss[r] * (1.f / DM) + EPS);
; #pragma unroll
;                     for (int j = 0; j < 4; ++j) { const f32x4 h = (x[r][j] * rs) * na[j] + ns[j]; u32x2 w; w.x = cvtpk(h.x, h.y); w.y = cvtpk(h.z, h.w); *(u32x2*)(H + (m + r) * DM + 4 * lane + 256 * j) = w; } }
	v_pk_fma_f32 v[62:63], v[14:15], v[202:203], v[62:63]
	v_lshlrev_b32_e32 v200, 16, v76
	v_and_b32_e32 v201, 0xffff0000, v76
	v_pk_mul_f32 v[200:201], v[200:201], v[210:211] op_sel_hi:[1,0]
	v_pk_fma_f32 v[64:65], v[16:17], v[200:201], v[64:65]
	v_lshlrev_b32_e32 v202, 16, v77
	v_and_b32_e32 v203, 0xffff0000, v77
	v_pk_mul_f32 v[202:203], v[202:203], v[210:211] op_sel_hi:[1,0]
	v_pk_fma_f32 v[66:67], v[18:19], v[202:203], v[66:67]
	v_lshlrev_b32_e32 v200, 16, v78
	v_and_b32_e32 v201, 0xffff0000, v78
	v_pk_mul_f32 v[200:201], v[200:201], v[210:211] op_sel_hi:[1,0]
	v_pk_fma_f32 v[68:69], v[20:21], v[200:201], v[68:69]
	v_lshlrev_b32_e32 v202, 16, v79
	v_and_b32_e32 v203, 0xffff0000, v79
	v_pk_mul_f32 v[202:203], v[202:203], v[210:211] op_sel_hi:[1,0]
	v_pk_fma_f32 v[70:71], v[22:23], v[202:203], v[70:71]
	s_add_i32 s81, s80, 0
	s_add_i32 s81, s81, s82
	s_and_b32 s81, s81, 31
	s_lshl_b32 s83, s81, 11
	v_add_u32_e32 v2, s83, v1
	v_cvt_pk_bf16_f32 v72, v56, v57
	v_cvt_pk_bf16_f32 v73, v58, v59
	v_cvt_pk_bf16_f32 v74, v60, v61
	v_cvt_pk_bf16_f32 v75, v62, v63
	v_cvt_pk_bf16_f32 v76, v64, v65
	v_cvt_pk_bf16_f32 v77, v66, v67
	v_cvt_pk_bf16_f32 v78, v68, v69
	v_cvt_pk_bf16_f32 v79, v70, v71
	global_store_dwordx4 v2, v[72:75], s[76:77] nt
	global_store_dwordx4 v2, v[76:79], s[76:77] offset:1024 nt
	v_pk_mul_f32 v[204:205], v[56:57], v[56:57]
	v_pk_mul_f32 v[206:207], v[58:59], v[58:59]
	v_pk_fma_f32 v[204:205], v[60:61], v[60:61], v[204:205]
	v_pk_fma_f32 v[206:207], v[62:63], v[62:63], v[206:207]
	v_pk_fma_f32 v[204:205], v[64:65], v[64:65], v[204:205]
	v_pk_fma_f32 v[206:207], v[66:67], v[66:67], v[206:207]
	v_pk_fma_f32 v[204:205], v[68:69], v[68:69], v[204:205]
	v_pk_fma_f32 v[206:207], v[70:71], v[70:71], v[206:207]
	v_pk_add_f32 v[204:205], v[204:205], v[206:207]
	v_add_f32_e32 v208, v204, v205
	s_nop 0
	s_nop 0
	v_add_f32_dpp v208, v208, v208 quad_perm:[1,0,3,2] row_mask:0xf bank_mask:0xf
	s_nop 0
	s_nop 0
	v_add_f32_dpp v208, v208, v208 quad_perm:[2,3,0,1] row_mask:0xf bank_mask:0xf
	s_nop 0
	s_nop 0
	v_add_f32_dpp v208, v208, v208 row_half_mirror row_mask:0xf bank_mask:0xf
	s_nop 0
	s_nop 0
	v_add_f32_dpp v208, v208, v208 row_mirror row_mask:0xf bank_mask:0xf
	s_nop 0
	s_nop 0
	v_add_f32_dpp v208, v208, v208 row_bcast:15 row_mask:0xa bank_mask:0xf
	s_nop 0
	s_nop 0
	v_add_f32_dpp v208, v208, v208 row_bcast:31 row_mask:0xc bank_mask:0xf
	s_nop 0
	s_nop 0
	v_readlane_b32 s60, v208, 63
	s_nop 1
	v_mov_b32_e32 v210, s60
	v_fmaak_f32 v210, v210, v212, 0x358637bd
	v_rsq_f32_e32 v210, v210
	s_nop 0
	v_pk_mul_f32 v[200:201], v[56:57], v[210:211] op_sel_hi:[1,0]
	v_pk_fma_f32 v[200:201], v[200:201], v[24:25], v[40:41]
	v_cvt_pk_bf16_f32 v72, v200, v201
	v_pk_mul_f32 v[202:203], v[58:59], v[210:211] op_sel_hi:[1,0]
	v_pk_fma_f32 v[202:203], v[202:203], v[26:27], v[42:43]
	v_cvt_pk_bf16_f32 v73, v202, v203
	v_pk_mul_f32 v[200:201], v[60:61], v[210:211] op_sel_hi:[1,0]
	v_pk_fma_f32 v[200:201], v[200:201], v[28:29], v[44:45]
	v_cvt_pk_bf16_f32 v74, v200, v201
	v_pk_mul_f32 v[202:203], v[62:63], v[210:211] op_sel_hi:[1,0]
	v_pk_fma_f32 v[202:203], v[202:203], v[30:31], v[46:47]
	v_cvt_pk_bf16_f32 v75, v202, v203
	v_pk_mul_f32 v[200:201], v[64:65], v[210:211] op_sel_hi:[1,0]
	v_pk_fma_f32 v[200:201], v[200:201], v[32:33], v[48:49]
	v_cvt_pk_bf16_f32 v76, v200, v201
	v_pk_mul_f32 v[202:203], v[66:67], v[210:211] op_sel_hi:[1,0]
	v_pk_fma_f32 v[202:203], v[202:203], v[34:35], v[50:51]
	v_cvt_pk_bf16_f32 v77, v202, v203
	v_pk_mul_f32 v[200:201], v[68:69], v[210:211] op_sel_hi:[1,0]
	v_pk_fma_f32 v[200:201], v[200:201], v[36:37], v[52:53]
	v_cvt_pk_bf16_f32 v78, v200, v201
	v_pk_mul_f32 v[202:203], v[70:71], v[210:211] op_sel_hi:[1,0]
	v_pk_fma_f32 v[202:203], v[202:203], v[38:39], v[54:55]
	v_cvt_pk_bf16_f32 v79, v202, v203
	global_store_dwordx4 v2, v[72:75], s[78:79] nt
	global_store_dwordx4 v2, v[76:79], s[78:79] offset:1024 nt
	s_add_i32 s81, s80, 3
	s_add_i32 s81, s81, s82
	s_and_b32 s81, s81, 31
	s_lshl_b32 s83, s81, 11
	v_add_u32_e32 v2, s83, v1
	s_lshl_b32 s83, s81, 12
	v_add_u32_e32 v213, s83, v3
	global_load_dwordx4 v[128:131], v213, s[72:73] nt
	global_load_dwordx4 v[132:135], v213, s[72:73] offset:16 nt
	global_load_dwordx4 v[136:139], v213, s[72:73] offset:2048 nt
	global_load_dwordx4 v[140:143], v213, s[72:73] offset:2064 nt
	global_load_dwordx4 v[144:147], v2, s[74:75] nt
	global_load_dwordx4 v[148:151], v2, s[74:75] offset:1024 nt
	s_waitcnt vmcnt(16)
; __device__ __forceinline__ float bflo(unsigned u) { return __uint_as_float(u << 16); }
; __device__ __forceinline__ void phase_rowwise(const void* xsrc_, bool sbf, void* xdst_, bool dbf, const bf16_t* Y, bf16_t* H, const float* mods, int lprev, int iprev, const float* lnpost, float resw, ...
;     ...
;             if (hasprev) {
;                 f32x4 y[2][4]; float ss[2] = {0.f, 0.f};
; #pragma unroll
;                 for (int r = 0; r < 2; ++r)
; #pragma unroll
;                     for (int j = 0; j < 4; ++j) { const u32x2 u = yr[r][j]; y[r][j] = (f32x4){bflo(u.x), bfhi(u.x), bflo(u.y), bfhi(u.y)};
;                         ss[r] += (y[r][j].x * y[r][j].x + y[r][j].y * y[r][j].y) + (y[r][j].z * y[r][j].z + y[r][j].w * y[r][j].w); }
; #pragma unroll
;                 for (int off = 1; off < 64; off <<= 1) { ss[0] += __shfl_xor(ss[0], off); ss[1] += __shfl_xor(ss[1], off); }
; #pragma unroll
;                 for (int r = 0; r < 2; ++r) { const float rs = __builtin_amdgcn_rsqf(ss[r] * (1.f / DM) + EPS);
; #pragma unroll
;                     for (int j = 0; j < 4; ++j) x[r][j] = x[r][j] + gp[j] * (y[r][j] * rs); }
;             }
; #pragma unroll
;             for (int r = 0; r < 2; ++r)
; #pragma unroll
;                 for (int j = 0; j < 4; ++j) { if (hasprev) { if (dbf) { u32x2 w; w.x = cvtpk(x[r][j].x, x[r][j].y); w.y = cvtpk(x[r][j].z, x[r][j].w); *(u32x2*)(xdstb + (m + r) * DM + 4 * lane + 256 * j) = w; } else *(f32x4*)(xdst + (m + r) * DM + 4 * lane + 256 * j) = x[r][j]; } }
;             if (hasnext) {
;                 float ss[2] = {0.f, 0.f};
; #pragma unroll
;                 for (int r = 0; r < 2; ++r)
; #pragma unroll
;                     for (int j = 0; j < 4; ++j) ss[r] += (x[r][j].x * x[r][j].x + x[r][j].y * x[r][j].y) + (x[r][j].z * x[r][j].z + x[r][j].w * x[r][j].w);
; #pragma unroll
;                 for (int off = 1; off < 64; off <<= 1) { ss[0] += __shfl_xor(ss[0], off); ss[1] += __shfl_xor(ss[1], off); }
; #pragma unroll
;                 for (int r = 0; r < 2; ++r) { const float rs = __builtin_amdgcn_rsqf(ss[r] * (1.f / DM) + EPS);
; #pragma unroll
;                     for (int j = 0; j < 4; ++j) { const f32x4 h = (x[r][j] * rs) * na[j] + ns[j]; u32x2 w; w.x = cvtpk(h.x, h.y); w.y = cvtpk(h.z, h.w); *(u32x2*)(H + (m + r) * DM + 4 * lane + 256 * j) = w; } }
	v_lshlrev_b32_e32 v200, 16, v96
	v_and_b32_e32 v201, 0xffff0000, v96
	v_pk_mul_f32 v[204:205], v[200:201], v[200:201]
	v_lshlrev_b32_e32 v202, 16, v97
	v_and_b32_e32 v203, 0xffff0000, v97
	v_pk_mul_f32 v[206:207], v[202:203], v[202:203]
	v_lshlrev_b32_e32 v200, 16, v98
	v_and_b32_e32 v201, 0xffff0000, v98
	v_pk_fma_f32 v[204:205], v[200:201], v[200:201], v[204:205]
	v_lshlrev_b32_e32 v202, 16, v99
	v_and_b32_e32 v203, 0xffff0000, v99
	v_pk_fma_f32 v[206:207], v[202:203], v[202:203], v[206:207]
	v_lshlrev_b32_e32 v200, 16, v100
	v_and_b32_e32 v201, 0xffff0000, v100
	v_pk_fma_f32 v[204:205], v[200:201], v[200:201], v[204:205]
	v_lshlrev_b32_e32 v202, 16, v101
	v_and_b32_e32 v203, 0xffff0000, v101
	v_pk_fma_f32 v[206:207], v[202:203], v[202:203], v[206:207]
	v_lshlrev_b32_e32 v200, 16, v102
	v_and_b32_e32 v201, 0xffff0000, v102
	v_pk_fma_f32 v[204:205], v[200:201], v[200:201], v[204:205]
	v_lshlrev_b32_e32 v202, 16, v103
	v_and_b32_e32 v203, 0xffff0000, v103
	v_pk_fma_f32 v[206:207], v[202:203], v[202:203], v[206:207]
	v_pk_add_f32 v[204:205], v[204:205], v[206:207]
	v_add_f32_e32 v208, v204, v205
	s_nop 0
	s_nop 0
	v_add_f32_dpp v208, v208, v208 quad_perm:[1,0,3,2] row_mask:0xf bank_mask:0xf
	s_nop 0
	s_nop 0
	v_add_f32_dpp v208, v208, v208 quad_perm:[2,3,0,1] row_mask:0xf bank_mask:0xf
	s_nop 0
	s_nop 0
	v_add_f32_dpp v208, v208, v208 row_half_mirror row_mask:0xf bank_mask:0xf
	s_nop 0
	s_nop 0
	v_add_f32_dpp v208, v208, v208 row_mirror row_mask:0xf bank_mask:0xf
	s_nop 0
	s_nop 0
	v_add_f32_dpp v208, v208, v208 row_bcast:15 row_mask:0xa bank_mask:0xf
	s_nop 0
	s_nop 0
	v_add_f32_dpp v208, v208, v208 row_bcast:31 row_mask:0xc bank_mask:0xf
	s_nop 0
	s_nop 0
	v_readlane_b32 s60, v208, 63
	s_nop 1
	v_mov_b32_e32 v210, s60
	v_fmaak_f32 v210, v210, v212, 0x358637bd
	v_rsq_f32_e32 v210, v210
	s_nop 0
	v_lshlrev_b32_e32 v200, 16, v96
	v_and_b32_e32 v201, 0xffff0000, v96
	v_pk_mul_f32 v[200:201], v[200:201], v[210:211] op_sel_hi:[1,0]
	v_pk_fma_f32 v[80:81], v[8:9], v[200:201], v[80:81]
	v_lshlrev_b32_e32 v202, 16, v97
	v_and_b32_e32 v203, 0xffff0000, v97
	v_pk_mul_f32 v[202:203], v[202:203], v[210:211] op_sel_hi:[1,0]
	v_pk_fma_f32 v[82:83], v[10:11], v[202:203], v[82:83]
	v_lshlrev_b32_e32 v200, 16, v98
	v_and_b32_e32 v201, 0xffff0000, v98
	v_pk_mul_f32 v[200:201], v[200:201], v[210:211] op_sel_hi:[1,0]
	v_pk_fma_f32 v[84:85], v[12:13], v[200:201], v[84:85]
	v_lshlrev_b32_e32 v202, 16, v99
	v_and_b32_e32 v203, 0xffff0000, v99
	v_pk_mul_f32 v[202:203], v[202:203], v[210:211] op_sel_hi:[1,0]
	v_pk_fma_f32 v[86:87], v[14:15], v[202:203], v[86:87]
	v_lshlrev_b32_e32 v200, 16, v100
	v_and_b32_e32 v201, 0xffff0000, v100
	v_pk_mul_f32 v[200:201], v[200:201], v[210:211] op_sel_hi:[1,0]
	v_pk_fma_f32 v[88:89], v[16:17], v[200:201], v[88:89]
	v_lshlrev_b32_e32 v202, 16, v101
	v_and_b32_e32 v203, 0xffff0000, v101
	v_pk_mul_f32 v[202:203], v[202:203], v[210:211] op_sel_hi:[1,0]
	v_pk_fma_f32 v[90:91], v[18:19], v[202:203], v[90:91]
	v_lshlrev_b32_e32 v200, 16, v102
	v_and_b32_e32 v201, 0xffff0000, v102
	v_pk_mul_f32 v[200:201], v[200:201], v[210:211] op_sel_hi:[1,0]
	v_pk_fma_f32 v[92:93], v[20:21], v[200:201], v[92:93]
	v_lshlrev_b32_e32 v202, 16, v103
	v_and_b32_e32 v203, 0xffff0000, v103
	v_pk_mul_f32 v[202:203], v[202:203], v[210:211] op_sel_hi:[1,0]
	v_pk_fma_f32 v[94:95], v[22:23], v[202:203], v[94:95]
	s_add_i32 s81, s80, 1
	s_add_i32 s81, s81, s82
	s_and_b32 s81, s81, 31
	s_lshl_b32 s83, s81, 11
	v_add_u32_e32 v2, s83, v1
	v_cvt_pk_bf16_f32 v96, v80, v81
	v_cvt_pk_bf16_f32 v97, v82, v83
	v_cvt_pk_bf16_f32 v98, v84, v85
	v_cvt_pk_bf16_f32 v99, v86, v87
	v_cvt_pk_bf16_f32 v100, v88, v89
	v_cvt_pk_bf16_f32 v101, v90, v91
	v_cvt_pk_bf16_f32 v102, v92, v93
	v_cvt_pk_bf16_f32 v103, v94, v95
	global_store_dwordx4 v2, v[96:99], s[76:77] nt
	global_store_dwordx4 v2, v[100:103], s[76:77] offset:1024 nt
	v_pk_mul_f32 v[204:205], v[80:81], v[80:81]
	v_pk_mul_f32 v[206:207], v[82:83], v[82:83]
	v_pk_fma_f32 v[204:205], v[84:85], v[84:85], v[204:205]
	v_pk_fma_f32 v[206:207], v[86:87], v[86:87], v[206:207]
	v_pk_fma_f32 v[204:205], v[88:89], v[88:89], v[204:205]
	v_pk_fma_f32 v[206:207], v[90:91], v[90:91], v[206:207]
	v_pk_fma_f32 v[204:205], v[92:93], v[92:93], v[204:205]
	v_pk_fma_f32 v[206:207], v[94:95], v[94:95], v[206:207]
	v_pk_add_f32 v[204:205], v[204:205], v[206:207]
	v_add_f32_e32 v208, v204, v205
	s_nop 0
	s_nop 0
	v_add_f32_dpp v208, v208, v208 quad_perm:[1,0,3,2] row_mask:0xf bank_mask:0xf
	s_nop 0
	s_nop 0
	v_add_f32_dpp v208, v208, v208 quad_perm:[2,3,0,1] row_mask:0xf bank_mask:0xf
	s_nop 0
	s_nop 0
	v_add_f32_dpp v208, v208, v208 row_half_mirror row_mask:0xf bank_mask:0xf
	s_nop 0
	s_nop 0
	v_add_f32_dpp v208, v208, v208 row_mirror row_mask:0xf bank_mask:0xf
	s_nop 0
	s_nop 0
	v_add_f32_dpp v208, v208, v208 row_bcast:15 row_mask:0xa bank_mask:0xf
	s_nop 0
	s_nop 0
	v_add_f32_dpp v208, v208, v208 row_bcast:31 row_mask:0xc bank_mask:0xf
	s_nop 0
	s_nop 0
	v_readlane_b32 s60, v208, 63
	s_nop 1
	v_mov_b32_e32 v210, s60
	v_fmaak_f32 v210, v210, v212, 0x358637bd
	v_rsq_f32_e32 v210, v210
	s_nop 0
	v_pk_mul_f32 v[200:201], v[80:81], v[210:211] op_sel_hi:[1,0]
	v_pk_fma_f32 v[200:201], v[200:201], v[24:25], v[40:41]
	v_cvt_pk_bf16_f32 v96, v200, v201
	v_pk_mul_f32 v[202:203], v[82:83], v[210:211] op_sel_hi:[1,0]
	v_pk_fma_f32 v[202:203], v[202:203], v[26:27], v[42:43]
	v_cvt_pk_bf16_f32 v97, v202, v203
	v_pk_mul_f32 v[200:201], v[84:85], v[210:211] op_sel_hi:[1,0]
	v_pk_fma_f32 v[200:201], v[200:201], v[28:29], v[44:45]
	v_cvt_pk_bf16_f32 v98, v200, v201
	v_pk_mul_f32 v[202:203], v[86:87], v[210:211] op_sel_hi:[1,0]
	v_pk_fma_f32 v[202:203], v[202:203], v[30:31], v[46:47]
	v_cvt_pk_bf16_f32 v99, v202, v203
	v_pk_mul_f32 v[200:201], v[88:89], v[210:211] op_sel_hi:[1,0]
	v_pk_fma_f32 v[200:201], v[200:201], v[32:33], v[48:49]
	v_cvt_pk_bf16_f32 v100, v200, v201
	v_pk_mul_f32 v[202:203], v[90:91], v[210:211] op_sel_hi:[1,0]
	v_pk_fma_f32 v[202:203], v[202:203], v[34:35], v[50:51]
	v_cvt_pk_bf16_f32 v101, v202, v203
	v_pk_mul_f32 v[200:201], v[92:93], v[210:211] op_sel_hi:[1,0]
	v_pk_fma_f32 v[200:201], v[200:201], v[36:37], v[52:53]
	v_cvt_pk_bf16_f32 v102, v200, v201
	v_pk_mul_f32 v[202:203], v[94:95], v[210:211] op_sel_hi:[1,0]
	v_pk_fma_f32 v[202:203], v[202:203], v[38:39], v[54:55]
	v_cvt_pk_bf16_f32 v103, v202, v203
	global_store_dwordx4 v2, v[96:99], s[78:79] nt
	global_store_dwordx4 v2, v[100:103], s[78:79] offset:1024 nt
	s_mov_b32 s82, 2
; __device__ __forceinline__ void phase_rowwise(const void* xsrc_, bool sbf, void* xdst_, bool dbf, const bf16_t* Y, bf16_t* H, const float* mods, int lprev, int iprev, const float* lnpost, float resw, ...
;     ...
;             if (rr + 2 < 32) {
; #pragma unroll
;                 for (int r = 0; r < 2; ++r)
; #pragma unroll
;                     for (int j = 0; j < 4; ++j) { if (sbf) xnb[r][j] = *(const u32x2*)(xsrcb + (m + 2 + r) * DM + 4 * lane + 256 * j); else xn[r][j] = *(const f32x4*)(xsrc + (m + 2 + r) * DM + 4 * lane + 256 * j); if (hasprev) yn[r][j] = *(const u32x2*)(Y + (m + 2 + r) * DM + 4 * lane + 256 * j); } }
.Lrw_FIRST_loop:
	s_add_i32 s81, s82, 2
	s_cmp_lt_u32 s81, 32
	s_cbranch_scc0 .Lrw_FIRST_l0_d
	s_add_i32 s81, s80, 2
	s_add_i32 s81, s81, s82
	s_and_b32 s81, s81, 31
	s_lshl_b32 s83, s81, 11
	v_add_u32_e32 v2, s83, v1
	s_lshl_b32 s83, s81, 12
	v_add_u32_e32 v213, s83, v3
	global_load_dwordx4 v[152:155], v213, s[72:73] nt
	global_load_dwordx4 v[156:159], v213, s[72:73] offset:16 nt
	global_load_dwordx4 v[160:163], v213, s[72:73] offset:2048 nt
	global_load_dwordx4 v[164:167], v213, s[72:73] offset:2064 nt
	global_load_dwordx4 v[168:171], v2, s[74:75] nt
	global_load_dwordx4 v[172:175], v2, s[74:75] offset:1024 nt
	s_branch .Lrw_FIRST_l0_e

; __device__ __forceinline__ float bflo(unsigned u) { return __uint_as_float(u << 16); }
; __device__ __forceinline__ void phase_rowwise(const void* xsrc_, bool sbf, void* xdst_, bool dbf, const bf16_t* Y, bf16_t* H, const float* mods, int lprev, int iprev, const float* lnpost, float resw, ...
;     ...
;             if (hasprev) {
;                 f32x4 y[2][4]; float ss[2] = {0.f, 0.f};
; #pragma unroll
;                 for (int r = 0; r < 2; ++r)
; #pragma unroll
;                     for (int j = 0; j < 4; ++j) { const u32x2 u = yr[r][j]; y[r][j] = (f32x4){bflo(u.x), bfhi(u.x), bflo(u.y), bfhi(u.y)};
;                         ss[r] += (y[r][j].x * y[r][j].x + y[r][j].y * y[r][j].y) + (y[r][j].z * y[r][j].z + y[r][j].w * y[r][j].w); }
; #pragma unroll
;                 for (int off = 1; off < 64; off <<= 1) { ss[0] += __shfl_xor(ss[0], off); ss[1] += __shfl_xor(ss[1], off); }
; #pragma unroll
;                 for (int r = 0; r < 2; ++r) { const float rs = __builtin_amdgcn_rsqf(ss[r] * (1.f / DM) + EPS);
; #pragma unroll
;                     for (int j = 0; j < 4; ++j) x[r][j] = x[r][j] + gp[j] * (y[r][j] * rs); }
;             }
; #pragma unroll
;             for (int r = 0; r < 2; ++r)
; #pragma unroll
;                 for (int j = 0; j < 4; ++j) { if (hasprev) { if (dbf) { u32x2 w; w.x = cvtpk(x[r][j].x, x[r][j].y); w.y = cvtpk(x[r][j].z, x[r][j].w); *(u32x2*)(xdstb + (m + r) * DM + 4 * lane + 256 * j) = w; } else *(f32x4*)(xdst + (m + r) * DM + 4 * lane + 256 * j) = x[r][j]; } }
;             if (hasnext) {
;                 float ss[2] = {0.f, 0.f};
; #pragma unroll
;                 for (int r = 0; r < 2; ++r)
; #pragma unroll
;                     for (int j = 0; j < 4; ++j) ss[r] += (x[r][j].x * x[r][j].x + x[r][j].y * x[r][j].y) + (x[r][j].z * x[r][j].z + x[r][j].w * x[r][j].w);
; #pragma unroll
;                 for (int off = 1; off < 64; off <<= 1) { ss[0] += __shfl_xor(ss[0], off); ss[1] += __shfl_xor(ss[1], off); }
; #pragma unroll
;                 for (int r = 0; r < 2; ++r) { const float rs = __builtin_amdgcn_rsqf(ss[r] * (1.f / DM) + EPS);
; #pragma unroll
;                     for (int j = 0; j < 4; ++j) { const f32x4 h = (x[r][j] * rs) * na[j] + ns[j]; u32x2 w; w.x = cvtpk(h.x, h.y); w.y = cvtpk(h.z, h.w); *(u32x2*)(H + (m + r) * DM + 4 * lane + 256 * j) = w; } }
.Lrw_FIRST_l0_e:
	s_waitcnt vmcnt(20)
	v_lshlrev_b32_e32 v200, 16, v120
	v_and_b32_e32 v201, 0xffff0000, v120
	v_pk_mul_f32 v[204:205], v[200:201], v[200:201]
	v_lshlrev_b32_e32 v202, 16, v121
	v_and_b32_e32 v203, 0xffff0000, v121
	v_pk_mul_f32 v[206:207], v[202:203], v[202:203]
	v_lshlrev_b32_e32 v200, 16, v122
	v_and_b32_e32 v201, 0xffff0000, v122
	v_pk_fma_f32 v[204:205], v[200:201], v[200:201], v[204:205]
	v_lshlrev_b32_e32 v202, 16, v123
	v_and_b32_e32 v203, 0xffff0000, v123
	v_pk_fma_f32 v[206:207], v[202:203], v[202:203], v[206:207]
	v_lshlrev_b32_e32 v200, 16, v124
	v_and_b32_e32 v201, 0xffff0000, v124
	v_pk_fma_f32 v[204:205], v[200:201], v[200:201], v[204:205]
	v_lshlrev_b32_e32 v202, 16, v125
	v_and_b32_e32 v203, 0xffff0000, v125
	v_pk_fma_f32 v[206:207], v[202:203], v[202:203], v[206:207]
	v_lshlrev_b32_e32 v200, 16, v126
	v_and_b32_e32 v201, 0xffff0000, v126
	v_pk_fma_f32 v[204:205], v[200:201], v[200:201], v[204:205]
	v_lshlrev_b32_e32 v202, 16, v127
	v_and_b32_e32 v203, 0xffff0000, v127
	v_pk_fma_f32 v[206:207], v[202:203], v[202:203], v[206:207]
	v_pk_add_f32 v[204:205], v[204:205], v[206:207]
	v_add_f32_e32 v208, v204, v205
	s_nop 0
	s_nop 0
	v_add_f32_dpp v208, v208, v208 quad_perm:[1,0,3,2] row_mask:0xf bank_mask:0xf
	s_nop 0
	s_nop 0
	v_add_f32_dpp v208, v208, v208 quad_perm:[2,3,0,1] row_mask:0xf bank_mask:0xf
	s_nop 0
	s_nop 0
	v_add_f32_dpp v208, v208, v208 row_half_mirror row_mask:0xf bank_mask:0xf
	s_nop 0
	s_nop 0
	v_add_f32_dpp v208, v208, v208 row_mirror row_mask:0xf bank_mask:0xf
	s_nop 0
	s_nop 0
	v_add_f32_dpp v208, v208, v208 row_bcast:15 row_mask:0xa bank_mask:0xf
	s_nop 0
	s_nop 0
	v_add_f32_dpp v208, v208, v208 row_bcast:31 row_mask:0xc bank_mask:0xf
	s_nop 0
	s_nop 0
	v_readlane_b32 s60, v208, 63
	s_nop 1
	v_mov_b32_e32 v210, s60
	v_fmaak_f32 v210, v210, v212, 0x358637bd
	v_rsq_f32_e32 v210, v210
	s_nop 0
	v_lshlrev_b32_e32 v200, 16, v120
	v_and_b32_e32 v201, 0xffff0000, v120
	v_pk_mul_f32 v[200:201], v[200:201], v[210:211] op_sel_hi:[1,0]
	v_pk_fma_f32 v[104:105], v[8:9], v[200:201], v[104:105]
	v_lshlrev_b32_e32 v202, 16, v121
	v_and_b32_e32 v203, 0xffff0000, v121
	v_pk_mul_f32 v[202:203], v[202:203], v[210:211] op_sel_hi:[1,0]
	v_pk_fma_f32 v[106:107], v[10:11], v[202:203], v[106:107]
	v_lshlrev_b32_e32 v200, 16, v122
	v_and_b32_e32 v201, 0xffff0000, v122
	v_pk_mul_f32 v[200:201], v[200:201], v[210:211] op_sel_hi:[1,0]
	v_pk_fma_f32 v[108:109], v[12:13], v[200:201], v[108:109]
	v_lshlrev_b32_e32 v202, 16, v123
	v_and_b32_e32 v203, 0xffff0000, v123
	v_pk_mul_f32 v[202:203], v[202:203], v[210:211] op_sel_hi:[1,0]
	v_pk_fma_f32 v[110:111], v[14:15], v[202:203], v[110:111]
	v_lshlrev_b32_e32 v200, 16, v124
	v_and_b32_e32 v201, 0xffff0000, v124
	v_pk_mul_f32 v[200:201], v[200:201], v[210:211] op_sel_hi:[1,0]
	v_pk_fma_f32 v[112:113], v[16:17], v[200:201], v[112:113]
	v_lshlrev_b32_e32 v202, 16, v125
	v_and_b32_e32 v203, 0xffff0000, v125
	v_pk_mul_f32 v[202:203], v[202:203], v[210:211] op_sel_hi:[1,0]
	v_pk_fma_f32 v[114:115], v[18:19], v[202:203], v[114:115]
	v_lshlrev_b32_e32 v200, 16, v126
	v_and_b32_e32 v201, 0xffff0000, v126
	v_pk_mul_f32 v[200:201], v[200:201], v[210:211] op_sel_hi:[1,0]
	v_pk_fma_f32 v[116:117], v[20:21], v[200:201], v[116:117]
	v_lshlrev_b32_e32 v202, 16, v127
	v_and_b32_e32 v203, 0xffff0000, v127
	v_pk_mul_f32 v[202:203], v[202:203], v[210:211] op_sel_hi:[1,0]
	v_pk_fma_f32 v[118:119], v[22:23], v[202:203], v[118:119]
	s_add_i32 s81, s80, 0
	s_add_i32 s81, s81, s82
	s_and_b32 s81, s81, 31
	s_lshl_b32 s83, s81, 11
	v_add_u32_e32 v2, s83, v1
	v_cvt_pk_bf16_f32 v120, v104, v105
	v_cvt_pk_bf16_f32 v121, v106, v107
	v_cvt_pk_bf16_f32 v122, v108, v109
	v_cvt_pk_bf16_f32 v123, v110, v111
	v_cvt_pk_bf16_f32 v124, v112, v113
	v_cvt_pk_bf16_f32 v125, v114, v115
	v_cvt_pk_bf16_f32 v126, v116, v117
	v_cvt_pk_bf16_f32 v127, v118, v119
	global_store_dwordx4 v2, v[120:123], s[76:77] nt
	global_store_dwordx4 v2, v[124:127], s[76:77] offset:1024 nt
	v_pk_mul_f32 v[204:205], v[104:105], v[104:105]
	v_pk_mul_f32 v[206:207], v[106:107], v[106:107]
	v_pk_fma_f32 v[204:205], v[108:109], v[108:109], v[204:205]
	v_pk_fma_f32 v[206:207], v[110:111], v[110:111], v[206:207]
	v_pk_fma_f32 v[204:205], v[112:113], v[112:113], v[204:205]
	v_pk_fma_f32 v[206:207], v[114:115], v[114:115], v[206:207]
	v_pk_fma_f32 v[204:205], v[116:117], v[116:117], v[204:205]
	v_pk_fma_f32 v[206:207], v[118:119], v[118:119], v[206:207]
	v_pk_add_f32 v[204:205], v[204:205], v[206:207]
	v_add_f32_e32 v208, v204, v205
	s_nop 0
	s_nop 0
	v_add_f32_dpp v208, v208, v208 quad_perm:[1,0,3,2] row_mask:0xf bank_mask:0xf
	s_nop 0
	s_nop 0
	v_add_f32_dpp v208, v208, v208 quad_perm:[2,3,0,1] row_mask:0xf bank_mask:0xf
	s_nop 0
	s_nop 0
	v_add_f32_dpp v208, v208, v208 row_half_mirror row_mask:0xf bank_mask:0xf
	s_nop 0
	s_nop 0
	v_add_f32_dpp v208, v208, v208 row_mirror row_mask:0xf bank_mask:0xf
	s_nop 0
	s_nop 0
	v_add_f32_dpp v208, v208, v208 row_bcast:15 row_mask:0xa bank_mask:0xf
	s_nop 0
	s_nop 0
	v_add_f32_dpp v208, v208, v208 row_bcast:31 row_mask:0xc bank_mask:0xf
	s_nop 0
	s_nop 0
	v_readlane_b32 s60, v208, 63
	s_nop 1
	v_mov_b32_e32 v210, s60
	v_fmaak_f32 v210, v210, v212, 0x358637bd
	v_rsq_f32_e32 v210, v210
	s_nop 0
	v_pk_mul_f32 v[200:201], v[104:105], v[210:211] op_sel_hi:[1,0]
	v_pk_fma_f32 v[200:201], v[200:201], v[24:25], v[40:41]
	v_cvt_pk_bf16_f32 v120, v200, v201
	v_pk_mul_f32 v[202:203], v[106:107], v[210:211] op_sel_hi:[1,0]
	v_pk_fma_f32 v[202:203], v[202:203], v[26:27], v[42:43]
	v_cvt_pk_bf16_f32 v121, v202, v203
	v_pk_mul_f32 v[200:201], v[108:109], v[210:211] op_sel_hi:[1,0]
	v_pk_fma_f32 v[200:201], v[200:201], v[28:29], v[44:45]
	v_cvt_pk_bf16_f32 v122, v200, v201
	v_pk_mul_f32 v[202:203], v[110:111], v[210:211] op_sel_hi:[1,0]
	v_pk_fma_f32 v[202:203], v[202:203], v[30:31], v[46:47]
	v_cvt_pk_bf16_f32 v123, v202, v203
	v_pk_mul_f32 v[200:201], v[112:113], v[210:211] op_sel_hi:[1,0]
	v_pk_fma_f32 v[200:201], v[200:201], v[32:33], v[48:49]
	v_cvt_pk_bf16_f32 v124, v200, v201
	v_pk_mul_f32 v[202:203], v[114:115], v[210:211] op_sel_hi:[1,0]
	v_pk_fma_f32 v[202:203], v[202:203], v[34:35], v[50:51]
	v_cvt_pk_bf16_f32 v125, v202, v203
	v_pk_mul_f32 v[200:201], v[116:117], v[210:211] op_sel_hi:[1,0]
	v_pk_fma_f32 v[200:201], v[200:201], v[36:37], v[52:53]
	v_cvt_pk_bf16_f32 v126, v200, v201
	v_pk_mul_f32 v[202:203], v[118:119], v[210:211] op_sel_hi:[1,0]
	v_pk_fma_f32 v[202:203], v[202:203], v[38:39], v[54:55]
	v_cvt_pk_bf16_f32 v127, v202, v203
	global_store_dwordx4 v2, v[120:123], s[78:79] nt
	global_store_dwordx4 v2, v[124:127], s[78:79] offset:1024 nt
	s_add_i32 s81, s82, 3
	s_cmp_lt_u32 s81, 32
	s_cbranch_scc0 .Lrw_FIRST_l1_d
; __device__ __forceinline__ void phase_rowwise(const void* xsrc_, bool sbf, void* xdst_, bool dbf, const bf16_t* Y, bf16_t* H, const float* mods, int lprev, int iprev, const float* lnpost, float resw, ...
;     ...
;             if (rr + 2 < 32) {
; #pragma unroll
;                 for (int r = 0; r < 2; ++r)
; #pragma unroll
;                     for (int j = 0; j < 4; ++j) { if (sbf) xnb[r][j] = *(const u32x2*)(xsrcb + (m + 2 + r) * DM + 4 * lane + 256 * j); else xn[r][j] = *(const f32x4*)(xsrc + (m + 2 + r) * DM + 4 * lane + 256 * j); if (hasprev) yn[r][j] = *(const u32x2*)(Y + (m + 2 + r) * DM + 4 * lane + 256 * j); } }
	s_add_i32 s81, s80, 3
	s_add_i32 s81, s81, s82
	s_and_b32 s81, s81, 31
	s_lshl_b32 s83, s81, 11
	v_add_u32_e32 v2, s83, v1
	s_lshl_b32 s83, s81, 12
	v_add_u32_e32 v213, s83, v3
	global_load_dwordx4 v[56:59], v213, s[72:73] nt
	global_load_dwordx4 v[60:63], v213, s[72:73] offset:16 nt
	global_load_dwordx4 v[64:67], v213, s[72:73] offset:2048 nt
	global_load_dwordx4 v[68:71], v213, s[72:73] offset:2064 nt
	global_load_dwordx4 v[72:75], v2, s[74:75] nt
	global_load_dwordx4 v[76:79], v2, s[74:75] offset:1024 nt
	s_branch .Lrw_FIRST_l1_e

; __device__ __forceinline__ float bflo(unsigned u) { return __uint_as_float(u << 16); }
; __device__ __forceinline__ void phase_rowwise(const void* xsrc_, bool sbf, void* xdst_, bool dbf, const bf16_t* Y, bf16_t* H, const float* mods, int lprev, int iprev, const float* lnpost, float resw, ...
;     ...
;             if (hasprev) {
;                 f32x4 y[2][4]; float ss[2] = {0.f, 0.f};
; #pragma unroll
;                 for (int r = 0; r < 2; ++r)
; #pragma unroll
;                     for (int j = 0; j < 4; ++j) { const u32x2 u = yr[r][j]; y[r][j] = (f32x4){bflo(u.x), bfhi(u.x), bflo(u.y), bfhi(u.y)};
;                         ss[r] += (y[r][j].x * y[r][j].x + y[r][j].y * y[r][j].y) + (y[r][j].z * y[r][j].z + y[r][j].w * y[r][j].w); }
; #pragma unroll
;                 for (int off = 1; off < 64; off <<= 1) { ss[0] += __shfl_xor(ss[0], off); ss[1] += __shfl_xor(ss[1], off); }
; #pragma unroll
;                 for (int r = 0; r < 2; ++r) { const float rs = __builtin_amdgcn_rsqf(ss[r] * (1.f / DM) + EPS);
; #pragma unroll
;                     for (int j = 0; j < 4; ++j) x[r][j] = x[r][j] + gp[j] * (y[r][j] * rs); }
;             }
; #pragma unroll
;             for (int r = 0; r < 2; ++r)
; #pragma unroll
;                 for (int j = 0; j < 4; ++j) { if (hasprev) { if (dbf) { u32x2 w; w.x = cvtpk(x[r][j].x, x[r][j].y); w.y = cvtpk(x[r][j].z, x[r][j].w); *(u32x2*)(xdstb + (m + r) * DM + 4 * lane + 256 * j) = w; } else *(f32x4*)(xdst + (m + r) * DM + 4 * lane + 256 * j) = x[r][j]; } }
;             if (hasnext) {
;                 float ss[2] = {0.f, 0.f};
; #pragma unroll
;                 for (int r = 0; r < 2; ++r)
; #pragma unroll
;                     for (int j = 0; j < 4; ++j) ss[r] += (x[r][j].x * x[r][j].x + x[r][j].y * x[r][j].y) + (x[r][j].z * x[r][j].z + x[r][j].w * x[r][j].w);
; #pragma unroll
;                 for (int off = 1; off < 64; off <<= 1) { ss[0] += __shfl_xor(ss[0], off); ss[1] += __shfl_xor(ss[1], off); }
; #pragma unroll
;                 for (int r = 0; r < 2; ++r) { const float rs = __builtin_amdgcn_rsqf(ss[r] * (1.f / DM) + EPS);
; #pragma unroll
;                     for (int j = 0; j < 4; ++j) { const f32x4 h = (x[r][j] * rs) * na[j] + ns[j]; u32x2 w; w.x = cvtpk(h.x, h.y); w.y = cvtpk(h.z, h.w); *(u32x2*)(H + (m + r) * DM + 4 * lane + 256 * j) = w; } }
.Lrw_FIRST_l1_e:
	s_waitcnt vmcnt(20)
	v_lshlrev_b32_e32 v200, 16, v144
	v_and_b32_e32 v201, 0xffff0000, v144
	v_pk_mul_f32 v[204:205], v[200:201], v[200:201]
	v_lshlrev_b32_e32 v202, 16, v145
	v_and_b32_e32 v203, 0xffff0000, v145
	v_pk_mul_f32 v[206:207], v[202:203], v[202:203]
	v_lshlrev_b32_e32 v200, 16, v146
	v_and_b32_e32 v201, 0xffff0000, v146
	v_pk_fma_f32 v[204:205], v[200:201], v[200:201], v[204:205]
	v_lshlrev_b32_e32 v202, 16, v147
	v_and_b32_e32 v203, 0xffff0000, v147
	v_pk_fma_f32 v[206:207], v[202:203], v[202:203], v[206:207]
	v_lshlrev_b32_e32 v200, 16, v148
	v_and_b32_e32 v201, 0xffff0000, v148
	v_pk_fma_f32 v[204:205], v[200:201], v[200:201], v[204:205]
	v_lshlrev_b32_e32 v202, 16, v149
	v_and_b32_e32 v203, 0xffff0000, v149
	v_pk_fma_f32 v[206:207], v[202:203], v[202:203], v[206:207]
	v_lshlrev_b32_e32 v200, 16, v150
	v_and_b32_e32 v201, 0xffff0000, v150
	v_pk_fma_f32 v[204:205], v[200:201], v[200:201], v[204:205]
	v_lshlrev_b32_e32 v202, 16, v151
	v_and_b32_e32 v203, 0xffff0000, v151
	v_pk_fma_f32 v[206:207], v[202:203], v[202:203], v[206:207]
	v_pk_add_f32 v[204:205], v[204:205], v[206:207]
	v_add_f32_e32 v208, v204, v205
	s_nop 0
	s_nop 0
	v_add_f32_dpp v208, v208, v208 quad_perm:[1,0,3,2] row_mask:0xf bank_mask:0xf
	s_nop 0
	s_nop 0
	v_add_f32_dpp v208, v208, v208 quad_perm:[2,3,0,1] row_mask:0xf bank_mask:0xf
	s_nop 0
	s_nop 0
	v_add_f32_dpp v208, v208, v208 row_half_mirror row_mask:0xf bank_mask:0xf
	s_nop 0
	s_nop 0
	v_add_f32_dpp v208, v208, v208 row_mirror row_mask:0xf bank_mask:0xf
	s_nop 0
	s_nop 0
	v_add_f32_dpp v208, v208, v208 row_bcast:15 row_mask:0xa bank_mask:0xf
	s_nop 0
	s_nop 0
	v_add_f32_dpp v208, v208, v208 row_bcast:31 row_mask:0xc bank_mask:0xf
	s_nop 0
	s_nop 0
	v_readlane_b32 s60, v208, 63
	s_nop 1
	v_mov_b32_e32 v210, s60
	v_fmaak_f32 v210, v210, v212, 0x358637bd
	v_rsq_f32_e32 v210, v210
	s_nop 0
	v_lshlrev_b32_e32 v200, 16, v144
	v_and_b32_e32 v201, 0xffff0000, v144
	v_pk_mul_f32 v[200:201], v[200:201], v[210:211] op_sel_hi:[1,0]
	v_pk_fma_f32 v[128:129], v[8:9], v[200:201], v[128:129]
	v_lshlrev_b32_e32 v202, 16, v145
	v_and_b32_e32 v203, 0xffff0000, v145
	v_pk_mul_f32 v[202:203], v[202:203], v[210:211] op_sel_hi:[1,0]
	v_pk_fma_f32 v[130:131], v[10:11], v[202:203], v[130:131]
	v_lshlrev_b32_e32 v200, 16, v146
	v_and_b32_e32 v201, 0xffff0000, v146
	v_pk_mul_f32 v[200:201], v[200:201], v[210:211] op_sel_hi:[1,0]
	v_pk_fma_f32 v[132:133], v[12:13], v[200:201], v[132:133]
	v_lshlrev_b32_e32 v202, 16, v147
	v_and_b32_e32 v203, 0xffff0000, v147
	v_pk_mul_f32 v[202:203], v[202:203], v[210:211] op_sel_hi:[1,0]
	v_pk_fma_f32 v[134:135], v[14:15], v[202:203], v[134:135]
	v_lshlrev_b32_e32 v200, 16, v148
	v_and_b32_e32 v201, 0xffff0000, v148
	v_pk_mul_f32 v[200:201], v[200:201], v[210:211] op_sel_hi:[1,0]
	v_pk_fma_f32 v[136:137], v[16:17], v[200:201], v[136:137]
	v_lshlrev_b32_e32 v202, 16, v149
	v_and_b32_e32 v203, 0xffff0000, v149
	v_pk_mul_f32 v[202:203], v[202:203], v[210:211] op_sel_hi:[1,0]
	v_pk_fma_f32 v[138:139], v[18:19], v[202:203], v[138:139]
	v_lshlrev_b32_e32 v200, 16, v150
	v_and_b32_e32 v201, 0xffff0000, v150
	v_pk_mul_f32 v[200:201], v[200:201], v[210:211] op_sel_hi:[1,0]
	v_pk_fma_f32 v[140:141], v[20:21], v[200:201], v[140:141]
	v_lshlrev_b32_e32 v202, 16, v151
	v_and_b32_e32 v203, 0xffff0000, v151
	v_pk_mul_f32 v[202:203], v[202:203], v[210:211] op_sel_hi:[1,0]
	v_pk_fma_f32 v[142:143], v[22:23], v[202:203], v[142:143]
	s_add_i32 s81, s80, 1
	s_add_i32 s81, s81, s82
	s_and_b32 s81, s81, 31
	s_lshl_b32 s83, s81, 11
	v_add_u32_e32 v2, s83, v1
	v_cvt_pk_bf16_f32 v144, v128, v129
	v_cvt_pk_bf16_f32 v145, v130, v131
	v_cvt_pk_bf16_f32 v146, v132, v133
	v_cvt_pk_bf16_f32 v147, v134, v135
	v_cvt_pk_bf16_f32 v148, v136, v137
	v_cvt_pk_bf16_f32 v149, v138, v139
	v_cvt_pk_bf16_f32 v150, v140, v141
	v_cvt_pk_bf16_f32 v151, v142, v143
	global_store_dwordx4 v2, v[144:147], s[76:77] nt
	global_store_dwordx4 v2, v[148:151], s[76:77] offset:1024 nt
	v_pk_mul_f32 v[204:205], v[128:129], v[128:129]
	v_pk_mul_f32 v[206:207], v[130:131], v[130:131]
	v_pk_fma_f32 v[204:205], v[132:133], v[132:133], v[204:205]
	v_pk_fma_f32 v[206:207], v[134:135], v[134:135], v[206:207]
	v_pk_fma_f32 v[204:205], v[136:137], v[136:137], v[204:205]
	v_pk_fma_f32 v[206:207], v[138:139], v[138:139], v[206:207]
	v_pk_fma_f32 v[204:205], v[140:141], v[140:141], v[204:205]
	v_pk_fma_f32 v[206:207], v[142:143], v[142:143], v[206:207]
	v_pk_add_f32 v[204:205], v[204:205], v[206:207]
	v_add_f32_e32 v208, v204, v205
	s_nop 0
	s_nop 0
	v_add_f32_dpp v208, v208, v208 quad_perm:[1,0,3,2] row_mask:0xf bank_mask:0xf
	s_nop 0
	s_nop 0
	v_add_f32_dpp v208, v208, v208 quad_perm:[2,3,0,1] row_mask:0xf bank_mask:0xf
	s_nop 0
	s_nop 0
	v_add_f32_dpp v208, v208, v208 row_half_mirror row_mask:0xf bank_mask:0xf
	s_nop 0
	s_nop 0
	v_add_f32_dpp v208, v208, v208 row_mirror row_mask:0xf bank_mask:0xf
	s_nop 0
	s_nop 0
	v_add_f32_dpp v208, v208, v208 row_bcast:15 row_mask:0xa bank_mask:0xf
	s_nop 0
	s_nop 0
	v_add_f32_dpp v208, v208, v208 row_bcast:31 row_mask:0xc bank_mask:0xf
	s_nop 0
	s_nop 0
	v_readlane_b32 s60, v208, 63
	s_nop 1
	v_mov_b32_e32 v210, s60
	v_fmaak_f32 v210, v210, v212, 0x358637bd
	v_rsq_f32_e32 v210, v210
	s_nop 0
	v_pk_mul_f32 v[200:201], v[128:129], v[210:211] op_sel_hi:[1,0]
	v_pk_fma_f32 v[200:201], v[200:201], v[24:25], v[40:41]
	v_cvt_pk_bf16_f32 v144, v200, v201
	v_pk_mul_f32 v[202:203], v[130:131], v[210:211] op_sel_hi:[1,0]
	v_pk_fma_f32 v[202:203], v[202:203], v[26:27], v[42:43]
	v_cvt_pk_bf16_f32 v145, v202, v203
	v_pk_mul_f32 v[200:201], v[132:133], v[210:211] op_sel_hi:[1,0]
	v_pk_fma_f32 v[200:201], v[200:201], v[28:29], v[44:45]
	v_cvt_pk_bf16_f32 v146, v200, v201
	v_pk_mul_f32 v[202:203], v[134:135], v[210:211] op_sel_hi:[1,0]
	v_pk_fma_f32 v[202:203], v[202:203], v[30:31], v[46:47]
	v_cvt_pk_bf16_f32 v147, v202, v203
	v_pk_mul_f32 v[200:201], v[136:137], v[210:211] op_sel_hi:[1,0]
	v_pk_fma_f32 v[200:201], v[200:201], v[32:33], v[48:49]
	v_cvt_pk_bf16_f32 v148, v200, v201
	v_pk_mul_f32 v[202:203], v[138:139], v[210:211] op_sel_hi:[1,0]
	v_pk_fma_f32 v[202:203], v[202:203], v[34:35], v[50:51]
	v_cvt_pk_bf16_f32 v149, v202, v203
	v_pk_mul_f32 v[200:201], v[140:141], v[210:211] op_sel_hi:[1,0]
	v_pk_fma_f32 v[200:201], v[200:201], v[36:37], v[52:53]
	v_cvt_pk_bf16_f32 v150, v200, v201
	v_pk_mul_f32 v[202:203], v[142:143], v[210:211] op_sel_hi:[1,0]
	v_pk_fma_f32 v[202:203], v[202:203], v[38:39], v[54:55]
	v_cvt_pk_bf16_f32 v151, v202, v203
	global_store_dwordx4 v2, v[144:147], s[78:79] nt
	global_store_dwordx4 v2, v[148:151], s[78:79] offset:1024 nt
	s_add_i32 s81, s82, 4
	s_cmp_lt_u32 s81, 32
	s_cbranch_scc0 .Lrw_FIRST_l2_d
; __device__ __forceinline__ void phase_rowwise(const void* xsrc_, bool sbf, void* xdst_, bool dbf, const bf16_t* Y, bf16_t* H, const float* mods, int lprev, int iprev, const float* lnpost, float resw, ...
;     ...
;             if (rr + 2 < 32) {
; #pragma unroll
;                 for (int r = 0; r < 2; ++r)
; #pragma unroll
;                     for (int j = 0; j < 4; ++j) { if (sbf) xnb[r][j] = *(const u32x2*)(xsrcb + (m + 2 + r) * DM + 4 * lane + 256 * j); else xn[r][j] = *(const f32x4*)(xsrc + (m + 2 + r) * DM + 4 * lane + 256 * j); if (hasprev) yn[r][j] = *(const u32x2*)(Y + (m + 2 + r) * DM + 4 * lane + 256 * j); } }
	s_add_i32 s81, s80, 4
	s_add_i32 s81, s81, s82
	s_and_b32 s81, s81, 31
	s_lshl_b32 s83, s81, 11
	v_add_u32_e32 v2, s83, v1
	s_lshl_b32 s83, s81, 12
	v_add_u32_e32 v213, s83, v3
	global_load_dwordx4 v[80:83], v213, s[72:73] nt
	global_load_dwordx4 v[84:87], v213, s[72:73] offset:16 nt
	global_load_dwordx4 v[88:91], v213, s[72:73] offset:2048 nt
	global_load_dwordx4 v[92:95], v213, s[72:73] offset:2064 nt
	global_load_dwordx4 v[96:99], v2, s[74:75] nt
	global_load_dwordx4 v[100:103], v2, s[74:75] offset:1024 nt
	s_branch .Lrw_FIRST_l2_e

; __device__ __forceinline__ float bflo(unsigned u) { return __uint_as_float(u << 16); }
; __device__ __forceinline__ void phase_rowwise(const void* xsrc_, bool sbf, void* xdst_, bool dbf, const bf16_t* Y, bf16_t* H, const float* mods, int lprev, int iprev, const float* lnpost, float resw, ...
;     ...
;             if (hasprev) {
;                 f32x4 y[2][4]; float ss[2] = {0.f, 0.f};
; #pragma unroll
;                 for (int r = 0; r < 2; ++r)
; #pragma unroll
;                     for (int j = 0; j < 4; ++j) { const u32x2 u = yr[r][j]; y[r][j] = (f32x4){bflo(u.x), bfhi(u.x), bflo(u.y), bfhi(u.y)};
;                         ss[r] += (y[r][j].x * y[r][j].x + y[r][j].y * y[r][j].y) + (y[r][j].z * y[r][j].z + y[r][j].w * y[r][j].w); }
; #pragma unroll
;                 for (int off = 1; off < 64; off <<= 1) { ss[0] += __shfl_xor(ss[0], off); ss[1] += __shfl_xor(ss[1], off); }
; #pragma unroll
;                 for (int r = 0; r < 2; ++r) { const float rs = __builtin_amdgcn_rsqf(ss[r] * (1.f / DM) + EPS);
; #pragma unroll
;                     for (int j = 0; j < 4; ++j) x[r][j] = x[r][j] + gp[j] * (y[r][j] * rs); }
;             }
; #pragma unroll
;             for (int r = 0; r < 2; ++r)
; #pragma unroll
;                 for (int j = 0; j < 4; ++j) { if (hasprev) { if (dbf) { u32x2 w; w.x = cvtpk(x[r][j].x, x[r][j].y); w.y = cvtpk(x[r][j].z, x[r][j].w); *(u32x2*)(xdstb + (m + r) * DM + 4 * lane + 256 * j) = w; } else *(f32x4*)(xdst + (m + r) * DM + 4 * lane + 256 * j) = x[r][j]; } }
;             if (hasnext) {
;                 float ss[2] = {0.f, 0.f};
; #pragma unroll
;                 for (int r = 0; r < 2; ++r)
; #pragma unroll
;                     for (int j = 0; j < 4; ++j) ss[r] += (x[r][j].x * x[r][j].x + x[r][j].y * x[r][j].y) + (x[r][j].z * x[r][j].z + x[r][j].w * x[r][j].w);
; #pragma unroll
;                 for (int off = 1; off < 64; off <<= 1) { ss[0] += __shfl_xor(ss[0], off); ss[1] += __shfl_xor(ss[1], off); }
; #pragma unroll
;                 for (int r = 0; r < 2; ++r) { const float rs = __builtin_amdgcn_rsqf(ss[r] * (1.f / DM) + EPS);
; #pragma unroll
;                     for (int j = 0; j < 4; ++j) { const f32x4 h = (x[r][j] * rs) * na[j] + ns[j]; u32x2 w; w.x = cvtpk(h.x, h.y); w.y = cvtpk(h.z, h.w); *(u32x2*)(H + (m + r) * DM + 4 * lane + 256 * j) = w; } }
.Lrw_FIRST_l2_e:
	s_waitcnt vmcnt(20)
	v_lshlrev_b32_e32 v200, 16, v168
	v_and_b32_e32 v201, 0xffff0000, v168
	v_pk_mul_f32 v[204:205], v[200:201], v[200:201]
	v_lshlrev_b32_e32 v202, 16, v169
	v_and_b32_e32 v203, 0xffff0000, v169
	v_pk_mul_f32 v[206:207], v[202:203], v[202:203]
	v_lshlrev_b32_e32 v200, 16, v170
	v_and_b32_e32 v201, 0xffff0000, v170
	v_pk_fma_f32 v[204:205], v[200:201], v[200:201], v[204:205]
	v_lshlrev_b32_e32 v202, 16, v171
	v_and_b32_e32 v203, 0xffff0000, v171
	v_pk_fma_f32 v[206:207], v[202:203], v[202:203], v[206:207]
	v_lshlrev_b32_e32 v200, 16, v172
	v_and_b32_e32 v201, 0xffff0000, v172
	v_pk_fma_f32 v[204:205], v[200:201], v[200:201], v[204:205]
	v_lshlrev_b32_e32 v202, 16, v173
	v_and_b32_e32 v203, 0xffff0000, v173
	v_pk_fma_f32 v[206:207], v[202:203], v[202:203], v[206:207]
	v_lshlrev_b32_e32 v200, 16, v174
	v_and_b32_e32 v201, 0xffff0000, v174
	v_pk_fma_f32 v[204:205], v[200:201], v[200:201], v[204:205]
	v_lshlrev_b32_e32 v202, 16, v175
	v_and_b32_e32 v203, 0xffff0000, v175
	v_pk_fma_f32 v[206:207], v[202:203], v[202:203], v[206:207]
	v_pk_add_f32 v[204:205], v[204:205], v[206:207]
	v_add_f32_e32 v208, v204, v205
	s_nop 0
	s_nop 0
	v_add_f32_dpp v208, v208, v208 quad_perm:[1,0,3,2] row_mask:0xf bank_mask:0xf
	s_nop 0
	s_nop 0
	v_add_f32_dpp v208, v208, v208 quad_perm:[2,3,0,1] row_mask:0xf bank_mask:0xf
	s_nop 0
	s_nop 0
	v_add_f32_dpp v208, v208, v208 row_half_mirror row_mask:0xf bank_mask:0xf
	s_nop 0
	s_nop 0
	v_add_f32_dpp v208, v208, v208 row_mirror row_mask:0xf bank_mask:0xf
	s_nop 0
	s_nop 0
	v_add_f32_dpp v208, v208, v208 row_bcast:15 row_mask:0xa bank_mask:0xf
	s_nop 0
	s_nop 0
	v_add_f32_dpp v208, v208, v208 row_bcast:31 row_mask:0xc bank_mask:0xf
	s_nop 0
	s_nop 0
	v_readlane_b32 s60, v208, 63
	s_nop 1
	v_mov_b32_e32 v210, s60
	v_fmaak_f32 v210, v210, v212, 0x358637bd
	v_rsq_f32_e32 v210, v210
	s_nop 0
	v_lshlrev_b32_e32 v200, 16, v168
	v_and_b32_e32 v201, 0xffff0000, v168
	v_pk_mul_f32 v[200:201], v[200:201], v[210:211] op_sel_hi:[1,0]
	v_pk_fma_f32 v[152:153], v[8:9], v[200:201], v[152:153]
	v_lshlrev_b32_e32 v202, 16, v169
	v_and_b32_e32 v203, 0xffff0000, v169
	v_pk_mul_f32 v[202:203], v[202:203], v[210:211] op_sel_hi:[1,0]
	v_pk_fma_f32 v[154:155], v[10:11], v[202:203], v[154:155]
	v_lshlrev_b32_e32 v200, 16, v170
	v_and_b32_e32 v201, 0xffff0000, v170
	v_pk_mul_f32 v[200:201], v[200:201], v[210:211] op_sel_hi:[1,0]
	v_pk_fma_f32 v[156:157], v[12:13], v[200:201], v[156:157]
	v_lshlrev_b32_e32 v202, 16, v171
	v_and_b32_e32 v203, 0xffff0000, v171
	v_pk_mul_f32 v[202:203], v[202:203], v[210:211] op_sel_hi:[1,0]
	v_pk_fma_f32 v[158:159], v[14:15], v[202:203], v[158:159]
	v_lshlrev_b32_e32 v200, 16, v172
	v_and_b32_e32 v201, 0xffff0000, v172
	v_pk_mul_f32 v[200:201], v[200:201], v[210:211] op_sel_hi:[1,0]
	v_pk_fma_f32 v[160:161], v[16:17], v[200:201], v[160:161]
	v_lshlrev_b32_e32 v202, 16, v173
	v_and_b32_e32 v203, 0xffff0000, v173
	v_pk_mul_f32 v[202:203], v[202:203], v[210:211] op_sel_hi:[1,0]
	v_pk_fma_f32 v[162:163], v[18:19], v[202:203], v[162:163]
	v_lshlrev_b32_e32 v200, 16, v174
	v_and_b32_e32 v201, 0xffff0000, v174
	v_pk_mul_f32 v[200:201], v[200:201], v[210:211] op_sel_hi:[1,0]
	v_pk_fma_f32 v[164:165], v[20:21], v[200:201], v[164:165]
	v_lshlrev_b32_e32 v202, 16, v175
	v_and_b32_e32 v203, 0xffff0000, v175
	v_pk_mul_f32 v[202:203], v[202:203], v[210:211] op_sel_hi:[1,0]
	v_pk_fma_f32 v[166:167], v[22:23], v[202:203], v[166:167]
	s_add_i32 s81, s80, 2
	s_add_i32 s81, s81, s82
	s_and_b32 s81, s81, 31
	s_lshl_b32 s83, s81, 11
	v_add_u32_e32 v2, s83, v1
	v_cvt_pk_bf16_f32 v168, v152, v153
	v_cvt_pk_bf16_f32 v169, v154, v155
	v_cvt_pk_bf16_f32 v170, v156, v157
	v_cvt_pk_bf16_f32 v171, v158, v159
	v_cvt_pk_bf16_f32 v172, v160, v161
	v_cvt_pk_bf16_f32 v173, v162, v163
	v_cvt_pk_bf16_f32 v174, v164, v165
	v_cvt_pk_bf16_f32 v175, v166, v167
	global_store_dwordx4 v2, v[168:171], s[76:77] nt
	global_store_dwordx4 v2, v[172:175], s[76:77] offset:1024 nt
	v_pk_mul_f32 v[204:205], v[152:153], v[152:153]
	v_pk_mul_f32 v[206:207], v[154:155], v[154:155]
	v_pk_fma_f32 v[204:205], v[156:157], v[156:157], v[204:205]
	v_pk_fma_f32 v[206:207], v[158:159], v[158:159], v[206:207]
	v_pk_fma_f32 v[204:205], v[160:161], v[160:161], v[204:205]
	v_pk_fma_f32 v[206:207], v[162:163], v[162:163], v[206:207]
	v_pk_fma_f32 v[204:205], v[164:165], v[164:165], v[204:205]
	v_pk_fma_f32 v[206:207], v[166:167], v[166:167], v[206:207]
	v_pk_add_f32 v[204:205], v[204:205], v[206:207]
	v_add_f32_e32 v208, v204, v205
	s_nop 0
	s_nop 0
	v_add_f32_dpp v208, v208, v208 quad_perm:[1,0,3,2] row_mask:0xf bank_mask:0xf
	s_nop 0
	s_nop 0
	v_add_f32_dpp v208, v208, v208 quad_perm:[2,3,0,1] row_mask:0xf bank_mask:0xf
	s_nop 0
	s_nop 0
	v_add_f32_dpp v208, v208, v208 row_half_mirror row_mask:0xf bank_mask:0xf
	s_nop 0
	s_nop 0
	v_add_f32_dpp v208, v208, v208 row_mirror row_mask:0xf bank_mask:0xf
	s_nop 0
	s_nop 0
	v_add_f32_dpp v208, v208, v208 row_bcast:15 row_mask:0xa bank_mask:0xf
	s_nop 0
	s_nop 0
	v_add_f32_dpp v208, v208, v208 row_bcast:31 row_mask:0xc bank_mask:0xf
	s_nop 0
	s_nop 0
	v_readlane_b32 s60, v208, 63
	s_nop 1
	v_mov_b32_e32 v210, s60
	v_fmaak_f32 v210, v210, v212, 0x358637bd
	v_rsq_f32_e32 v210, v210
	s_nop 0
	v_pk_mul_f32 v[200:201], v[152:153], v[210:211] op_sel_hi:[1,0]
	v_pk_fma_f32 v[200:201], v[200:201], v[24:25], v[40:41]
	v_cvt_pk_bf16_f32 v168, v200, v201
	v_pk_mul_f32 v[202:203], v[154:155], v[210:211] op_sel_hi:[1,0]
	v_pk_fma_f32 v[202:203], v[202:203], v[26:27], v[42:43]
	v_cvt_pk_bf16_f32 v169, v202, v203
	v_pk_mul_f32 v[200:201], v[156:157], v[210:211] op_sel_hi:[1,0]
	v_pk_fma_f32 v[200:201], v[200:201], v[28:29], v[44:45]
	v_cvt_pk_bf16_f32 v170, v200, v201
	v_pk_mul_f32 v[202:203], v[158:159], v[210:211] op_sel_hi:[1,0]
	v_pk_fma_f32 v[202:203], v[202:203], v[30:31], v[46:47]
	v_cvt_pk_bf16_f32 v171, v202, v203
	v_pk_mul_f32 v[200:201], v[160:161], v[210:211] op_sel_hi:[1,0]
	v_pk_fma_f32 v[200:201], v[200:201], v[32:33], v[48:49]
	v_cvt_pk_bf16_f32 v172, v200, v201
	v_pk_mul_f32 v[202:203], v[162:163], v[210:211] op_sel_hi:[1,0]
	v_pk_fma_f32 v[202:203], v[202:203], v[34:35], v[50:51]
	v_cvt_pk_bf16_f32 v173, v202, v203
	v_pk_mul_f32 v[200:201], v[164:165], v[210:211] op_sel_hi:[1,0]
	v_pk_fma_f32 v[200:201], v[200:201], v[36:37], v[52:53]
	v_cvt_pk_bf16_f32 v174, v200, v201
	v_pk_mul_f32 v[202:203], v[166:167], v[210:211] op_sel_hi:[1,0]
	v_pk_fma_f32 v[202:203], v[202:203], v[38:39], v[54:55]
	v_cvt_pk_bf16_f32 v175, v202, v203
	global_store_dwordx4 v2, v[168:171], s[78:79] nt
	global_store_dwordx4 v2, v[172:175], s[78:79] offset:1024 nt
	s_add_i32 s81, s82, 5
	s_cmp_lt_u32 s81, 32
	s_cbranch_scc0 .Lrw_FIRST_l3_d
; __device__ __forceinline__ void phase_rowwise(const void* xsrc_, bool sbf, void* xdst_, bool dbf, const bf16_t* Y, bf16_t* H, const float* mods, int lprev, int iprev, const float* lnpost, float resw, ...
;     ...
;             if (rr + 2 < 32) {
; #pragma unroll
;                 for (int r = 0; r < 2; ++r)
; #pragma unroll
;                     for (int j = 0; j < 4; ++j) { if (sbf) xnb[r][j] = *(const u32x2*)(xsrcb + (m + 2 + r) * DM + 4 * lane + 256 * j); else xn[r][j] = *(const f32x4*)(xsrc + (m + 2 + r) * DM + 4 * lane + 256 * j); if (hasprev) yn[r][j] = *(const u32x2*)(Y + (m + 2 + r) * DM + 4 * lane + 256 * j); } }
	s_add_i32 s81, s80, 5
	s_add_i32 s81, s81, s82
	s_and_b32 s81, s81, 31
	s_lshl_b32 s83, s81, 11
	v_add_u32_e32 v2, s83, v1
	s_lshl_b32 s83, s81, 12
	v_add_u32_e32 v213, s83, v3
	global_load_dwordx4 v[104:107], v213, s[72:73] nt
	global_load_dwordx4 v[108:111], v213, s[72:73] offset:16 nt
	global_load_dwordx4 v[112:115], v213, s[72:73] offset:2048 nt
	global_load_dwordx4 v[116:119], v213, s[72:73] offset:2064 nt
	global_load_dwordx4 v[120:123], v2, s[74:75] nt
	global_load_dwordx4 v[124:127], v2, s[74:75] offset:1024 nt
	s_branch .Lrw_FIRST_l3_e

; __device__ __forceinline__ float bflo(unsigned u) { return __uint_as_float(u << 16); }
; __device__ __forceinline__ void phase_rowwise(const void* xsrc_, bool sbf, void* xdst_, bool dbf, const bf16_t* Y, bf16_t* H, const float* mods, int lprev, int iprev, const float* lnpost, float resw, ...
;     ...
;             if (hasprev) {
;                 f32x4 y[2][4]; float ss[2] = {0.f, 0.f};
; #pragma unroll
;                 for (int r = 0; r < 2; ++r)
; #pragma unroll
;                     for (int j = 0; j < 4; ++j) { const u32x2 u = yr[r][j]; y[r][j] = (f32x4){bflo(u.x), bfhi(u.x), bflo(u.y), bfhi(u.y)};
;                         ss[r] += (y[r][j].x * y[r][j].x + y[r][j].y * y[r][j].y) + (y[r][j].z * y[r][j].z + y[r][j].w * y[r][j].w); }
; #pragma unroll
;                 for (int off = 1; off < 64; off <<= 1) { ss[0] += __shfl_xor(ss[0], off); ss[1] += __shfl_xor(ss[1], off); }
; #pragma unroll
;                 for (int r = 0; r < 2; ++r) { const float rs = __builtin_amdgcn_rsqf(ss[r] * (1.f / DM) + EPS);
; #pragma unroll
;                     for (int j = 0; j < 4; ++j) x[r][j] = x[r][j] + gp[j] * (y[r][j] * rs); }
;             }
; #pragma unroll
;             for (int r = 0; r < 2; ++r)
; #pragma unroll
;                 for (int j = 0; j < 4; ++j) { if (hasprev) { if (dbf) { u32x2 w; w.x = cvtpk(x[r][j].x, x[r][j].y); w.y = cvtpk(x[r][j].z, x[r][j].w); *(u32x2*)(xdstb + (m + r) * DM + 4 * lane + 256 * j) = w; } else *(f32x4*)(xdst + (m + r) * DM + 4 * lane + 256 * j) = x[r][j]; } }
;             if (hasnext) {
;                 float ss[2] = {0.f, 0.f};
; #pragma unroll
;                 for (int r = 0; r < 2; ++r)
; #pragma unroll
;                     for (int j = 0; j < 4; ++j) ss[r] += (x[r][j].x * x[r][j].x + x[r][j].y * x[r][j].y) + (x[r][j].z * x[r][j].z + x[r][j].w * x[r][j].w);
; #pragma unroll
;                 for (int off = 1; off < 64; off <<= 1) { ss[0] += __shfl_xor(ss[0], off); ss[1] += __shfl_xor(ss[1], off); }
; #pragma unroll
;                 for (int r = 0; r < 2; ++r) { const float rs = __builtin_amdgcn_rsqf(ss[r] * (1.f / DM) + EPS);
; #pragma unroll
;                     for (int j = 0; j < 4; ++j) { const f32x4 h = (x[r][j] * rs) * na[j] + ns[j]; u32x2 w; w.x = cvtpk(h.x, h.y); w.y = cvtpk(h.z, h.w); *(u32x2*)(H + (m + r) * DM + 4 * lane + 256 * j) = w; } }
.Lrw_FIRST_l3_e:
	s_waitcnt vmcnt(20)
	v_lshlrev_b32_e32 v200, 16, v72
	v_and_b32_e32 v201, 0xffff0000, v72
	v_pk_mul_f32 v[204:205], v[200:201], v[200:201]
	v_lshlrev_b32_e32 v202, 16, v73
	v_and_b32_e32 v203, 0xffff0000, v73
	v_pk_mul_f32 v[206:207], v[202:203], v[202:203]
	v_lshlrev_b32_e32 v200, 16, v74
	v_and_b32_e32 v201, 0xffff0000, v74
	v_pk_fma_f32 v[204:205], v[200:201], v[200:201], v[204:205]
	v_lshlrev_b32_e32 v202, 16, v75
	v_and_b32_e32 v203, 0xffff0000, v75
	v_pk_fma_f32 v[206:207], v[202:203], v[202:203], v[206:207]
	v_lshlrev_b32_e32 v200, 16, v76
	v_and_b32_e32 v201, 0xffff0000, v76
	v_pk_fma_f32 v[204:205], v[200:201], v[200:201], v[204:205]
	v_lshlrev_b32_e32 v202, 16, v77
	v_and_b32_e32 v203, 0xffff0000, v77
	v_pk_fma_f32 v[206:207], v[202:203], v[202:203], v[206:207]
	v_lshlrev_b32_e32 v200, 16, v78
	v_and_b32_e32 v201, 0xffff0000, v78
	v_pk_fma_f32 v[204:205], v[200:201], v[200:201], v[204:205]
	v_lshlrev_b32_e32 v202, 16, v79
	v_and_b32_e32 v203, 0xffff0000, v79
	v_pk_fma_f32 v[206:207], v[202:203], v[202:203], v[206:207]
	v_pk_add_f32 v[204:205], v[204:205], v[206:207]
	v_add_f32_e32 v208, v204, v205
	s_nop 0
	s_nop 0
	v_add_f32_dpp v208, v208, v208 quad_perm:[1,0,3,2] row_mask:0xf bank_mask:0xf
	s_nop 0
	s_nop 0
	v_add_f32_dpp v208, v208, v208 quad_perm:[2,3,0,1] row_mask:0xf bank_mask:0xf
	s_nop 0
	s_nop 0
	v_add_f32_dpp v208, v208, v208 row_half_mirror row_mask:0xf bank_mask:0xf
	s_nop 0
	s_nop 0
	v_add_f32_dpp v208, v208, v208 row_mirror row_mask:0xf bank_mask:0xf
	s_nop 0
	s_nop 0
	v_add_f32_dpp v208, v208, v208 row_bcast:15 row_mask:0xa bank_mask:0xf
	s_nop 0
	s_nop 0
	v_add_f32_dpp v208, v208, v208 row_bcast:31 row_mask:0xc bank_mask:0xf
	s_nop 0
	s_nop 0
	v_readlane_b32 s60, v208, 63
	s_nop 1
	v_mov_b32_e32 v210, s60
	v_fmaak_f32 v210, v210, v212, 0x358637bd
	v_rsq_f32_e32 v210, v210
	s_nop 0
	v_lshlrev_b32_e32 v200, 16, v72
	v_and_b32_e32 v201, 0xffff0000, v72
	v_pk_mul_f32 v[200:201], v[200:201], v[210:211] op_sel_hi:[1,0]
	v_pk_fma_f32 v[56:57], v[8:9], v[200:201], v[56:57]
	v_lshlrev_b32_e32 v202, 16, v73
	v_and_b32_e32 v203, 0xffff0000, v73
	v_pk_mul_f32 v[202:203], v[202:203], v[210:211] op_sel_hi:[1,0]
	v_pk_fma_f32 v[58:59], v[10:11], v[202:203], v[58:59]
	v_lshlrev_b32_e32 v200, 16, v74
	v_and_b32_e32 v201, 0xffff0000, v74
	v_pk_mul_f32 v[200:201], v[200:201], v[210:211] op_sel_hi:[1,0]
	v_pk_fma_f32 v[60:61], v[12:13], v[200:201], v[60:61]
	v_lshlrev_b32_e32 v202, 16, v75
	v_and_b32_e32 v203, 0xffff0000, v75
	v_pk_mul_f32 v[202:203], v[202:203], v[210:211] op_sel_hi:[1,0]
	v_pk_fma_f32 v[62:63], v[14:15], v[202:203], v[62:63]
	v_lshlrev_b32_e32 v200, 16, v76
	v_and_b32_e32 v201, 0xffff0000, v76
	v_pk_mul_f32 v[200:201], v[200:201], v[210:211] op_sel_hi:[1,0]
	v_pk_fma_f32 v[64:65], v[16:17], v[200:201], v[64:65]
	v_lshlrev_b32_e32 v202, 16, v77
	v_and_b32_e32 v203, 0xffff0000, v77
	v_pk_mul_f32 v[202:203], v[202:203], v[210:211] op_sel_hi:[1,0]
	v_pk_fma_f32 v[66:67], v[18:19], v[202:203], v[66:67]
	v_lshlrev_b32_e32 v200, 16, v78
	v_and_b32_e32 v201, 0xffff0000, v78
	v_pk_mul_f32 v[200:201], v[200:201], v[210:211] op_sel_hi:[1,0]
	v_pk_fma_f32 v[68:69], v[20:21], v[200:201], v[68:69]
	v_lshlrev_b32_e32 v202, 16, v79
	v_and_b32_e32 v203, 0xffff0000, v79
	v_pk_mul_f32 v[202:203], v[202:203], v[210:211] op_sel_hi:[1,0]
	v_pk_fma_f32 v[70:71], v[22:23], v[202:203], v[70:71]
	s_add_i32 s81, s80, 3
	s_add_i32 s81, s81, s82
	s_and_b32 s81, s81, 31
	s_lshl_b32 s83, s81, 11
	v_add_u32_e32 v2, s83, v1
	v_cvt_pk_bf16_f32 v72, v56, v57
	v_cvt_pk_bf16_f32 v73, v58, v59
	v_cvt_pk_bf16_f32 v74, v60, v61
	v_cvt_pk_bf16_f32 v75, v62, v63
	v_cvt_pk_bf16_f32 v76, v64, v65
	v_cvt_pk_bf16_f32 v77, v66, v67
	v_cvt_pk_bf16_f32 v78, v68, v69
	v_cvt_pk_bf16_f32 v79, v70, v71
	global_store_dwordx4 v2, v[72:75], s[76:77] nt
	global_store_dwordx4 v2, v[76:79], s[76:77] offset:1024 nt
	v_pk_mul_f32 v[204:205], v[56:57], v[56:57]
	v_pk_mul_f32 v[206:207], v[58:59], v[58:59]
	v_pk_fma_f32 v[204:205], v[60:61], v[60:61], v[204:205]
	v_pk_fma_f32 v[206:207], v[62:63], v[62:63], v[206:207]
	v_pk_fma_f32 v[204:205], v[64:65], v[64:65], v[204:205]
	v_pk_fma_f32 v[206:207], v[66:67], v[66:67], v[206:207]
	v_pk_fma_f32 v[204:205], v[68:69], v[68:69], v[204:205]
	v_pk_fma_f32 v[206:207], v[70:71], v[70:71], v[206:207]
	v_pk_add_f32 v[204:205], v[204:205], v[206:207]
	v_add_f32_e32 v208, v204, v205
	s_nop 0
	s_nop 0
	v_add_f32_dpp v208, v208, v208 quad_perm:[1,0,3,2] row_mask:0xf bank_mask:0xf
	s_nop 0
	s_nop 0
	v_add_f32_dpp v208, v208, v208 quad_perm:[2,3,0,1] row_mask:0xf bank_mask:0xf
	s_nop 0
	s_nop 0
	v_add_f32_dpp v208, v208, v208 row_half_mirror row_mask:0xf bank_mask:0xf
	s_nop 0
	s_nop 0
	v_add_f32_dpp v208, v208, v208 row_mirror row_mask:0xf bank_mask:0xf
	s_nop 0
	s_nop 0
	v_add_f32_dpp v208, v208, v208 row_bcast:15 row_mask:0xa bank_mask:0xf
	s_nop 0
	s_nop 0
	v_add_f32_dpp v208, v208, v208 row_bcast:31 row_mask:0xc bank_mask:0xf
	s_nop 0
	s_nop 0
	v_readlane_b32 s60, v208, 63
	s_nop 1
	v_mov_b32_e32 v210, s60
	v_fmaak_f32 v210, v210, v212, 0x358637bd
	v_rsq_f32_e32 v210, v210
	s_nop 0
	v_pk_mul_f32 v[200:201], v[56:57], v[210:211] op_sel_hi:[1,0]
	v_pk_fma_f32 v[200:201], v[200:201], v[24:25], v[40:41]
	v_cvt_pk_bf16_f32 v72, v200, v201
	v_pk_mul_f32 v[202:203], v[58:59], v[210:211] op_sel_hi:[1,0]
	v_pk_fma_f32 v[202:203], v[202:203], v[26:27], v[42:43]
	v_cvt_pk_bf16_f32 v73, v202, v203
	v_pk_mul_f32 v[200:201], v[60:61], v[210:211] op_sel_hi:[1,0]
	v_pk_fma_f32 v[200:201], v[200:201], v[28:29], v[44:45]
	v_cvt_pk_bf16_f32 v74, v200, v201
	v_pk_mul_f32 v[202:203], v[62:63], v[210:211] op_sel_hi:[1,0]
	v_pk_fma_f32 v[202:203], v[202:203], v[30:31], v[46:47]
	v_cvt_pk_bf16_f32 v75, v202, v203
	v_pk_mul_f32 v[200:201], v[64:65], v[210:211] op_sel_hi:[1,0]
	v_pk_fma_f32 v[200:201], v[200:201], v[32:33], v[48:49]
	v_cvt_pk_bf16_f32 v76, v200, v201
	v_pk_mul_f32 v[202:203], v[66:67], v[210:211] op_sel_hi:[1,0]
	v_pk_fma_f32 v[202:203], v[202:203], v[34:35], v[50:51]
	v_cvt_pk_bf16_f32 v77, v202, v203
	v_pk_mul_f32 v[200:201], v[68:69], v[210:211] op_sel_hi:[1,0]
	v_pk_fma_f32 v[200:201], v[200:201], v[36:37], v[52:53]
	v_cvt_pk_bf16_f32 v78, v200, v201
	v_pk_mul_f32 v[202:203], v[70:71], v[210:211] op_sel_hi:[1,0]
	v_pk_fma_f32 v[202:203], v[202:203], v[38:39], v[54:55]
	v_cvt_pk_bf16_f32 v79, v202, v203
	global_store_dwordx4 v2, v[72:75], s[78:79] nt
	global_store_dwordx4 v2, v[76:79], s[78:79] offset:1024 nt
	s_add_i32 s81, s82, 6
	s_cmp_lt_u32 s81, 32
	s_cbranch_scc0 .Lrw_FIRST_l4_d
; __device__ __forceinline__ void phase_rowwise(const void* xsrc_, bool sbf, void* xdst_, bool dbf, const bf16_t* Y, bf16_t* H, const float* mods, int lprev, int iprev, const float* lnpost, float resw, ...
;     ...
;             if (rr + 2 < 32) {
; #pragma unroll
;                 for (int r = 0; r < 2; ++r)
; #pragma unroll
;                     for (int j = 0; j < 4; ++j) { if (sbf) xnb[r][j] = *(const u32x2*)(xsrcb + (m + 2 + r) * DM + 4 * lane + 256 * j); else xn[r][j] = *(const f32x4*)(xsrc + (m + 2 + r) * DM + 4 * lane + 256 * j); if (hasprev) yn[r][j] = *(const u32x2*)(Y + (m + 2 + r) * DM + 4 * lane + 256 * j); } }
	s_add_i32 s81, s80, 6
	s_add_i32 s81, s81, s82
	s_and_b32 s81, s81, 31
	s_lshl_b32 s83, s81, 11
	v_add_u32_e32 v2, s83, v1
	s_lshl_b32 s83, s81, 12
	v_add_u32_e32 v213, s83, v3
	global_load_dwordx4 v[128:131], v213, s[72:73] nt
	global_load_dwordx4 v[132:135], v213, s[72:73] offset:16 nt
	global_load_dwordx4 v[136:139], v213, s[72:73] offset:2048 nt
	global_load_dwordx4 v[140:143], v213, s[72:73] offset:2064 nt
	global_load_dwordx4 v[144:147], v2, s[74:75] nt
	global_load_dwordx4 v[148:151], v2, s[74:75] offset:1024 nt
	s_branch .Lrw_FIRST_l4_e

; __device__ __forceinline__ float bflo(unsigned u) { return __uint_as_float(u << 16); }
; __device__ __forceinline__ void phase_rowwise(const void* xsrc_, bool sbf, void* xdst_, bool dbf, const bf16_t* Y, bf16_t* H, const float* mods, int lprev, int iprev, const float* lnpost, float resw, ...
;     ...
;             if (hasprev) {
;                 f32x4 y[2][4]; float ss[2] = {0.f, 0.f};
; #pragma unroll
;                 for (int r = 0; r < 2; ++r)
; #pragma unroll
;                     for (int j = 0; j < 4; ++j) { const u32x2 u = yr[r][j]; y[r][j] = (f32x4){bflo(u.x), bfhi(u.x), bflo(u.y), bfhi(u.y)};
;                         ss[r] += (y[r][j].x * y[r][j].x + y[r][j].y * y[r][j].y) + (y[r][j].z * y[r][j].z + y[r][j].w * y[r][j].w); }
; #pragma unroll
;                 for (int off = 1; off < 64; off <<= 1) { ss[0] += __shfl_xor(ss[0], off); ss[1] += __shfl_xor(ss[1], off); }
; #pragma unroll
;                 for (int r = 0; r < 2; ++r) { const float rs = __builtin_amdgcn_rsqf(ss[r] * (1.f / DM) + EPS);
; #pragma unroll
;                     for (int j = 0; j < 4; ++j) x[r][j] = x[r][j] + gp[j] * (y[r][j] * rs); }
;             }
; #pragma unroll
;             for (int r = 0; r < 2; ++r)
; #pragma unroll
;                 for (int j = 0; j < 4; ++j) { if (hasprev) { if (dbf) { u32x2 w; w.x = cvtpk(x[r][j].x, x[r][j].y); w.y = cvtpk(x[r][j].z, x[r][j].w); *(u32x2*)(xdstb + (m + r) * DM + 4 * lane + 256 * j) = w; } else *(f32x4*)(xdst + (m + r) * DM + 4 * lane + 256 * j) = x[r][j]; } }
;             if (hasnext) {
;                 float ss[2] = {0.f, 0.f};
; #pragma unroll
;                 for (int r = 0; r < 2; ++r)
; #pragma unroll
;                     for (int j = 0; j < 4; ++j) ss[r] += (x[r][j].x * x[r][j].x + x[r][j].y * x[r][j].y) + (x[r][j].z * x[r][j].z + x[r][j].w * x[r][j].w);
; #pragma unroll
;                 for (int off = 1; off < 64; off <<= 1) { ss[0] += __shfl_xor(ss[0], off); ss[1] += __shfl_xor(ss[1], off); }
; #pragma unroll
;                 for (int r = 0; r < 2; ++r) { const float rs = __builtin_amdgcn_rsqf(ss[r] * (1.f / DM) + EPS);
; #pragma unroll
;                     for (int j = 0; j < 4; ++j) { const f32x4 h = (x[r][j] * rs) * na[j] + ns[j]; u32x2 w; w.x = cvtpk(h.x, h.y); w.y = cvtpk(h.z, h.w); *(u32x2*)(H + (m + r) * DM + 4 * lane + 256 * j) = w; } }
.Lrw_FIRST_l4_e:
	s_waitcnt vmcnt(20)
	v_lshlrev_b32_e32 v200, 16, v96
	v_and_b32_e32 v201, 0xffff0000, v96
	v_pk_mul_f32 v[204:205], v[200:201], v[200:201]
	v_lshlrev_b32_e32 v202, 16, v97
	v_and_b32_e32 v203, 0xffff0000, v97
	v_pk_mul_f32 v[206:207], v[202:203], v[202:203]
	v_lshlrev_b32_e32 v200, 16, v98
	v_and_b32_e32 v201, 0xffff0000, v98
	v_pk_fma_f32 v[204:205], v[200:201], v[200:201], v[204:205]
	v_lshlrev_b32_e32 v202, 16, v99
	v_and_b32_e32 v203, 0xffff0000, v99
	v_pk_fma_f32 v[206:207], v[202:203], v[202:203], v[206:207]
	v_lshlrev_b32_e32 v200, 16, v100
	v_and_b32_e32 v201, 0xffff0000, v100
	v_pk_fma_f32 v[204:205], v[200:201], v[200:201], v[204:205]
	v_lshlrev_b32_e32 v202, 16, v101
	v_and_b32_e32 v203, 0xffff0000, v101
	v_pk_fma_f32 v[206:207], v[202:203], v[202:203], v[206:207]
	v_lshlrev_b32_e32 v200, 16, v102
	v_and_b32_e32 v201, 0xffff0000, v102
	v_pk_fma_f32 v[204:205], v[200:201], v[200:201], v[204:205]
	v_lshlrev_b32_e32 v202, 16, v103
	v_and_b32_e32 v203, 0xffff0000, v103
	v_pk_fma_f32 v[206:207], v[202:203], v[202:203], v[206:207]
	v_pk_add_f32 v[204:205], v[204:205], v[206:207]
	v_add_f32_e32 v208, v204, v205
	s_nop 0
	s_nop 0
	v_add_f32_dpp v208, v208, v208 quad_perm:[1,0,3,2] row_mask:0xf bank_mask:0xf
	s_nop 0
	s_nop 0
	v_add_f32_dpp v208, v208, v208 quad_perm:[2,3,0,1] row_mask:0xf bank_mask:0xf
	s_nop 0
	s_nop 0
	v_add_f32_dpp v208, v208, v208 row_half_mirror row_mask:0xf bank_mask:0xf
	s_nop 0
	s_nop 0
	v_add_f32_dpp v208, v208, v208 row_mirror row_mask:0xf bank_mask:0xf
	s_nop 0
	s_nop 0
	v_add_f32_dpp v208, v208, v208 row_bcast:15 row_mask:0xa bank_mask:0xf
	s_nop 0
	s_nop 0
	v_add_f32_dpp v208, v208, v208 row_bcast:31 row_mask:0xc bank_mask:0xf
	s_nop 0
	s_nop 0
	v_readlane_b32 s60, v208, 63
	s_nop 1
	v_mov_b32_e32 v210, s60
	v_fmaak_f32 v210, v210, v212, 0x358637bd
	v_rsq_f32_e32 v210, v210
	s_nop 0
	v_lshlrev_b32_e32 v200, 16, v96
	v_and_b32_e32 v201, 0xffff0000, v96
	v_pk_mul_f32 v[200:201], v[200:201], v[210:211] op_sel_hi:[1,0]
	v_pk_fma_f32 v[80:81], v[8:9], v[200:201], v[80:81]
	v_lshlrev_b32_e32 v202, 16, v97
	v_and_b32_e32 v203, 0xffff0000, v97
	v_pk_mul_f32 v[202:203], v[202:203], v[210:211] op_sel_hi:[1,0]
	v_pk_fma_f32 v[82:83], v[10:11], v[202:203], v[82:83]
	v_lshlrev_b32_e32 v200, 16, v98
	v_and_b32_e32 v201, 0xffff0000, v98
	v_pk_mul_f32 v[200:201], v[200:201], v[210:211] op_sel_hi:[1,0]
	v_pk_fma_f32 v[84:85], v[12:13], v[200:201], v[84:85]
	v_lshlrev_b32_e32 v202, 16, v99
	v_and_b32_e32 v203, 0xffff0000, v99
	v_pk_mul_f32 v[202:203], v[202:203], v[210:211] op_sel_hi:[1,0]
	v_pk_fma_f32 v[86:87], v[14:15], v[202:203], v[86:87]
	v_lshlrev_b32_e32 v200, 16, v100
	v_and_b32_e32 v201, 0xffff0000, v100
	v_pk_mul_f32 v[200:201], v[200:201], v[210:211] op_sel_hi:[1,0]
	v_pk_fma_f32 v[88:89], v[16:17], v[200:201], v[88:89]
	v_lshlrev_b32_e32 v202, 16, v101
	v_and_b32_e32 v203, 0xffff0000, v101
	v_pk_mul_f32 v[202:203], v[202:203], v[210:211] op_sel_hi:[1,0]
	v_pk_fma_f32 v[90:91], v[18:19], v[202:203], v[90:91]
	v_lshlrev_b32_e32 v200, 16, v102
	v_and_b32_e32 v201, 0xffff0000, v102
	v_pk_mul_f32 v[200:201], v[200:201], v[210:211] op_sel_hi:[1,0]
	v_pk_fma_f32 v[92:93], v[20:21], v[200:201], v[92:93]
	v_lshlrev_b32_e32 v202, 16, v103
	v_and_b32_e32 v203, 0xffff0000, v103
	v_pk_mul_f32 v[202:203], v[202:203], v[210:211] op_sel_hi:[1,0]
	v_pk_fma_f32 v[94:95], v[22:23], v[202:203], v[94:95]
	s_add_i32 s81, s80, 4
	s_add_i32 s81, s81, s82
	s_and_b32 s81, s81, 31
	s_lshl_b32 s83, s81, 11
	v_add_u32_e32 v2, s83, v1
	v_cvt_pk_bf16_f32 v96, v80, v81
	v_cvt_pk_bf16_f32 v97, v82, v83
	v_cvt_pk_bf16_f32 v98, v84, v85
	v_cvt_pk_bf16_f32 v99, v86, v87
	v_cvt_pk_bf16_f32 v100, v88, v89
	v_cvt_pk_bf16_f32 v101, v90, v91
	v_cvt_pk_bf16_f32 v102, v92, v93
	v_cvt_pk_bf16_f32 v103, v94, v95
	global_store_dwordx4 v2, v[96:99], s[76:77] nt
	global_store_dwordx4 v2, v[100:103], s[76:77] offset:1024 nt
	v_pk_mul_f32 v[204:205], v[80:81], v[80:81]
	v_pk_mul_f32 v[206:207], v[82:83], v[82:83]
	v_pk_fma_f32 v[204:205], v[84:85], v[84:85], v[204:205]
	v_pk_fma_f32 v[206:207], v[86:87], v[86:87], v[206:207]
	v_pk_fma_f32 v[204:205], v[88:89], v[88:89], v[204:205]
	v_pk_fma_f32 v[206:207], v[90:91], v[90:91], v[206:207]
	v_pk_fma_f32 v[204:205], v[92:93], v[92:93], v[204:205]
	v_pk_fma_f32 v[206:207], v[94:95], v[94:95], v[206:207]
	v_pk_add_f32 v[204:205], v[204:205], v[206:207]
	v_add_f32_e32 v208, v204, v205
	s_nop 0
	s_nop 0
	v_add_f32_dpp v208, v208, v208 quad_perm:[1,0,3,2] row_mask:0xf bank_mask:0xf
	s_nop 0
	s_nop 0
	v_add_f32_dpp v208, v208, v208 quad_perm:[2,3,0,1] row_mask:0xf bank_mask:0xf
	s_nop 0
	s_nop 0
	v_add_f32_dpp v208, v208, v208 row_half_mirror row_mask:0xf bank_mask:0xf
	s_nop 0
	s_nop 0
	v_add_f32_dpp v208, v208, v208 row_mirror row_mask:0xf bank_mask:0xf
	s_nop 0
	s_nop 0
	v_add_f32_dpp v208, v208, v208 row_bcast:15 row_mask:0xa bank_mask:0xf
	s_nop 0
	s_nop 0
	v_add_f32_dpp v208, v208, v208 row_bcast:31 row_mask:0xc bank_mask:0xf
	s_nop 0
	s_nop 0
	v_readlane_b32 s60, v208, 63
	s_nop 1
	v_mov_b32_e32 v210, s60
	v_fmaak_f32 v210, v210, v212, 0x358637bd
	v_rsq_f32_e32 v210, v210
	s_nop 0
	v_pk_mul_f32 v[200:201], v[80:81], v[210:211] op_sel_hi:[1,0]
	v_pk_fma_f32 v[200:201], v[200:201], v[24:25], v[40:41]
	v_cvt_pk_bf16_f32 v96, v200, v201
	v_pk_mul_f32 v[202:203], v[82:83], v[210:211] op_sel_hi:[1,0]
	v_pk_fma_f32 v[202:203], v[202:203], v[26:27], v[42:43]
	v_cvt_pk_bf16_f32 v97, v202, v203
	v_pk_mul_f32 v[200:201], v[84:85], v[210:211] op_sel_hi:[1,0]
	v_pk_fma_f32 v[200:201], v[200:201], v[28:29], v[44:45]
	v_cvt_pk_bf16_f32 v98, v200, v201
	v_pk_mul_f32 v[202:203], v[86:87], v[210:211] op_sel_hi:[1,0]
	v_pk_fma_f32 v[202:203], v[202:203], v[30:31], v[46:47]
	v_cvt_pk_bf16_f32 v99, v202, v203
	v_pk_mul_f32 v[200:201], v[88:89], v[210:211] op_sel_hi:[1,0]
	v_pk_fma_f32 v[200:201], v[200:201], v[32:33], v[48:49]
	v_cvt_pk_bf16_f32 v100, v200, v201
	v_pk_mul_f32 v[202:203], v[90:91], v[210:211] op_sel_hi:[1,0]
	v_pk_fma_f32 v[202:203], v[202:203], v[34:35], v[50:51]
	v_cvt_pk_bf16_f32 v101, v202, v203
	v_pk_mul_f32 v[200:201], v[92:93], v[210:211] op_sel_hi:[1,0]
	v_pk_fma_f32 v[200:201], v[200:201], v[36:37], v[52:53]
	v_cvt_pk_bf16_f32 v102, v200, v201
	v_pk_mul_f32 v[202:203], v[94:95], v[210:211] op_sel_hi:[1,0]
	v_pk_fma_f32 v[202:203], v[202:203], v[38:39], v[54:55]
	v_cvt_pk_bf16_f32 v103, v202, v203
	global_store_dwordx4 v2, v[96:99], s[78:79] nt
	global_store_dwordx4 v2, v[100:103], s[78:79] offset:1024 nt
	s_add_i32 s82, s82, 5
	s_cmp_lt_u32 s82, 32
	s_cbranch_scc1 .Lrw_FIRST_loop
	s_branch .LBB0_1024
; __device__ __forceinline__ float bflo(unsigned u) { return __uint_as_float(u << 16); }
; __device__ __forceinline__ float bfhi(unsigned u) { return __uint_as_float(u & 0xffff0000u); }
; __device__ __forceinline__ void phase_rowwise(const void* xsrc_, bool sbf, void* xdst_, bool dbf, const bf16_t* Y, bf16_t* H, const float* mods, int lprev, int iprev, const float* lnpost, float resw, ...
;     ...
;     for (int ch = gw; ch < M / 32; ch += NGW) {
;         const int b = ch >> 6;
;         f32x4 gp[4], na[4], ns[4];
; #pragma unroll
;         for (int j = 0; j < 4; ++j) { const int c = 4 * lane + 256 * j;
;             if (hasprev) { const f32x4 g = *(const f32x4*)(mods + ((size_t)lprev * 32 + b) * 9216 + iprev * 3072 + 2048 + c); const f32x4 lp = *(const f32x4*)(lnpost + c); gp[j] = g * lp * resw; }
;             else gp[j] = (f32x4){0.f, 0.f, 0.f, 0.f};
;             if (hasnext) { const f32x4 sh = *(const f32x4*)(mods + ((size_t)lnext * 32 + b) * 9216 + inext * 3072 + c); const f32x4 scl = *(const f32x4*)(mods + ((size_t)lnext * 32 + b) * 9216 + inext * 3072 + 1024 + c);
;                 const f32x4 lp = *(const f32x4*)(lnpre + c); na[j] = lp * (scl + 1.0f); ns[j] = sh; }
;             else { na[j] = (f32x4){0.f, 0.f, 0.f, 0.f}; ns[j] = na[j]; } }
;         f32x4 xn[2][4]; u32x2 xnb[2][4]; u32x2 yn[2][4];
;         { const size_t m0 = (size_t)ch * 32;
; #pragma unroll
;           for (int r = 0; r < 2; ++r)
; #pragma unroll
;             for (int j = 0; j < 4; ++j) { if (sbf) { xnb[r][j] = *(const u32x2*)(xsrcb + (m0 + r) * DM + 4 * lane + 256 * j); xn[r][j] = (f32x4){0.f, 0.f, 0.f, 0.f}; } else { xn[r][j] = *(const f32x4*)(xsrc + (m0 + r) * DM + 4 * lane + 256 * j); xnb[r][j] = (u32x2){0u, 0u}; }
;                 yn[r][j] = hasprev ? *(const u32x2*)(Y + (m0 + r) * DM + 4 * lane + 256 * j) : (u32x2){0u, 0u}; } }
;         for (int rr = 0; rr < 32; rr += 2) {
;             const size_t m = (size_t)ch * 32 + rr;
;             f32x4 x[2][4]; u32x2 yr[2][4];
; #pragma unroll
;             for (int r = 0; r < 2; ++r)
; #pragma unroll
;                 for (int j = 0; j < 4; ++j) { if (sbf) { const u32x2 u = xnb[r][j]; x[r][j] = (f32x4){bflo(u.x), bfhi(u.x), bflo(u.y), bfhi(u.y)}; } else x[r][j] = xn[r][j]; yr[r][j] = yn[r][j]; }
;             if (rr + 2 < 32) {
; #pragma unroll
;                 for (int r = 0; r < 2; ++r)
; #pragma unroll
.Lrw_LAST:
	v_readfirstlane_b32 s40, v214
	v_readlane_b32 s41, v254, 46
	s_lshr_b32 s40, s40, 6
	s_add_i32 s40, s40, s41
	s_lshr_b32 s41, s40, 6
	v_and_b32_e32 v1, 63, v214
	v_lshlrev_b32_e32 v3, 5, v1
	v_lshlrev_b32_e32 v1, 4, v1
	v_mov_b32_e32 v212, 0x3a800000
	s_cmp_eq_u32 s74, 2
	s_cselect_b32 s42, 1, 0
	s_add_i32 s42, s73, s42
	s_add_i32 s43, s74, 1
	s_cmp_eq_u32 s74, 2
	s_cselect_b32 s43, 0, s43
	s_cmp_eq_u32 s74, 1
	s_cselect_b32 s90, 1.0, 0.5
	s_mov_b32 s91, s90
	v_readlane_b32 s44, v255, 22
	v_readlane_b32 s45, v255, 23
	s_lshl_b32 s46, s73, 5
	s_add_i32 s46, s46, s41
	s_mul_i32 s46, s46, 0x9000
	s_mul_i32 s47, s74, 0x3000
	s_add_i32 s46, s46, s47
	s_add_i32 s46, s46, 0x2000
	s_add_u32 s48, s44, s46
	s_addc_u32 s49, s45, 0
	v_readlane_b32 s52, v255, 16
	v_readlane_b32 s53, v255, 17
	s_mul_i32 s46, s73, 3
	s_add_i32 s46, s46, s74
	s_lshl_b32 s46, s46, 12
	s_add_u32 s52, s52, s46
	s_addc_u32 s53, s53, 0
	global_load_dwordx4 v[8:11], v3, s[48:49]
	global_load_dwordx4 v[12:15], v3, s[48:49] offset:16
	global_load_dwordx4 v[16:19], v3, s[48:49] offset:2048
	global_load_dwordx4 v[20:23], v3, s[48:49] offset:2064
	global_load_dwordx4 v[56:59], v3, s[52:53]
	global_load_dwordx4 v[60:63], v3, s[52:53] offset:16
	global_load_dwordx4 v[64:67], v3, s[52:53] offset:2048
	global_load_dwordx4 v[68:71], v3, s[52:53] offset:2064
	s_lshl_b32 s46, s40, 16
	s_lshl_b32 s47, s40, 17
	v_readlane_b32 s72, v252, 26
	v_readlane_b32 s73, v252, 27
	s_add_u32 s72, s72, s46
	s_addc_u32 s73, s73, 0
	v_readlane_b32 s74, v252, 22
	v_readlane_b32 s75, v252, 23
	s_add_u32 s74, s74, s46
	s_addc_u32 s75, s75, 0
	v_readlane_b32 s76, v252, 6
	v_readlane_b32 s77, v252, 7
	s_add_u32 s76, s76, s47
	s_addc_u32 s77, s77, 0
	s_and_b32 s80, s40, 15
	s_lshl_b32 s80, s80, 1
	s_waitcnt vmcnt(0)
	v_pk_mul_f32 v[8:9], v[8:9], v[56:57]
	v_pk_mul_f32 v[10:11], v[10:11], v[58:59]
	v_pk_mul_f32 v[12:13], v[12:13], v[60:61]
	v_pk_mul_f32 v[14:15], v[14:15], v[62:63]
	v_pk_mul_f32 v[16:17], v[16:17], v[64:65]
	v_pk_mul_f32 v[18:19], v[18:19], v[66:67]
	v_pk_mul_f32 v[20:21], v[20:21], v[68:69]
	v_pk_mul_f32 v[22:23], v[22:23], v[70:71]
	v_pk_mul_f32 v[8:9], v[8:9], s[90:91]
	v_pk_mul_f32 v[10:11], v[10:11], s[90:91]
	v_pk_mul_f32 v[12:13], v[12:13], s[90:91]
	v_pk_mul_f32 v[14:15], v[14:15], s[90:91]
	v_pk_mul_f32 v[16:17], v[16:17], s[90:91]
	v_pk_mul_f32 v[18:19], v[18:19], s[90:91]
	v_pk_mul_f32 v[20:21], v[20:21], s[90:91]
	v_pk_mul_f32 v[22:23], v[22:23], s[90:91]
	s_waitcnt vmcnt(0)
	s_mov_b32 s82, 0
	s_add_i32 s81, s80, 0
	s_add_i32 s81, s81, s82
	s_and_b32 s81, s81, 31
	s_lshl_b32 s83, s81, 11
	v_add_u32_e32 v2, s83, v1
	global_load_dwordx4 v[56:59], v2, s[72:73] nt
	global_load_dwordx4 v[60:63], v2, s[72:73] offset:1024 nt
	global_load_dwordx4 v[64:67], v2, s[74:75] nt
	global_load_dwordx4 v[68:71], v2, s[74:75] offset:1024 nt
	s_add_i32 s81, s80, 1
	s_add_i32 s81, s81, s82
	s_and_b32 s81, s81, 31
	s_lshl_b32 s83, s81, 11
	v_add_u32_e32 v2, s83, v1
	global_load_dwordx4 v[72:75], v2, s[72:73] nt
	global_load_dwordx4 v[76:79], v2, s[72:73] offset:1024 nt
	global_load_dwordx4 v[80:83], v2, s[74:75] nt
	global_load_dwordx4 v[84:87], v2, s[74:75] offset:1024 nt
	s_add_i32 s81, s80, 2
	s_add_i32 s81, s81, s82
	s_and_b32 s81, s81, 31
	s_lshl_b32 s83, s81, 11
	v_add_u32_e32 v2, s83, v1
	global_load_dwordx4 v[88:91], v2, s[72:73] nt
	global_load_dwordx4 v[92:95], v2, s[72:73] offset:1024 nt
	global_load_dwordx4 v[96:99], v2, s[74:75] nt
	global_load_dwordx4 v[100:103], v2, s[74:75] offset:1024 nt
	s_add_i32 s81, s80, 3
	s_add_i32 s81, s81, s82
	s_and_b32 s81, s81, 31
	s_lshl_b32 s83, s81, 11
	v_add_u32_e32 v2, s83, v1
	global_load_dwordx4 v[104:107], v2, s[72:73] nt
	global_load_dwordx4 v[108:111], v2, s[72:73] offset:1024 nt
	global_load_dwordx4 v[112:115], v2, s[74:75] nt
	global_load_dwordx4 v[116:119], v2, s[74:75] offset:1024 nt
	s_add_i32 s81, s80, 4
	s_add_i32 s81, s81, s82
	s_and_b32 s81, s81, 31
	s_lshl_b32 s83, s81, 11
	v_add_u32_e32 v2, s83, v1
	global_load_dwordx4 v[120:123], v2, s[72:73] nt
	global_load_dwordx4 v[124:127], v2, s[72:73] offset:1024 nt
	global_load_dwordx4 v[128:131], v2, s[74:75] nt
	global_load_dwordx4 v[132:135], v2, s[74:75] offset:1024 nt
	s_waitcnt vmcnt(16)
	v_lshlrev_b32_e32 v200, 16, v64
	v_and_b32_e32 v201, 0xffff0000, v64
	v_pk_mul_f32 v[204:205], v[200:201], v[200:201]
	v_lshlrev_b32_e32 v202, 16, v65
	v_and_b32_e32 v203, 0xffff0000, v65
	v_pk_mul_f32 v[206:207], v[202:203], v[202:203]
	v_lshlrev_b32_e32 v200, 16, v66
	v_and_b32_e32 v201, 0xffff0000, v66
	v_pk_fma_f32 v[204:205], v[200:201], v[200:201], v[204:205]
	v_lshlrev_b32_e32 v202, 16, v67
	v_and_b32_e32 v203, 0xffff0000, v67
	v_pk_fma_f32 v[206:207], v[202:203], v[202:203], v[206:207]
	v_lshlrev_b32_e32 v200, 16, v68
	v_and_b32_e32 v201, 0xffff0000, v68
	v_pk_fma_f32 v[204:205], v[200:201], v[200:201], v[204:205]
	v_lshlrev_b32_e32 v202, 16, v69
	v_and_b32_e32 v203, 0xffff0000, v69
	v_pk_fma_f32 v[206:207], v[202:203], v[202:203], v[206:207]
	v_lshlrev_b32_e32 v200, 16, v70
	v_and_b32_e32 v201, 0xffff0000, v70
	v_pk_fma_f32 v[204:205], v[200:201], v[200:201], v[204:205]
	v_lshlrev_b32_e32 v202, 16, v71
	v_and_b32_e32 v203, 0xffff0000, v71
	v_pk_fma_f32 v[206:207], v[202:203], v[202:203], v[206:207]
	v_pk_add_f32 v[204:205], v[204:205], v[206:207]
	v_add_f32_e32 v208, v204, v205
	v_lshlrev_b32_e32 v184, 16, v56
	v_and_b32_e32 v185, 0xffff0000, v56
	v_add_f32_dpp v208, v208, v208 quad_perm:[1,0,3,2] row_mask:0xf bank_mask:0xf
	v_lshlrev_b32_e32 v186, 16, v57
	v_and_b32_e32 v187, 0xffff0000, v57
	v_add_f32_dpp v208, v208, v208 quad_perm:[2,3,0,1] row_mask:0xf bank_mask:0xf
; __device__ __forceinline__ float bflo(unsigned u) { return __uint_as_float(u << 16); }
; __device__ __forceinline__ void phase_rowwise(const void* xsrc_, bool sbf, void* xdst_, bool dbf, const bf16_t* Y, bf16_t* H, const float* mods, int lprev, int iprev, const float* lnpost, float resw, ...
;     ...
;         for (int rr = 0; rr < 32; rr += 2) {
;             const size_t m = (size_t)ch * 32 + rr;
;             f32x4 x[2][4]; u32x2 yr[2][4];
; #pragma unroll
;             for (int r = 0; r < 2; ++r)
; #pragma unroll
;                 for (int j = 0; j < 4; ++j) { if (sbf) { const u32x2 u = xnb[r][j]; x[r][j] = (f32x4){bflo(u.x), bfhi(u.x), bflo(u.y), bfhi(u.y)}; } else x[r][j] = xn[r][j]; yr[r][j] = yn[r][j]; }
;             if (rr + 2 < 32) {
; #pragma unroll
;                 for (int r = 0; r < 2; ++r)
; #pragma unroll
;                     for (int j = 0; j < 4; ++j) { if (sbf) xnb[r][j] = *(const u32x2*)(xsrcb + (m + 2 + r) * DM + 4 * lane + 256 * j); else xn[r][j] = *(const f32x4*)(xsrc + (m + 2 + r) * DM + 4 * lane + 256 * j); if (hasprev) yn[r][j] = *(const u32x2*)(Y + (m + 2 + r) * DM + 4 * lane + 256 * j); } }
;             if (hasprev) {
;                 f32x4 y[2][4]; float ss[2] = {0.f, 0.f};
; #pragma unroll
;                 for (int r = 0; r < 2; ++r)
; #pragma unroll
;                     for (int j = 0; j < 4; ++j) { const u32x2 u = yr[r][j]; y[r][j] = (f32x4){bflo(u.x), bfhi(u.x), bflo(u.y), bfhi(u.y)};
;                         ss[r] += (y[r][j].x * y[r][j].x + y[r][j].y * y[r][j].y) + (y[r][j].z * y[r][j].z + y[r][j].w * y[r][j].w); }
; #pragma unroll
;                 for (int off = 1; off < 64; off <<= 1) { ss[0] += __shfl_xor(ss[0], off); ss[1] += __shfl_xor(ss[1], off); }
; #pragma unroll
;                 for (int r = 0; r < 2; ++r) { const float rs = __builtin_amdgcn_rsqf(ss[r] * (1.f / DM) + EPS);
; #pragma unroll
;                     for (int j = 0; j < 4; ++j) x[r][j] = x[r][j] + gp[j] * (y[r][j] * rs); }
;             }
; #pragma unroll
;             for (int r = 0; r < 2; ++r)
; #pragma unroll
;                 for (int j = 0; j < 4; ++j) { if (hasprev) { if (dbf) { u32x2 w; w.x = cvtpk(x[r][j].x, x[r][j].y); w.y = cvtpk(x[r][j].z, x[r][j].w); *(u32x2*)(xdstb + (m + r) * DM + 4 * lane + 256 * j) = w; } else *(f32x4*)(xdst + (m + r) * DM + 4 * lane + 256 * j) = x[r][j]; } }
	v_lshlrev_b32_e32 v188, 16, v58
	v_and_b32_e32 v189, 0xffff0000, v58
	v_add_f32_dpp v208, v208, v208 row_half_mirror row_mask:0xf bank_mask:0xf
	v_lshlrev_b32_e32 v190, 16, v59
	v_and_b32_e32 v191, 0xffff0000, v59
	v_add_f32_dpp v208, v208, v208 row_mirror row_mask:0xf bank_mask:0xf
	v_lshlrev_b32_e32 v192, 16, v60
	v_and_b32_e32 v193, 0xffff0000, v60
	v_add_f32_dpp v208, v208, v208 row_bcast:15 row_mask:0xa bank_mask:0xf
	v_lshlrev_b32_e32 v194, 16, v61
	v_and_b32_e32 v195, 0xffff0000, v61
	v_add_f32_dpp v208, v208, v208 row_bcast:31 row_mask:0xc bank_mask:0xf
	v_lshlrev_b32_e32 v196, 16, v62
	v_and_b32_e32 v197, 0xffff0000, v62
	v_readlane_b32 s60, v208, 63
	s_nop 1
	v_lshlrev_b32_e32 v198, 16, v63
	v_and_b32_e32 v199, 0xffff0000, v63
	v_mov_b32_e32 v210, s60
	v_fmaak_f32 v210, v210, v212, 0x358637bd
	v_rsq_f32_e32 v210, v210
	s_nop 0
	v_lshlrev_b32_e32 v200, 16, v64
	v_and_b32_e32 v201, 0xffff0000, v64
	v_pk_mul_f32 v[200:201], v[200:201], v[210:211] op_sel_hi:[1,0]
	v_pk_fma_f32 v[184:185], v[8:9], v[200:201], v[184:185]
	v_lshlrev_b32_e32 v202, 16, v65
	v_and_b32_e32 v203, 0xffff0000, v65
	v_pk_mul_f32 v[202:203], v[202:203], v[210:211] op_sel_hi:[1,0]
	v_pk_fma_f32 v[186:187], v[10:11], v[202:203], v[186:187]
	v_lshlrev_b32_e32 v200, 16, v66
	v_and_b32_e32 v201, 0xffff0000, v66
	v_pk_mul_f32 v[200:201], v[200:201], v[210:211] op_sel_hi:[1,0]
	v_pk_fma_f32 v[188:189], v[12:13], v[200:201], v[188:189]
	v_lshlrev_b32_e32 v202, 16, v67
	v_and_b32_e32 v203, 0xffff0000, v67
	v_pk_mul_f32 v[202:203], v[202:203], v[210:211] op_sel_hi:[1,0]
	v_pk_fma_f32 v[190:191], v[14:15], v[202:203], v[190:191]
	v_lshlrev_b32_e32 v200, 16, v68
	v_and_b32_e32 v201, 0xffff0000, v68
	v_pk_mul_f32 v[200:201], v[200:201], v[210:211] op_sel_hi:[1,0]
	v_pk_fma_f32 v[192:193], v[16:17], v[200:201], v[192:193]
	v_lshlrev_b32_e32 v202, 16, v69
	v_and_b32_e32 v203, 0xffff0000, v69
	v_pk_mul_f32 v[202:203], v[202:203], v[210:211] op_sel_hi:[1,0]
	v_pk_fma_f32 v[194:195], v[18:19], v[202:203], v[194:195]
	v_lshlrev_b32_e32 v200, 16, v70
	v_and_b32_e32 v201, 0xffff0000, v70
	v_pk_mul_f32 v[200:201], v[200:201], v[210:211] op_sel_hi:[1,0]
	v_pk_fma_f32 v[196:197], v[20:21], v[200:201], v[196:197]
	v_lshlrev_b32_e32 v202, 16, v71
	v_and_b32_e32 v203, 0xffff0000, v71
	v_pk_mul_f32 v[202:203], v[202:203], v[210:211] op_sel_hi:[1,0]
	v_pk_fma_f32 v[198:199], v[22:23], v[202:203], v[198:199]
	s_add_i32 s81, s80, 0
	s_add_i32 s81, s81, s82
	s_and_b32 s81, s81, 31
	s_lshl_b32 s83, s81, 12
	v_add_u32_e32 v213, s83, v3
	global_store_dwordx4 v213, v[184:187], s[76:77] nt
	global_store_dwordx4 v213, v[188:191], s[76:77] offset:16 nt
	global_store_dwordx4 v213, v[192:195], s[76:77] offset:2048 nt
	global_store_dwordx4 v213, v[196:199], s[76:77] offset:2064 nt
	s_add_i32 s81, s80, 5
	s_add_i32 s81, s81, s82
	s_and_b32 s81, s81, 31
	s_lshl_b32 s83, s81, 11
	v_add_u32_e32 v2, s83, v1
	global_load_dwordx4 v[136:139], v2, s[72:73] nt
	global_load_dwordx4 v[140:143], v2, s[72:73] offset:1024 nt
	global_load_dwordx4 v[144:147], v2, s[74:75] nt
	global_load_dwordx4 v[148:151], v2, s[74:75] offset:1024 nt
	s_waitcnt vmcnt(20)
	v_lshlrev_b32_e32 v200, 16, v80
	v_and_b32_e32 v201, 0xffff0000, v80
	v_pk_mul_f32 v[204:205], v[200:201], v[200:201]
	v_lshlrev_b32_e32 v202, 16, v81
	v_and_b32_e32 v203, 0xffff0000, v81
	v_pk_mul_f32 v[206:207], v[202:203], v[202:203]
	v_lshlrev_b32_e32 v200, 16, v82
	v_and_b32_e32 v201, 0xffff0000, v82
	v_pk_fma_f32 v[204:205], v[200:201], v[200:201], v[204:205]
	v_lshlrev_b32_e32 v202, 16, v83
	v_and_b32_e32 v203, 0xffff0000, v83
	v_pk_fma_f32 v[206:207], v[202:203], v[202:203], v[206:207]
	v_lshlrev_b32_e32 v200, 16, v84
	v_and_b32_e32 v201, 0xffff0000, v84
	v_pk_fma_f32 v[204:205], v[200:201], v[200:201], v[204:205]
	v_lshlrev_b32_e32 v202, 16, v85
	v_and_b32_e32 v203, 0xffff0000, v85
	v_pk_fma_f32 v[206:207], v[202:203], v[202:203], v[206:207]
	v_lshlrev_b32_e32 v200, 16, v86
	v_and_b32_e32 v201, 0xffff0000, v86
	v_pk_fma_f32 v[204:205], v[200:201], v[200:201], v[204:205]
	v_lshlrev_b32_e32 v202, 16, v87
	v_and_b32_e32 v203, 0xffff0000, v87
	v_pk_fma_f32 v[206:207], v[202:203], v[202:203], v[206:207]
	v_pk_add_f32 v[204:205], v[204:205], v[206:207]
	v_add_f32_e32 v208, v204, v205
	v_lshlrev_b32_e32 v184, 16, v72
	v_and_b32_e32 v185, 0xffff0000, v72
	v_add_f32_dpp v208, v208, v208 quad_perm:[1,0,3,2] row_mask:0xf bank_mask:0xf
	v_lshlrev_b32_e32 v186, 16, v73
	v_and_b32_e32 v187, 0xffff0000, v73
	v_add_f32_dpp v208, v208, v208 quad_perm:[2,3,0,1] row_mask:0xf bank_mask:0xf
	v_lshlrev_b32_e32 v188, 16, v74
	v_and_b32_e32 v189, 0xffff0000, v74
	v_add_f32_dpp v208, v208, v208 row_half_mirror row_mask:0xf bank_mask:0xf
	v_lshlrev_b32_e32 v190, 16, v75
	v_and_b32_e32 v191, 0xffff0000, v75
	v_add_f32_dpp v208, v208, v208 row_mirror row_mask:0xf bank_mask:0xf
	v_lshlrev_b32_e32 v192, 16, v76
	v_and_b32_e32 v193, 0xffff0000, v76
	v_add_f32_dpp v208, v208, v208 row_bcast:15 row_mask:0xa bank_mask:0xf
	v_lshlrev_b32_e32 v194, 16, v77
	v_and_b32_e32 v195, 0xffff0000, v77
	v_add_f32_dpp v208, v208, v208 row_bcast:31 row_mask:0xc bank_mask:0xf
	v_lshlrev_b32_e32 v196, 16, v78
	v_and_b32_e32 v197, 0xffff0000, v78
	v_readlane_b32 s60, v208, 63
	s_nop 1
	v_lshlrev_b32_e32 v198, 16, v79
	v_and_b32_e32 v199, 0xffff0000, v79
	v_mov_b32_e32 v210, s60
	v_fmaak_f32 v210, v210, v212, 0x358637bd
	v_rsq_f32_e32 v210, v210
	s_nop 0
	v_lshlrev_b32_e32 v200, 16, v80
	v_and_b32_e32 v201, 0xffff0000, v80
	v_pk_mul_f32 v[200:201], v[200:201], v[210:211] op_sel_hi:[1,0]
	v_pk_fma_f32 v[184:185], v[8:9], v[200:201], v[184:185]
	v_lshlrev_b32_e32 v202, 16, v81
	v_and_b32_e32 v203, 0xffff0000, v81
; __device__ __forceinline__ float bflo(unsigned u) { return __uint_as_float(u << 16); }
; __device__ __forceinline__ void phase_rowwise(const void* xsrc_, bool sbf, void* xdst_, bool dbf, const bf16_t* Y, bf16_t* H, const float* mods, int lprev, int iprev, const float* lnpost, float resw, ...
;     ...
;         for (int rr = 0; rr < 32; rr += 2) {
;             const size_t m = (size_t)ch * 32 + rr;
;             f32x4 x[2][4]; u32x2 yr[2][4];
; #pragma unroll
;             for (int r = 0; r < 2; ++r)
; #pragma unroll
;                 for (int j = 0; j < 4; ++j) { if (sbf) { const u32x2 u = xnb[r][j]; x[r][j] = (f32x4){bflo(u.x), bfhi(u.x), bflo(u.y), bfhi(u.y)}; } else x[r][j] = xn[r][j]; yr[r][j] = yn[r][j]; }
;             if (rr + 2 < 32) {
; #pragma unroll
;                 for (int r = 0; r < 2; ++r)
; #pragma unroll
;                     for (int j = 0; j < 4; ++j) { if (sbf) xnb[r][j] = *(const u32x2*)(xsrcb + (m + 2 + r) * DM + 4 * lane + 256 * j); else xn[r][j] = *(const f32x4*)(xsrc + (m + 2 + r) * DM + 4 * lane + 256 * j); if (hasprev) yn[r][j] = *(const u32x2*)(Y + (m + 2 + r) * DM + 4 * lane + 256 * j); } }
;             if (hasprev) {
;                 f32x4 y[2][4]; float ss[2] = {0.f, 0.f};
; #pragma unroll
;                 for (int r = 0; r < 2; ++r)
; #pragma unroll
;                     for (int j = 0; j < 4; ++j) { const u32x2 u = yr[r][j]; y[r][j] = (f32x4){bflo(u.x), bfhi(u.x), bflo(u.y), bfhi(u.y)};
;                         ss[r] += (y[r][j].x * y[r][j].x + y[r][j].y * y[r][j].y) + (y[r][j].z * y[r][j].z + y[r][j].w * y[r][j].w); }
; #pragma unroll
;                 for (int off = 1; off < 64; off <<= 1) { ss[0] += __shfl_xor(ss[0], off); ss[1] += __shfl_xor(ss[1], off); }
; #pragma unroll
;                 for (int r = 0; r < 2; ++r) { const float rs = __builtin_amdgcn_rsqf(ss[r] * (1.f / DM) + EPS);
; #pragma unroll
;                     for (int j = 0; j < 4; ++j) x[r][j] = x[r][j] + gp[j] * (y[r][j] * rs); }
;             }
; #pragma unroll
;             for (int r = 0; r < 2; ++r)
; #pragma unroll
;                 for (int j = 0; j < 4; ++j) { if (hasprev) { if (dbf) { u32x2 w; w.x = cvtpk(x[r][j].x, x[r][j].y); w.y = cvtpk(x[r][j].z, x[r][j].w); *(u32x2*)(xdstb + (m + r) * DM + 4 * lane + 256 * j) = w; } else *(f32x4*)(xdst + (m + r) * DM + 4 * lane + 256 * j) = x[r][j]; } }
	v_pk_mul_f32 v[202:203], v[202:203], v[210:211] op_sel_hi:[1,0]
	v_pk_fma_f32 v[186:187], v[10:11], v[202:203], v[186:187]
	v_lshlrev_b32_e32 v200, 16, v82
	v_and_b32_e32 v201, 0xffff0000, v82
	v_pk_mul_f32 v[200:201], v[200:201], v[210:211] op_sel_hi:[1,0]
	v_pk_fma_f32 v[188:189], v[12:13], v[200:201], v[188:189]
	v_lshlrev_b32_e32 v202, 16, v83
	v_and_b32_e32 v203, 0xffff0000, v83
	v_pk_mul_f32 v[202:203], v[202:203], v[210:211] op_sel_hi:[1,0]
	v_pk_fma_f32 v[190:191], v[14:15], v[202:203], v[190:191]
	v_lshlrev_b32_e32 v200, 16, v84
	v_and_b32_e32 v201, 0xffff0000, v84
	v_pk_mul_f32 v[200:201], v[200:201], v[210:211] op_sel_hi:[1,0]
	v_pk_fma_f32 v[192:193], v[16:17], v[200:201], v[192:193]
	v_lshlrev_b32_e32 v202, 16, v85
	v_and_b32_e32 v203, 0xffff0000, v85
	v_pk_mul_f32 v[202:203], v[202:203], v[210:211] op_sel_hi:[1,0]
	v_pk_fma_f32 v[194:195], v[18:19], v[202:203], v[194:195]
	v_lshlrev_b32_e32 v200, 16, v86
	v_and_b32_e32 v201, 0xffff0000, v86
	v_pk_mul_f32 v[200:201], v[200:201], v[210:211] op_sel_hi:[1,0]
	v_pk_fma_f32 v[196:197], v[20:21], v[200:201], v[196:197]
	v_lshlrev_b32_e32 v202, 16, v87
	v_and_b32_e32 v203, 0xffff0000, v87
	v_pk_mul_f32 v[202:203], v[202:203], v[210:211] op_sel_hi:[1,0]
	v_pk_fma_f32 v[198:199], v[22:23], v[202:203], v[198:199]
	s_add_i32 s81, s80, 1
	s_add_i32 s81, s81, s82
	s_and_b32 s81, s81, 31
	s_lshl_b32 s83, s81, 12
	v_add_u32_e32 v213, s83, v3
	global_store_dwordx4 v213, v[184:187], s[76:77] nt
	global_store_dwordx4 v213, v[188:191], s[76:77] offset:16 nt
	global_store_dwordx4 v213, v[192:195], s[76:77] offset:2048 nt
	global_store_dwordx4 v213, v[196:199], s[76:77] offset:2064 nt
	s_add_i32 s81, s80, 6
	s_add_i32 s81, s81, s82
	s_and_b32 s81, s81, 31
	s_lshl_b32 s83, s81, 11
	v_add_u32_e32 v2, s83, v1
	global_load_dwordx4 v[152:155], v2, s[72:73] nt
	global_load_dwordx4 v[156:159], v2, s[72:73] offset:1024 nt
	global_load_dwordx4 v[160:163], v2, s[74:75] nt
	global_load_dwordx4 v[164:167], v2, s[74:75] offset:1024 nt
	s_waitcnt vmcnt(24)
	v_lshlrev_b32_e32 v200, 16, v96
	v_and_b32_e32 v201, 0xffff0000, v96
	v_pk_mul_f32 v[204:205], v[200:201], v[200:201]
	v_lshlrev_b32_e32 v202, 16, v97
	v_and_b32_e32 v203, 0xffff0000, v97
	v_pk_mul_f32 v[206:207], v[202:203], v[202:203]
	v_lshlrev_b32_e32 v200, 16, v98
	v_and_b32_e32 v201, 0xffff0000, v98
	v_pk_fma_f32 v[204:205], v[200:201], v[200:201], v[204:205]
	v_lshlrev_b32_e32 v202, 16, v99
	v_and_b32_e32 v203, 0xffff0000, v99
	v_pk_fma_f32 v[206:207], v[202:203], v[202:203], v[206:207]
	v_lshlrev_b32_e32 v200, 16, v100
	v_and_b32_e32 v201, 0xffff0000, v100
	v_pk_fma_f32 v[204:205], v[200:201], v[200:201], v[204:205]
	v_lshlrev_b32_e32 v202, 16, v101
	v_and_b32_e32 v203, 0xffff0000, v101
	v_pk_fma_f32 v[206:207], v[202:203], v[202:203], v[206:207]
	v_lshlrev_b32_e32 v200, 16, v102
	v_and_b32_e32 v201, 0xffff0000, v102
	v_pk_fma_f32 v[204:205], v[200:201], v[200:201], v[204:205]
	v_lshlrev_b32_e32 v202, 16, v103
	v_and_b32_e32 v203, 0xffff0000, v103
	v_pk_fma_f32 v[206:207], v[202:203], v[202:203], v[206:207]
	v_pk_add_f32 v[204:205], v[204:205], v[206:207]
	v_add_f32_e32 v208, v204, v205
	v_lshlrev_b32_e32 v184, 16, v88
	v_and_b32_e32 v185, 0xffff0000, v88
	v_add_f32_dpp v208, v208, v208 quad_perm:[1,0,3,2] row_mask:0xf bank_mask:0xf
	v_lshlrev_b32_e32 v186, 16, v89
	v_and_b32_e32 v187, 0xffff0000, v89
	v_add_f32_dpp v208, v208, v208 quad_perm:[2,3,0,1] row_mask:0xf bank_mask:0xf
	v_lshlrev_b32_e32 v188, 16, v90
	v_and_b32_e32 v189, 0xffff0000, v90
	v_add_f32_dpp v208, v208, v208 row_half_mirror row_mask:0xf bank_mask:0xf
	v_lshlrev_b32_e32 v190, 16, v91
	v_and_b32_e32 v191, 0xffff0000, v91
	v_add_f32_dpp v208, v208, v208 row_mirror row_mask:0xf bank_mask:0xf
	v_lshlrev_b32_e32 v192, 16, v92
	v_and_b32_e32 v193, 0xffff0000, v92
	v_add_f32_dpp v208, v208, v208 row_bcast:15 row_mask:0xa bank_mask:0xf
	v_lshlrev_b32_e32 v194, 16, v93
	v_and_b32_e32 v195, 0xffff0000, v93
	v_add_f32_dpp v208, v208, v208 row_bcast:31 row_mask:0xc bank_mask:0xf
	v_lshlrev_b32_e32 v196, 16, v94
	v_and_b32_e32 v197, 0xffff0000, v94
	v_readlane_b32 s60, v208, 63
	s_nop 1
	v_lshlrev_b32_e32 v198, 16, v95
	v_and_b32_e32 v199, 0xffff0000, v95
	v_mov_b32_e32 v210, s60
	v_fmaak_f32 v210, v210, v212, 0x358637bd
	v_rsq_f32_e32 v210, v210
	s_nop 0
	v_lshlrev_b32_e32 v200, 16, v96
	v_and_b32_e32 v201, 0xffff0000, v96
	v_pk_mul_f32 v[200:201], v[200:201], v[210:211] op_sel_hi:[1,0]
	v_pk_fma_f32 v[184:185], v[8:9], v[200:201], v[184:185]
	v_lshlrev_b32_e32 v202, 16, v97
	v_and_b32_e32 v203, 0xffff0000, v97
	v_pk_mul_f32 v[202:203], v[202:203], v[210:211] op_sel_hi:[1,0]
	v_pk_fma_f32 v[186:187], v[10:11], v[202:203], v[186:187]
	v_lshlrev_b32_e32 v200, 16, v98
	v_and_b32_e32 v201, 0xffff0000, v98
	v_pk_mul_f32 v[200:201], v[200:201], v[210:211] op_sel_hi:[1,0]
	v_pk_fma_f32 v[188:189], v[12:13], v[200:201], v[188:189]
	v_lshlrev_b32_e32 v202, 16, v99
	v_and_b32_e32 v203, 0xffff0000, v99
	v_pk_mul_f32 v[202:203], v[202:203], v[210:211] op_sel_hi:[1,0]
	v_pk_fma_f32 v[190:191], v[14:15], v[202:203], v[190:191]
	v_lshlrev_b32_e32 v200, 16, v100
	v_and_b32_e32 v201, 0xffff0000, v100
	v_pk_mul_f32 v[200:201], v[200:201], v[210:211] op_sel_hi:[1,0]
	v_pk_fma_f32 v[192:193], v[16:17], v[200:201], v[192:193]
	v_lshlrev_b32_e32 v202, 16, v101
	v_and_b32_e32 v203, 0xffff0000, v101
	v_pk_mul_f32 v[202:203], v[202:203], v[210:211] op_sel_hi:[1,0]
	v_pk_fma_f32 v[194:195], v[18:19], v[202:203], v[194:195]
	v_lshlrev_b32_e32 v200, 16, v102
	v_and_b32_e32 v201, 0xffff0000, v102
	v_pk_mul_f32 v[200:201], v[200:201], v[210:211] op_sel_hi:[1,0]
	v_pk_fma_f32 v[196:197], v[20:21], v[200:201], v[196:197]
	v_lshlrev_b32_e32 v202, 16, v103
	v_and_b32_e32 v203, 0xffff0000, v103
	v_pk_mul_f32 v[202:203], v[202:203], v[210:211] op_sel_hi:[1,0]
	v_pk_fma_f32 v[198:199], v[22:23], v[202:203], v[198:199]
	s_add_i32 s81, s80, 2
	s_add_i32 s81, s81, s82
	s_and_b32 s81, s81, 31
	s_lshl_b32 s83, s81, 12
	v_add_u32_e32 v213, s83, v3
	global_store_dwordx4 v213, v[184:187], s[76:77] nt
	global_store_dwordx4 v213, v[188:191], s[76:77] offset:16 nt
	global_store_dwordx4 v213, v[192:195], s[76:77] offset:2048 nt
	global_store_dwordx4 v213, v[196:199], s[76:77] offset:2064 nt
	s_add_i32 s81, s80, 7
	s_add_i32 s81, s81, s82
	s_and_b32 s81, s81, 31
	s_lshl_b32 s83, s81, 11
	v_add_u32_e32 v2, s83, v1
	global_load_dwordx4 v[56:59], v2, s[72:73] nt
	global_load_dwordx4 v[60:63], v2, s[72:73] offset:1024 nt
	global_load_dwordx4 v[64:67], v2, s[74:75] nt
	global_load_dwordx4 v[68:71], v2, s[74:75] offset:1024 nt
	s_waitcnt vmcnt(28)
; __device__ __forceinline__ float bflo(unsigned u) { return __uint_as_float(u << 16); }
; __device__ __forceinline__ void phase_rowwise(const void* xsrc_, bool sbf, void* xdst_, bool dbf, const bf16_t* Y, bf16_t* H, const float* mods, int lprev, int iprev, const float* lnpost, float resw, ...
;     ...
;         for (int rr = 0; rr < 32; rr += 2) {
;             const size_t m = (size_t)ch * 32 + rr;
;             f32x4 x[2][4]; u32x2 yr[2][4];
; #pragma unroll
;             for (int r = 0; r < 2; ++r)
; #pragma unroll
;                 for (int j = 0; j < 4; ++j) { if (sbf) { const u32x2 u = xnb[r][j]; x[r][j] = (f32x4){bflo(u.x), bfhi(u.x), bflo(u.y), bfhi(u.y)}; } else x[r][j] = xn[r][j]; yr[r][j] = yn[r][j]; }
;             if (rr + 2 < 32) {
; #pragma unroll
;                 for (int r = 0; r < 2; ++r)
; #pragma unroll
;                     for (int j = 0; j < 4; ++j) { if (sbf) xnb[r][j] = *(const u32x2*)(xsrcb + (m + 2 + r) * DM + 4 * lane + 256 * j); else xn[r][j] = *(const f32x4*)(xsrc + (m + 2 + r) * DM + 4 * lane + 256 * j); if (hasprev) yn[r][j] = *(const u32x2*)(Y + (m + 2 + r) * DM + 4 * lane + 256 * j); } }
;             if (hasprev) {
;                 f32x4 y[2][4]; float ss[2] = {0.f, 0.f};
; #pragma unroll
;                 for (int r = 0; r < 2; ++r)
; #pragma unroll
;                     for (int j = 0; j < 4; ++j) { const u32x2 u = yr[r][j]; y[r][j] = (f32x4){bflo(u.x), bfhi(u.x), bflo(u.y), bfhi(u.y)};
;                         ss[r] += (y[r][j].x * y[r][j].x + y[r][j].y * y[r][j].y) + (y[r][j].z * y[r][j].z + y[r][j].w * y[r][j].w); }
; #pragma unroll
;                 for (int off = 1; off < 64; off <<= 1) { ss[0] += __shfl_xor(ss[0], off); ss[1] += __shfl_xor(ss[1], off); }
; #pragma unroll
;                 for (int r = 0; r < 2; ++r) { const float rs = __builtin_amdgcn_rsqf(ss[r] * (1.f / DM) + EPS);
; #pragma unroll
;                     for (int j = 0; j < 4; ++j) x[r][j] = x[r][j] + gp[j] * (y[r][j] * rs); }
;             }
; #pragma unroll
;             for (int r = 0; r < 2; ++r)
; #pragma unroll
;                 for (int j = 0; j < 4; ++j) { if (hasprev) { if (dbf) { u32x2 w; w.x = cvtpk(x[r][j].x, x[r][j].y); w.y = cvtpk(x[r][j].z, x[r][j].w); *(u32x2*)(xdstb + (m + r) * DM + 4 * lane + 256 * j) = w; } else *(f32x4*)(xdst + (m + r) * DM + 4 * lane + 256 * j) = x[r][j]; } }
	v_lshlrev_b32_e32 v200, 16, v112
	v_and_b32_e32 v201, 0xffff0000, v112
	v_pk_mul_f32 v[204:205], v[200:201], v[200:201]
	v_lshlrev_b32_e32 v202, 16, v113
	v_and_b32_e32 v203, 0xffff0000, v113
	v_pk_mul_f32 v[206:207], v[202:203], v[202:203]
	v_lshlrev_b32_e32 v200, 16, v114
	v_and_b32_e32 v201, 0xffff0000, v114
	v_pk_fma_f32 v[204:205], v[200:201], v[200:201], v[204:205]
	v_lshlrev_b32_e32 v202, 16, v115
	v_and_b32_e32 v203, 0xffff0000, v115
	v_pk_fma_f32 v[206:207], v[202:203], v[202:203], v[206:207]
	v_lshlrev_b32_e32 v200, 16, v116
	v_and_b32_e32 v201, 0xffff0000, v116
	v_pk_fma_f32 v[204:205], v[200:201], v[200:201], v[204:205]
	v_lshlrev_b32_e32 v202, 16, v117
	v_and_b32_e32 v203, 0xffff0000, v117
	v_pk_fma_f32 v[206:207], v[202:203], v[202:203], v[206:207]
	v_lshlrev_b32_e32 v200, 16, v118
	v_and_b32_e32 v201, 0xffff0000, v118
	v_pk_fma_f32 v[204:205], v[200:201], v[200:201], v[204:205]
	v_lshlrev_b32_e32 v202, 16, v119
	v_and_b32_e32 v203, 0xffff0000, v119
	v_pk_fma_f32 v[206:207], v[202:203], v[202:203], v[206:207]
	v_pk_add_f32 v[204:205], v[204:205], v[206:207]
	v_add_f32_e32 v208, v204, v205
	v_lshlrev_b32_e32 v184, 16, v104
	v_and_b32_e32 v185, 0xffff0000, v104
	v_add_f32_dpp v208, v208, v208 quad_perm:[1,0,3,2] row_mask:0xf bank_mask:0xf
	v_lshlrev_b32_e32 v186, 16, v105
	v_and_b32_e32 v187, 0xffff0000, v105
	v_add_f32_dpp v208, v208, v208 quad_perm:[2,3,0,1] row_mask:0xf bank_mask:0xf
	v_lshlrev_b32_e32 v188, 16, v106
	v_and_b32_e32 v189, 0xffff0000, v106
	v_add_f32_dpp v208, v208, v208 row_half_mirror row_mask:0xf bank_mask:0xf
	v_lshlrev_b32_e32 v190, 16, v107
	v_and_b32_e32 v191, 0xffff0000, v107
	v_add_f32_dpp v208, v208, v208 row_mirror row_mask:0xf bank_mask:0xf
	v_lshlrev_b32_e32 v192, 16, v108
	v_and_b32_e32 v193, 0xffff0000, v108
	v_add_f32_dpp v208, v208, v208 row_bcast:15 row_mask:0xa bank_mask:0xf
	v_lshlrev_b32_e32 v194, 16, v109
	v_and_b32_e32 v195, 0xffff0000, v109
	v_add_f32_dpp v208, v208, v208 row_bcast:31 row_mask:0xc bank_mask:0xf
	v_lshlrev_b32_e32 v196, 16, v110
	v_and_b32_e32 v197, 0xffff0000, v110
	v_readlane_b32 s60, v208, 63
	s_nop 1
	v_lshlrev_b32_e32 v198, 16, v111
	v_and_b32_e32 v199, 0xffff0000, v111
	v_mov_b32_e32 v210, s60
	v_fmaak_f32 v210, v210, v212, 0x358637bd
	v_rsq_f32_e32 v210, v210
	s_nop 0
	v_lshlrev_b32_e32 v200, 16, v112
	v_and_b32_e32 v201, 0xffff0000, v112
	v_pk_mul_f32 v[200:201], v[200:201], v[210:211] op_sel_hi:[1,0]
	v_pk_fma_f32 v[184:185], v[8:9], v[200:201], v[184:185]
	v_lshlrev_b32_e32 v202, 16, v113
	v_and_b32_e32 v203, 0xffff0000, v113
	v_pk_mul_f32 v[202:203], v[202:203], v[210:211] op_sel_hi:[1,0]
	v_pk_fma_f32 v[186:187], v[10:11], v[202:203], v[186:187]
	v_lshlrev_b32_e32 v200, 16, v114
	v_and_b32_e32 v201, 0xffff0000, v114
	v_pk_mul_f32 v[200:201], v[200:201], v[210:211] op_sel_hi:[1,0]
	v_pk_fma_f32 v[188:189], v[12:13], v[200:201], v[188:189]
	v_lshlrev_b32_e32 v202, 16, v115
	v_and_b32_e32 v203, 0xffff0000, v115
	v_pk_mul_f32 v[202:203], v[202:203], v[210:211] op_sel_hi:[1,0]
	v_pk_fma_f32 v[190:191], v[14:15], v[202:203], v[190:191]
	v_lshlrev_b32_e32 v200, 16, v116
	v_and_b32_e32 v201, 0xffff0000, v116
	v_pk_mul_f32 v[200:201], v[200:201], v[210:211] op_sel_hi:[1,0]
	v_pk_fma_f32 v[192:193], v[16:17], v[200:201], v[192:193]
	v_lshlrev_b32_e32 v202, 16, v117
	v_and_b32_e32 v203, 0xffff0000, v117
	v_pk_mul_f32 v[202:203], v[202:203], v[210:211] op_sel_hi:[1,0]
	v_pk_fma_f32 v[194:195], v[18:19], v[202:203], v[194:195]
	v_lshlrev_b32_e32 v200, 16, v118
	v_and_b32_e32 v201, 0xffff0000, v118
	v_pk_mul_f32 v[200:201], v[200:201], v[210:211] op_sel_hi:[1,0]
	v_pk_fma_f32 v[196:197], v[20:21], v[200:201], v[196:197]
	v_lshlrev_b32_e32 v202, 16, v119
	v_and_b32_e32 v203, 0xffff0000, v119
	v_pk_mul_f32 v[202:203], v[202:203], v[210:211] op_sel_hi:[1,0]
	v_pk_fma_f32 v[198:199], v[22:23], v[202:203], v[198:199]
	s_add_i32 s81, s80, 3
	s_add_i32 s81, s81, s82
	s_and_b32 s81, s81, 31
	s_lshl_b32 s83, s81, 12
	v_add_u32_e32 v213, s83, v3
	global_store_dwordx4 v213, v[184:187], s[76:77] nt
	global_store_dwordx4 v213, v[188:191], s[76:77] offset:16 nt
	global_store_dwordx4 v213, v[192:195], s[76:77] offset:2048 nt
	global_store_dwordx4 v213, v[196:199], s[76:77] offset:2064 nt
	s_mov_b32 s82, 4

; __device__ __forceinline__ float bflo(unsigned u) { return __uint_as_float(u << 16); }
; __device__ __forceinline__ void phase_rowwise(const void* xsrc_, bool sbf, void* xdst_, bool dbf, const bf16_t* Y, bf16_t* H, const float* mods, int lprev, int iprev, const float* lnpost, float resw, ...
;     ...
;         for (int rr = 0; rr < 32; rr += 2) {
;             const size_t m = (size_t)ch * 32 + rr;
;             f32x4 x[2][4]; u32x2 yr[2][4];
; #pragma unroll
;             for (int r = 0; r < 2; ++r)
; #pragma unroll
;                 for (int j = 0; j < 4; ++j) { if (sbf) { const u32x2 u = xnb[r][j]; x[r][j] = (f32x4){bflo(u.x), bfhi(u.x), bflo(u.y), bfhi(u.y)}; } else x[r][j] = xn[r][j]; yr[r][j] = yn[r][j]; }
;             if (rr + 2 < 32) {
; #pragma unroll
;                 for (int r = 0; r < 2; ++r)
; #pragma unroll
;                     for (int j = 0; j < 4; ++j) { if (sbf) xnb[r][j] = *(const u32x2*)(xsrcb + (m + 2 + r) * DM + 4 * lane + 256 * j); else xn[r][j] = *(const f32x4*)(xsrc + (m + 2 + r) * DM + 4 * lane + 256 * j); if (hasprev) yn[r][j] = *(const u32x2*)(Y + (m + 2 + r) * DM + 4 * lane + 256 * j); } }
;             if (hasprev) {
;                 f32x4 y[2][4]; float ss[2] = {0.f, 0.f};
; #pragma unroll
;                 for (int r = 0; r < 2; ++r)
; #pragma unroll
;                     for (int j = 0; j < 4; ++j) { const u32x2 u = yr[r][j]; y[r][j] = (f32x4){bflo(u.x), bfhi(u.x), bflo(u.y), bfhi(u.y)};
;                         ss[r] += (y[r][j].x * y[r][j].x + y[r][j].y * y[r][j].y) + (y[r][j].z * y[r][j].z + y[r][j].w * y[r][j].w); }
; #pragma unroll
;                 for (int off = 1; off < 64; off <<= 1) { ss[0] += __shfl_xor(ss[0], off); ss[1] += __shfl_xor(ss[1], off); }
; #pragma unroll
;                 for (int r = 0; r < 2; ++r) { const float rs = __builtin_amdgcn_rsqf(ss[r] * (1.f / DM) + EPS);
; #pragma unroll
;                     for (int j = 0; j < 4; ++j) x[r][j] = x[r][j] + gp[j] * (y[r][j] * rs); }
;             }
; #pragma unroll
;             for (int r = 0; r < 2; ++r)
; #pragma unroll
;                 for (int j = 0; j < 4; ++j) { if (hasprev) { if (dbf) { u32x2 w; w.x = cvtpk(x[r][j].x, x[r][j].y); w.y = cvtpk(x[r][j].z, x[r][j].w); *(u32x2*)(xdstb + (m + r) * DM + 4 * lane + 256 * j) = w; } else *(f32x4*)(xdst + (m + r) * DM + 4 * lane + 256 * j) = x[r][j]; } }
.Lrw_LAST_l0_e:
	s_waitcnt vmcnt(32)
	v_lshlrev_b32_e32 v200, 16, v128
	v_and_b32_e32 v201, 0xffff0000, v128
	v_pk_mul_f32 v[204:205], v[200:201], v[200:201]
	v_lshlrev_b32_e32 v202, 16, v129
	v_and_b32_e32 v203, 0xffff0000, v129
	v_pk_mul_f32 v[206:207], v[202:203], v[202:203]
	v_lshlrev_b32_e32 v200, 16, v130
	v_and_b32_e32 v201, 0xffff0000, v130
	v_pk_fma_f32 v[204:205], v[200:201], v[200:201], v[204:205]
	v_lshlrev_b32_e32 v202, 16, v131
	v_and_b32_e32 v203, 0xffff0000, v131
	v_pk_fma_f32 v[206:207], v[202:203], v[202:203], v[206:207]
	v_lshlrev_b32_e32 v200, 16, v132
	v_and_b32_e32 v201, 0xffff0000, v132
	v_pk_fma_f32 v[204:205], v[200:201], v[200:201], v[204:205]
	v_lshlrev_b32_e32 v202, 16, v133
	v_and_b32_e32 v203, 0xffff0000, v133
	v_pk_fma_f32 v[206:207], v[202:203], v[202:203], v[206:207]
	v_lshlrev_b32_e32 v200, 16, v134
	v_and_b32_e32 v201, 0xffff0000, v134
	v_pk_fma_f32 v[204:205], v[200:201], v[200:201], v[204:205]
	v_lshlrev_b32_e32 v202, 16, v135
	v_and_b32_e32 v203, 0xffff0000, v135
	v_pk_fma_f32 v[206:207], v[202:203], v[202:203], v[206:207]
	v_pk_add_f32 v[204:205], v[204:205], v[206:207]
	v_add_f32_e32 v208, v204, v205
	v_lshlrev_b32_e32 v184, 16, v120
	v_and_b32_e32 v185, 0xffff0000, v120
	v_add_f32_dpp v208, v208, v208 quad_perm:[1,0,3,2] row_mask:0xf bank_mask:0xf
	v_lshlrev_b32_e32 v186, 16, v121
	v_and_b32_e32 v187, 0xffff0000, v121
	v_add_f32_dpp v208, v208, v208 quad_perm:[2,3,0,1] row_mask:0xf bank_mask:0xf
	v_lshlrev_b32_e32 v188, 16, v122
	v_and_b32_e32 v189, 0xffff0000, v122
	v_add_f32_dpp v208, v208, v208 row_half_mirror row_mask:0xf bank_mask:0xf
	v_lshlrev_b32_e32 v190, 16, v123
	v_and_b32_e32 v191, 0xffff0000, v123
	v_add_f32_dpp v208, v208, v208 row_mirror row_mask:0xf bank_mask:0xf
	v_lshlrev_b32_e32 v192, 16, v124
	v_and_b32_e32 v193, 0xffff0000, v124
	v_add_f32_dpp v208, v208, v208 row_bcast:15 row_mask:0xa bank_mask:0xf
	v_lshlrev_b32_e32 v194, 16, v125
	v_and_b32_e32 v195, 0xffff0000, v125
	v_add_f32_dpp v208, v208, v208 row_bcast:31 row_mask:0xc bank_mask:0xf
	v_lshlrev_b32_e32 v196, 16, v126
	v_and_b32_e32 v197, 0xffff0000, v126
	v_readlane_b32 s60, v208, 63
	s_nop 1
	v_lshlrev_b32_e32 v198, 16, v127
	v_and_b32_e32 v199, 0xffff0000, v127
	v_mov_b32_e32 v210, s60
	v_fmaak_f32 v210, v210, v212, 0x358637bd
	v_rsq_f32_e32 v210, v210
	s_nop 0
	v_lshlrev_b32_e32 v200, 16, v128
	v_and_b32_e32 v201, 0xffff0000, v128
	v_pk_mul_f32 v[200:201], v[200:201], v[210:211] op_sel_hi:[1,0]
	v_pk_fma_f32 v[184:185], v[8:9], v[200:201], v[184:185]
	v_lshlrev_b32_e32 v202, 16, v129
	v_and_b32_e32 v203, 0xffff0000, v129
	v_pk_mul_f32 v[202:203], v[202:203], v[210:211] op_sel_hi:[1,0]
	v_pk_fma_f32 v[186:187], v[10:11], v[202:203], v[186:187]
	v_lshlrev_b32_e32 v200, 16, v130
	v_and_b32_e32 v201, 0xffff0000, v130
	v_pk_mul_f32 v[200:201], v[200:201], v[210:211] op_sel_hi:[1,0]
	v_pk_fma_f32 v[188:189], v[12:13], v[200:201], v[188:189]
	v_lshlrev_b32_e32 v202, 16, v131
	v_and_b32_e32 v203, 0xffff0000, v131
	v_pk_mul_f32 v[202:203], v[202:203], v[210:211] op_sel_hi:[1,0]
	v_pk_fma_f32 v[190:191], v[14:15], v[202:203], v[190:191]
	v_lshlrev_b32_e32 v200, 16, v132
	v_and_b32_e32 v201, 0xffff0000, v132
	v_pk_mul_f32 v[200:201], v[200:201], v[210:211] op_sel_hi:[1,0]
	v_pk_fma_f32 v[192:193], v[16:17], v[200:201], v[192:193]
	v_lshlrev_b32_e32 v202, 16, v133
	v_and_b32_e32 v203, 0xffff0000, v133
	v_pk_mul_f32 v[202:203], v[202:203], v[210:211] op_sel_hi:[1,0]
	v_pk_fma_f32 v[194:195], v[18:19], v[202:203], v[194:195]
	v_lshlrev_b32_e32 v200, 16, v134
	v_and_b32_e32 v201, 0xffff0000, v134
	v_pk_mul_f32 v[200:201], v[200:201], v[210:211] op_sel_hi:[1,0]
	v_pk_fma_f32 v[196:197], v[20:21], v[200:201], v[196:197]
	v_lshlrev_b32_e32 v202, 16, v135
	v_and_b32_e32 v203, 0xffff0000, v135
	v_pk_mul_f32 v[202:203], v[202:203], v[210:211] op_sel_hi:[1,0]
	v_pk_fma_f32 v[198:199], v[22:23], v[202:203], v[198:199]
	s_add_i32 s81, s80, 0
	s_add_i32 s81, s81, s82
	s_and_b32 s81, s81, 31
	s_lshl_b32 s83, s81, 12
	v_add_u32_e32 v213, s83, v3
	global_store_dwordx4 v213, v[184:187], s[76:77] nt
	global_store_dwordx4 v213, v[188:191], s[76:77] offset:16 nt
	global_store_dwordx4 v213, v[192:195], s[76:77] offset:2048 nt
	global_store_dwordx4 v213, v[196:199], s[76:77] offset:2064 nt
	s_add_i32 s81, s82, 5
	s_cmp_lt_u32 s81, 32
	s_cbranch_scc0 .Lrw_LAST_l1_d
	s_add_i32 s81, s80, 5
	s_add_i32 s81, s81, s82
	s_and_b32 s81, s81, 31
	s_lshl_b32 s83, s81, 11
	v_add_u32_e32 v2, s83, v1
	global_load_dwordx4 v[88:91], v2, s[72:73] nt
	global_load_dwordx4 v[92:95], v2, s[72:73] offset:1024 nt
	global_load_dwordx4 v[96:99], v2, s[74:75] nt
	global_load_dwordx4 v[100:103], v2, s[74:75] offset:1024 nt
	s_branch .Lrw_LAST_l1_e

; __device__ __forceinline__ float bflo(unsigned u) { return __uint_as_float(u << 16); }
; __device__ __forceinline__ void phase_rowwise(const void* xsrc_, bool sbf, void* xdst_, bool dbf, const bf16_t* Y, bf16_t* H, const float* mods, int lprev, int iprev, const float* lnpost, float resw, ...
;     ...
;         for (int rr = 0; rr < 32; rr += 2) {
;             const size_t m = (size_t)ch * 32 + rr;
;             f32x4 x[2][4]; u32x2 yr[2][4];
; #pragma unroll
;             for (int r = 0; r < 2; ++r)
; #pragma unroll
;                 for (int j = 0; j < 4; ++j) { if (sbf) { const u32x2 u = xnb[r][j]; x[r][j] = (f32x4){bflo(u.x), bfhi(u.x), bflo(u.y), bfhi(u.y)}; } else x[r][j] = xn[r][j]; yr[r][j] = yn[r][j]; }
;             if (rr + 2 < 32) {
; #pragma unroll
;                 for (int r = 0; r < 2; ++r)
; #pragma unroll
;                     for (int j = 0; j < 4; ++j) { if (sbf) xnb[r][j] = *(const u32x2*)(xsrcb + (m + 2 + r) * DM + 4 * lane + 256 * j); else xn[r][j] = *(const f32x4*)(xsrc + (m + 2 + r) * DM + 4 * lane + 256 * j); if (hasprev) yn[r][j] = *(const u32x2*)(Y + (m + 2 + r) * DM + 4 * lane + 256 * j); } }
;             if (hasprev) {
;                 f32x4 y[2][4]; float ss[2] = {0.f, 0.f};
; #pragma unroll
;                 for (int r = 0; r < 2; ++r)
; #pragma unroll
;                     for (int j = 0; j < 4; ++j) { const u32x2 u = yr[r][j]; y[r][j] = (f32x4){bflo(u.x), bfhi(u.x), bflo(u.y), bfhi(u.y)};
;                         ss[r] += (y[r][j].x * y[r][j].x + y[r][j].y * y[r][j].y) + (y[r][j].z * y[r][j].z + y[r][j].w * y[r][j].w); }
; #pragma unroll
;                 for (int off = 1; off < 64; off <<= 1) { ss[0] += __shfl_xor(ss[0], off); ss[1] += __shfl_xor(ss[1], off); }
; #pragma unroll
;                 for (int r = 0; r < 2; ++r) { const float rs = __builtin_amdgcn_rsqf(ss[r] * (1.f / DM) + EPS);
; #pragma unroll
;                     for (int j = 0; j < 4; ++j) x[r][j] = x[r][j] + gp[j] * (y[r][j] * rs); }
;             }
; #pragma unroll
;             for (int r = 0; r < 2; ++r)
; #pragma unroll
;                 for (int j = 0; j < 4; ++j) { if (hasprev) { if (dbf) { u32x2 w; w.x = cvtpk(x[r][j].x, x[r][j].y); w.y = cvtpk(x[r][j].z, x[r][j].w); *(u32x2*)(xdstb + (m + r) * DM + 4 * lane + 256 * j) = w; } else *(f32x4*)(xdst + (m + r) * DM + 4 * lane + 256 * j) = x[r][j]; } }
.Lrw_LAST_l1_e:
	s_waitcnt vmcnt(32)
	v_lshlrev_b32_e32 v200, 16, v144
	v_and_b32_e32 v201, 0xffff0000, v144
	v_pk_mul_f32 v[204:205], v[200:201], v[200:201]
	v_lshlrev_b32_e32 v202, 16, v145
	v_and_b32_e32 v203, 0xffff0000, v145
	v_pk_mul_f32 v[206:207], v[202:203], v[202:203]
	v_lshlrev_b32_e32 v200, 16, v146
	v_and_b32_e32 v201, 0xffff0000, v146
	v_pk_fma_f32 v[204:205], v[200:201], v[200:201], v[204:205]
	v_lshlrev_b32_e32 v202, 16, v147
	v_and_b32_e32 v203, 0xffff0000, v147
	v_pk_fma_f32 v[206:207], v[202:203], v[202:203], v[206:207]
	v_lshlrev_b32_e32 v200, 16, v148
	v_and_b32_e32 v201, 0xffff0000, v148
	v_pk_fma_f32 v[204:205], v[200:201], v[200:201], v[204:205]
	v_lshlrev_b32_e32 v202, 16, v149
	v_and_b32_e32 v203, 0xffff0000, v149
	v_pk_fma_f32 v[206:207], v[202:203], v[202:203], v[206:207]
	v_lshlrev_b32_e32 v200, 16, v150
	v_and_b32_e32 v201, 0xffff0000, v150
	v_pk_fma_f32 v[204:205], v[200:201], v[200:201], v[204:205]
	v_lshlrev_b32_e32 v202, 16, v151
	v_and_b32_e32 v203, 0xffff0000, v151
	v_pk_fma_f32 v[206:207], v[202:203], v[202:203], v[206:207]
	v_pk_add_f32 v[204:205], v[204:205], v[206:207]
	v_add_f32_e32 v208, v204, v205
	v_lshlrev_b32_e32 v184, 16, v136
	v_and_b32_e32 v185, 0xffff0000, v136
	v_add_f32_dpp v208, v208, v208 quad_perm:[1,0,3,2] row_mask:0xf bank_mask:0xf
	v_lshlrev_b32_e32 v186, 16, v137
	v_and_b32_e32 v187, 0xffff0000, v137
	v_add_f32_dpp v208, v208, v208 quad_perm:[2,3,0,1] row_mask:0xf bank_mask:0xf
	v_lshlrev_b32_e32 v188, 16, v138
	v_and_b32_e32 v189, 0xffff0000, v138
	v_add_f32_dpp v208, v208, v208 row_half_mirror row_mask:0xf bank_mask:0xf
	v_lshlrev_b32_e32 v190, 16, v139
	v_and_b32_e32 v191, 0xffff0000, v139
	v_add_f32_dpp v208, v208, v208 row_mirror row_mask:0xf bank_mask:0xf
	v_lshlrev_b32_e32 v192, 16, v140
	v_and_b32_e32 v193, 0xffff0000, v140
	v_add_f32_dpp v208, v208, v208 row_bcast:15 row_mask:0xa bank_mask:0xf
	v_lshlrev_b32_e32 v194, 16, v141
	v_and_b32_e32 v195, 0xffff0000, v141
	v_add_f32_dpp v208, v208, v208 row_bcast:31 row_mask:0xc bank_mask:0xf
	v_lshlrev_b32_e32 v196, 16, v142
	v_and_b32_e32 v197, 0xffff0000, v142
	v_readlane_b32 s60, v208, 63
	s_nop 1
	v_lshlrev_b32_e32 v198, 16, v143
	v_and_b32_e32 v199, 0xffff0000, v143
	v_mov_b32_e32 v210, s60
	v_fmaak_f32 v210, v210, v212, 0x358637bd
	v_rsq_f32_e32 v210, v210
	s_nop 0
	v_lshlrev_b32_e32 v200, 16, v144
	v_and_b32_e32 v201, 0xffff0000, v144
	v_pk_mul_f32 v[200:201], v[200:201], v[210:211] op_sel_hi:[1,0]
	v_pk_fma_f32 v[184:185], v[8:9], v[200:201], v[184:185]
	v_lshlrev_b32_e32 v202, 16, v145
	v_and_b32_e32 v203, 0xffff0000, v145
	v_pk_mul_f32 v[202:203], v[202:203], v[210:211] op_sel_hi:[1,0]
	v_pk_fma_f32 v[186:187], v[10:11], v[202:203], v[186:187]
	v_lshlrev_b32_e32 v200, 16, v146
	v_and_b32_e32 v201, 0xffff0000, v146
	v_pk_mul_f32 v[200:201], v[200:201], v[210:211] op_sel_hi:[1,0]
	v_pk_fma_f32 v[188:189], v[12:13], v[200:201], v[188:189]
	v_lshlrev_b32_e32 v202, 16, v147
	v_and_b32_e32 v203, 0xffff0000, v147
	v_pk_mul_f32 v[202:203], v[202:203], v[210:211] op_sel_hi:[1,0]
	v_pk_fma_f32 v[190:191], v[14:15], v[202:203], v[190:191]
	v_lshlrev_b32_e32 v200, 16, v148
	v_and_b32_e32 v201, 0xffff0000, v148
	v_pk_mul_f32 v[200:201], v[200:201], v[210:211] op_sel_hi:[1,0]
	v_pk_fma_f32 v[192:193], v[16:17], v[200:201], v[192:193]
	v_lshlrev_b32_e32 v202, 16, v149
	v_and_b32_e32 v203, 0xffff0000, v149
	v_pk_mul_f32 v[202:203], v[202:203], v[210:211] op_sel_hi:[1,0]
	v_pk_fma_f32 v[194:195], v[18:19], v[202:203], v[194:195]
	v_lshlrev_b32_e32 v200, 16, v150
	v_and_b32_e32 v201, 0xffff0000, v150
	v_pk_mul_f32 v[200:201], v[200:201], v[210:211] op_sel_hi:[1,0]
	v_pk_fma_f32 v[196:197], v[20:21], v[200:201], v[196:197]
	v_lshlrev_b32_e32 v202, 16, v151
	v_and_b32_e32 v203, 0xffff0000, v151
	v_pk_mul_f32 v[202:203], v[202:203], v[210:211] op_sel_hi:[1,0]
	v_pk_fma_f32 v[198:199], v[22:23], v[202:203], v[198:199]
	s_add_i32 s81, s80, 1
	s_add_i32 s81, s81, s82
	s_and_b32 s81, s81, 31
	s_lshl_b32 s83, s81, 12
	v_add_u32_e32 v213, s83, v3
	global_store_dwordx4 v213, v[184:187], s[76:77] nt
	global_store_dwordx4 v213, v[188:191], s[76:77] offset:16 nt
	global_store_dwordx4 v213, v[192:195], s[76:77] offset:2048 nt
	global_store_dwordx4 v213, v[196:199], s[76:77] offset:2064 nt
	s_add_i32 s81, s82, 6
	s_cmp_lt_u32 s81, 32
	s_cbranch_scc0 .Lrw_LAST_l2_d
	s_add_i32 s81, s80, 6
	s_add_i32 s81, s81, s82
	s_and_b32 s81, s81, 31
	s_lshl_b32 s83, s81, 11
	v_add_u32_e32 v2, s83, v1
	global_load_dwordx4 v[104:107], v2, s[72:73] nt
	global_load_dwordx4 v[108:111], v2, s[72:73] offset:1024 nt
	global_load_dwordx4 v[112:115], v2, s[74:75] nt
	global_load_dwordx4 v[116:119], v2, s[74:75] offset:1024 nt
	s_branch .Lrw_LAST_l2_e

; __device__ __forceinline__ float bflo(unsigned u) { return __uint_as_float(u << 16); }
; __device__ __forceinline__ void phase_rowwise(const void* xsrc_, bool sbf, void* xdst_, bool dbf, const bf16_t* Y, bf16_t* H, const float* mods, int lprev, int iprev, const float* lnpost, float resw, ...
;     ...
;         for (int rr = 0; rr < 32; rr += 2) {
;             const size_t m = (size_t)ch * 32 + rr;
;             f32x4 x[2][4]; u32x2 yr[2][4];
; #pragma unroll
;             for (int r = 0; r < 2; ++r)
; #pragma unroll
;                 for (int j = 0; j < 4; ++j) { if (sbf) { const u32x2 u = xnb[r][j]; x[r][j] = (f32x4){bflo(u.x), bfhi(u.x), bflo(u.y), bfhi(u.y)}; } else x[r][j] = xn[r][j]; yr[r][j] = yn[r][j]; }
;             if (rr + 2 < 32) {
; #pragma unroll
;                 for (int r = 0; r < 2; ++r)
; #pragma unroll
;                     for (int j = 0; j < 4; ++j) { if (sbf) xnb[r][j] = *(const u32x2*)(xsrcb + (m + 2 + r) * DM + 4 * lane + 256 * j); else xn[r][j] = *(const f32x4*)(xsrc + (m + 2 + r) * DM + 4 * lane + 256 * j); if (hasprev) yn[r][j] = *(const u32x2*)(Y + (m + 2 + r) * DM + 4 * lane + 256 * j); } }
;             if (hasprev) {
;                 f32x4 y[2][4]; float ss[2] = {0.f, 0.f};
; #pragma unroll
;                 for (int r = 0; r < 2; ++r)
; #pragma unroll
;                     for (int j = 0; j < 4; ++j) { const u32x2 u = yr[r][j]; y[r][j] = (f32x4){bflo(u.x), bfhi(u.x), bflo(u.y), bfhi(u.y)};
;                         ss[r] += (y[r][j].x * y[r][j].x + y[r][j].y * y[r][j].y) + (y[r][j].z * y[r][j].z + y[r][j].w * y[r][j].w); }
; #pragma unroll
;                 for (int off = 1; off < 64; off <<= 1) { ss[0] += __shfl_xor(ss[0], off); ss[1] += __shfl_xor(ss[1], off); }
; #pragma unroll
;                 for (int r = 0; r < 2; ++r) { const float rs = __builtin_amdgcn_rsqf(ss[r] * (1.f / DM) + EPS);
; #pragma unroll
;                     for (int j = 0; j < 4; ++j) x[r][j] = x[r][j] + gp[j] * (y[r][j] * rs); }
;             }
; #pragma unroll
;             for (int r = 0; r < 2; ++r)
; #pragma unroll
;                 for (int j = 0; j < 4; ++j) { if (hasprev) { if (dbf) { u32x2 w; w.x = cvtpk(x[r][j].x, x[r][j].y); w.y = cvtpk(x[r][j].z, x[r][j].w); *(u32x2*)(xdstb + (m + r) * DM + 4 * lane + 256 * j) = w; } else *(f32x4*)(xdst + (m + r) * DM + 4 * lane + 256 * j) = x[r][j]; } }
.Lrw_LAST_l2_e:
	s_waitcnt vmcnt(32)
	v_lshlrev_b32_e32 v200, 16, v160
	v_and_b32_e32 v201, 0xffff0000, v160
	v_pk_mul_f32 v[204:205], v[200:201], v[200:201]
	v_lshlrev_b32_e32 v202, 16, v161
	v_and_b32_e32 v203, 0xffff0000, v161
	v_pk_mul_f32 v[206:207], v[202:203], v[202:203]
	v_lshlrev_b32_e32 v200, 16, v162
	v_and_b32_e32 v201, 0xffff0000, v162
	v_pk_fma_f32 v[204:205], v[200:201], v[200:201], v[204:205]
	v_lshlrev_b32_e32 v202, 16, v163
	v_and_b32_e32 v203, 0xffff0000, v163
	v_pk_fma_f32 v[206:207], v[202:203], v[202:203], v[206:207]
	v_lshlrev_b32_e32 v200, 16, v164
	v_and_b32_e32 v201, 0xffff0000, v164
	v_pk_fma_f32 v[204:205], v[200:201], v[200:201], v[204:205]
	v_lshlrev_b32_e32 v202, 16, v165
	v_and_b32_e32 v203, 0xffff0000, v165
	v_pk_fma_f32 v[206:207], v[202:203], v[202:203], v[206:207]
	v_lshlrev_b32_e32 v200, 16, v166
	v_and_b32_e32 v201, 0xffff0000, v166
	v_pk_fma_f32 v[204:205], v[200:201], v[200:201], v[204:205]
	v_lshlrev_b32_e32 v202, 16, v167
	v_and_b32_e32 v203, 0xffff0000, v167
	v_pk_fma_f32 v[206:207], v[202:203], v[202:203], v[206:207]
	v_pk_add_f32 v[204:205], v[204:205], v[206:207]
	v_add_f32_e32 v208, v204, v205
	v_lshlrev_b32_e32 v184, 16, v152
	v_and_b32_e32 v185, 0xffff0000, v152
	v_add_f32_dpp v208, v208, v208 quad_perm:[1,0,3,2] row_mask:0xf bank_mask:0xf
	v_lshlrev_b32_e32 v186, 16, v153
	v_and_b32_e32 v187, 0xffff0000, v153
	v_add_f32_dpp v208, v208, v208 quad_perm:[2,3,0,1] row_mask:0xf bank_mask:0xf
	v_lshlrev_b32_e32 v188, 16, v154
	v_and_b32_e32 v189, 0xffff0000, v154
	v_add_f32_dpp v208, v208, v208 row_half_mirror row_mask:0xf bank_mask:0xf
	v_lshlrev_b32_e32 v190, 16, v155
	v_and_b32_e32 v191, 0xffff0000, v155
	v_add_f32_dpp v208, v208, v208 row_mirror row_mask:0xf bank_mask:0xf
	v_lshlrev_b32_e32 v192, 16, v156
	v_and_b32_e32 v193, 0xffff0000, v156
	v_add_f32_dpp v208, v208, v208 row_bcast:15 row_mask:0xa bank_mask:0xf
	v_lshlrev_b32_e32 v194, 16, v157
	v_and_b32_e32 v195, 0xffff0000, v157
	v_add_f32_dpp v208, v208, v208 row_bcast:31 row_mask:0xc bank_mask:0xf
	v_lshlrev_b32_e32 v196, 16, v158
	v_and_b32_e32 v197, 0xffff0000, v158
	v_readlane_b32 s60, v208, 63
	s_nop 1
	v_lshlrev_b32_e32 v198, 16, v159
	v_and_b32_e32 v199, 0xffff0000, v159
	v_mov_b32_e32 v210, s60
	v_fmaak_f32 v210, v210, v212, 0x358637bd
	v_rsq_f32_e32 v210, v210
	s_nop 0
	v_lshlrev_b32_e32 v200, 16, v160
	v_and_b32_e32 v201, 0xffff0000, v160
	v_pk_mul_f32 v[200:201], v[200:201], v[210:211] op_sel_hi:[1,0]
	v_pk_fma_f32 v[184:185], v[8:9], v[200:201], v[184:185]
	v_lshlrev_b32_e32 v202, 16, v161
	v_and_b32_e32 v203, 0xffff0000, v161
	v_pk_mul_f32 v[202:203], v[202:203], v[210:211] op_sel_hi:[1,0]
	v_pk_fma_f32 v[186:187], v[10:11], v[202:203], v[186:187]
	v_lshlrev_b32_e32 v200, 16, v162
	v_and_b32_e32 v201, 0xffff0000, v162
	v_pk_mul_f32 v[200:201], v[200:201], v[210:211] op_sel_hi:[1,0]
	v_pk_fma_f32 v[188:189], v[12:13], v[200:201], v[188:189]
	v_lshlrev_b32_e32 v202, 16, v163
	v_and_b32_e32 v203, 0xffff0000, v163
	v_pk_mul_f32 v[202:203], v[202:203], v[210:211] op_sel_hi:[1,0]
	v_pk_fma_f32 v[190:191], v[14:15], v[202:203], v[190:191]
	v_lshlrev_b32_e32 v200, 16, v164
	v_and_b32_e32 v201, 0xffff0000, v164
	v_pk_mul_f32 v[200:201], v[200:201], v[210:211] op_sel_hi:[1,0]
	v_pk_fma_f32 v[192:193], v[16:17], v[200:201], v[192:193]
	v_lshlrev_b32_e32 v202, 16, v165
	v_and_b32_e32 v203, 0xffff0000, v165
	v_pk_mul_f32 v[202:203], v[202:203], v[210:211] op_sel_hi:[1,0]
	v_pk_fma_f32 v[194:195], v[18:19], v[202:203], v[194:195]
	v_lshlrev_b32_e32 v200, 16, v166
	v_and_b32_e32 v201, 0xffff0000, v166
	v_pk_mul_f32 v[200:201], v[200:201], v[210:211] op_sel_hi:[1,0]
	v_pk_fma_f32 v[196:197], v[20:21], v[200:201], v[196:197]
	v_lshlrev_b32_e32 v202, 16, v167
	v_and_b32_e32 v203, 0xffff0000, v167
	v_pk_mul_f32 v[202:203], v[202:203], v[210:211] op_sel_hi:[1,0]
	v_pk_fma_f32 v[198:199], v[22:23], v[202:203], v[198:199]
	s_add_i32 s81, s80, 2
	s_add_i32 s81, s81, s82
	s_and_b32 s81, s81, 31
	s_lshl_b32 s83, s81, 12
	v_add_u32_e32 v213, s83, v3
	global_store_dwordx4 v213, v[184:187], s[76:77] nt
	global_store_dwordx4 v213, v[188:191], s[76:77] offset:16 nt
	global_store_dwordx4 v213, v[192:195], s[76:77] offset:2048 nt
	global_store_dwordx4 v213, v[196:199], s[76:77] offset:2064 nt
	s_add_i32 s81, s82, 7
	s_cmp_lt_u32 s81, 32
	s_cbranch_scc0 .Lrw_LAST_l3_d
	s_add_i32 s81, s80, 7
	s_add_i32 s81, s81, s82
	s_and_b32 s81, s81, 31
	s_lshl_b32 s83, s81, 11
	v_add_u32_e32 v2, s83, v1
	global_load_dwordx4 v[120:123], v2, s[72:73] nt
	global_load_dwordx4 v[124:127], v2, s[72:73] offset:1024 nt
	global_load_dwordx4 v[128:131], v2, s[74:75] nt
	global_load_dwordx4 v[132:135], v2, s[74:75] offset:1024 nt
	s_branch .Lrw_LAST_l3_e

; __device__ __forceinline__ float bflo(unsigned u) { return __uint_as_float(u << 16); }
; __device__ __forceinline__ void phase_rowwise(const void* xsrc_, bool sbf, void* xdst_, bool dbf, const bf16_t* Y, bf16_t* H, const float* mods, int lprev, int iprev, const float* lnpost, float resw, ...
;     ...
;         for (int rr = 0; rr < 32; rr += 2) {
;             const size_t m = (size_t)ch * 32 + rr;
;             f32x4 x[2][4]; u32x2 yr[2][4];
; #pragma unroll
;             for (int r = 0; r < 2; ++r)
; #pragma unroll
;                 for (int j = 0; j < 4; ++j) { if (sbf) { const u32x2 u = xnb[r][j]; x[r][j] = (f32x4){bflo(u.x), bfhi(u.x), bflo(u.y), bfhi(u.y)}; } else x[r][j] = xn[r][j]; yr[r][j] = yn[r][j]; }
;             if (rr + 2 < 32) {
; #pragma unroll
;                 for (int r = 0; r < 2; ++r)
; #pragma unroll
;                     for (int j = 0; j < 4; ++j) { if (sbf) xnb[r][j] = *(const u32x2*)(xsrcb + (m + 2 + r) * DM + 4 * lane + 256 * j); else xn[r][j] = *(const f32x4*)(xsrc + (m + 2 + r) * DM + 4 * lane + 256 * j); if (hasprev) yn[r][j] = *(const u32x2*)(Y + (m + 2 + r) * DM + 4 * lane + 256 * j); } }
;             if (hasprev) {
;                 f32x4 y[2][4]; float ss[2] = {0.f, 0.f};
; #pragma unroll
;                 for (int r = 0; r < 2; ++r)
; #pragma unroll
;                     for (int j = 0; j < 4; ++j) { const u32x2 u = yr[r][j]; y[r][j] = (f32x4){bflo(u.x), bfhi(u.x), bflo(u.y), bfhi(u.y)};
;                         ss[r] += (y[r][j].x * y[r][j].x + y[r][j].y * y[r][j].y) + (y[r][j].z * y[r][j].z + y[r][j].w * y[r][j].w); }
; #pragma unroll
;                 for (int off = 1; off < 64; off <<= 1) { ss[0] += __shfl_xor(ss[0], off); ss[1] += __shfl_xor(ss[1], off); }
; #pragma unroll
;                 for (int r = 0; r < 2; ++r) { const float rs = __builtin_amdgcn_rsqf(ss[r] * (1.f / DM) + EPS);
; #pragma unroll
;                     for (int j = 0; j < 4; ++j) x[r][j] = x[r][j] + gp[j] * (y[r][j] * rs); }
;             }
; #pragma unroll
;             for (int r = 0; r < 2; ++r)
; #pragma unroll
;                 for (int j = 0; j < 4; ++j) { if (hasprev) { if (dbf) { u32x2 w; w.x = cvtpk(x[r][j].x, x[r][j].y); w.y = cvtpk(x[r][j].z, x[r][j].w); *(u32x2*)(xdstb + (m + r) * DM + 4 * lane + 256 * j) = w; } else *(f32x4*)(xdst + (m + r) * DM + 4 * lane + 256 * j) = x[r][j]; } }
.Lrw_LAST_l3_e:
	s_waitcnt vmcnt(32)
	v_lshlrev_b32_e32 v200, 16, v64
	v_and_b32_e32 v201, 0xffff0000, v64
	v_pk_mul_f32 v[204:205], v[200:201], v[200:201]
	v_lshlrev_b32_e32 v202, 16, v65
	v_and_b32_e32 v203, 0xffff0000, v65
	v_pk_mul_f32 v[206:207], v[202:203], v[202:203]
	v_lshlrev_b32_e32 v200, 16, v66
	v_and_b32_e32 v201, 0xffff0000, v66
	v_pk_fma_f32 v[204:205], v[200:201], v[200:201], v[204:205]
	v_lshlrev_b32_e32 v202, 16, v67
	v_and_b32_e32 v203, 0xffff0000, v67
	v_pk_fma_f32 v[206:207], v[202:203], v[202:203], v[206:207]
	v_lshlrev_b32_e32 v200, 16, v68
	v_and_b32_e32 v201, 0xffff0000, v68
	v_pk_fma_f32 v[204:205], v[200:201], v[200:201], v[204:205]
	v_lshlrev_b32_e32 v202, 16, v69
	v_and_b32_e32 v203, 0xffff0000, v69
	v_pk_fma_f32 v[206:207], v[202:203], v[202:203], v[206:207]
	v_lshlrev_b32_e32 v200, 16, v70
	v_and_b32_e32 v201, 0xffff0000, v70
	v_pk_fma_f32 v[204:205], v[200:201], v[200:201], v[204:205]
	v_lshlrev_b32_e32 v202, 16, v71
	v_and_b32_e32 v203, 0xffff0000, v71
	v_pk_fma_f32 v[206:207], v[202:203], v[202:203], v[206:207]
	v_pk_add_f32 v[204:205], v[204:205], v[206:207]
	v_add_f32_e32 v208, v204, v205
	v_lshlrev_b32_e32 v184, 16, v56
	v_and_b32_e32 v185, 0xffff0000, v56
	v_add_f32_dpp v208, v208, v208 quad_perm:[1,0,3,2] row_mask:0xf bank_mask:0xf
	v_lshlrev_b32_e32 v186, 16, v57
	v_and_b32_e32 v187, 0xffff0000, v57
	v_add_f32_dpp v208, v208, v208 quad_perm:[2,3,0,1] row_mask:0xf bank_mask:0xf
	v_lshlrev_b32_e32 v188, 16, v58
	v_and_b32_e32 v189, 0xffff0000, v58
	v_add_f32_dpp v208, v208, v208 row_half_mirror row_mask:0xf bank_mask:0xf
	v_lshlrev_b32_e32 v190, 16, v59
	v_and_b32_e32 v191, 0xffff0000, v59
	v_add_f32_dpp v208, v208, v208 row_mirror row_mask:0xf bank_mask:0xf
	v_lshlrev_b32_e32 v192, 16, v60
	v_and_b32_e32 v193, 0xffff0000, v60
	v_add_f32_dpp v208, v208, v208 row_bcast:15 row_mask:0xa bank_mask:0xf
	v_lshlrev_b32_e32 v194, 16, v61
	v_and_b32_e32 v195, 0xffff0000, v61
	v_add_f32_dpp v208, v208, v208 row_bcast:31 row_mask:0xc bank_mask:0xf
	v_lshlrev_b32_e32 v196, 16, v62
	v_and_b32_e32 v197, 0xffff0000, v62
	v_readlane_b32 s60, v208, 63
	s_nop 1
	v_lshlrev_b32_e32 v198, 16, v63
	v_and_b32_e32 v199, 0xffff0000, v63
	v_mov_b32_e32 v210, s60
	v_fmaak_f32 v210, v210, v212, 0x358637bd
	v_rsq_f32_e32 v210, v210
	s_nop 0
	v_lshlrev_b32_e32 v200, 16, v64
	v_and_b32_e32 v201, 0xffff0000, v64
	v_pk_mul_f32 v[200:201], v[200:201], v[210:211] op_sel_hi:[1,0]
	v_pk_fma_f32 v[184:185], v[8:9], v[200:201], v[184:185]
	v_lshlrev_b32_e32 v202, 16, v65
	v_and_b32_e32 v203, 0xffff0000, v65
	v_pk_mul_f32 v[202:203], v[202:203], v[210:211] op_sel_hi:[1,0]
	v_pk_fma_f32 v[186:187], v[10:11], v[202:203], v[186:187]
	v_lshlrev_b32_e32 v200, 16, v66
	v_and_b32_e32 v201, 0xffff0000, v66
	v_pk_mul_f32 v[200:201], v[200:201], v[210:211] op_sel_hi:[1,0]
	v_pk_fma_f32 v[188:189], v[12:13], v[200:201], v[188:189]
	v_lshlrev_b32_e32 v202, 16, v67
	v_and_b32_e32 v203, 0xffff0000, v67
	v_pk_mul_f32 v[202:203], v[202:203], v[210:211] op_sel_hi:[1,0]
	v_pk_fma_f32 v[190:191], v[14:15], v[202:203], v[190:191]
	v_lshlrev_b32_e32 v200, 16, v68
	v_and_b32_e32 v201, 0xffff0000, v68
	v_pk_mul_f32 v[200:201], v[200:201], v[210:211] op_sel_hi:[1,0]
	v_pk_fma_f32 v[192:193], v[16:17], v[200:201], v[192:193]
	v_lshlrev_b32_e32 v202, 16, v69
	v_and_b32_e32 v203, 0xffff0000, v69
	v_pk_mul_f32 v[202:203], v[202:203], v[210:211] op_sel_hi:[1,0]
	v_pk_fma_f32 v[194:195], v[18:19], v[202:203], v[194:195]
	v_lshlrev_b32_e32 v200, 16, v70
	v_and_b32_e32 v201, 0xffff0000, v70
	v_pk_mul_f32 v[200:201], v[200:201], v[210:211] op_sel_hi:[1,0]
	v_pk_fma_f32 v[196:197], v[20:21], v[200:201], v[196:197]
	v_lshlrev_b32_e32 v202, 16, v71
	v_and_b32_e32 v203, 0xffff0000, v71
	v_pk_mul_f32 v[202:203], v[202:203], v[210:211] op_sel_hi:[1,0]
	v_pk_fma_f32 v[198:199], v[22:23], v[202:203], v[198:199]
	s_add_i32 s81, s80, 3
	s_add_i32 s81, s81, s82
	s_and_b32 s81, s81, 31
	s_lshl_b32 s83, s81, 12
	v_add_u32_e32 v213, s83, v3
	global_store_dwordx4 v213, v[184:187], s[76:77] nt
	global_store_dwordx4 v213, v[188:191], s[76:77] offset:16 nt
	global_store_dwordx4 v213, v[192:195], s[76:77] offset:2048 nt
	global_store_dwordx4 v213, v[196:199], s[76:77] offset:2064 nt
	s_add_i32 s81, s82, 8
	s_cmp_lt_u32 s81, 32
	s_cbranch_scc0 .Lrw_LAST_l4_d
	s_add_i32 s81, s80, 8
	s_add_i32 s81, s81, s82
	s_and_b32 s81, s81, 31
	s_lshl_b32 s83, s81, 11
	v_add_u32_e32 v2, s83, v1
	global_load_dwordx4 v[136:139], v2, s[72:73] nt
	global_load_dwordx4 v[140:143], v2, s[72:73] offset:1024 nt
	global_load_dwordx4 v[144:147], v2, s[74:75] nt
	global_load_dwordx4 v[148:151], v2, s[74:75] offset:1024 nt
	s_branch .Lrw_LAST_l4_e

; __device__ __forceinline__ float bflo(unsigned u) { return __uint_as_float(u << 16); }
; __device__ __forceinline__ void phase_rowwise(const void* xsrc_, bool sbf, void* xdst_, bool dbf, const bf16_t* Y, bf16_t* H, const float* mods, int lprev, int iprev, const float* lnpost, float resw, ...
;     ...
;         for (int rr = 0; rr < 32; rr += 2) {
;             const size_t m = (size_t)ch * 32 + rr;
;             f32x4 x[2][4]; u32x2 yr[2][4];
; #pragma unroll
;             for (int r = 0; r < 2; ++r)
; #pragma unroll
;                 for (int j = 0; j < 4; ++j) { if (sbf) { const u32x2 u = xnb[r][j]; x[r][j] = (f32x4){bflo(u.x), bfhi(u.x), bflo(u.y), bfhi(u.y)}; } else x[r][j] = xn[r][j]; yr[r][j] = yn[r][j]; }
;             if (rr + 2 < 32) {
; #pragma unroll
;                 for (int r = 0; r < 2; ++r)
; #pragma unroll
;                     for (int j = 0; j < 4; ++j) { if (sbf) xnb[r][j] = *(const u32x2*)(xsrcb + (m + 2 + r) * DM + 4 * lane + 256 * j); else xn[r][j] = *(const f32x4*)(xsrc + (m + 2 + r) * DM + 4 * lane + 256 * j); if (hasprev) yn[r][j] = *(const u32x2*)(Y + (m + 2 + r) * DM + 4 * lane + 256 * j); } }
;             if (hasprev) {
;                 f32x4 y[2][4]; float ss[2] = {0.f, 0.f};
; #pragma unroll
;                 for (int r = 0; r < 2; ++r)
; #pragma unroll
;                     for (int j = 0; j < 4; ++j) { const u32x2 u = yr[r][j]; y[r][j] = (f32x4){bflo(u.x), bfhi(u.x), bflo(u.y), bfhi(u.y)};
;                         ss[r] += (y[r][j].x * y[r][j].x + y[r][j].y * y[r][j].y) + (y[r][j].z * y[r][j].z + y[r][j].w * y[r][j].w); }
; #pragma unroll
;                 for (int off = 1; off < 64; off <<= 1) { ss[0] += __shfl_xor(ss[0], off); ss[1] += __shfl_xor(ss[1], off); }
; #pragma unroll
;                 for (int r = 0; r < 2; ++r) { const float rs = __builtin_amdgcn_rsqf(ss[r] * (1.f / DM) + EPS);
; #pragma unroll
;                     for (int j = 0; j < 4; ++j) x[r][j] = x[r][j] + gp[j] * (y[r][j] * rs); }
;             }
; #pragma unroll
;             for (int r = 0; r < 2; ++r)
; #pragma unroll
;                 for (int j = 0; j < 4; ++j) { if (hasprev) { if (dbf) { u32x2 w; w.x = cvtpk(x[r][j].x, x[r][j].y); w.y = cvtpk(x[r][j].z, x[r][j].w); *(u32x2*)(xdstb + (m + r) * DM + 4 * lane + 256 * j) = w; } else *(f32x4*)(xdst + (m + r) * DM + 4 * lane + 256 * j) = x[r][j]; } }
.Lrw_LAST_l4_e:
	s_waitcnt vmcnt(32)
	v_lshlrev_b32_e32 v200, 16, v80
	v_and_b32_e32 v201, 0xffff0000, v80
	v_pk_mul_f32 v[204:205], v[200:201], v[200:201]
	v_lshlrev_b32_e32 v202, 16, v81
	v_and_b32_e32 v203, 0xffff0000, v81
	v_pk_mul_f32 v[206:207], v[202:203], v[202:203]
	v_lshlrev_b32_e32 v200, 16, v82
	v_and_b32_e32 v201, 0xffff0000, v82
	v_pk_fma_f32 v[204:205], v[200:201], v[200:201], v[204:205]
	v_lshlrev_b32_e32 v202, 16, v83
	v_and_b32_e32 v203, 0xffff0000, v83
	v_pk_fma_f32 v[206:207], v[202:203], v[202:203], v[206:207]
	v_lshlrev_b32_e32 v200, 16, v84
	v_and_b32_e32 v201, 0xffff0000, v84
	v_pk_fma_f32 v[204:205], v[200:201], v[200:201], v[204:205]
	v_lshlrev_b32_e32 v202, 16, v85
	v_and_b32_e32 v203, 0xffff0000, v85
	v_pk_fma_f32 v[206:207], v[202:203], v[202:203], v[206:207]
	v_lshlrev_b32_e32 v200, 16, v86
	v_and_b32_e32 v201, 0xffff0000, v86
	v_pk_fma_f32 v[204:205], v[200:201], v[200:201], v[204:205]
	v_lshlrev_b32_e32 v202, 16, v87
	v_and_b32_e32 v203, 0xffff0000, v87
	v_pk_fma_f32 v[206:207], v[202:203], v[202:203], v[206:207]
	v_pk_add_f32 v[204:205], v[204:205], v[206:207]
	v_add_f32_e32 v208, v204, v205
	v_lshlrev_b32_e32 v184, 16, v72
	v_and_b32_e32 v185, 0xffff0000, v72
	v_add_f32_dpp v208, v208, v208 quad_perm:[1,0,3,2] row_mask:0xf bank_mask:0xf
	v_lshlrev_b32_e32 v186, 16, v73
	v_and_b32_e32 v187, 0xffff0000, v73
	v_add_f32_dpp v208, v208, v208 quad_perm:[2,3,0,1] row_mask:0xf bank_mask:0xf
	v_lshlrev_b32_e32 v188, 16, v74
	v_and_b32_e32 v189, 0xffff0000, v74
	v_add_f32_dpp v208, v208, v208 row_half_mirror row_mask:0xf bank_mask:0xf
	v_lshlrev_b32_e32 v190, 16, v75
	v_and_b32_e32 v191, 0xffff0000, v75
	v_add_f32_dpp v208, v208, v208 row_mirror row_mask:0xf bank_mask:0xf
	v_lshlrev_b32_e32 v192, 16, v76
	v_and_b32_e32 v193, 0xffff0000, v76
	v_add_f32_dpp v208, v208, v208 row_bcast:15 row_mask:0xa bank_mask:0xf
	v_lshlrev_b32_e32 v194, 16, v77
	v_and_b32_e32 v195, 0xffff0000, v77
	v_add_f32_dpp v208, v208, v208 row_bcast:31 row_mask:0xc bank_mask:0xf
	v_lshlrev_b32_e32 v196, 16, v78
	v_and_b32_e32 v197, 0xffff0000, v78
	v_readlane_b32 s60, v208, 63
	s_nop 1
	v_lshlrev_b32_e32 v198, 16, v79
	v_and_b32_e32 v199, 0xffff0000, v79
	v_mov_b32_e32 v210, s60
	v_fmaak_f32 v210, v210, v212, 0x358637bd
	v_rsq_f32_e32 v210, v210
	s_nop 0
	v_lshlrev_b32_e32 v200, 16, v80
	v_and_b32_e32 v201, 0xffff0000, v80
	v_pk_mul_f32 v[200:201], v[200:201], v[210:211] op_sel_hi:[1,0]
	v_pk_fma_f32 v[184:185], v[8:9], v[200:201], v[184:185]
	v_lshlrev_b32_e32 v202, 16, v81
	v_and_b32_e32 v203, 0xffff0000, v81
	v_pk_mul_f32 v[202:203], v[202:203], v[210:211] op_sel_hi:[1,0]
	v_pk_fma_f32 v[186:187], v[10:11], v[202:203], v[186:187]
	v_lshlrev_b32_e32 v200, 16, v82
	v_and_b32_e32 v201, 0xffff0000, v82
	v_pk_mul_f32 v[200:201], v[200:201], v[210:211] op_sel_hi:[1,0]
	v_pk_fma_f32 v[188:189], v[12:13], v[200:201], v[188:189]
	v_lshlrev_b32_e32 v202, 16, v83
	v_and_b32_e32 v203, 0xffff0000, v83
	v_pk_mul_f32 v[202:203], v[202:203], v[210:211] op_sel_hi:[1,0]
	v_pk_fma_f32 v[190:191], v[14:15], v[202:203], v[190:191]
	v_lshlrev_b32_e32 v200, 16, v84
	v_and_b32_e32 v201, 0xffff0000, v84
	v_pk_mul_f32 v[200:201], v[200:201], v[210:211] op_sel_hi:[1,0]
	v_pk_fma_f32 v[192:193], v[16:17], v[200:201], v[192:193]
	v_lshlrev_b32_e32 v202, 16, v85
	v_and_b32_e32 v203, 0xffff0000, v85
	v_pk_mul_f32 v[202:203], v[202:203], v[210:211] op_sel_hi:[1,0]
	v_pk_fma_f32 v[194:195], v[18:19], v[202:203], v[194:195]
	v_lshlrev_b32_e32 v200, 16, v86
	v_and_b32_e32 v201, 0xffff0000, v86
	v_pk_mul_f32 v[200:201], v[200:201], v[210:211] op_sel_hi:[1,0]
	v_pk_fma_f32 v[196:197], v[20:21], v[200:201], v[196:197]
	v_lshlrev_b32_e32 v202, 16, v87
	v_and_b32_e32 v203, 0xffff0000, v87
	v_pk_mul_f32 v[202:203], v[202:203], v[210:211] op_sel_hi:[1,0]
	v_pk_fma_f32 v[198:199], v[22:23], v[202:203], v[198:199]
	s_add_i32 s81, s80, 4
	s_add_i32 s81, s81, s82
	s_and_b32 s81, s81, 31
	s_lshl_b32 s83, s81, 12
	v_add_u32_e32 v213, s83, v3
	global_store_dwordx4 v213, v[184:187], s[76:77] nt
	global_store_dwordx4 v213, v[188:191], s[76:77] offset:16 nt
	global_store_dwordx4 v213, v[192:195], s[76:77] offset:2048 nt
	global_store_dwordx4 v213, v[196:199], s[76:77] offset:2064 nt
	s_add_i32 s81, s82, 9
	s_cmp_lt_u32 s81, 32
	s_cbranch_scc0 .Lrw_LAST_l5_d
	s_add_i32 s81, s80, 9
	s_add_i32 s81, s81, s82
	s_and_b32 s81, s81, 31
	s_lshl_b32 s83, s81, 11
	v_add_u32_e32 v2, s83, v1
	global_load_dwordx4 v[152:155], v2, s[72:73] nt
	global_load_dwordx4 v[156:159], v2, s[72:73] offset:1024 nt
	global_load_dwordx4 v[160:163], v2, s[74:75] nt
	global_load_dwordx4 v[164:167], v2, s[74:75] offset:1024 nt
	s_branch .Lrw_LAST_l5_e

; __device__ __forceinline__ float bflo(unsigned u) { return __uint_as_float(u << 16); }
; __device__ __forceinline__ void phase_rowwise(const void* xsrc_, bool sbf, void* xdst_, bool dbf, const bf16_t* Y, bf16_t* H, const float* mods, int lprev, int iprev, const float* lnpost, float resw, ...
;     ...
;         for (int rr = 0; rr < 32; rr += 2) {
;             const size_t m = (size_t)ch * 32 + rr;
;             f32x4 x[2][4]; u32x2 yr[2][4];
; #pragma unroll
;             for (int r = 0; r < 2; ++r)
; #pragma unroll
;                 for (int j = 0; j < 4; ++j) { if (sbf) { const u32x2 u = xnb[r][j]; x[r][j] = (f32x4){bflo(u.x), bfhi(u.x), bflo(u.y), bfhi(u.y)}; } else x[r][j] = xn[r][j]; yr[r][j] = yn[r][j]; }
;             if (rr + 2 < 32) {
; #pragma unroll
;                 for (int r = 0; r < 2; ++r)
; #pragma unroll
;                     for (int j = 0; j < 4; ++j) { if (sbf) xnb[r][j] = *(const u32x2*)(xsrcb + (m + 2 + r) * DM + 4 * lane + 256 * j); else xn[r][j] = *(const f32x4*)(xsrc + (m + 2 + r) * DM + 4 * lane + 256 * j); if (hasprev) yn[r][j] = *(const u32x2*)(Y + (m + 2 + r) * DM + 4 * lane + 256 * j); } }
;             if (hasprev) {
;                 f32x4 y[2][4]; float ss[2] = {0.f, 0.f};
; #pragma unroll
;                 for (int r = 0; r < 2; ++r)
; #pragma unroll
;                     for (int j = 0; j < 4; ++j) { const u32x2 u = yr[r][j]; y[r][j] = (f32x4){bflo(u.x), bfhi(u.x), bflo(u.y), bfhi(u.y)};
;                         ss[r] += (y[r][j].x * y[r][j].x + y[r][j].y * y[r][j].y) + (y[r][j].z * y[r][j].z + y[r][j].w * y[r][j].w); }
; #pragma unroll
;                 for (int off = 1; off < 64; off <<= 1) { ss[0] += __shfl_xor(ss[0], off); ss[1] += __shfl_xor(ss[1], off); }
; #pragma unroll
;                 for (int r = 0; r < 2; ++r) { const float rs = __builtin_amdgcn_rsqf(ss[r] * (1.f / DM) + EPS);
; #pragma unroll
;                     for (int j = 0; j < 4; ++j) x[r][j] = x[r][j] + gp[j] * (y[r][j] * rs); }
;             }
; #pragma unroll
;             for (int r = 0; r < 2; ++r)
; #pragma unroll
;                 for (int j = 0; j < 4; ++j) { if (hasprev) { if (dbf) { u32x2 w; w.x = cvtpk(x[r][j].x, x[r][j].y); w.y = cvtpk(x[r][j].z, x[r][j].w); *(u32x2*)(xdstb + (m + r) * DM + 4 * lane + 256 * j) = w; } else *(f32x4*)(xdst + (m + r) * DM + 4 * lane + 256 * j) = x[r][j]; } }
.Lrw_LAST_l5_e:
	s_waitcnt vmcnt(32)
	v_lshlrev_b32_e32 v200, 16, v96
	v_and_b32_e32 v201, 0xffff0000, v96
	v_pk_mul_f32 v[204:205], v[200:201], v[200:201]
	v_lshlrev_b32_e32 v202, 16, v97
	v_and_b32_e32 v203, 0xffff0000, v97
	v_pk_mul_f32 v[206:207], v[202:203], v[202:203]
	v_lshlrev_b32_e32 v200, 16, v98
	v_and_b32_e32 v201, 0xffff0000, v98
	v_pk_fma_f32 v[204:205], v[200:201], v[200:201], v[204:205]
	v_lshlrev_b32_e32 v202, 16, v99
	v_and_b32_e32 v203, 0xffff0000, v99
	v_pk_fma_f32 v[206:207], v[202:203], v[202:203], v[206:207]
	v_lshlrev_b32_e32 v200, 16, v100
	v_and_b32_e32 v201, 0xffff0000, v100
	v_pk_fma_f32 v[204:205], v[200:201], v[200:201], v[204:205]
	v_lshlrev_b32_e32 v202, 16, v101
	v_and_b32_e32 v203, 0xffff0000, v101
	v_pk_fma_f32 v[206:207], v[202:203], v[202:203], v[206:207]
	v_lshlrev_b32_e32 v200, 16, v102
	v_and_b32_e32 v201, 0xffff0000, v102
	v_pk_fma_f32 v[204:205], v[200:201], v[200:201], v[204:205]
	v_lshlrev_b32_e32 v202, 16, v103
	v_and_b32_e32 v203, 0xffff0000, v103
	v_pk_fma_f32 v[206:207], v[202:203], v[202:203], v[206:207]
	v_pk_add_f32 v[204:205], v[204:205], v[206:207]
	v_add_f32_e32 v208, v204, v205
	v_lshlrev_b32_e32 v184, 16, v88
	v_and_b32_e32 v185, 0xffff0000, v88
	v_add_f32_dpp v208, v208, v208 quad_perm:[1,0,3,2] row_mask:0xf bank_mask:0xf
	v_lshlrev_b32_e32 v186, 16, v89
	v_and_b32_e32 v187, 0xffff0000, v89
	v_add_f32_dpp v208, v208, v208 quad_perm:[2,3,0,1] row_mask:0xf bank_mask:0xf
	v_lshlrev_b32_e32 v188, 16, v90
	v_and_b32_e32 v189, 0xffff0000, v90
	v_add_f32_dpp v208, v208, v208 row_half_mirror row_mask:0xf bank_mask:0xf
	v_lshlrev_b32_e32 v190, 16, v91
	v_and_b32_e32 v191, 0xffff0000, v91
	v_add_f32_dpp v208, v208, v208 row_mirror row_mask:0xf bank_mask:0xf
	v_lshlrev_b32_e32 v192, 16, v92
	v_and_b32_e32 v193, 0xffff0000, v92
	v_add_f32_dpp v208, v208, v208 row_bcast:15 row_mask:0xa bank_mask:0xf
	v_lshlrev_b32_e32 v194, 16, v93
	v_and_b32_e32 v195, 0xffff0000, v93
	v_add_f32_dpp v208, v208, v208 row_bcast:31 row_mask:0xc bank_mask:0xf
	v_lshlrev_b32_e32 v196, 16, v94
	v_and_b32_e32 v197, 0xffff0000, v94
	v_readlane_b32 s60, v208, 63
	s_nop 1
	v_lshlrev_b32_e32 v198, 16, v95
	v_and_b32_e32 v199, 0xffff0000, v95
	v_mov_b32_e32 v210, s60
	v_fmaak_f32 v210, v210, v212, 0x358637bd
	v_rsq_f32_e32 v210, v210
	s_nop 0
	v_lshlrev_b32_e32 v200, 16, v96
	v_and_b32_e32 v201, 0xffff0000, v96
	v_pk_mul_f32 v[200:201], v[200:201], v[210:211] op_sel_hi:[1,0]
	v_pk_fma_f32 v[184:185], v[8:9], v[200:201], v[184:185]
	v_lshlrev_b32_e32 v202, 16, v97
	v_and_b32_e32 v203, 0xffff0000, v97
	v_pk_mul_f32 v[202:203], v[202:203], v[210:211] op_sel_hi:[1,0]
	v_pk_fma_f32 v[186:187], v[10:11], v[202:203], v[186:187]
	v_lshlrev_b32_e32 v200, 16, v98
	v_and_b32_e32 v201, 0xffff0000, v98
	v_pk_mul_f32 v[200:201], v[200:201], v[210:211] op_sel_hi:[1,0]
	v_pk_fma_f32 v[188:189], v[12:13], v[200:201], v[188:189]
	v_lshlrev_b32_e32 v202, 16, v99
	v_and_b32_e32 v203, 0xffff0000, v99
	v_pk_mul_f32 v[202:203], v[202:203], v[210:211] op_sel_hi:[1,0]
	v_pk_fma_f32 v[190:191], v[14:15], v[202:203], v[190:191]
	v_lshlrev_b32_e32 v200, 16, v100
	v_and_b32_e32 v201, 0xffff0000, v100
	v_pk_mul_f32 v[200:201], v[200:201], v[210:211] op_sel_hi:[1,0]
	v_pk_fma_f32 v[192:193], v[16:17], v[200:201], v[192:193]
	v_lshlrev_b32_e32 v202, 16, v101
	v_and_b32_e32 v203, 0xffff0000, v101
	v_pk_mul_f32 v[202:203], v[202:203], v[210:211] op_sel_hi:[1,0]
	v_pk_fma_f32 v[194:195], v[18:19], v[202:203], v[194:195]
	v_lshlrev_b32_e32 v200, 16, v102
	v_and_b32_e32 v201, 0xffff0000, v102
	v_pk_mul_f32 v[200:201], v[200:201], v[210:211] op_sel_hi:[1,0]
	v_pk_fma_f32 v[196:197], v[20:21], v[200:201], v[196:197]
	v_lshlrev_b32_e32 v202, 16, v103
	v_and_b32_e32 v203, 0xffff0000, v103
	v_pk_mul_f32 v[202:203], v[202:203], v[210:211] op_sel_hi:[1,0]
	v_pk_fma_f32 v[198:199], v[22:23], v[202:203], v[198:199]
	s_add_i32 s81, s80, 5
	s_add_i32 s81, s81, s82
	s_and_b32 s81, s81, 31
	s_lshl_b32 s83, s81, 12
	v_add_u32_e32 v213, s83, v3
	global_store_dwordx4 v213, v[184:187], s[76:77] nt
	global_store_dwordx4 v213, v[188:191], s[76:77] offset:16 nt
	global_store_dwordx4 v213, v[192:195], s[76:77] offset:2048 nt
	global_store_dwordx4 v213, v[196:199], s[76:77] offset:2064 nt
	s_add_i32 s81, s82, 10
	s_cmp_lt_u32 s81, 32
	s_cbranch_scc0 .Lrw_LAST_l6_d
	s_add_i32 s81, s80, 10
	s_add_i32 s81, s81, s82
	s_and_b32 s81, s81, 31
	s_lshl_b32 s83, s81, 11
	v_add_u32_e32 v2, s83, v1
	global_load_dwordx4 v[56:59], v2, s[72:73] nt
	global_load_dwordx4 v[60:63], v2, s[72:73] offset:1024 nt
	global_load_dwordx4 v[64:67], v2, s[74:75] nt
	global_load_dwordx4 v[68:71], v2, s[74:75] offset:1024 nt
	s_branch .Lrw_LAST_l6_e

; __device__ __forceinline__ float bflo(unsigned u) { return __uint_as_float(u << 16); }
; __device__ __forceinline__ void phase_rowwise(const void* xsrc_, bool sbf, void* xdst_, bool dbf, const bf16_t* Y, bf16_t* H, const float* mods, int lprev, int iprev, const float* lnpost, float resw, ...
;     ...
;         for (int rr = 0; rr < 32; rr += 2) {
;             const size_t m = (size_t)ch * 32 + rr;
;             f32x4 x[2][4]; u32x2 yr[2][4];
; #pragma unroll
;             for (int r = 0; r < 2; ++r)
; #pragma unroll
;                 for (int j = 0; j < 4; ++j) { if (sbf) { const u32x2 u = xnb[r][j]; x[r][j] = (f32x4){bflo(u.x), bfhi(u.x), bflo(u.y), bfhi(u.y)}; } else x[r][j] = xn[r][j]; yr[r][j] = yn[r][j]; }
;             if (rr + 2 < 32) {
; #pragma unroll
;                 for (int r = 0; r < 2; ++r)
; #pragma unroll
;                     for (int j = 0; j < 4; ++j) { if (sbf) xnb[r][j] = *(const u32x2*)(xsrcb + (m + 2 + r) * DM + 4 * lane + 256 * j); else xn[r][j] = *(const f32x4*)(xsrc + (m + 2 + r) * DM + 4 * lane + 256 * j); if (hasprev) yn[r][j] = *(const u32x2*)(Y + (m + 2 + r) * DM + 4 * lane + 256 * j); } }
;             if (hasprev) {
;                 f32x4 y[2][4]; float ss[2] = {0.f, 0.f};
; #pragma unroll
;                 for (int r = 0; r < 2; ++r)
; #pragma unroll
;                     for (int j = 0; j < 4; ++j) { const u32x2 u = yr[r][j]; y[r][j] = (f32x4){bflo(u.x), bfhi(u.x), bflo(u.y), bfhi(u.y)};
;                         ss[r] += (y[r][j].x * y[r][j].x + y[r][j].y * y[r][j].y) + (y[r][j].z * y[r][j].z + y[r][j].w * y[r][j].w); }
; #pragma unroll
;                 for (int off = 1; off < 64; off <<= 1) { ss[0] += __shfl_xor(ss[0], off); ss[1] += __shfl_xor(ss[1], off); }
; #pragma unroll
;                 for (int r = 0; r < 2; ++r) { const float rs = __builtin_amdgcn_rsqf(ss[r] * (1.f / DM) + EPS);
; #pragma unroll
;                     for (int j = 0; j < 4; ++j) x[r][j] = x[r][j] + gp[j] * (y[r][j] * rs); }
;             }
; #pragma unroll
;             for (int r = 0; r < 2; ++r)
; #pragma unroll
;                 for (int j = 0; j < 4; ++j) { if (hasprev) { if (dbf) { u32x2 w; w.x = cvtpk(x[r][j].x, x[r][j].y); w.y = cvtpk(x[r][j].z, x[r][j].w); *(u32x2*)(xdstb + (m + r) * DM + 4 * lane + 256 * j) = w; } else *(f32x4*)(xdst + (m + r) * DM + 4 * lane + 256 * j) = x[r][j]; } }
.Lrw_LAST_l6_e:
	s_waitcnt vmcnt(32)
	v_lshlrev_b32_e32 v200, 16, v112
	v_and_b32_e32 v201, 0xffff0000, v112
	v_pk_mul_f32 v[204:205], v[200:201], v[200:201]
	v_lshlrev_b32_e32 v202, 16, v113
	v_and_b32_e32 v203, 0xffff0000, v113
	v_pk_mul_f32 v[206:207], v[202:203], v[202:203]
	v_lshlrev_b32_e32 v200, 16, v114
	v_and_b32_e32 v201, 0xffff0000, v114
	v_pk_fma_f32 v[204:205], v[200:201], v[200:201], v[204:205]
	v_lshlrev_b32_e32 v202, 16, v115
	v_and_b32_e32 v203, 0xffff0000, v115
	v_pk_fma_f32 v[206:207], v[202:203], v[202:203], v[206:207]
	v_lshlrev_b32_e32 v200, 16, v116
	v_and_b32_e32 v201, 0xffff0000, v116
	v_pk_fma_f32 v[204:205], v[200:201], v[200:201], v[204:205]
	v_lshlrev_b32_e32 v202, 16, v117
	v_and_b32_e32 v203, 0xffff0000, v117
	v_pk_fma_f32 v[206:207], v[202:203], v[202:203], v[206:207]
	v_lshlrev_b32_e32 v200, 16, v118
	v_and_b32_e32 v201, 0xffff0000, v118
	v_pk_fma_f32 v[204:205], v[200:201], v[200:201], v[204:205]
	v_lshlrev_b32_e32 v202, 16, v119
	v_and_b32_e32 v203, 0xffff0000, v119
	v_pk_fma_f32 v[206:207], v[202:203], v[202:203], v[206:207]
	v_pk_add_f32 v[204:205], v[204:205], v[206:207]
	v_add_f32_e32 v208, v204, v205
	v_lshlrev_b32_e32 v184, 16, v104
	v_and_b32_e32 v185, 0xffff0000, v104
	v_add_f32_dpp v208, v208, v208 quad_perm:[1,0,3,2] row_mask:0xf bank_mask:0xf
	v_lshlrev_b32_e32 v186, 16, v105
	v_and_b32_e32 v187, 0xffff0000, v105
	v_add_f32_dpp v208, v208, v208 quad_perm:[2,3,0,1] row_mask:0xf bank_mask:0xf
	v_lshlrev_b32_e32 v188, 16, v106
	v_and_b32_e32 v189, 0xffff0000, v106
	v_add_f32_dpp v208, v208, v208 row_half_mirror row_mask:0xf bank_mask:0xf
	v_lshlrev_b32_e32 v190, 16, v107
	v_and_b32_e32 v191, 0xffff0000, v107
	v_add_f32_dpp v208, v208, v208 row_mirror row_mask:0xf bank_mask:0xf
	v_lshlrev_b32_e32 v192, 16, v108
	v_and_b32_e32 v193, 0xffff0000, v108
	v_add_f32_dpp v208, v208, v208 row_bcast:15 row_mask:0xa bank_mask:0xf
	v_lshlrev_b32_e32 v194, 16, v109
	v_and_b32_e32 v195, 0xffff0000, v109
	v_add_f32_dpp v208, v208, v208 row_bcast:31 row_mask:0xc bank_mask:0xf
	v_lshlrev_b32_e32 v196, 16, v110
	v_and_b32_e32 v197, 0xffff0000, v110
	v_readlane_b32 s60, v208, 63
	s_nop 1
	v_lshlrev_b32_e32 v198, 16, v111
	v_and_b32_e32 v199, 0xffff0000, v111
	v_mov_b32_e32 v210, s60
	v_fmaak_f32 v210, v210, v212, 0x358637bd
	v_rsq_f32_e32 v210, v210
	s_nop 0
	v_lshlrev_b32_e32 v200, 16, v112
	v_and_b32_e32 v201, 0xffff0000, v112
	v_pk_mul_f32 v[200:201], v[200:201], v[210:211] op_sel_hi:[1,0]
	v_pk_fma_f32 v[184:185], v[8:9], v[200:201], v[184:185]
	v_lshlrev_b32_e32 v202, 16, v113
	v_and_b32_e32 v203, 0xffff0000, v113
	v_pk_mul_f32 v[202:203], v[202:203], v[210:211] op_sel_hi:[1,0]
	v_pk_fma_f32 v[186:187], v[10:11], v[202:203], v[186:187]
	v_lshlrev_b32_e32 v200, 16, v114
	v_and_b32_e32 v201, 0xffff0000, v114
	v_pk_mul_f32 v[200:201], v[200:201], v[210:211] op_sel_hi:[1,0]
	v_pk_fma_f32 v[188:189], v[12:13], v[200:201], v[188:189]
	v_lshlrev_b32_e32 v202, 16, v115
	v_and_b32_e32 v203, 0xffff0000, v115
	v_pk_mul_f32 v[202:203], v[202:203], v[210:211] op_sel_hi:[1,0]
	v_pk_fma_f32 v[190:191], v[14:15], v[202:203], v[190:191]
	v_lshlrev_b32_e32 v200, 16, v116
	v_and_b32_e32 v201, 0xffff0000, v116
	v_pk_mul_f32 v[200:201], v[200:201], v[210:211] op_sel_hi:[1,0]
	v_pk_fma_f32 v[192:193], v[16:17], v[200:201], v[192:193]
	v_lshlrev_b32_e32 v202, 16, v117
	v_and_b32_e32 v203, 0xffff0000, v117
	v_pk_mul_f32 v[202:203], v[202:203], v[210:211] op_sel_hi:[1,0]
	v_pk_fma_f32 v[194:195], v[18:19], v[202:203], v[194:195]
	v_lshlrev_b32_e32 v200, 16, v118
	v_and_b32_e32 v201, 0xffff0000, v118
	v_pk_mul_f32 v[200:201], v[200:201], v[210:211] op_sel_hi:[1,0]
	v_pk_fma_f32 v[196:197], v[20:21], v[200:201], v[196:197]
	v_lshlrev_b32_e32 v202, 16, v119
	v_and_b32_e32 v203, 0xffff0000, v119
	v_pk_mul_f32 v[202:203], v[202:203], v[210:211] op_sel_hi:[1,0]
	v_pk_fma_f32 v[198:199], v[22:23], v[202:203], v[198:199]
	s_add_i32 s81, s80, 6
	s_add_i32 s81, s81, s82
	s_and_b32 s81, s81, 31
	s_lshl_b32 s83, s81, 12
	v_add_u32_e32 v213, s83, v3
	global_store_dwordx4 v213, v[184:187], s[76:77] nt
	global_store_dwordx4 v213, v[188:191], s[76:77] offset:16 nt
	global_store_dwordx4 v213, v[192:195], s[76:77] offset:2048 nt
	global_store_dwordx4 v213, v[196:199], s[76:77] offset:2064 nt
	s_add_i32 s82, s82, 7
	s_cmp_lt_u32 s82, 32
	s_cbranch_scc1 .Lrw_LAST_loop
	s_branch .LBB0_1024
